# epilogue stores write-through (sc1) in GEMM and rms phases
# baseline (speedup 1.0000x reference)
.LBB0_123:
	v_cvt_pk_bf16_f32 v4, v4, v5
	v_cvt_pk_bf16_f32 v5, v6, v7
	v_cvt_pk_bf16_f32 v6, v0, v1
	v_cvt_pk_bf16_f32 v7, v2, v3
	flat_store_dwordx4 v[16:17], v[4:7] offset:256 sc1

.LBB0_135:
	v_mov_b32_e32 v174, v168
	v_mov_b32_e32 v128, v169
	s_cmp_lg_u32 s7, 0
	v_lshl_add_u32 v146, v128, 3, s58
	s_cbranch_scc0 .LBB0_201
	s_cmpk_lt_i32 s6, 0x800
	s_cselect_b64 s[48:49], -1, 0
	s_cmpk_gt_i32 s6, 0x7ff
	s_cselect_b64 s[4:5], -1, 0
	s_and_b64 vcc, s[4:5], exec
	s_cselect_b32 s5, s64, 0x4800000
	s_cselect_b32 s4, 0xfffff800, 0
	s_add_u32 s46, s20, s5
	s_addc_u32 s47, s21, 0
	s_add_i32 s4, s4, s6
	v_add_u32_e32 v148, s4, v146
	s_add_i32 s4, s3, s57
	v_add_u32_e32 v150, s4, v174
	v_ashrrev_i32_e32 v151, 31, v150
	v_lshlrev_b64 v[128:129], 13, v[150:151]
	v_lshlrev_b64 v[152:153], 11, v[150:151]
	v_lshl_add_u64 v[128:129], s[46:47], 0, v[128:129]
	v_ashrrev_i32_e32 v149, 31, v148
	v_lshl_add_u64 v[156:157], v[148:149], 2, v[128:129]
	s_mov_b64 s[4:5], -1
	v_lshl_add_u64 v[154:155], v[152:153], 1, s[10:11]
	flat_store_dwordx4 v[156:157], v[120:123] sc1
	flat_store_dwordx4 v[156:157], v[124:127] offset:16 sc1
	v_cvt_pk_bf16_f32 v128, v120, v121
	v_cvt_pk_bf16_f32 v129, v122, v123
	v_cvt_pk_bf16_f32 v130, v124, v125
	v_cvt_pk_bf16_f32 v131, v126, v127
	s_cbranch_vccnz .LBB0_138
	v_lshl_add_u64 v[152:153], v[148:149], 1, v[154:155]
	s_mov_b64 s[4:5], 0
	flat_store_dwordx4 v[152:153], v[128:131] sc1

.LBB0_140:
	v_cndmask_b32_e64 v147, 0, 1, s[48:49]
	v_cmp_ne_u32_e64 s[4:5], 1, v147
	s_andn2_b64 vcc, exec, s[48:49]
	s_mov_b64 s[48:49], -1
	flat_store_dwordx4 v[156:157], v[116:119] offset:512 sc1
	flat_store_dwordx4 v[156:157], v[112:115] offset:528 sc1
	v_cvt_pk_bf16_f32 v128, v116, v117
	v_cvt_pk_bf16_f32 v129, v118, v119
	v_cvt_pk_bf16_f32 v130, v112, v113
	v_cvt_pk_bf16_f32 v131, v114, v115
	s_cbranch_vccnz .LBB0_142
	v_lshl_add_u64 v[154:155], v[148:149], 1, v[154:155]
	s_mov_b64 s[48:49], 0
	flat_store_dwordx4 v[154:155], v[128:131] offset:256 sc1

.LBB0_144:
	v_add_u32_e32 v162, 16, v150
	v_ashrrev_i32_e32 v163, 31, v162
	v_lshlrev_b64 v[128:129], 13, v[162:163]
	v_lshlrev_b64 v[158:159], 11, v[162:163]
	v_lshl_add_u64 v[128:129], s[46:47], 0, v[128:129]
	v_lshl_add_u64 v[156:157], v[148:149], 2, v[128:129]
	s_mov_b64 s[48:49], -1
	s_and_b64 vcc, exec, s[4:5]
	v_lshl_add_u64 v[158:159], v[158:159], 1, s[10:11]
	flat_store_dwordx4 v[156:157], v[104:107] sc1
	flat_store_dwordx4 v[156:157], v[108:111] offset:16 sc1
	v_cvt_pk_bf16_f32 v128, v104, v105
	v_cvt_pk_bf16_f32 v129, v106, v107
	v_cvt_pk_bf16_f32 v130, v108, v109
	v_cvt_pk_bf16_f32 v131, v110, v111
	s_cbranch_vccnz .LBB0_146
	v_lshl_add_u64 v[160:161], v[148:149], 1, v[158:159]
	s_mov_b64 s[48:49], 0
	flat_store_dwordx4 v[160:161], v[128:131] sc1

.LBB0_148:
	s_and_b64 vcc, exec, s[4:5]
	s_mov_b64 s[48:49], -1
	flat_store_dwordx4 v[156:157], v[100:103] offset:512 sc1
	flat_store_dwordx4 v[156:157], v[96:99] offset:528 sc1
	v_cvt_pk_bf16_f32 v128, v100, v101
	v_cvt_pk_bf16_f32 v129, v102, v103
	v_cvt_pk_bf16_f32 v130, v96, v97
	v_cvt_pk_bf16_f32 v131, v98, v99
	s_cbranch_vccnz .LBB0_150
	v_lshl_add_u64 v[156:157], v[148:149], 1, v[158:159]
	s_mov_b64 s[48:49], 0
	flat_store_dwordx4 v[156:157], v[128:131] offset:256 sc1

.LBB0_152:
	v_add_u32_e32 v162, 32, v150
	v_ashrrev_i32_e32 v163, 31, v162
	v_lshlrev_b64 v[128:129], 13, v[162:163]
	v_lshlrev_b64 v[158:159], 11, v[162:163]
	v_lshl_add_u64 v[128:129], s[46:47], 0, v[128:129]
	v_lshl_add_u64 v[156:157], v[148:149], 2, v[128:129]
	s_mov_b64 s[48:49], -1
	s_and_b64 vcc, exec, s[4:5]
	v_lshl_add_u64 v[158:159], v[158:159], 1, s[10:11]
	flat_store_dwordx4 v[156:157], v[88:91] sc1
	flat_store_dwordx4 v[156:157], v[92:95] offset:16 sc1
	v_cvt_pk_bf16_f32 v128, v88, v89
	v_cvt_pk_bf16_f32 v129, v90, v91
	v_cvt_pk_bf16_f32 v130, v92, v93
	v_cvt_pk_bf16_f32 v131, v94, v95
	s_cbranch_vccnz .LBB0_154
	v_lshl_add_u64 v[160:161], v[148:149], 1, v[158:159]
	s_mov_b64 s[48:49], 0
	flat_store_dwordx4 v[160:161], v[128:131] sc1

.LBB0_156:
	s_and_b64 vcc, exec, s[4:5]
	s_mov_b64 s[48:49], -1
	flat_store_dwordx4 v[156:157], v[84:87] offset:512 sc1
	flat_store_dwordx4 v[156:157], v[80:83] offset:528 sc1
	v_cvt_pk_bf16_f32 v128, v84, v85
	v_cvt_pk_bf16_f32 v129, v86, v87
	v_cvt_pk_bf16_f32 v130, v80, v81
	v_cvt_pk_bf16_f32 v131, v82, v83
	s_cbranch_vccnz .LBB0_158
	v_lshl_add_u64 v[156:157], v[148:149], 1, v[158:159]
	s_mov_b64 s[48:49], 0
	flat_store_dwordx4 v[156:157], v[128:131] offset:256 sc1

.LBB0_160:
	v_add_u32_e32 v162, 48, v150
	v_ashrrev_i32_e32 v163, 31, v162
	v_lshlrev_b64 v[128:129], 13, v[162:163]
	v_lshlrev_b64 v[158:159], 11, v[162:163]
	v_lshl_add_u64 v[128:129], s[46:47], 0, v[128:129]
	v_lshl_add_u64 v[156:157], v[148:149], 2, v[128:129]
	s_mov_b64 s[48:49], -1
	s_and_b64 vcc, exec, s[4:5]
	v_lshl_add_u64 v[158:159], v[158:159], 1, s[10:11]
	flat_store_dwordx4 v[156:157], v[72:75] sc1
	flat_store_dwordx4 v[156:157], v[76:79] offset:16 sc1
	v_cvt_pk_bf16_f32 v128, v72, v73
	v_cvt_pk_bf16_f32 v129, v74, v75
	v_cvt_pk_bf16_f32 v130, v76, v77
	v_cvt_pk_bf16_f32 v131, v78, v79
	s_cbranch_vccnz .LBB0_162
	v_lshl_add_u64 v[160:161], v[148:149], 1, v[158:159]
	s_mov_b64 s[48:49], 0
	flat_store_dwordx4 v[160:161], v[128:131] sc1

.LBB0_164:
	s_and_b64 vcc, exec, s[4:5]
	s_mov_b64 s[48:49], -1
	flat_store_dwordx4 v[156:157], v[68:71] offset:512 sc1
	flat_store_dwordx4 v[156:157], v[64:67] offset:528 sc1
	v_cvt_pk_bf16_f32 v128, v68, v69
	v_cvt_pk_bf16_f32 v129, v70, v71
	v_cvt_pk_bf16_f32 v130, v64, v65
	v_cvt_pk_bf16_f32 v131, v66, v67
	s_cbranch_vccnz .LBB0_166
	v_lshl_add_u64 v[156:157], v[148:149], 1, v[158:159]
	s_mov_b64 s[48:49], 0
	flat_store_dwordx4 v[156:157], v[128:131] offset:256 sc1

.LBB0_168:
	v_add_u32_e32 v162, 0x80, v150
	v_ashrrev_i32_e32 v163, 31, v162
	v_lshlrev_b64 v[128:129], 13, v[162:163]
	v_lshlrev_b64 v[158:159], 11, v[162:163]
	v_lshl_add_u64 v[128:129], s[46:47], 0, v[128:129]
	v_lshl_add_u64 v[156:157], v[148:149], 2, v[128:129]
	s_mov_b64 s[48:49], -1
	s_and_b64 vcc, exec, s[4:5]
	v_lshl_add_u64 v[158:159], v[158:159], 1, s[10:11]
	flat_store_dwordx4 v[156:157], v[56:59] sc1
	flat_store_dwordx4 v[156:157], v[60:63] offset:16 sc1
	v_cvt_pk_bf16_f32 v128, v56, v57
	v_cvt_pk_bf16_f32 v129, v58, v59
	v_cvt_pk_bf16_f32 v130, v60, v61
	v_cvt_pk_bf16_f32 v131, v62, v63
	s_cbranch_vccnz .LBB0_170
	v_lshl_add_u64 v[160:161], v[148:149], 1, v[158:159]
	s_mov_b64 s[48:49], 0
	flat_store_dwordx4 v[160:161], v[128:131] sc1

.LBB0_172:
	s_and_b64 vcc, exec, s[4:5]
	s_mov_b64 s[48:49], -1
	flat_store_dwordx4 v[156:157], v[52:55] offset:512 sc1
	flat_store_dwordx4 v[156:157], v[48:51] offset:528 sc1
	v_cvt_pk_bf16_f32 v128, v52, v53
	v_cvt_pk_bf16_f32 v129, v54, v55
	v_cvt_pk_bf16_f32 v130, v48, v49
	v_cvt_pk_bf16_f32 v131, v50, v51
	s_cbranch_vccnz .LBB0_174
	v_lshl_add_u64 v[156:157], v[148:149], 1, v[158:159]
	s_mov_b64 s[48:49], 0
	flat_store_dwordx4 v[156:157], v[128:131] offset:256 sc1

.LBB0_176:
	v_add_u32_e32 v162, 0x90, v150
	v_ashrrev_i32_e32 v163, 31, v162
	v_lshlrev_b64 v[128:129], 13, v[162:163]
	v_lshlrev_b64 v[158:159], 11, v[162:163]
	v_lshl_add_u64 v[128:129], s[46:47], 0, v[128:129]
	v_lshl_add_u64 v[156:157], v[148:149], 2, v[128:129]
	s_mov_b64 s[48:49], -1
	s_and_b64 vcc, exec, s[4:5]
	v_lshl_add_u64 v[158:159], v[158:159], 1, s[10:11]
	flat_store_dwordx4 v[156:157], v[40:43] sc1
	flat_store_dwordx4 v[156:157], v[44:47] offset:16 sc1
	v_cvt_pk_bf16_f32 v128, v40, v41
	v_cvt_pk_bf16_f32 v129, v42, v43
	v_cvt_pk_bf16_f32 v130, v44, v45
	v_cvt_pk_bf16_f32 v131, v46, v47
	s_cbranch_vccnz .LBB0_178
	v_lshl_add_u64 v[160:161], v[148:149], 1, v[158:159]
	s_mov_b64 s[48:49], 0
	flat_store_dwordx4 v[160:161], v[128:131] sc1

.LBB0_180:
	s_and_b64 vcc, exec, s[4:5]
	s_mov_b64 s[48:49], -1
	flat_store_dwordx4 v[156:157], v[36:39] offset:512 sc1
	flat_store_dwordx4 v[156:157], v[32:35] offset:528 sc1
	v_cvt_pk_bf16_f32 v128, v36, v37
	v_cvt_pk_bf16_f32 v129, v38, v39
	v_cvt_pk_bf16_f32 v130, v32, v33
	v_cvt_pk_bf16_f32 v131, v34, v35
	s_cbranch_vccnz .LBB0_182
	v_lshl_add_u64 v[156:157], v[148:149], 1, v[158:159]
	s_mov_b64 s[48:49], 0
	flat_store_dwordx4 v[156:157], v[128:131] offset:256 sc1

.LBB0_184:
	v_add_u32_e32 v162, 0xa0, v150
	v_ashrrev_i32_e32 v163, 31, v162
	v_lshlrev_b64 v[128:129], 13, v[162:163]
	v_lshlrev_b64 v[158:159], 11, v[162:163]
	v_lshl_add_u64 v[128:129], s[46:47], 0, v[128:129]
	v_lshl_add_u64 v[156:157], v[148:149], 2, v[128:129]
	s_mov_b64 s[48:49], -1
	s_and_b64 vcc, exec, s[4:5]
	v_lshl_add_u64 v[158:159], v[158:159], 1, s[10:11]
	flat_store_dwordx4 v[156:157], v[24:27] sc1
	flat_store_dwordx4 v[156:157], v[28:31] offset:16 sc1
	v_cvt_pk_bf16_f32 v128, v24, v25
	v_cvt_pk_bf16_f32 v129, v26, v27
	v_cvt_pk_bf16_f32 v130, v28, v29
	v_cvt_pk_bf16_f32 v131, v30, v31
	s_cbranch_vccnz .LBB0_186
	v_lshl_add_u64 v[160:161], v[148:149], 1, v[158:159]
	s_mov_b64 s[48:49], 0
	flat_store_dwordx4 v[160:161], v[128:131] sc1

.LBB0_188:
	s_and_b64 vcc, exec, s[4:5]
	s_mov_b64 s[48:49], -1
	flat_store_dwordx4 v[156:157], v[20:23] offset:512 sc1
	flat_store_dwordx4 v[156:157], v[16:19] offset:528 sc1
	v_cvt_pk_bf16_f32 v128, v20, v21
	v_cvt_pk_bf16_f32 v129, v22, v23
	v_cvt_pk_bf16_f32 v130, v16, v17
	v_cvt_pk_bf16_f32 v131, v18, v19
	s_cbranch_vccnz .LBB0_190
	v_lshl_add_u64 v[156:157], v[148:149], 1, v[158:159]
	s_mov_b64 s[48:49], 0
	flat_store_dwordx4 v[156:157], v[128:131] offset:256 sc1

.LBB0_192:
	v_add_u32_e32 v160, 0xb0, v150
	v_ashrrev_i32_e32 v161, 31, v160
	v_lshlrev_b64 v[128:129], 13, v[160:161]
	v_lshlrev_b64 v[156:157], 11, v[160:161]
	v_lshl_add_u64 v[128:129], s[46:47], 0, v[128:129]
	v_lshl_add_u64 v[150:151], v[148:149], 2, v[128:129]
	s_mov_b64 s[46:47], -1
	s_and_b64 vcc, exec, s[4:5]
	v_lshl_add_u64 v[156:157], v[156:157], 1, s[10:11]
	flat_store_dwordx4 v[150:151], v[8:11] sc1
	flat_store_dwordx4 v[150:151], v[12:15] offset:16 sc1
	v_cvt_pk_bf16_f32 v128, v8, v9
	v_cvt_pk_bf16_f32 v129, v10, v11
	v_cvt_pk_bf16_f32 v130, v12, v13
	v_cvt_pk_bf16_f32 v131, v14, v15
	s_cbranch_vccnz .LBB0_194
	v_lshl_add_u64 v[158:159], v[148:149], 1, v[156:157]
	s_mov_b64 s[46:47], 0
	flat_store_dwordx4 v[158:159], v[128:131] sc1

.LBB0_196:
	s_and_b64 vcc, exec, s[4:5]
	s_mov_b64 s[4:5], -1
	flat_store_dwordx4 v[150:151], v[4:7] offset:512 sc1
	flat_store_dwordx4 v[150:151], v[0:3] offset:528 sc1
	v_cvt_pk_bf16_f32 v128, v4, v5
	v_cvt_pk_bf16_f32 v129, v6, v7
	v_cvt_pk_bf16_f32 v130, v0, v1
	v_cvt_pk_bf16_f32 v131, v2, v3
	s_cbranch_vccnz .LBB0_198
	v_lshl_add_u64 v[148:149], v[148:149], 1, v[156:157]
	s_mov_b64 s[4:5], 0
	flat_store_dwordx4 v[148:149], v[128:131] offset:256 sc1

.LBB0_204:
	s_add_i32 s3, s3, s57
	v_add_u32_e32 v130, s3, v174
	v_mov_b64_e32 v[128:129], s[8:9]
	v_mad_i64_i32 v[128:129], s[4:5], v130, s65, v[128:129]
	s_ashr_i32 s7, s6, 31
	v_ashrrev_i32_e32 v147, 31, v146
	v_lshl_add_u64 v[128:129], s[6:7], 1, v[128:129]
	v_cvt_pk_bf16_f32 v120, v120, v121
	v_cvt_pk_bf16_f32 v121, v122, v123
	v_cvt_pk_bf16_f32 v122, v124, v125
	v_cndmask_b32_e64 v124, 0, 1, s[46:47]
	v_lshl_add_u64 v[128:129], v[146:147], 1, v[128:129]
	v_cmp_ne_u32_e64 s[4:5], 1, v124
	s_andn2_b64 vcc, exec, s[46:47]
	v_cvt_pk_bf16_f32 v123, v126, v127
	flat_store_dwordx4 v[128:129], v[120:123] sc1
	s_cbranch_vccnz .LBB0_206
	v_add_f32_e32 v113, 1.0, v152
	v_add_f32_e32 v114, 1.0, v151
	v_add_f32_e32 v115, 1.0, v150
	v_rcp_f32_e32 v113, v113
	v_rcp_f32_e32 v115, v115
	v_rcp_f32_e32 v114, v114
	v_add_f32_e32 v118, 1.0, v140
	v_add_f32_e32 v112, 1.0, v153
	v_max_f32_e32 v116, 0xda24260, v113
	v_max_f32_e32 v117, 0xda24260, v115
	v_max_f32_e32 v113, 0xda24260, v114
	v_add_f32_e32 v114, 1.0, v149
	v_add_f32_e32 v115, 1.0, v148
	v_rcp_f32_e32 v119, v118
	v_add_f32_e32 v118, 1.0, v131
	v_rcp_f32_e32 v112, v112
	v_rcp_f32_e32 v114, v114
	v_rcp_f32_e32 v115, v115
	v_rcp_f32_e32 v120, v118
	v_max_f32_e32 v112, 0xda24260, v112
	v_max_f32_e32 v114, 0xda24260, v114
	v_max_f32_e32 v118, 0xda24260, v115
	v_max_f32_e32 v115, 0xda24260, v119
	v_max_f32_e32 v119, 0xda24260, v120
.LBB0_206:
	v_cvt_pk_bf16_f32 v124, v116, v117
	v_cvt_pk_bf16_f32 v125, v118, v119
	v_cvt_pk_bf16_f32 v126, v112, v113
	v_mul_f32_e32 v112, 0xbfb8aa3b, v96
	v_mul_f32_e32 v113, 0xbfb8aa3b, v100
	v_mul_f32_e32 v116, 0xbfb8aa3b, v97
	v_mul_f32_e32 v117, 0xbfb8aa3b, v101
	v_mul_f32_e32 v118, 0xbfb8aa3b, v98
	v_mul_f32_e32 v127, 0xbfb8aa3b, v102
	v_mul_f32_e32 v131, 0xbfb8aa3b, v99
	v_mul_f32_e32 v140, 0xbfb8aa3b, v103
	v_exp_f32_e32 v123, v112
	v_exp_f32_e32 v122, v113
	v_exp_f32_e32 v121, v116
	v_exp_f32_e32 v120, v117
	v_exp_f32_e32 v119, v118
	v_exp_f32_e32 v118, v127
	v_exp_f32_e32 v117, v131
	v_exp_f32_e32 v116, v140
	s_and_b64 vcc, exec, s[4:5]
	v_cvt_pk_bf16_f32 v127, v114, v115
	flat_store_dwordx4 v[128:129], v[124:127] offset:256 sc1
	s_cbranch_vccnz .LBB0_208
	v_add_f32_e32 v112, 1.0, v123
	v_rcp_f32_e32 v113, v112
	v_add_f32_e32 v124, 1.0, v119
	v_rcp_f32_e32 v125, v124
	v_add_f32_e32 v126, 1.0, v117
	v_rcp_f32_e32 v127, v126
	v_max_f32_e32 v113, 0xda24260, v113
	v_rcp_f32_e32 v114, v113
	v_add_f32_e32 v113, 1.0, v121
	v_max_f32_e32 v125, 0xda24260, v125
	v_mul_f32_e32 v104, 0xbfb8aa3b, v104
	v_add_f32_e32 v112, 1.0, v122
	v_mul_f32_e32 v108, 0xbfb8aa3b, v108
	v_mul_f32_e32 v105, 0xbfb8aa3b, v105
	v_rcp_f32_e32 v115, v113
	v_add_f32_e32 v113, 1.0, v120
	v_mul_f32_e32 v109, 0xbfb8aa3b, v109
	v_mul_f32_e32 v106, 0xbfb8aa3b, v106
	v_add_f32_e32 v124, 1.0, v118
	v_mul_f32_e32 v110, 0xbfb8aa3b, v110
	v_mul_f32_e32 v111, 0xbfb8aa3b, v111
	v_rcp_f32_e32 v126, v125
	v_max_f32_e32 v125, 0xda24260, v127
	v_mul_f32_e32 v107, 0xbfb8aa3b, v107
	v_add_f32_e32 v127, 1.0, v116
	v_exp_f32_e32 v104, v104
	v_rcp_f32_e32 v112, v112
	v_exp_f32_e32 v108, v108
	v_exp_f32_e32 v105, v105
	v_rcp_f32_e32 v113, v113
	v_exp_f32_e32 v109, v109
	v_exp_f32_e32 v106, v106
	v_rcp_f32_e32 v124, v124
	v_exp_f32_e32 v110, v110
	v_exp_f32_e32 v111, v111
	v_exp_f32_e32 v107, v107
	v_rcp_f32_e32 v128, v127
	v_add_f32_e32 v104, 1.0, v104
	v_max_f32_e32 v112, 0xda24260, v112
	v_add_f32_e32 v108, 1.0, v108
	v_add_f32_e32 v105, 1.0, v105
	v_max_f32_e32 v113, 0xda24260, v113
	v_add_f32_e32 v109, 1.0, v109
	v_max_f32_e32 v115, 0xda24260, v115
	v_add_f32_e32 v106, 1.0, v106
	v_max_f32_e32 v124, 0xda24260, v124
	v_add_f32_e32 v110, 1.0, v110
	v_add_f32_e32 v111, 1.0, v111
	v_rcp_f32_e32 v127, v125
	v_add_f32_e32 v107, 1.0, v107
	v_max_f32_e32 v125, 0xda24260, v128
	v_rcp_f32_e32 v104, v104
	v_rcp_f32_e32 v112, v112
	v_rcp_f32_e32 v108, v108
	v_rcp_f32_e32 v105, v105
	v_rcp_f32_e32 v113, v113
	v_rcp_f32_e32 v109, v109
	v_rcp_f32_e32 v115, v115
	v_rcp_f32_e32 v106, v106
	v_rcp_f32_e32 v124, v124
	v_rcp_f32_e32 v110, v110
	v_rcp_f32_e32 v111, v111
	v_rcp_f32_e32 v107, v107
	v_rcp_f32_e32 v125, v125
	v_pk_mul_f32 v[108:109], v[114:115], v[108:109]
	v_pk_mul_f32 v[110:111], v[126:127], v[110:111]
	v_pk_mul_f32 v[104:105], v[112:113], v[104:105]
	v_pk_mul_f32 v[106:107], v[124:125], v[106:107]
.LBB0_208:
	v_add_u32_e32 v114, 16, v130
	v_mov_b64_e32 v[112:113], s[8:9]
	v_mad_i64_i32 v[112:113], s[46:47], v114, s65, v[112:113]
	v_lshl_add_u64 v[112:113], s[6:7], 1, v[112:113]
	v_lshl_add_u64 v[112:113], v[146:147], 1, v[112:113]
	s_and_b64 vcc, exec, s[4:5]
	v_cvt_pk_bf16_f32 v104, v104, v105
	v_cvt_pk_bf16_f32 v105, v106, v107
	v_cvt_pk_bf16_f32 v106, v108, v109
	v_cvt_pk_bf16_f32 v107, v110, v111
	flat_store_dwordx4 v[112:113], v[104:107] sc1
	s_cbranch_vccnz .LBB0_210
	v_add_f32_e32 v97, 1.0, v122
	v_add_f32_e32 v98, 1.0, v121
	v_add_f32_e32 v99, 1.0, v120
	v_rcp_f32_e32 v97, v97
	v_rcp_f32_e32 v99, v99
	v_rcp_f32_e32 v98, v98
	v_add_f32_e32 v102, 1.0, v117
	v_add_f32_e32 v96, 1.0, v123
	v_max_f32_e32 v100, 0xda24260, v97
	v_max_f32_e32 v101, 0xda24260, v99
	v_max_f32_e32 v97, 0xda24260, v98
	v_add_f32_e32 v98, 1.0, v119
	v_add_f32_e32 v99, 1.0, v118
	v_rcp_f32_e32 v103, v102
	v_add_f32_e32 v102, 1.0, v116
	v_rcp_f32_e32 v96, v96
	v_rcp_f32_e32 v98, v98
	v_rcp_f32_e32 v99, v99
	v_rcp_f32_e32 v104, v102
	v_max_f32_e32 v96, 0xda24260, v96
	v_max_f32_e32 v98, 0xda24260, v98
	v_max_f32_e32 v102, 0xda24260, v99
	v_max_f32_e32 v99, 0xda24260, v103
	v_max_f32_e32 v103, 0xda24260, v104
.LBB0_210:
	v_cvt_pk_bf16_f32 v108, v100, v101
	v_cvt_pk_bf16_f32 v109, v102, v103
	v_cvt_pk_bf16_f32 v110, v96, v97
	v_mul_f32_e32 v96, 0xbfb8aa3b, v80
	v_mul_f32_e32 v97, 0xbfb8aa3b, v84
	v_mul_f32_e32 v100, 0xbfb8aa3b, v81
	v_mul_f32_e32 v101, 0xbfb8aa3b, v85
	v_mul_f32_e32 v102, 0xbfb8aa3b, v82
	v_mul_f32_e32 v111, 0xbfb8aa3b, v86
	v_mul_f32_e32 v114, 0xbfb8aa3b, v83
	v_mul_f32_e32 v115, 0xbfb8aa3b, v87
	v_exp_f32_e32 v107, v96
	v_exp_f32_e32 v106, v97
	v_exp_f32_e32 v105, v100
	v_exp_f32_e32 v104, v101
	v_exp_f32_e32 v103, v102
	v_exp_f32_e32 v102, v111
	v_exp_f32_e32 v101, v114
	v_exp_f32_e32 v100, v115
	s_and_b64 vcc, exec, s[4:5]
	v_cvt_pk_bf16_f32 v111, v98, v99
	flat_store_dwordx4 v[112:113], v[108:111] offset:256 sc1
	s_cbranch_vccnz .LBB0_212
	v_add_f32_e32 v96, 1.0, v107
	v_rcp_f32_e32 v97, v96
	v_add_f32_e32 v108, 1.0, v103
	v_rcp_f32_e32 v109, v108
	v_add_f32_e32 v110, 1.0, v101
	v_rcp_f32_e32 v111, v110
	v_max_f32_e32 v97, 0xda24260, v97
	v_rcp_f32_e32 v98, v97
	v_add_f32_e32 v97, 1.0, v105
	v_max_f32_e32 v109, 0xda24260, v109
	v_mul_f32_e32 v88, 0xbfb8aa3b, v88
	v_add_f32_e32 v96, 1.0, v106
	v_mul_f32_e32 v92, 0xbfb8aa3b, v92
	v_mul_f32_e32 v89, 0xbfb8aa3b, v89
	v_rcp_f32_e32 v99, v97
	v_add_f32_e32 v97, 1.0, v104
	v_mul_f32_e32 v93, 0xbfb8aa3b, v93
	v_mul_f32_e32 v90, 0xbfb8aa3b, v90
	v_add_f32_e32 v108, 1.0, v102
	v_mul_f32_e32 v94, 0xbfb8aa3b, v94
	v_mul_f32_e32 v95, 0xbfb8aa3b, v95
	v_rcp_f32_e32 v110, v109
	v_max_f32_e32 v109, 0xda24260, v111
	v_mul_f32_e32 v91, 0xbfb8aa3b, v91
	v_add_f32_e32 v111, 1.0, v100
	v_exp_f32_e32 v88, v88
	v_rcp_f32_e32 v96, v96
	v_exp_f32_e32 v92, v92
	v_exp_f32_e32 v89, v89
	v_rcp_f32_e32 v97, v97
	v_exp_f32_e32 v93, v93
	v_exp_f32_e32 v90, v90
	v_rcp_f32_e32 v108, v108
	v_exp_f32_e32 v94, v94
	v_exp_f32_e32 v95, v95
	v_exp_f32_e32 v91, v91
	v_rcp_f32_e32 v112, v111
	v_add_f32_e32 v88, 1.0, v88
	v_max_f32_e32 v96, 0xda24260, v96
	v_add_f32_e32 v92, 1.0, v92
	v_add_f32_e32 v89, 1.0, v89
	v_max_f32_e32 v97, 0xda24260, v97
	v_add_f32_e32 v93, 1.0, v93
	v_max_f32_e32 v99, 0xda24260, v99
	v_add_f32_e32 v90, 1.0, v90
	v_max_f32_e32 v108, 0xda24260, v108
	v_add_f32_e32 v94, 1.0, v94
	v_add_f32_e32 v95, 1.0, v95
	v_rcp_f32_e32 v111, v109
	v_add_f32_e32 v91, 1.0, v91
	v_max_f32_e32 v109, 0xda24260, v112
	v_rcp_f32_e32 v88, v88
	v_rcp_f32_e32 v96, v96
	v_rcp_f32_e32 v92, v92
	v_rcp_f32_e32 v89, v89
	v_rcp_f32_e32 v97, v97
	v_rcp_f32_e32 v93, v93
	v_rcp_f32_e32 v99, v99
	v_rcp_f32_e32 v90, v90
	v_rcp_f32_e32 v108, v108
	v_rcp_f32_e32 v94, v94
	v_rcp_f32_e32 v95, v95
	v_rcp_f32_e32 v91, v91
	v_rcp_f32_e32 v109, v109
	v_pk_mul_f32 v[92:93], v[98:99], v[92:93]
	v_pk_mul_f32 v[94:95], v[110:111], v[94:95]
	v_pk_mul_f32 v[88:89], v[96:97], v[88:89]
	v_pk_mul_f32 v[90:91], v[108:109], v[90:91]
.LBB0_212:
	v_add_u32_e32 v98, 32, v130
	v_mov_b64_e32 v[96:97], s[8:9]
	v_mad_i64_i32 v[96:97], s[46:47], v98, s65, v[96:97]
	v_lshl_add_u64 v[96:97], s[6:7], 1, v[96:97]
	v_lshl_add_u64 v[96:97], v[146:147], 1, v[96:97]
	s_and_b64 vcc, exec, s[4:5]
	v_cvt_pk_bf16_f32 v88, v88, v89
	v_cvt_pk_bf16_f32 v89, v90, v91
	v_cvt_pk_bf16_f32 v90, v92, v93
	v_cvt_pk_bf16_f32 v91, v94, v95
	flat_store_dwordx4 v[96:97], v[88:91] sc1
	s_cbranch_vccnz .LBB0_214
	v_add_f32_e32 v81, 1.0, v106
	v_add_f32_e32 v82, 1.0, v105
	v_add_f32_e32 v83, 1.0, v104
	v_rcp_f32_e32 v81, v81
	v_rcp_f32_e32 v83, v83
	v_rcp_f32_e32 v82, v82
	v_add_f32_e32 v86, 1.0, v101
	v_add_f32_e32 v80, 1.0, v107
	v_max_f32_e32 v84, 0xda24260, v81
	v_max_f32_e32 v85, 0xda24260, v83
	v_max_f32_e32 v81, 0xda24260, v82
	v_add_f32_e32 v82, 1.0, v103
	v_add_f32_e32 v83, 1.0, v102
	v_rcp_f32_e32 v87, v86
	v_add_f32_e32 v86, 1.0, v100
	v_rcp_f32_e32 v80, v80
	v_rcp_f32_e32 v82, v82
	v_rcp_f32_e32 v83, v83
	v_rcp_f32_e32 v88, v86
	v_max_f32_e32 v80, 0xda24260, v80
	v_max_f32_e32 v82, 0xda24260, v82
	v_max_f32_e32 v86, 0xda24260, v83
	v_max_f32_e32 v83, 0xda24260, v87
	v_max_f32_e32 v87, 0xda24260, v88
.LBB0_214:
	v_cvt_pk_bf16_f32 v92, v84, v85
	v_cvt_pk_bf16_f32 v93, v86, v87
	v_cvt_pk_bf16_f32 v94, v80, v81
	v_mul_f32_e32 v80, 0xbfb8aa3b, v64
	v_mul_f32_e32 v81, 0xbfb8aa3b, v68
	v_mul_f32_e32 v84, 0xbfb8aa3b, v65
	v_mul_f32_e32 v85, 0xbfb8aa3b, v69
	v_mul_f32_e32 v86, 0xbfb8aa3b, v66
	v_mul_f32_e32 v95, 0xbfb8aa3b, v70
	v_mul_f32_e32 v98, 0xbfb8aa3b, v67
	v_mul_f32_e32 v99, 0xbfb8aa3b, v71
	v_exp_f32_e32 v91, v80
	v_exp_f32_e32 v90, v81
	v_exp_f32_e32 v89, v84
	v_exp_f32_e32 v88, v85
	v_exp_f32_e32 v87, v86
	v_exp_f32_e32 v86, v95
	v_exp_f32_e32 v85, v98
	v_exp_f32_e32 v84, v99
	s_and_b64 vcc, exec, s[4:5]
	v_cvt_pk_bf16_f32 v95, v82, v83
	flat_store_dwordx4 v[96:97], v[92:95] offset:256 sc1
	s_cbranch_vccnz .LBB0_216
	v_add_f32_e32 v80, 1.0, v91
	v_rcp_f32_e32 v81, v80
	v_add_f32_e32 v92, 1.0, v87
	v_rcp_f32_e32 v93, v92
	v_add_f32_e32 v94, 1.0, v85
	v_rcp_f32_e32 v95, v94
	v_max_f32_e32 v81, 0xda24260, v81
	v_rcp_f32_e32 v82, v81
	v_add_f32_e32 v81, 1.0, v89
	v_max_f32_e32 v93, 0xda24260, v93
	v_mul_f32_e32 v72, 0xbfb8aa3b, v72
	v_add_f32_e32 v80, 1.0, v90
	v_mul_f32_e32 v76, 0xbfb8aa3b, v76
	v_mul_f32_e32 v73, 0xbfb8aa3b, v73
	v_rcp_f32_e32 v83, v81
	v_add_f32_e32 v81, 1.0, v88
	v_mul_f32_e32 v77, 0xbfb8aa3b, v77
	v_mul_f32_e32 v74, 0xbfb8aa3b, v74
	v_add_f32_e32 v92, 1.0, v86
	v_mul_f32_e32 v78, 0xbfb8aa3b, v78
	v_mul_f32_e32 v79, 0xbfb8aa3b, v79
	v_rcp_f32_e32 v94, v93
	v_max_f32_e32 v93, 0xda24260, v95
	v_mul_f32_e32 v75, 0xbfb8aa3b, v75
	v_add_f32_e32 v95, 1.0, v84
	v_exp_f32_e32 v72, v72
	v_rcp_f32_e32 v80, v80
	v_exp_f32_e32 v76, v76
	v_exp_f32_e32 v73, v73
	v_rcp_f32_e32 v81, v81
	v_exp_f32_e32 v77, v77
	v_exp_f32_e32 v74, v74
	v_rcp_f32_e32 v92, v92
	v_exp_f32_e32 v78, v78
	v_exp_f32_e32 v79, v79
	v_exp_f32_e32 v75, v75
	v_rcp_f32_e32 v96, v95
	v_add_f32_e32 v72, 1.0, v72
	v_max_f32_e32 v80, 0xda24260, v80
	v_add_f32_e32 v76, 1.0, v76
	v_add_f32_e32 v73, 1.0, v73
	v_max_f32_e32 v81, 0xda24260, v81
	v_add_f32_e32 v77, 1.0, v77
	v_max_f32_e32 v83, 0xda24260, v83
	v_add_f32_e32 v74, 1.0, v74
	v_max_f32_e32 v92, 0xda24260, v92
	v_add_f32_e32 v78, 1.0, v78
	v_add_f32_e32 v79, 1.0, v79
	v_rcp_f32_e32 v95, v93
	v_add_f32_e32 v75, 1.0, v75
	v_max_f32_e32 v93, 0xda24260, v96
	v_rcp_f32_e32 v72, v72
	v_rcp_f32_e32 v80, v80
	v_rcp_f32_e32 v76, v76
	v_rcp_f32_e32 v73, v73
	v_rcp_f32_e32 v81, v81
	v_rcp_f32_e32 v77, v77
	v_rcp_f32_e32 v83, v83
	v_rcp_f32_e32 v74, v74
	v_rcp_f32_e32 v92, v92
	v_rcp_f32_e32 v78, v78
	v_rcp_f32_e32 v79, v79
	v_rcp_f32_e32 v75, v75
	v_rcp_f32_e32 v93, v93
	v_pk_mul_f32 v[76:77], v[82:83], v[76:77]
	v_pk_mul_f32 v[78:79], v[94:95], v[78:79]
	v_pk_mul_f32 v[72:73], v[80:81], v[72:73]
	v_pk_mul_f32 v[74:75], v[92:93], v[74:75]
.LBB0_216:
	v_add_u32_e32 v82, 48, v130
	v_mov_b64_e32 v[80:81], s[8:9]
	v_mad_i64_i32 v[80:81], s[46:47], v82, s65, v[80:81]
	v_lshl_add_u64 v[80:81], s[6:7], 1, v[80:81]
	v_lshl_add_u64 v[80:81], v[146:147], 1, v[80:81]
	s_and_b64 vcc, exec, s[4:5]
	v_cvt_pk_bf16_f32 v72, v72, v73
	v_cvt_pk_bf16_f32 v73, v74, v75
	v_cvt_pk_bf16_f32 v74, v76, v77
	v_cvt_pk_bf16_f32 v75, v78, v79
	flat_store_dwordx4 v[80:81], v[72:75] sc1
	s_cbranch_vccnz .LBB0_218
	v_add_f32_e32 v65, 1.0, v90
	v_add_f32_e32 v66, 1.0, v89
	v_add_f32_e32 v67, 1.0, v88
	v_rcp_f32_e32 v65, v65
	v_rcp_f32_e32 v67, v67
	v_rcp_f32_e32 v66, v66
	v_add_f32_e32 v70, 1.0, v85
	v_add_f32_e32 v64, 1.0, v91
	v_max_f32_e32 v68, 0xda24260, v65
	v_max_f32_e32 v69, 0xda24260, v67
	v_max_f32_e32 v65, 0xda24260, v66
	v_add_f32_e32 v66, 1.0, v87
	v_add_f32_e32 v67, 1.0, v86
	v_rcp_f32_e32 v71, v70
	v_add_f32_e32 v70, 1.0, v84
	v_rcp_f32_e32 v64, v64
	v_rcp_f32_e32 v66, v66
	v_rcp_f32_e32 v67, v67
	v_rcp_f32_e32 v72, v70
	v_max_f32_e32 v64, 0xda24260, v64
	v_max_f32_e32 v66, 0xda24260, v66
	v_max_f32_e32 v70, 0xda24260, v67
	v_max_f32_e32 v67, 0xda24260, v71
	v_max_f32_e32 v71, 0xda24260, v72
.LBB0_218:
	v_cvt_pk_bf16_f32 v76, v68, v69
	v_cvt_pk_bf16_f32 v77, v70, v71
	v_cvt_pk_bf16_f32 v78, v64, v65
	v_mul_f32_e32 v64, 0xbfb8aa3b, v48
	v_mul_f32_e32 v65, 0xbfb8aa3b, v52
	v_mul_f32_e32 v68, 0xbfb8aa3b, v49
	v_mul_f32_e32 v69, 0xbfb8aa3b, v53
	v_mul_f32_e32 v70, 0xbfb8aa3b, v50
	v_mul_f32_e32 v79, 0xbfb8aa3b, v54
	v_mul_f32_e32 v82, 0xbfb8aa3b, v51
	v_mul_f32_e32 v83, 0xbfb8aa3b, v55
	v_exp_f32_e32 v75, v64
	v_exp_f32_e32 v74, v65
	v_exp_f32_e32 v73, v68
	v_exp_f32_e32 v72, v69
	v_exp_f32_e32 v71, v70
	v_exp_f32_e32 v70, v79
	v_exp_f32_e32 v69, v82
	v_exp_f32_e32 v68, v83
	s_and_b64 vcc, exec, s[4:5]
	v_cvt_pk_bf16_f32 v79, v66, v67
	flat_store_dwordx4 v[80:81], v[76:79] offset:256 sc1
	s_cbranch_vccnz .LBB0_220
	v_add_f32_e32 v64, 1.0, v75
	v_rcp_f32_e32 v65, v64
	v_add_f32_e32 v76, 1.0, v71
	v_rcp_f32_e32 v77, v76
	v_add_f32_e32 v78, 1.0, v69
	v_rcp_f32_e32 v79, v78
	v_max_f32_e32 v65, 0xda24260, v65
	v_rcp_f32_e32 v66, v65
	v_add_f32_e32 v65, 1.0, v73
	v_max_f32_e32 v77, 0xda24260, v77
	v_mul_f32_e32 v56, 0xbfb8aa3b, v56
	v_add_f32_e32 v64, 1.0, v74
	v_mul_f32_e32 v60, 0xbfb8aa3b, v60
	v_mul_f32_e32 v57, 0xbfb8aa3b, v57
	v_rcp_f32_e32 v67, v65
	v_add_f32_e32 v65, 1.0, v72
	v_mul_f32_e32 v61, 0xbfb8aa3b, v61
	v_mul_f32_e32 v58, 0xbfb8aa3b, v58
	v_add_f32_e32 v76, 1.0, v70
	v_mul_f32_e32 v62, 0xbfb8aa3b, v62
	v_mul_f32_e32 v63, 0xbfb8aa3b, v63
	v_rcp_f32_e32 v78, v77
	v_max_f32_e32 v77, 0xda24260, v79
	v_mul_f32_e32 v59, 0xbfb8aa3b, v59
	v_add_f32_e32 v79, 1.0, v68
	v_exp_f32_e32 v56, v56
	v_rcp_f32_e32 v64, v64
	v_exp_f32_e32 v60, v60
	v_exp_f32_e32 v57, v57
	v_rcp_f32_e32 v65, v65
	v_exp_f32_e32 v61, v61
	v_exp_f32_e32 v58, v58
	v_rcp_f32_e32 v76, v76
	v_exp_f32_e32 v62, v62
	v_exp_f32_e32 v63, v63
	v_exp_f32_e32 v59, v59
	v_rcp_f32_e32 v80, v79
	v_add_f32_e32 v56, 1.0, v56
	v_max_f32_e32 v64, 0xda24260, v64
	v_add_f32_e32 v60, 1.0, v60
	v_add_f32_e32 v57, 1.0, v57
	v_max_f32_e32 v65, 0xda24260, v65
	v_add_f32_e32 v61, 1.0, v61
	v_max_f32_e32 v67, 0xda24260, v67
	v_add_f32_e32 v58, 1.0, v58
	v_max_f32_e32 v76, 0xda24260, v76
	v_add_f32_e32 v62, 1.0, v62
	v_add_f32_e32 v63, 1.0, v63
	v_rcp_f32_e32 v79, v77
	v_add_f32_e32 v59, 1.0, v59
	v_max_f32_e32 v77, 0xda24260, v80
	v_rcp_f32_e32 v56, v56
	v_rcp_f32_e32 v64, v64
	v_rcp_f32_e32 v60, v60
	v_rcp_f32_e32 v57, v57
	v_rcp_f32_e32 v65, v65
	v_rcp_f32_e32 v61, v61
	v_rcp_f32_e32 v67, v67
	v_rcp_f32_e32 v58, v58
	v_rcp_f32_e32 v76, v76
	v_rcp_f32_e32 v62, v62
	v_rcp_f32_e32 v63, v63
	v_rcp_f32_e32 v59, v59
	v_rcp_f32_e32 v77, v77
	v_pk_mul_f32 v[60:61], v[66:67], v[60:61]
	v_pk_mul_f32 v[62:63], v[78:79], v[62:63]
	v_pk_mul_f32 v[56:57], v[64:65], v[56:57]
	v_pk_mul_f32 v[58:59], v[76:77], v[58:59]
.LBB0_220:
	v_add_u32_e32 v66, 0x80, v130
	v_mov_b64_e32 v[64:65], s[8:9]
	v_mad_i64_i32 v[64:65], s[46:47], v66, s65, v[64:65]
	v_lshl_add_u64 v[64:65], s[6:7], 1, v[64:65]
	v_lshl_add_u64 v[64:65], v[146:147], 1, v[64:65]
	s_and_b64 vcc, exec, s[4:5]
	v_cvt_pk_bf16_f32 v56, v56, v57
	v_cvt_pk_bf16_f32 v57, v58, v59
	v_cvt_pk_bf16_f32 v58, v60, v61
	v_cvt_pk_bf16_f32 v59, v62, v63
	flat_store_dwordx4 v[64:65], v[56:59] sc1
	s_cbranch_vccnz .LBB0_222
	v_add_f32_e32 v49, 1.0, v74
	v_add_f32_e32 v50, 1.0, v73
	v_add_f32_e32 v51, 1.0, v72
	v_rcp_f32_e32 v49, v49
	v_rcp_f32_e32 v51, v51
	v_rcp_f32_e32 v50, v50
	v_add_f32_e32 v54, 1.0, v69
	v_add_f32_e32 v48, 1.0, v75
	v_max_f32_e32 v52, 0xda24260, v49
	v_max_f32_e32 v53, 0xda24260, v51
	v_max_f32_e32 v49, 0xda24260, v50
	v_add_f32_e32 v50, 1.0, v71
	v_add_f32_e32 v51, 1.0, v70
	v_rcp_f32_e32 v55, v54
	v_add_f32_e32 v54, 1.0, v68
	v_rcp_f32_e32 v48, v48
	v_rcp_f32_e32 v50, v50
	v_rcp_f32_e32 v51, v51
	v_rcp_f32_e32 v56, v54
	v_max_f32_e32 v48, 0xda24260, v48
	v_max_f32_e32 v50, 0xda24260, v50
	v_max_f32_e32 v54, 0xda24260, v51
	v_max_f32_e32 v51, 0xda24260, v55
	v_max_f32_e32 v55, 0xda24260, v56
.LBB0_222:
	v_cvt_pk_bf16_f32 v60, v52, v53
	v_cvt_pk_bf16_f32 v61, v54, v55
	v_cvt_pk_bf16_f32 v62, v48, v49
	v_mul_f32_e32 v48, 0xbfb8aa3b, v32
	v_mul_f32_e32 v49, 0xbfb8aa3b, v36
	v_mul_f32_e32 v52, 0xbfb8aa3b, v33
	v_mul_f32_e32 v53, 0xbfb8aa3b, v37
	v_mul_f32_e32 v54, 0xbfb8aa3b, v34
	v_mul_f32_e32 v63, 0xbfb8aa3b, v38
	v_mul_f32_e32 v66, 0xbfb8aa3b, v35
	v_mul_f32_e32 v67, 0xbfb8aa3b, v39
	v_exp_f32_e32 v59, v48
	v_exp_f32_e32 v58, v49
	v_exp_f32_e32 v57, v52
	v_exp_f32_e32 v56, v53
	v_exp_f32_e32 v55, v54
	v_exp_f32_e32 v54, v63
	v_exp_f32_e32 v53, v66
	v_exp_f32_e32 v52, v67
	s_and_b64 vcc, exec, s[4:5]
	v_cvt_pk_bf16_f32 v63, v50, v51
	flat_store_dwordx4 v[64:65], v[60:63] offset:256 sc1
	s_cbranch_vccnz .LBB0_224
	v_add_f32_e32 v48, 1.0, v59
	v_rcp_f32_e32 v49, v48
	v_add_f32_e32 v60, 1.0, v55
	v_rcp_f32_e32 v61, v60
	v_add_f32_e32 v62, 1.0, v53
	v_rcp_f32_e32 v63, v62
	v_max_f32_e32 v49, 0xda24260, v49
	v_rcp_f32_e32 v50, v49
	v_add_f32_e32 v49, 1.0, v57
	v_max_f32_e32 v61, 0xda24260, v61
	v_mul_f32_e32 v40, 0xbfb8aa3b, v40
	v_add_f32_e32 v48, 1.0, v58
	v_mul_f32_e32 v44, 0xbfb8aa3b, v44
	v_mul_f32_e32 v41, 0xbfb8aa3b, v41
	v_rcp_f32_e32 v51, v49
	v_add_f32_e32 v49, 1.0, v56
	v_mul_f32_e32 v45, 0xbfb8aa3b, v45
	v_mul_f32_e32 v42, 0xbfb8aa3b, v42
	v_add_f32_e32 v60, 1.0, v54
	v_mul_f32_e32 v46, 0xbfb8aa3b, v46
	v_mul_f32_e32 v47, 0xbfb8aa3b, v47
	v_rcp_f32_e32 v62, v61
	v_max_f32_e32 v61, 0xda24260, v63
	v_mul_f32_e32 v43, 0xbfb8aa3b, v43
	v_add_f32_e32 v63, 1.0, v52
	v_exp_f32_e32 v40, v40
	v_rcp_f32_e32 v48, v48
	v_exp_f32_e32 v44, v44
	v_exp_f32_e32 v41, v41
	v_rcp_f32_e32 v49, v49
	v_exp_f32_e32 v45, v45
	v_exp_f32_e32 v42, v42
	v_rcp_f32_e32 v60, v60
	v_exp_f32_e32 v46, v46
	v_exp_f32_e32 v47, v47
	v_exp_f32_e32 v43, v43
	v_rcp_f32_e32 v64, v63
	v_add_f32_e32 v40, 1.0, v40
	v_max_f32_e32 v48, 0xda24260, v48
	v_add_f32_e32 v44, 1.0, v44
	v_add_f32_e32 v41, 1.0, v41
	v_max_f32_e32 v49, 0xda24260, v49
	v_add_f32_e32 v45, 1.0, v45
	v_max_f32_e32 v51, 0xda24260, v51
	v_add_f32_e32 v42, 1.0, v42
	v_max_f32_e32 v60, 0xda24260, v60
	v_add_f32_e32 v46, 1.0, v46
	v_add_f32_e32 v47, 1.0, v47
	v_rcp_f32_e32 v63, v61
	v_add_f32_e32 v43, 1.0, v43
	v_max_f32_e32 v61, 0xda24260, v64
	v_rcp_f32_e32 v40, v40
	v_rcp_f32_e32 v48, v48
	v_rcp_f32_e32 v44, v44
	v_rcp_f32_e32 v41, v41
	v_rcp_f32_e32 v49, v49
	v_rcp_f32_e32 v45, v45
	v_rcp_f32_e32 v51, v51
	v_rcp_f32_e32 v42, v42
	v_rcp_f32_e32 v60, v60
	v_rcp_f32_e32 v46, v46
	v_rcp_f32_e32 v47, v47
	v_rcp_f32_e32 v43, v43
	v_rcp_f32_e32 v61, v61
	v_pk_mul_f32 v[44:45], v[50:51], v[44:45]
	v_pk_mul_f32 v[46:47], v[62:63], v[46:47]
	v_pk_mul_f32 v[40:41], v[48:49], v[40:41]
	v_pk_mul_f32 v[42:43], v[60:61], v[42:43]
.LBB0_224:
	v_add_u32_e32 v50, 0x90, v130
	v_mov_b64_e32 v[48:49], s[8:9]
	v_mad_i64_i32 v[48:49], s[46:47], v50, s65, v[48:49]
	v_lshl_add_u64 v[48:49], s[6:7], 1, v[48:49]
	v_lshl_add_u64 v[48:49], v[146:147], 1, v[48:49]
	s_and_b64 vcc, exec, s[4:5]
	v_cvt_pk_bf16_f32 v40, v40, v41
	v_cvt_pk_bf16_f32 v41, v42, v43
	v_cvt_pk_bf16_f32 v42, v44, v45
	v_cvt_pk_bf16_f32 v43, v46, v47
	flat_store_dwordx4 v[48:49], v[40:43] sc1
	s_cbranch_vccnz .LBB0_226
	v_add_f32_e32 v33, 1.0, v58
	v_add_f32_e32 v34, 1.0, v57
	v_add_f32_e32 v35, 1.0, v56
	v_rcp_f32_e32 v33, v33
	v_rcp_f32_e32 v35, v35
	v_rcp_f32_e32 v34, v34
	v_add_f32_e32 v38, 1.0, v53
	v_add_f32_e32 v32, 1.0, v59
	v_max_f32_e32 v36, 0xda24260, v33
	v_max_f32_e32 v37, 0xda24260, v35
	v_max_f32_e32 v33, 0xda24260, v34
	v_add_f32_e32 v34, 1.0, v55
	v_add_f32_e32 v35, 1.0, v54
	v_rcp_f32_e32 v39, v38
	v_add_f32_e32 v38, 1.0, v52
	v_rcp_f32_e32 v32, v32
	v_rcp_f32_e32 v34, v34
	v_rcp_f32_e32 v35, v35
	v_rcp_f32_e32 v40, v38
	v_max_f32_e32 v32, 0xda24260, v32
	v_max_f32_e32 v34, 0xda24260, v34
	v_max_f32_e32 v38, 0xda24260, v35
	v_max_f32_e32 v35, 0xda24260, v39
	v_max_f32_e32 v39, 0xda24260, v40
.LBB0_226:
	v_cvt_pk_bf16_f32 v44, v36, v37
	v_cvt_pk_bf16_f32 v45, v38, v39
	v_cvt_pk_bf16_f32 v46, v32, v33
	v_mul_f32_e32 v32, 0xbfb8aa3b, v16
	v_mul_f32_e32 v33, 0xbfb8aa3b, v20
	v_mul_f32_e32 v36, 0xbfb8aa3b, v17
	v_mul_f32_e32 v37, 0xbfb8aa3b, v21
	v_mul_f32_e32 v38, 0xbfb8aa3b, v18
	v_mul_f32_e32 v47, 0xbfb8aa3b, v22
	v_mul_f32_e32 v50, 0xbfb8aa3b, v19
	v_mul_f32_e32 v51, 0xbfb8aa3b, v23
	v_exp_f32_e32 v43, v32
	v_exp_f32_e32 v42, v33
	v_exp_f32_e32 v41, v36
	v_exp_f32_e32 v40, v37
	v_exp_f32_e32 v39, v38
	v_exp_f32_e32 v38, v47
	v_exp_f32_e32 v37, v50
	v_exp_f32_e32 v36, v51
	s_and_b64 vcc, exec, s[4:5]
	v_cvt_pk_bf16_f32 v47, v34, v35
	flat_store_dwordx4 v[48:49], v[44:47] offset:256 sc1
	s_cbranch_vccnz .LBB0_228
	v_add_f32_e32 v32, 1.0, v43
	v_rcp_f32_e32 v33, v32
	v_add_f32_e32 v44, 1.0, v39
	v_rcp_f32_e32 v45, v44
	v_add_f32_e32 v46, 1.0, v37
	v_rcp_f32_e32 v47, v46
	v_max_f32_e32 v33, 0xda24260, v33
	v_rcp_f32_e32 v34, v33
	v_add_f32_e32 v33, 1.0, v41
	v_max_f32_e32 v45, 0xda24260, v45
	v_mul_f32_e32 v24, 0xbfb8aa3b, v24
	v_add_f32_e32 v32, 1.0, v42
	v_mul_f32_e32 v28, 0xbfb8aa3b, v28
	v_mul_f32_e32 v25, 0xbfb8aa3b, v25
	v_rcp_f32_e32 v35, v33
	v_add_f32_e32 v33, 1.0, v40
	v_mul_f32_e32 v29, 0xbfb8aa3b, v29
	v_mul_f32_e32 v26, 0xbfb8aa3b, v26
	v_add_f32_e32 v44, 1.0, v38
	v_mul_f32_e32 v30, 0xbfb8aa3b, v30
	v_mul_f32_e32 v31, 0xbfb8aa3b, v31
	v_rcp_f32_e32 v46, v45
	v_max_f32_e32 v45, 0xda24260, v47
	v_mul_f32_e32 v27, 0xbfb8aa3b, v27
	v_add_f32_e32 v47, 1.0, v36
	v_exp_f32_e32 v24, v24
	v_rcp_f32_e32 v32, v32
	v_exp_f32_e32 v28, v28
	v_exp_f32_e32 v25, v25
	v_rcp_f32_e32 v33, v33
	v_exp_f32_e32 v29, v29
	v_exp_f32_e32 v26, v26
	v_rcp_f32_e32 v44, v44
	v_exp_f32_e32 v30, v30
	v_exp_f32_e32 v31, v31
	v_exp_f32_e32 v27, v27
	v_rcp_f32_e32 v48, v47
	v_add_f32_e32 v24, 1.0, v24
	v_max_f32_e32 v32, 0xda24260, v32
	v_add_f32_e32 v28, 1.0, v28
	v_add_f32_e32 v25, 1.0, v25
	v_max_f32_e32 v33, 0xda24260, v33
	v_add_f32_e32 v29, 1.0, v29
	v_max_f32_e32 v35, 0xda24260, v35
	v_add_f32_e32 v26, 1.0, v26
	v_max_f32_e32 v44, 0xda24260, v44
	v_add_f32_e32 v30, 1.0, v30
	v_add_f32_e32 v31, 1.0, v31
	v_rcp_f32_e32 v47, v45
	v_add_f32_e32 v27, 1.0, v27
	v_max_f32_e32 v45, 0xda24260, v48
	v_rcp_f32_e32 v24, v24
	v_rcp_f32_e32 v32, v32
	v_rcp_f32_e32 v28, v28
	v_rcp_f32_e32 v25, v25
	v_rcp_f32_e32 v33, v33
	v_rcp_f32_e32 v29, v29
	v_rcp_f32_e32 v35, v35
	v_rcp_f32_e32 v26, v26
	v_rcp_f32_e32 v44, v44
	v_rcp_f32_e32 v30, v30
	v_rcp_f32_e32 v31, v31
	v_rcp_f32_e32 v27, v27
	v_rcp_f32_e32 v45, v45
	v_pk_mul_f32 v[28:29], v[34:35], v[28:29]
	v_pk_mul_f32 v[30:31], v[46:47], v[30:31]
	v_pk_mul_f32 v[24:25], v[32:33], v[24:25]
	v_pk_mul_f32 v[26:27], v[44:45], v[26:27]
.LBB0_228:
	v_add_u32_e32 v34, 0xa0, v130
	v_mov_b64_e32 v[32:33], s[8:9]
	v_mad_i64_i32 v[32:33], s[46:47], v34, s65, v[32:33]
	v_lshl_add_u64 v[32:33], s[6:7], 1, v[32:33]
	v_lshl_add_u64 v[32:33], v[146:147], 1, v[32:33]
	s_and_b64 vcc, exec, s[4:5]
	v_cvt_pk_bf16_f32 v24, v24, v25
	v_cvt_pk_bf16_f32 v25, v26, v27
	v_cvt_pk_bf16_f32 v26, v28, v29
	v_cvt_pk_bf16_f32 v27, v30, v31
	flat_store_dwordx4 v[32:33], v[24:27] sc1
	s_cbranch_vccnz .LBB0_230
	v_add_f32_e32 v17, 1.0, v42
	v_add_f32_e32 v18, 1.0, v41
	v_add_f32_e32 v19, 1.0, v40
	v_rcp_f32_e32 v17, v17
	v_rcp_f32_e32 v19, v19
	v_rcp_f32_e32 v18, v18
	v_add_f32_e32 v22, 1.0, v37
	v_add_f32_e32 v16, 1.0, v43
	v_max_f32_e32 v20, 0xda24260, v17
	v_max_f32_e32 v21, 0xda24260, v19
	v_max_f32_e32 v17, 0xda24260, v18
	v_add_f32_e32 v18, 1.0, v39
	v_add_f32_e32 v19, 1.0, v38
	v_rcp_f32_e32 v23, v22
	v_add_f32_e32 v22, 1.0, v36
	v_rcp_f32_e32 v16, v16
	v_rcp_f32_e32 v18, v18
	v_rcp_f32_e32 v19, v19
	v_rcp_f32_e32 v24, v22
	v_max_f32_e32 v16, 0xda24260, v16
	v_max_f32_e32 v18, 0xda24260, v18
	v_max_f32_e32 v22, 0xda24260, v19
	v_max_f32_e32 v19, 0xda24260, v23
	v_max_f32_e32 v23, 0xda24260, v24
.LBB0_230:
	v_cvt_pk_bf16_f32 v28, v20, v21
	v_cvt_pk_bf16_f32 v29, v22, v23
	v_cvt_pk_bf16_f32 v30, v16, v17
	v_mul_f32_e32 v16, 0xbfb8aa3b, v0
	v_mul_f32_e32 v17, 0xbfb8aa3b, v4
	v_mul_f32_e32 v20, 0xbfb8aa3b, v1
	v_mul_f32_e32 v21, 0xbfb8aa3b, v5
	v_mul_f32_e32 v22, 0xbfb8aa3b, v2
	v_mul_f32_e32 v31, 0xbfb8aa3b, v6
	v_mul_f32_e32 v34, 0xbfb8aa3b, v3
	v_mul_f32_e32 v35, 0xbfb8aa3b, v7
	v_exp_f32_e32 v27, v16
	v_exp_f32_e32 v26, v17
	v_exp_f32_e32 v25, v20
	v_exp_f32_e32 v24, v21
	v_exp_f32_e32 v23, v22
	v_exp_f32_e32 v22, v31
	v_exp_f32_e32 v21, v34
	v_exp_f32_e32 v20, v35
	s_and_b64 vcc, exec, s[4:5]
	v_cvt_pk_bf16_f32 v31, v18, v19
	flat_store_dwordx4 v[32:33], v[28:31] offset:256 sc1
	s_cbranch_vccnz .LBB0_232
	v_add_f32_e32 v16, 1.0, v27
	v_rcp_f32_e32 v17, v16
	v_add_f32_e32 v28, 1.0, v23
	v_rcp_f32_e32 v29, v28
	v_add_f32_e32 v30, 1.0, v21
	v_rcp_f32_e32 v31, v30
	v_max_f32_e32 v17, 0xda24260, v17
	v_rcp_f32_e32 v18, v17
	v_add_f32_e32 v17, 1.0, v25
	v_max_f32_e32 v29, 0xda24260, v29
	v_mul_f32_e32 v8, 0xbfb8aa3b, v8
	v_add_f32_e32 v16, 1.0, v26
	v_mul_f32_e32 v12, 0xbfb8aa3b, v12
	v_mul_f32_e32 v9, 0xbfb8aa3b, v9
	v_rcp_f32_e32 v19, v17
	v_add_f32_e32 v17, 1.0, v24
	v_mul_f32_e32 v13, 0xbfb8aa3b, v13
	v_mul_f32_e32 v10, 0xbfb8aa3b, v10
	v_add_f32_e32 v28, 1.0, v22
	v_mul_f32_e32 v14, 0xbfb8aa3b, v14
	v_mul_f32_e32 v15, 0xbfb8aa3b, v15
	v_rcp_f32_e32 v30, v29
	v_max_f32_e32 v29, 0xda24260, v31
	v_mul_f32_e32 v11, 0xbfb8aa3b, v11
	v_add_f32_e32 v31, 1.0, v20
	v_exp_f32_e32 v8, v8
	v_rcp_f32_e32 v16, v16
	v_exp_f32_e32 v12, v12
	v_exp_f32_e32 v9, v9
	v_rcp_f32_e32 v17, v17
	v_exp_f32_e32 v13, v13
	v_exp_f32_e32 v10, v10
	v_rcp_f32_e32 v28, v28
	v_exp_f32_e32 v14, v14
	v_exp_f32_e32 v15, v15
	v_exp_f32_e32 v11, v11
	v_rcp_f32_e32 v32, v31
	v_add_f32_e32 v8, 1.0, v8
	v_max_f32_e32 v16, 0xda24260, v16
	v_add_f32_e32 v12, 1.0, v12
	v_add_f32_e32 v9, 1.0, v9
	v_max_f32_e32 v17, 0xda24260, v17
	v_add_f32_e32 v13, 1.0, v13
	v_max_f32_e32 v19, 0xda24260, v19
	v_add_f32_e32 v10, 1.0, v10
	v_max_f32_e32 v28, 0xda24260, v28
	v_add_f32_e32 v14, 1.0, v14
	v_add_f32_e32 v15, 1.0, v15
	v_rcp_f32_e32 v31, v29
	v_add_f32_e32 v11, 1.0, v11
	v_max_f32_e32 v29, 0xda24260, v32
	v_rcp_f32_e32 v8, v8
	v_rcp_f32_e32 v16, v16
	v_rcp_f32_e32 v12, v12
	v_rcp_f32_e32 v9, v9
	v_rcp_f32_e32 v17, v17
	v_rcp_f32_e32 v13, v13
	v_rcp_f32_e32 v19, v19
	v_rcp_f32_e32 v10, v10
	v_rcp_f32_e32 v28, v28
	v_rcp_f32_e32 v14, v14
	v_rcp_f32_e32 v15, v15
	v_rcp_f32_e32 v11, v11
	v_rcp_f32_e32 v29, v29
	v_pk_mul_f32 v[12:13], v[18:19], v[12:13]
	v_pk_mul_f32 v[14:15], v[30:31], v[14:15]
	v_pk_mul_f32 v[8:9], v[16:17], v[8:9]
	v_pk_mul_f32 v[10:11], v[28:29], v[10:11]
.LBB0_232:
	v_add_u32_e32 v18, 0xb0, v130
	v_mov_b64_e32 v[16:17], s[8:9]
	v_mad_i64_i32 v[16:17], s[46:47], v18, s65, v[16:17]
	v_lshl_add_u64 v[16:17], s[6:7], 1, v[16:17]
	v_lshl_add_u64 v[16:17], v[146:147], 1, v[16:17]
	s_and_b64 vcc, exec, s[4:5]
	v_cvt_pk_bf16_f32 v8, v8, v9
	v_cvt_pk_bf16_f32 v9, v10, v11
	v_cvt_pk_bf16_f32 v10, v12, v13
	v_cvt_pk_bf16_f32 v11, v14, v15
	flat_store_dwordx4 v[16:17], v[8:11] sc1
	s_cbranch_vccnz .LBB0_123
	v_add_f32_e32 v1, 1.0, v26
	v_add_f32_e32 v2, 1.0, v25
	v_add_f32_e32 v3, 1.0, v24
	v_rcp_f32_e32 v1, v1
	v_rcp_f32_e32 v3, v3
	v_rcp_f32_e32 v2, v2
	v_add_f32_e32 v6, 1.0, v21
	v_add_f32_e32 v0, 1.0, v27
	v_max_f32_e32 v4, 0xda24260, v1
	v_max_f32_e32 v5, 0xda24260, v3
	v_max_f32_e32 v1, 0xda24260, v2
	v_add_f32_e32 v2, 1.0, v23
	v_add_f32_e32 v3, 1.0, v22
	v_rcp_f32_e32 v7, v6
	v_add_f32_e32 v6, 1.0, v20
	v_rcp_f32_e32 v0, v0
	v_rcp_f32_e32 v2, v2
	v_rcp_f32_e32 v3, v3
	v_rcp_f32_e32 v8, v6
	v_max_f32_e32 v0, 0xda24260, v0
	v_max_f32_e32 v2, 0xda24260, v2
	v_max_f32_e32 v6, 0xda24260, v3
	v_max_f32_e32 v3, 0xda24260, v7
	v_max_f32_e32 v7, 0xda24260, v8
	s_branch .LBB0_123

.LBB0_271:
	s_ashr_i32 s9, s8, 31
	s_lshl_b64 s[8:9], s[8:9], 3
	s_add_u32 s10, s0, s8
	s_addc_u32 s11, s1, s9
	s_lshr_b32 s8, s38, 5
	v_cvt_f32_u32_e32 v8, s8
	s_load_dwordx2 s[40:41], s[10:11], 0x0
	s_sub_i32 s10, 0, s8
	s_abs_i32 s13, s29
	v_rcp_iflag_f32_e32 v8, v8
	s_ashr_i32 s12, s29, 31
	s_mov_b32 s9, 0
	s_mov_b32 s39, 1
	v_mul_f32_e32 v8, 0x4f7ffffe, v8
	v_cvt_u32_f32_e32 v8, v8
	s_nop 0
	v_readfirstlane_b32 s11, v8
	s_mul_i32 s10, s10, s11
	s_mul_hi_u32 s10, s11, s10
	s_add_i32 s11, s11, s10
	s_mul_hi_u32 s10, s13, s11
	s_mul_i32 s11, s10, s8
	s_sub_i32 s11, s13, s11
	s_add_i32 s42, s10, 1
	s_sub_i32 s13, s11, s8
	s_cmp_ge_u32 s11, s8
	s_cselect_b32 s10, s42, s10
	s_cselect_b32 s11, s13, s11
	s_add_i32 s13, s10, 1
	s_cmp_ge_u32 s11, s8
	s_cselect_b32 s10, s13, s10
	s_xor_b32 s10, s10, s12
	s_sub_i32 s10, s10, s12
	s_mul_i32 s8, s10, s8
	s_sub_i32 s11, s29, s8
	s_lshl_b32 s8, s10, 6
	s_lshl_b32 s10, s11, 5
	s_ashr_i32 s11, s10, 31
	s_lshl_b64 s[42:43], s[10:11], 2
	s_waitcnt lgkmcnt(0)
	s_add_u32 s40, s40, s42
	s_addc_u32 s41, s41, s43
	s_mul_i32 s70, s8, s38
	s_lshl_b32 s71, s38, 2
	s_lshl_b32 s70, s70, 2
	s_add_u32 s40, s40, s70
	s_addc_u32 s41, s41, 0
	v_mad_u32_u24 v210, v0, s71, v2
	v_mad_u32_u24 v211, v0, s15, v4
	s_lshl_b32 s71, s71, 1
	global_load_dword v166, v210, s[40:41]
	s_add_u32 s40, s40, s71
	s_addc_u32 s41, s41, 0
	global_load_dword v167, v210, s[40:41]
	s_add_u32 s40, s40, s71
	s_addc_u32 s41, s41, 0
	global_load_dword v168, v210, s[40:41]
	s_add_u32 s40, s40, s71
	s_addc_u32 s41, s41, 0
	global_load_dword v169, v210, s[40:41]
	s_add_u32 s40, s40, s71
	s_addc_u32 s41, s41, 0
	global_load_dword v170, v210, s[40:41]
	s_add_u32 s40, s40, s71
	s_addc_u32 s41, s41, 0
	global_load_dword v171, v210, s[40:41]
	s_add_u32 s40, s40, s71
	s_addc_u32 s41, s41, 0
	global_load_dword v172, v210, s[40:41]
	s_add_u32 s40, s40, s71
	s_addc_u32 s41, s41, 0
	global_load_dword v173, v210, s[40:41]
	s_add_u32 s40, s40, s71
	s_addc_u32 s41, s41, 0
	global_load_dword v174, v210, s[40:41]
	s_add_u32 s40, s40, s71
	s_addc_u32 s41, s41, 0
	global_load_dword v175, v210, s[40:41]
	s_add_u32 s40, s40, s71
	s_addc_u32 s41, s41, 0
	global_load_dword v176, v210, s[40:41]
	s_add_u32 s40, s40, s71
	s_addc_u32 s41, s41, 0
	global_load_dword v177, v210, s[40:41]
	s_add_u32 s40, s40, s71
	s_addc_u32 s41, s41, 0
	global_load_dword v178, v210, s[40:41]
	s_add_u32 s40, s40, s71
	s_addc_u32 s41, s41, 0
	global_load_dword v179, v210, s[40:41]
	s_add_u32 s40, s40, s71
	s_addc_u32 s41, s41, 0
	global_load_dword v180, v210, s[40:41]
	s_add_u32 s40, s40, s71
	s_addc_u32 s41, s41, 0
	global_load_dword v181, v210, s[40:41]
	s_add_u32 s40, s40, s71
	s_addc_u32 s41, s41, 0
	global_load_dword v182, v210, s[40:41]
	s_add_u32 s40, s40, s71
	s_addc_u32 s41, s41, 0
	global_load_dword v183, v210, s[40:41]
	s_add_u32 s40, s40, s71
	s_addc_u32 s41, s41, 0
	global_load_dword v184, v210, s[40:41]
	s_add_u32 s40, s40, s71
	s_addc_u32 s41, s41, 0
	global_load_dword v185, v210, s[40:41]
	s_add_u32 s40, s40, s71
	s_addc_u32 s41, s41, 0
	global_load_dword v186, v210, s[40:41]
	s_add_u32 s40, s40, s71
	s_addc_u32 s41, s41, 0
	global_load_dword v187, v210, s[40:41]
	s_add_u32 s40, s40, s71
	s_addc_u32 s41, s41, 0
	global_load_dword v188, v210, s[40:41]
	s_add_u32 s40, s40, s71
	s_addc_u32 s41, s41, 0
	global_load_dword v189, v210, s[40:41]
	s_add_u32 s40, s40, s71
	s_addc_u32 s41, s41, 0
	global_load_dword v190, v210, s[40:41]
	s_add_u32 s40, s40, s71
	s_addc_u32 s41, s41, 0
	global_load_dword v191, v210, s[40:41]
	s_add_u32 s40, s40, s71
	s_addc_u32 s41, s41, 0
	global_load_dword v192, v210, s[40:41]
	s_add_u32 s40, s40, s71
	s_addc_u32 s41, s41, 0
	global_load_dword v193, v210, s[40:41]
	s_add_u32 s40, s40, s71
	s_addc_u32 s41, s41, 0
	global_load_dword v194, v210, s[40:41]
	s_add_u32 s40, s40, s71
	s_addc_u32 s41, s41, 0
	global_load_dword v195, v210, s[40:41]
	s_add_u32 s40, s40, s71
	s_addc_u32 s41, s41, 0
	global_load_dword v198, v210, s[40:41]
	s_add_u32 s40, s40, s71
	s_addc_u32 s41, s41, 0
	global_load_dword v199, v210, s[40:41]
	s_waitcnt vmcnt(31)
	ds_write_b32 v211, v166
	s_waitcnt vmcnt(30)
	ds_write_b32 v211, v167 offset:264
	s_waitcnt vmcnt(29)
	ds_write_b32 v211, v168 offset:528
	s_waitcnt vmcnt(28)
	ds_write_b32 v211, v169 offset:792
	s_waitcnt vmcnt(27)
	ds_write_b32 v211, v170 offset:1056
	s_waitcnt vmcnt(26)
	ds_write_b32 v211, v171 offset:1320
	s_waitcnt vmcnt(25)
	ds_write_b32 v211, v172 offset:1584
	s_waitcnt vmcnt(24)
	ds_write_b32 v211, v173 offset:1848
	s_waitcnt vmcnt(23)
	ds_write_b32 v211, v174 offset:2112
	s_waitcnt vmcnt(22)
	ds_write_b32 v211, v175 offset:2376
	s_waitcnt vmcnt(21)
	ds_write_b32 v211, v176 offset:2640
	s_waitcnt vmcnt(20)
	ds_write_b32 v211, v177 offset:2904
	s_waitcnt vmcnt(19)
	ds_write_b32 v211, v178 offset:3168
	s_waitcnt vmcnt(18)
	ds_write_b32 v211, v179 offset:3432
	s_waitcnt vmcnt(17)
	ds_write_b32 v211, v180 offset:3696
	s_waitcnt vmcnt(16)
	ds_write_b32 v211, v181 offset:3960
	s_waitcnt vmcnt(15)
	ds_write_b32 v211, v182 offset:4224
	s_waitcnt vmcnt(14)
	ds_write_b32 v211, v183 offset:4488
	s_waitcnt vmcnt(13)
	ds_write_b32 v211, v184 offset:4752
	s_waitcnt vmcnt(12)
	ds_write_b32 v211, v185 offset:5016
	s_waitcnt vmcnt(11)
	ds_write_b32 v211, v186 offset:5280
	s_waitcnt vmcnt(10)
	ds_write_b32 v211, v187 offset:5544
	s_waitcnt vmcnt(9)
	ds_write_b32 v211, v188 offset:5808
	s_waitcnt vmcnt(8)
	ds_write_b32 v211, v189 offset:6072
	s_waitcnt vmcnt(7)
	ds_write_b32 v211, v190 offset:6336
	s_waitcnt vmcnt(6)
	ds_write_b32 v211, v191 offset:6600
	s_waitcnt vmcnt(5)
	ds_write_b32 v211, v192 offset:6864
	s_waitcnt vmcnt(4)
	ds_write_b32 v211, v193 offset:7128
	s_waitcnt vmcnt(3)
	ds_write_b32 v211, v194 offset:7392
	s_waitcnt vmcnt(2)
	ds_write_b32 v211, v195 offset:7656
	s_waitcnt vmcnt(1)
	ds_write_b32 v211, v198 offset:7920
	s_waitcnt vmcnt(0)
	ds_write_b32 v211, v199 offset:8184
	s_add_u32 s6, s34, s6
	s_waitcnt lgkmcnt(0)
	s_addc_u32 s7, s35, s7
	s_add_i32 s10, s10, s25
	s_lshl_b64 s[4:5], s[4:5], 1
	s_add_u32 s6, s6, s4
	ds_read2_b32 v[166:167], v10 offset1:33
	ds_read2_b32 v[168:169], v10 offset0:66 offset1:99
	ds_read2_b32 v[170:171], v10 offset0:132 offset1:165
	ds_read2_b32 v[172:173], v10 offset0:198 offset1:231
	ds_read2_b32 v[174:175], v10 offset0:8 offset1:41
	ds_read2_b32 v[176:177], v10 offset0:74 offset1:107
	ds_read2_b32 v[178:179], v10 offset0:140 offset1:173
	ds_read2_b32 v[180:181], v10 offset0:206 offset1:239
	ds_read2_b32 v[182:183], v10 offset0:16 offset1:49
	ds_read2_b32 v[184:185], v10 offset0:82 offset1:115
	ds_read2_b32 v[186:187], v10 offset0:148 offset1:181
	ds_read2_b32 v[188:189], v10 offset0:214 offset1:247
	ds_read2_b32 v[190:191], v10 offset0:24 offset1:57
	ds_read2_b32 v[192:193], v10 offset0:90 offset1:123
	ds_read2_b32 v[194:195], v10 offset0:156 offset1:189
	ds_read2_b32 v[198:199], v10 offset0:222 offset1:255
	s_addc_u32 s7, s7, s5
	s_ashr_i32 s9, s8, 31
	s_waitcnt lgkmcnt(12)
	v_cvt_pk_bf16_f32 v14, v166, v167
	s_lshl_b64 s[4:5], s[8:9], 1
	s_waitcnt lgkmcnt(12)
	v_cvt_pk_bf16_f32 v15, v168, v169
	v_add_u32_e32 v18, s10, v5
	s_add_u32 s4, s6, s4
	v_ashrrev_i32_e32 v19, 31, v18
	s_waitcnt lgkmcnt(12)
	v_cvt_pk_bf16_f32 v16, v170, v171
	s_addc_u32 s5, s7, s5
	v_lshl_add_u64 v[20:21], s[4:5], 0, v[6:7]
	s_waitcnt lgkmcnt(12)
	v_cvt_pk_bf16_f32 v17, v172, v173
	v_lshlrev_b64 v[8:9], 12, v[18:19]
	v_lshl_add_u64 v[8:9], v[20:21], 0, v[8:9]
	global_store_dwordx4 v[8:9], v[14:17], off sc1
	s_nop 1
	v_add_u32_e32 v18, s10, v11
	v_ashrrev_i32_e32 v19, 31, v18
	s_waitcnt lgkmcnt(8)
	v_cvt_pk_bf16_f32 v14, v174, v175
	v_lshlrev_b64 v[18:19], 12, v[18:19]
	s_waitcnt lgkmcnt(8)
	v_cvt_pk_bf16_f32 v15, v176, v177
	v_lshl_add_u64 v[18:19], v[20:21], 0, v[18:19]
	s_waitcnt lgkmcnt(8)
	v_cvt_pk_bf16_f32 v16, v178, v179
	s_waitcnt lgkmcnt(8)
	v_cvt_pk_bf16_f32 v17, v180, v181
	global_store_dwordx4 v[18:19], v[14:17], off sc1
	s_nop 1
	v_add_u32_e32 v18, s10, v12
	v_ashrrev_i32_e32 v19, 31, v18
	s_waitcnt lgkmcnt(4)
	v_cvt_pk_bf16_f32 v14, v182, v183
	v_lshlrev_b64 v[18:19], 12, v[18:19]
	s_waitcnt lgkmcnt(4)
	v_cvt_pk_bf16_f32 v15, v184, v185
	v_lshl_add_u64 v[18:19], v[20:21], 0, v[18:19]
	s_waitcnt lgkmcnt(4)
	v_cvt_pk_bf16_f32 v16, v186, v187
	s_waitcnt lgkmcnt(4)
	v_cvt_pk_bf16_f32 v17, v188, v189
	global_store_dwordx4 v[18:19], v[14:17], off sc1
	s_nop 1
	v_add_u32_e32 v18, s10, v13
	v_ashrrev_i32_e32 v19, 31, v18
	s_waitcnt lgkmcnt(0)
	v_cvt_pk_bf16_f32 v14, v190, v191
	v_lshlrev_b64 v[18:19], 12, v[18:19]
	s_waitcnt lgkmcnt(0)
	v_cvt_pk_bf16_f32 v15, v192, v193
	v_lshl_add_u64 v[18:19], v[20:21], 0, v[18:19]
	s_waitcnt lgkmcnt(0)
	v_cvt_pk_bf16_f32 v16, v194, v195
	s_waitcnt lgkmcnt(0)
	v_cvt_pk_bf16_f32 v17, v198, v199
	global_store_dwordx4 v[18:19], v[14:17], off sc1
	s_nop 1
	s_waitcnt lgkmcnt(0)
	s_add_i32 s3, s3, s14
	s_cmpk_lt_i32 s3, 0x5400
	s_cbranch_scc1 .LBB0_240
	s_branch .LBB0_275

.LBB0_446:
	v_mov_b32_e32 v128, v155
	v_mov_b32_e32 v129, v156
	s_add_i32 s12, s88, s66
	v_add_u32_e32 v128, s12, v128
	v_mov_b64_e32 v[132:133], s[8:9]
	v_mad_i64_i32 v[132:133], s[40:41], v128, s70, v[132:133]
	s_lshl_b32 s12, s87, 1
	s_and_b32 s40, s12, 0xffffff00
	v_lshl_add_u32 v130, v129, 3, s67
	s_ashr_i32 s41, s40, 31
	v_lshl_add_u64 v[132:133], s[40:41], 1, v[132:133]
	v_ashrrev_i32_e32 v131, 31, v130
	v_lshl_add_u64 v[132:133], v[130:131], 1, v[132:133]
	v_add_co_u32_e32 v134, vcc, s65, v132
	v_ashrrev_i32_e32 v129, 31, v128
	s_nop 0
	v_addc_co_u32_e32 v135, vcc, 0, v133, vcc
	flat_load_dwordx4 v[134:137], v[134:135] offset:2304
	v_add_u32_e32 v130, s87, v130
	v_lshlrev_b64 v[138:139], 12, v[128:129]
	v_ashrrev_i32_e32 v131, 31, v130
	v_lshl_add_u64 v[138:139], s[10:11], 0, v[138:139]
	v_lshlrev_b64 v[130:131], 1, v[130:131]
	v_lshl_add_u64 v[138:139], v[138:139], 0, v[130:131]
	v_lshl_add_u64 v[152:153], v[132:133], 0, s[44:45]
	s_waitcnt vmcnt(0) lgkmcnt(0)
	v_lshlrev_b32_e32 v161, 16, v137
	v_and_b32_e32 v137, 0xffff0000, v137
	v_lshlrev_b32_e32 v129, 16, v134
	v_and_b32_e32 v134, 0xffff0000, v134
	v_lshlrev_b32_e32 v159, 16, v135
	v_and_b32_e32 v135, 0xffff0000, v135
	v_lshlrev_b32_e32 v160, 16, v136
	v_and_b32_e32 v136, 0xffff0000, v136
	v_mul_f32_e32 v123, v123, v137
	v_mul_f32_e32 v124, v124, v129
	v_mul_f32_e32 v125, v125, v134
	v_mul_f32_e32 v126, v126, v159
	v_mul_f32_e32 v127, v127, v135
	v_mul_f32_e32 v129, v120, v160
	v_mul_f32_e32 v134, v121, v136
	v_mul_f32_e32 v135, v122, v161
	v_cvt_pk_bf16_f32 v120, v124, v125
	v_cvt_pk_bf16_f32 v121, v126, v127
	v_cvt_pk_bf16_f32 v122, v129, v134
	v_cvt_pk_bf16_f32 v123, v135, v123
	flat_store_dwordx4 v[138:139], v[120:123] sc1
	flat_load_dwordx4 v[120:123], v[152:153] offset:512
	v_add_co_u32_e32 v124, vcc, s71, v132
	s_waitcnt vmcnt(0) lgkmcnt(0)
	v_lshlrev_b32_e32 v134, 16, v123
	v_and_b32_e32 v123, 0xffff0000, v123
	v_lshlrev_b32_e32 v126, 16, v120
	v_and_b32_e32 v120, 0xffff0000, v120
	v_lshlrev_b32_e32 v127, 16, v121
	v_and_b32_e32 v121, 0xffff0000, v121
	v_lshlrev_b32_e32 v129, 16, v122
	v_and_b32_e32 v122, 0xffff0000, v122
	v_mul_f32_e32 v115, v115, v123
	v_addc_co_u32_e32 v125, vcc, 0, v133, vcc
	v_mul_f32_e32 v116, v116, v126
	v_mul_f32_e32 v117, v117, v120
	v_mul_f32_e32 v118, v118, v127
	v_mul_f32_e32 v119, v119, v121
	v_mul_f32_e32 v120, v112, v129
	v_mul_f32_e32 v121, v113, v122
	v_mul_f32_e32 v122, v114, v134
	v_cvt_pk_bf16_f32 v112, v116, v117
	v_cvt_pk_bf16_f32 v113, v118, v119
	v_cvt_pk_bf16_f32 v114, v120, v121
	v_cvt_pk_bf16_f32 v115, v122, v115
	flat_store_dwordx4 v[138:139], v[112:115] offset:256 sc1
	flat_load_dwordx4 v[112:115], v[124:125] offset:2304
	v_add_u32_e32 v116, 16, v128
	v_ashrrev_i32_e32 v117, 31, v116
	v_lshlrev_b64 v[116:117], 12, v[116:117]
	v_lshl_add_u64 v[116:117], s[10:11], 0, v[116:117]
	v_lshl_add_u64 v[116:117], v[116:117], 0, v[130:131]
	s_waitcnt vmcnt(0) lgkmcnt(0)
	v_lshlrev_b32_e32 v121, 16, v115
	v_and_b32_e32 v115, 0xffff0000, v115
	v_lshlrev_b32_e32 v118, 16, v112
	v_and_b32_e32 v112, 0xffff0000, v112
	v_lshlrev_b32_e32 v119, 16, v113
	v_and_b32_e32 v113, 0xffff0000, v113
	v_lshlrev_b32_e32 v120, 16, v114
	v_and_b32_e32 v114, 0xffff0000, v114
	v_mul_f32_e32 v107, v107, v115
	v_mul_f32_e32 v108, v108, v118
	v_mul_f32_e32 v109, v109, v112
	v_mul_f32_e32 v110, v110, v119
	v_mul_f32_e32 v111, v111, v113
	v_mul_f32_e32 v112, v104, v120
	v_mul_f32_e32 v113, v105, v114
	v_mul_f32_e32 v114, v106, v121
	v_cvt_pk_bf16_f32 v104, v108, v109
	v_cvt_pk_bf16_f32 v105, v110, v111
	v_cvt_pk_bf16_f32 v106, v112, v113
	v_cvt_pk_bf16_f32 v107, v114, v107
	flat_store_dwordx4 v[116:117], v[104:107] sc1
	flat_load_dwordx4 v[104:107], v[124:125] offset:2816
	v_add_co_u32_e32 v108, vcc, s72, v132
	s_waitcnt vmcnt(0) lgkmcnt(0)
	v_lshlrev_b32_e32 v113, 16, v107
	v_and_b32_e32 v107, 0xffff0000, v107
	v_lshlrev_b32_e32 v110, 16, v104
	v_and_b32_e32 v104, 0xffff0000, v104
	v_lshlrev_b32_e32 v111, 16, v105
	v_and_b32_e32 v105, 0xffff0000, v105
	v_lshlrev_b32_e32 v112, 16, v106
	v_and_b32_e32 v106, 0xffff0000, v106
	v_mul_f32_e32 v99, v99, v107
	v_addc_co_u32_e32 v109, vcc, 0, v133, vcc
	v_mul_f32_e32 v100, v100, v110
	v_mul_f32_e32 v101, v101, v104
	v_mul_f32_e32 v102, v102, v111
	v_mul_f32_e32 v103, v103, v105
	v_mul_f32_e32 v104, v96, v112
	v_mul_f32_e32 v105, v97, v106
	v_mul_f32_e32 v106, v98, v113
	v_cvt_pk_bf16_f32 v96, v100, v101
	v_cvt_pk_bf16_f32 v97, v102, v103
	v_cvt_pk_bf16_f32 v98, v104, v105
	v_cvt_pk_bf16_f32 v99, v106, v99
	flat_store_dwordx4 v[116:117], v[96:99] offset:256 sc1
	flat_load_dwordx4 v[96:99], v[108:109] offset:2304
	v_add_u32_e32 v100, 32, v128
	v_ashrrev_i32_e32 v101, 31, v100
	v_lshlrev_b64 v[100:101], 12, v[100:101]
	v_lshl_add_u64 v[100:101], s[10:11], 0, v[100:101]
	v_lshl_add_u64 v[100:101], v[100:101], 0, v[130:131]
	s_waitcnt vmcnt(0) lgkmcnt(0)
	v_lshlrev_b32_e32 v105, 16, v99
	v_and_b32_e32 v99, 0xffff0000, v99
	v_lshlrev_b32_e32 v102, 16, v96
	v_and_b32_e32 v96, 0xffff0000, v96
	v_lshlrev_b32_e32 v103, 16, v97
	v_and_b32_e32 v97, 0xffff0000, v97
	v_lshlrev_b32_e32 v104, 16, v98
	v_and_b32_e32 v98, 0xffff0000, v98
	v_mul_f32_e32 v91, v91, v99
	v_mul_f32_e32 v92, v92, v102
	v_mul_f32_e32 v93, v93, v96
	v_mul_f32_e32 v94, v94, v103
	v_mul_f32_e32 v95, v95, v97
	v_mul_f32_e32 v96, v88, v104
	v_mul_f32_e32 v97, v89, v98
	v_mul_f32_e32 v98, v90, v105
	v_cvt_pk_bf16_f32 v88, v92, v93
	v_cvt_pk_bf16_f32 v89, v94, v95
	v_cvt_pk_bf16_f32 v90, v96, v97
	v_cvt_pk_bf16_f32 v91, v98, v91
	flat_store_dwordx4 v[100:101], v[88:91] sc1
	flat_load_dwordx4 v[88:91], v[108:109] offset:2816
	v_add_co_u32_e32 v92, vcc, s73, v132
	s_waitcnt vmcnt(0) lgkmcnt(0)
	v_lshlrev_b32_e32 v97, 16, v91
	v_and_b32_e32 v91, 0xffff0000, v91
	v_lshlrev_b32_e32 v94, 16, v88
	v_and_b32_e32 v88, 0xffff0000, v88
	v_lshlrev_b32_e32 v95, 16, v89
	v_and_b32_e32 v89, 0xffff0000, v89
	v_lshlrev_b32_e32 v96, 16, v90
	v_and_b32_e32 v90, 0xffff0000, v90
	v_mul_f32_e32 v83, v83, v91
	v_addc_co_u32_e32 v93, vcc, 0, v133, vcc
	v_mul_f32_e32 v84, v84, v94
	v_mul_f32_e32 v85, v85, v88
	v_mul_f32_e32 v86, v86, v95
	v_mul_f32_e32 v87, v87, v89
	v_mul_f32_e32 v88, v80, v96
	v_mul_f32_e32 v89, v81, v90
	v_mul_f32_e32 v90, v82, v97
	v_cvt_pk_bf16_f32 v80, v84, v85
	v_cvt_pk_bf16_f32 v81, v86, v87
	v_cvt_pk_bf16_f32 v82, v88, v89
	v_cvt_pk_bf16_f32 v83, v90, v83
	flat_store_dwordx4 v[100:101], v[80:83] offset:256 sc1
	flat_load_dwordx4 v[80:83], v[92:93] offset:2304
	v_add_u32_e32 v84, 48, v128
	v_ashrrev_i32_e32 v85, 31, v84
	v_lshlrev_b64 v[84:85], 12, v[84:85]
	v_lshl_add_u64 v[84:85], s[10:11], 0, v[84:85]
	v_lshl_add_u64 v[84:85], v[84:85], 0, v[130:131]
	s_waitcnt vmcnt(0) lgkmcnt(0)
	v_lshlrev_b32_e32 v89, 16, v83
	v_and_b32_e32 v83, 0xffff0000, v83
	v_lshlrev_b32_e32 v86, 16, v80
	v_and_b32_e32 v80, 0xffff0000, v80
	v_lshlrev_b32_e32 v87, 16, v81
	v_and_b32_e32 v81, 0xffff0000, v81
	v_lshlrev_b32_e32 v88, 16, v82
	v_and_b32_e32 v82, 0xffff0000, v82
	v_mul_f32_e32 v75, v75, v83
	v_mul_f32_e32 v76, v76, v86
	v_mul_f32_e32 v77, v77, v80
	v_mul_f32_e32 v78, v78, v87
	v_mul_f32_e32 v79, v79, v81
	v_mul_f32_e32 v80, v72, v88
	v_mul_f32_e32 v81, v73, v82
	v_mul_f32_e32 v82, v74, v89
	v_cvt_pk_bf16_f32 v72, v76, v77
	v_cvt_pk_bf16_f32 v73, v78, v79
	v_cvt_pk_bf16_f32 v74, v80, v81
	v_cvt_pk_bf16_f32 v75, v82, v75
	flat_store_dwordx4 v[84:85], v[72:75] sc1
	flat_load_dwordx4 v[72:75], v[92:93] offset:2816
	v_add_co_u32_e32 v76, vcc, s74, v132
	s_waitcnt vmcnt(0) lgkmcnt(0)
	v_lshlrev_b32_e32 v81, 16, v75
	v_and_b32_e32 v75, 0xffff0000, v75
	v_lshlrev_b32_e32 v78, 16, v72
	v_and_b32_e32 v72, 0xffff0000, v72
	v_lshlrev_b32_e32 v79, 16, v73
	v_and_b32_e32 v73, 0xffff0000, v73
	v_lshlrev_b32_e32 v80, 16, v74
	v_and_b32_e32 v74, 0xffff0000, v74
	v_mul_f32_e32 v67, v67, v75
	v_addc_co_u32_e32 v77, vcc, 0, v133, vcc
	v_mul_f32_e32 v68, v68, v78
	v_mul_f32_e32 v69, v69, v72
	v_mul_f32_e32 v70, v70, v79
	v_mul_f32_e32 v71, v71, v73
	v_mul_f32_e32 v72, v64, v80
	v_mul_f32_e32 v73, v65, v74
	v_mul_f32_e32 v74, v66, v81
	v_cvt_pk_bf16_f32 v64, v68, v69
	v_cvt_pk_bf16_f32 v65, v70, v71
	v_cvt_pk_bf16_f32 v66, v72, v73
	v_cvt_pk_bf16_f32 v67, v74, v67
	flat_store_dwordx4 v[84:85], v[64:67] offset:256 sc1
	flat_load_dwordx4 v[64:67], v[76:77] offset:2304
	v_add_u32_e32 v68, 0x80, v128
	v_ashrrev_i32_e32 v69, 31, v68
	v_lshlrev_b64 v[68:69], 12, v[68:69]
	v_lshl_add_u64 v[68:69], s[10:11], 0, v[68:69]
	v_lshl_add_u64 v[68:69], v[68:69], 0, v[130:131]
	s_waitcnt vmcnt(0) lgkmcnt(0)
	v_lshlrev_b32_e32 v73, 16, v67
	v_and_b32_e32 v67, 0xffff0000, v67
	v_lshlrev_b32_e32 v70, 16, v64
	v_and_b32_e32 v64, 0xffff0000, v64
	v_lshlrev_b32_e32 v71, 16, v65
	v_and_b32_e32 v65, 0xffff0000, v65
	v_lshlrev_b32_e32 v72, 16, v66
	v_and_b32_e32 v66, 0xffff0000, v66
	v_mul_f32_e32 v59, v59, v67
	v_mul_f32_e32 v60, v60, v70
	v_mul_f32_e32 v61, v61, v64
	v_mul_f32_e32 v62, v62, v71
	v_mul_f32_e32 v63, v63, v65
	v_mul_f32_e32 v64, v56, v72
	v_mul_f32_e32 v65, v57, v66
	v_mul_f32_e32 v66, v58, v73
	v_cvt_pk_bf16_f32 v56, v60, v61
	v_cvt_pk_bf16_f32 v57, v62, v63
	v_cvt_pk_bf16_f32 v58, v64, v65
	v_cvt_pk_bf16_f32 v59, v66, v59
	flat_store_dwordx4 v[68:69], v[56:59] sc1
	flat_load_dwordx4 v[56:59], v[76:77] offset:2816
	v_add_co_u32_e32 v60, vcc, s75, v132
	s_waitcnt vmcnt(0) lgkmcnt(0)
	v_lshlrev_b32_e32 v65, 16, v59
	v_and_b32_e32 v59, 0xffff0000, v59
	v_lshlrev_b32_e32 v62, 16, v56
	v_and_b32_e32 v56, 0xffff0000, v56
	v_lshlrev_b32_e32 v63, 16, v57
	v_and_b32_e32 v57, 0xffff0000, v57
	v_lshlrev_b32_e32 v64, 16, v58
	v_and_b32_e32 v58, 0xffff0000, v58
	v_mul_f32_e32 v51, v51, v59
	v_addc_co_u32_e32 v61, vcc, 0, v133, vcc
	v_mul_f32_e32 v52, v52, v62
	v_mul_f32_e32 v53, v53, v56
	v_mul_f32_e32 v54, v54, v63
	v_mul_f32_e32 v55, v55, v57
	v_mul_f32_e32 v56, v48, v64
	v_mul_f32_e32 v57, v49, v58
	v_mul_f32_e32 v58, v50, v65
	v_cvt_pk_bf16_f32 v48, v52, v53
	v_cvt_pk_bf16_f32 v49, v54, v55
	v_cvt_pk_bf16_f32 v50, v56, v57
	v_cvt_pk_bf16_f32 v51, v58, v51
	flat_store_dwordx4 v[68:69], v[48:51] offset:256 sc1
	flat_load_dwordx4 v[48:51], v[60:61] offset:2304
	v_add_u32_e32 v52, 0x90, v128
	v_ashrrev_i32_e32 v53, 31, v52
	v_lshlrev_b64 v[52:53], 12, v[52:53]
	v_lshl_add_u64 v[52:53], s[10:11], 0, v[52:53]
	v_lshl_add_u64 v[52:53], v[52:53], 0, v[130:131]
	s_waitcnt vmcnt(0) lgkmcnt(0)
	v_lshlrev_b32_e32 v57, 16, v51
	v_and_b32_e32 v51, 0xffff0000, v51
	v_lshlrev_b32_e32 v54, 16, v48
	v_and_b32_e32 v48, 0xffff0000, v48
	v_lshlrev_b32_e32 v55, 16, v49
	v_and_b32_e32 v49, 0xffff0000, v49
	v_lshlrev_b32_e32 v56, 16, v50
	v_and_b32_e32 v50, 0xffff0000, v50
	v_mul_f32_e32 v43, v43, v51
	v_mul_f32_e32 v44, v44, v54
	v_mul_f32_e32 v45, v45, v48
	v_mul_f32_e32 v46, v46, v55
	v_mul_f32_e32 v47, v47, v49
	v_mul_f32_e32 v48, v40, v56
	v_mul_f32_e32 v49, v41, v50
	v_mul_f32_e32 v50, v42, v57
	v_cvt_pk_bf16_f32 v40, v44, v45
	v_cvt_pk_bf16_f32 v41, v46, v47
	v_cvt_pk_bf16_f32 v42, v48, v49
	v_cvt_pk_bf16_f32 v43, v50, v43
	flat_store_dwordx4 v[52:53], v[40:43] sc1
	flat_load_dwordx4 v[40:43], v[60:61] offset:2816
	v_add_co_u32_e32 v44, vcc, s76, v132
	s_waitcnt vmcnt(0) lgkmcnt(0)
	v_lshlrev_b32_e32 v49, 16, v43
	v_and_b32_e32 v43, 0xffff0000, v43
	v_lshlrev_b32_e32 v46, 16, v40
	v_and_b32_e32 v40, 0xffff0000, v40
	v_lshlrev_b32_e32 v47, 16, v41
	v_and_b32_e32 v41, 0xffff0000, v41
	v_lshlrev_b32_e32 v48, 16, v42
	v_and_b32_e32 v42, 0xffff0000, v42
	v_mul_f32_e32 v35, v35, v43
	v_addc_co_u32_e32 v45, vcc, 0, v133, vcc
	v_mul_f32_e32 v36, v36, v46
	v_mul_f32_e32 v37, v37, v40
	v_mul_f32_e32 v38, v38, v47
	v_mul_f32_e32 v39, v39, v41
	v_mul_f32_e32 v40, v32, v48
	v_mul_f32_e32 v41, v33, v42
	v_mul_f32_e32 v42, v34, v49
	v_cvt_pk_bf16_f32 v32, v36, v37
	v_cvt_pk_bf16_f32 v33, v38, v39
	v_cvt_pk_bf16_f32 v34, v40, v41
	v_cvt_pk_bf16_f32 v35, v42, v35
	flat_store_dwordx4 v[52:53], v[32:35] offset:256 sc1
	flat_load_dwordx4 v[32:35], v[44:45] offset:2304
	v_add_u32_e32 v36, 0xa0, v128
	v_ashrrev_i32_e32 v37, 31, v36
	v_lshlrev_b64 v[36:37], 12, v[36:37]
	v_lshl_add_u64 v[36:37], s[10:11], 0, v[36:37]
	v_lshl_add_u64 v[36:37], v[36:37], 0, v[130:131]
	s_waitcnt vmcnt(0) lgkmcnt(0)
	v_lshlrev_b32_e32 v41, 16, v35
	v_and_b32_e32 v35, 0xffff0000, v35
	v_lshlrev_b32_e32 v38, 16, v32
	v_and_b32_e32 v32, 0xffff0000, v32
	v_lshlrev_b32_e32 v39, 16, v33
	v_and_b32_e32 v33, 0xffff0000, v33
	v_lshlrev_b32_e32 v40, 16, v34
	v_and_b32_e32 v34, 0xffff0000, v34
	v_mul_f32_e32 v27, v27, v35
	v_mul_f32_e32 v28, v28, v38
	v_mul_f32_e32 v29, v29, v32
	v_mul_f32_e32 v30, v30, v39
	v_mul_f32_e32 v31, v31, v33
	v_mul_f32_e32 v32, v24, v40
	v_mul_f32_e32 v33, v25, v34
	v_mul_f32_e32 v34, v26, v41
	v_cvt_pk_bf16_f32 v24, v28, v29
	v_cvt_pk_bf16_f32 v25, v30, v31
	v_cvt_pk_bf16_f32 v26, v32, v33
	v_cvt_pk_bf16_f32 v27, v34, v27
	flat_store_dwordx4 v[36:37], v[24:27] sc1
	flat_load_dwordx4 v[24:27], v[44:45] offset:2816
	v_add_co_u32_e32 v28, vcc, s79, v132
	s_waitcnt vmcnt(0) lgkmcnt(0)
	v_lshlrev_b32_e32 v33, 16, v27
	v_and_b32_e32 v27, 0xffff0000, v27
	v_lshlrev_b32_e32 v30, 16, v24
	v_and_b32_e32 v24, 0xffff0000, v24
	v_lshlrev_b32_e32 v31, 16, v25
	v_and_b32_e32 v25, 0xffff0000, v25
	v_lshlrev_b32_e32 v32, 16, v26
	v_and_b32_e32 v26, 0xffff0000, v26
	v_mul_f32_e32 v19, v19, v27
	v_addc_co_u32_e32 v29, vcc, 0, v133, vcc
	v_mul_f32_e32 v20, v20, v30
	v_mul_f32_e32 v21, v21, v24
	v_mul_f32_e32 v22, v22, v31
	v_mul_f32_e32 v23, v23, v25
	v_mul_f32_e32 v24, v16, v32
	v_mul_f32_e32 v25, v17, v26
	v_mul_f32_e32 v26, v18, v33
	v_cvt_pk_bf16_f32 v16, v20, v21
	v_cvt_pk_bf16_f32 v17, v22, v23
	v_cvt_pk_bf16_f32 v18, v24, v25
	v_cvt_pk_bf16_f32 v19, v26, v19
	flat_store_dwordx4 v[36:37], v[16:19] offset:256 sc1
	flat_load_dwordx4 v[16:19], v[28:29] offset:2304
	v_add_u32_e32 v20, 0xb0, v128
	v_ashrrev_i32_e32 v21, 31, v20
	v_lshlrev_b64 v[20:21], 12, v[20:21]
	v_lshl_add_u64 v[20:21], s[10:11], 0, v[20:21]
	v_lshl_add_u64 v[20:21], v[20:21], 0, v[130:131]
	s_andn2_b64 vcc, exec, s[50:51]
	s_mov_b64 s[50:51], -1
	s_waitcnt vmcnt(0) lgkmcnt(0)
	v_lshlrev_b32_e32 v25, 16, v19
	v_and_b32_e32 v19, 0xffff0000, v19
	v_lshlrev_b32_e32 v22, 16, v16
	v_and_b32_e32 v16, 0xffff0000, v16
	v_lshlrev_b32_e32 v23, 16, v17
	v_and_b32_e32 v17, 0xffff0000, v17
	v_lshlrev_b32_e32 v24, 16, v18
	v_and_b32_e32 v18, 0xffff0000, v18
	v_mul_f32_e32 v11, v11, v19
	v_mul_f32_e32 v12, v12, v22
	v_mul_f32_e32 v13, v13, v16
	v_mul_f32_e32 v14, v14, v23
	v_mul_f32_e32 v15, v15, v17
	v_mul_f32_e32 v16, v8, v24
	v_mul_f32_e32 v17, v9, v18
	v_mul_f32_e32 v18, v10, v25
	v_cvt_pk_bf16_f32 v8, v12, v13
	v_cvt_pk_bf16_f32 v9, v14, v15
	v_cvt_pk_bf16_f32 v10, v16, v17
	v_cvt_pk_bf16_f32 v11, v18, v11
	flat_store_dwordx4 v[20:21], v[8:11] sc1
	flat_load_dwordx4 v[8:11], v[28:29] offset:2816
	s_waitcnt vmcnt(0) lgkmcnt(0)
	v_lshlrev_b32_e32 v15, 16, v11
	v_and_b32_e32 v11, 0xffff0000, v11
	v_lshlrev_b32_e32 v12, 16, v8
	v_and_b32_e32 v8, 0xffff0000, v8
	v_lshlrev_b32_e32 v13, 16, v9
	v_and_b32_e32 v9, 0xffff0000, v9
	v_lshlrev_b32_e32 v14, 16, v10
	v_and_b32_e32 v10, 0xffff0000, v10
	v_mul_f32_e32 v3, v3, v11
	v_mul_f32_e32 v4, v4, v12
	v_mul_f32_e32 v5, v5, v8
	v_mul_f32_e32 v6, v6, v13
	v_mul_f32_e32 v7, v7, v9
	v_mul_f32_e32 v8, v0, v14
	v_mul_f32_e32 v9, v1, v10
	v_mul_f32_e32 v10, v2, v15
	v_cvt_pk_bf16_f32 v0, v4, v5
	v_cvt_pk_bf16_f32 v1, v6, v7
	v_cvt_pk_bf16_f32 v2, v8, v9
	v_cvt_pk_bf16_f32 v3, v10, v3
	flat_store_dwordx4 v[20:21], v[0:3] offset:256 sc1
	s_cbranch_vccnz .LBB0_436
	s_andn2_b64 vcc, exec, s[6:7]
	s_cbranch_vccnz .LBB0_435
	s_barrier
	s_branch .LBB0_435

.LBB0_490:
	s_ashr_i32 s9, s8, 31
	s_lshl_b64 s[8:9], s[8:9], 3
	s_add_u32 s10, s0, s8
	s_addc_u32 s11, s1, s9
	s_lshr_b32 s8, s19, 5
	v_cvt_f32_u32_e32 v8, s8
	s_load_dwordx2 s[40:41], s[10:11], 0x0
	s_sub_i32 s10, 0, s8
	s_abs_i32 s13, s29
	v_rcp_iflag_f32_e32 v8, v8
	s_ashr_i32 s12, s29, 31
	s_mov_b32 s9, 0
	s_mov_b32 s38, 1
	v_mul_f32_e32 v8, 0x4f7ffffe, v8
	v_cvt_u32_f32_e32 v8, v8
	s_nop 0
	v_readfirstlane_b32 s11, v8
	s_mul_i32 s10, s10, s11
	s_mul_hi_u32 s10, s11, s10
	s_add_i32 s11, s11, s10
	s_mul_hi_u32 s10, s13, s11
	s_mul_i32 s11, s10, s8
	s_sub_i32 s11, s13, s11
	s_add_i32 s39, s10, 1
	s_sub_i32 s13, s11, s8
	s_cmp_ge_u32 s11, s8
	s_cselect_b32 s10, s39, s10
	s_cselect_b32 s11, s13, s11
	s_add_i32 s13, s10, 1
	s_cmp_ge_u32 s11, s8
	s_cselect_b32 s10, s13, s10
	s_xor_b32 s10, s10, s12
	s_sub_i32 s10, s10, s12
	s_mul_i32 s8, s10, s8
	s_sub_i32 s11, s29, s8
	s_lshl_b32 s8, s10, 6
	s_lshl_b32 s10, s11, 5
	s_ashr_i32 s11, s10, 31
	s_lshl_b64 s[42:43], s[10:11], 2
	s_waitcnt lgkmcnt(0)
	s_add_u32 s40, s40, s42
	s_addc_u32 s41, s41, s43
	s_mul_i32 s70, s8, s19
	s_lshl_b32 s71, s19, 2
	s_lshl_b32 s70, s70, 2
	s_add_u32 s40, s40, s70
	s_addc_u32 s41, s41, 0
	v_mad_u32_u24 v210, v0, s71, v6
	v_mad_u32_u24 v211, v0, s15, v4
	s_lshl_b32 s71, s71, 1
	global_load_dword v166, v210, s[40:41]
	s_add_u32 s40, s40, s71
	s_addc_u32 s41, s41, 0
	global_load_dword v167, v210, s[40:41]
	s_add_u32 s40, s40, s71
	s_addc_u32 s41, s41, 0
	global_load_dword v168, v210, s[40:41]
	s_add_u32 s40, s40, s71
	s_addc_u32 s41, s41, 0
	global_load_dword v169, v210, s[40:41]
	s_add_u32 s40, s40, s71
	s_addc_u32 s41, s41, 0
	global_load_dword v170, v210, s[40:41]
	s_add_u32 s40, s40, s71
	s_addc_u32 s41, s41, 0
	global_load_dword v171, v210, s[40:41]
	s_add_u32 s40, s40, s71
	s_addc_u32 s41, s41, 0
	global_load_dword v172, v210, s[40:41]
	s_add_u32 s40, s40, s71
	s_addc_u32 s41, s41, 0
	global_load_dword v173, v210, s[40:41]
	s_add_u32 s40, s40, s71
	s_addc_u32 s41, s41, 0
	global_load_dword v174, v210, s[40:41]
	s_add_u32 s40, s40, s71
	s_addc_u32 s41, s41, 0
	global_load_dword v175, v210, s[40:41]
	s_add_u32 s40, s40, s71
	s_addc_u32 s41, s41, 0
	global_load_dword v176, v210, s[40:41]
	s_add_u32 s40, s40, s71
	s_addc_u32 s41, s41, 0
	global_load_dword v177, v210, s[40:41]
	s_add_u32 s40, s40, s71
	s_addc_u32 s41, s41, 0
	global_load_dword v178, v210, s[40:41]
	s_add_u32 s40, s40, s71
	s_addc_u32 s41, s41, 0
	global_load_dword v179, v210, s[40:41]
	s_add_u32 s40, s40, s71
	s_addc_u32 s41, s41, 0
	global_load_dword v180, v210, s[40:41]
	s_add_u32 s40, s40, s71
	s_addc_u32 s41, s41, 0
	global_load_dword v181, v210, s[40:41]
	s_add_u32 s40, s40, s71
	s_addc_u32 s41, s41, 0
	global_load_dword v182, v210, s[40:41]
	s_add_u32 s40, s40, s71
	s_addc_u32 s41, s41, 0
	global_load_dword v183, v210, s[40:41]
	s_add_u32 s40, s40, s71
	s_addc_u32 s41, s41, 0
	global_load_dword v184, v210, s[40:41]
	s_add_u32 s40, s40, s71
	s_addc_u32 s41, s41, 0
	global_load_dword v185, v210, s[40:41]
	s_add_u32 s40, s40, s71
	s_addc_u32 s41, s41, 0
	global_load_dword v186, v210, s[40:41]
	s_add_u32 s40, s40, s71
	s_addc_u32 s41, s41, 0
	global_load_dword v187, v210, s[40:41]
	s_add_u32 s40, s40, s71
	s_addc_u32 s41, s41, 0
	global_load_dword v188, v210, s[40:41]
	s_add_u32 s40, s40, s71
	s_addc_u32 s41, s41, 0
	global_load_dword v189, v210, s[40:41]
	s_add_u32 s40, s40, s71
	s_addc_u32 s41, s41, 0
	global_load_dword v190, v210, s[40:41]
	s_add_u32 s40, s40, s71
	s_addc_u32 s41, s41, 0
	global_load_dword v191, v210, s[40:41]
	s_add_u32 s40, s40, s71
	s_addc_u32 s41, s41, 0
	global_load_dword v192, v210, s[40:41]
	s_add_u32 s40, s40, s71
	s_addc_u32 s41, s41, 0
	global_load_dword v193, v210, s[40:41]
	s_add_u32 s40, s40, s71
	s_addc_u32 s41, s41, 0
	global_load_dword v194, v210, s[40:41]
	s_add_u32 s40, s40, s71
	s_addc_u32 s41, s41, 0
	global_load_dword v195, v210, s[40:41]
	s_add_u32 s40, s40, s71
	s_addc_u32 s41, s41, 0
	global_load_dword v198, v210, s[40:41]
	s_add_u32 s40, s40, s71
	s_addc_u32 s41, s41, 0
	global_load_dword v199, v210, s[40:41]
	s_waitcnt vmcnt(31)
	ds_write_b32 v211, v166
	s_waitcnt vmcnt(30)
	ds_write_b32 v211, v167 offset:264
	s_waitcnt vmcnt(29)
	ds_write_b32 v211, v168 offset:528
	s_waitcnt vmcnt(28)
	ds_write_b32 v211, v169 offset:792
	s_waitcnt vmcnt(27)
	ds_write_b32 v211, v170 offset:1056
	s_waitcnt vmcnt(26)
	ds_write_b32 v211, v171 offset:1320
	s_waitcnt vmcnt(25)
	ds_write_b32 v211, v172 offset:1584
	s_waitcnt vmcnt(24)
	ds_write_b32 v211, v173 offset:1848
	s_waitcnt vmcnt(23)
	ds_write_b32 v211, v174 offset:2112
	s_waitcnt vmcnt(22)
	ds_write_b32 v211, v175 offset:2376
	s_waitcnt vmcnt(21)
	ds_write_b32 v211, v176 offset:2640
	s_waitcnt vmcnt(20)
	ds_write_b32 v211, v177 offset:2904
	s_waitcnt vmcnt(19)
	ds_write_b32 v211, v178 offset:3168
	s_waitcnt vmcnt(18)
	ds_write_b32 v211, v179 offset:3432
	s_waitcnt vmcnt(17)
	ds_write_b32 v211, v180 offset:3696
	s_waitcnt vmcnt(16)
	ds_write_b32 v211, v181 offset:3960
	s_waitcnt vmcnt(15)
	ds_write_b32 v211, v182 offset:4224
	s_waitcnt vmcnt(14)
	ds_write_b32 v211, v183 offset:4488
	s_waitcnt vmcnt(13)
	ds_write_b32 v211, v184 offset:4752
	s_waitcnt vmcnt(12)
	ds_write_b32 v211, v185 offset:5016
	s_waitcnt vmcnt(11)
	ds_write_b32 v211, v186 offset:5280
	s_waitcnt vmcnt(10)
	ds_write_b32 v211, v187 offset:5544
	s_waitcnt vmcnt(9)
	ds_write_b32 v211, v188 offset:5808
	s_waitcnt vmcnt(8)
	ds_write_b32 v211, v189 offset:6072
	s_waitcnt vmcnt(7)
	ds_write_b32 v211, v190 offset:6336
	s_waitcnt vmcnt(6)
	ds_write_b32 v211, v191 offset:6600
	s_waitcnt vmcnt(5)
	ds_write_b32 v211, v192 offset:6864
	s_waitcnt vmcnt(4)
	ds_write_b32 v211, v193 offset:7128
	s_waitcnt vmcnt(3)
	ds_write_b32 v211, v194 offset:7392
	s_waitcnt vmcnt(2)
	ds_write_b32 v211, v195 offset:7656
	s_waitcnt vmcnt(1)
	ds_write_b32 v211, v198 offset:7920
	s_waitcnt vmcnt(0)
	ds_write_b32 v211, v199 offset:8184
	s_add_u32 s9, s34, s4
	s_waitcnt lgkmcnt(0)
	s_addc_u32 s11, s35, s5
	s_add_i32 s10, s10, s25
	s_lshl_b64 s[4:5], s[6:7], 1
	s_add_u32 s6, s9, s4
	ds_read2_b32 v[166:167], v10 offset1:33
	ds_read2_b32 v[168:169], v10 offset0:66 offset1:99
	ds_read2_b32 v[170:171], v10 offset0:132 offset1:165
	ds_read2_b32 v[172:173], v10 offset0:198 offset1:231
	ds_read2_b32 v[174:175], v10 offset0:8 offset1:41
	ds_read2_b32 v[176:177], v10 offset0:74 offset1:107
	ds_read2_b32 v[178:179], v10 offset0:140 offset1:173
	ds_read2_b32 v[180:181], v10 offset0:206 offset1:239
	ds_read2_b32 v[182:183], v10 offset0:16 offset1:49
	ds_read2_b32 v[184:185], v10 offset0:82 offset1:115
	ds_read2_b32 v[186:187], v10 offset0:148 offset1:181
	ds_read2_b32 v[188:189], v10 offset0:214 offset1:247
	ds_read2_b32 v[190:191], v10 offset0:24 offset1:57
	ds_read2_b32 v[192:193], v10 offset0:90 offset1:123
	ds_read2_b32 v[194:195], v10 offset0:156 offset1:189
	ds_read2_b32 v[198:199], v10 offset0:222 offset1:255
	s_addc_u32 s7, s11, s5
	s_ashr_i32 s9, s8, 31
	s_waitcnt lgkmcnt(12)
	v_cvt_pk_bf16_f32 v14, v166, v167
	s_lshl_b64 s[4:5], s[8:9], 1
	s_waitcnt lgkmcnt(12)
	v_cvt_pk_bf16_f32 v15, v168, v169
	v_add_u32_e32 v18, s10, v5
	s_add_u32 s4, s6, s4
	v_ashrrev_i32_e32 v19, 31, v18
	s_waitcnt lgkmcnt(12)
	v_cvt_pk_bf16_f32 v16, v170, v171
	s_addc_u32 s5, s7, s5
	v_lshl_add_u64 v[20:21], s[4:5], 0, v[2:3]
	s_waitcnt lgkmcnt(12)
	v_cvt_pk_bf16_f32 v17, v172, v173
	v_lshlrev_b64 v[8:9], 12, v[18:19]
	v_lshl_add_u64 v[8:9], v[20:21], 0, v[8:9]
	global_store_dwordx4 v[8:9], v[14:17], off sc1
	s_nop 1
	v_add_u32_e32 v18, s10, v11
	v_ashrrev_i32_e32 v19, 31, v18
	s_waitcnt lgkmcnt(8)
	v_cvt_pk_bf16_f32 v14, v174, v175
	v_lshlrev_b64 v[18:19], 12, v[18:19]
	s_waitcnt lgkmcnt(8)
	v_cvt_pk_bf16_f32 v15, v176, v177
	v_lshl_add_u64 v[18:19], v[20:21], 0, v[18:19]
	s_waitcnt lgkmcnt(8)
	v_cvt_pk_bf16_f32 v16, v178, v179
	s_waitcnt lgkmcnt(8)
	v_cvt_pk_bf16_f32 v17, v180, v181
	global_store_dwordx4 v[18:19], v[14:17], off sc1
	s_nop 1
	v_add_u32_e32 v18, s10, v12
	v_ashrrev_i32_e32 v19, 31, v18
	s_waitcnt lgkmcnt(4)
	v_cvt_pk_bf16_f32 v14, v182, v183
	v_lshlrev_b64 v[18:19], 12, v[18:19]
	s_waitcnt lgkmcnt(4)
	v_cvt_pk_bf16_f32 v15, v184, v185
	v_lshl_add_u64 v[18:19], v[20:21], 0, v[18:19]
	s_waitcnt lgkmcnt(4)
	v_cvt_pk_bf16_f32 v16, v186, v187
	s_waitcnt lgkmcnt(4)
	v_cvt_pk_bf16_f32 v17, v188, v189
	global_store_dwordx4 v[18:19], v[14:17], off sc1
	s_nop 1
	v_add_u32_e32 v18, s10, v13
	v_ashrrev_i32_e32 v19, 31, v18
	s_waitcnt lgkmcnt(0)
	v_cvt_pk_bf16_f32 v14, v190, v191
	v_lshlrev_b64 v[18:19], 12, v[18:19]
	s_waitcnt lgkmcnt(0)
	v_cvt_pk_bf16_f32 v15, v192, v193
	v_lshl_add_u64 v[18:19], v[20:21], 0, v[18:19]
	s_waitcnt lgkmcnt(0)
	v_cvt_pk_bf16_f32 v16, v194, v195
	s_waitcnt lgkmcnt(0)
	v_cvt_pk_bf16_f32 v17, v198, v199
	global_store_dwordx4 v[18:19], v[14:17], off sc1
	s_nop 1
	s_waitcnt lgkmcnt(0)
	s_add_i32 s3, s3, s14
	s_cmpk_lt_i32 s3, 0x7400
	s_cbranch_scc1 .LBB0_454

.LBB0_564:
	v_mov_b32_e32 v140, v158
	v_mov_b32_e32 v166, v159
	s_cmp_lg_u32 s8, 0
	v_add_u32_e32 v156, s83, v140
	v_ashrrev_i32_e32 v157, 31, v156
	v_add_u32_e32 v154, 16, v156
	v_add_u32_e32 v152, 32, v156
	v_add_u32_e32 v150, 48, v156
	v_add_u32_e32 v146, 0x80, v156
	v_add_u32_e32 v144, 0x90, v156
	v_add_u32_e32 v142, 0xa0, v156
	v_add_u32_e32 v140, 0xb0, v156
	s_cbranch_scc0 .LBB0_571
	s_add_i32 s8, s8, -1
	s_lshl_b64 s[12:13], s[8:9], 22
	s_add_u32 s8, s79, s12
	s_addc_u32 s41, s82, s13
	s_ashr_i32 s59, s58, 31
	s_lshl_b64 s[12:13], s[58:59], 12
	s_add_u32 s8, s8, s12
	s_addc_u32 s41, s41, s13
	s_ashr_i32 s51, s50, 31
	s_lshl_b64 s[12:13], s[50:51], 1
	s_add_u32 s8, s8, s12
	s_addc_u32 s13, s41, s13
	s_add_u32 s12, s8, s92
	v_lshlrev_b32_e32 v148, 3, v166
	s_addc_u32 s13, s13, 0
	v_ashrrev_i32_e32 v149, 31, v148
	v_lshl_add_u64 v[148:149], v[148:149], 1, s[12:13]
	v_lshlrev_b64 v[168:169], 12, v[156:157]
	v_lshl_add_u64 v[172:173], v[148:149], 0, v[168:169]
	v_cvt_pk_bf16_f32 v168, v124, v125
	v_cvt_pk_bf16_f32 v169, v126, v127
	v_cvt_pk_bf16_f32 v170, v120, v121
	v_cvt_pk_bf16_f32 v171, v122, v123
	flat_store_dwordx4 v[172:173], v[168:171] sc1
	v_ashrrev_i32_e32 v155, 31, v154
	v_ashrrev_i32_e32 v153, 31, v152
	v_cvt_pk_bf16_f32 v168, v116, v117
	v_cvt_pk_bf16_f32 v169, v118, v119
	v_cvt_pk_bf16_f32 v170, v112, v113
	v_cvt_pk_bf16_f32 v171, v114, v115
	flat_store_dwordx4 v[172:173], v[168:171] offset:256 sc1
	v_ashrrev_i32_e32 v151, 31, v150
	v_ashrrev_i32_e32 v147, 31, v146
	v_lshlrev_b64 v[168:169], 12, v[154:155]
	v_lshl_add_u64 v[172:173], v[148:149], 0, v[168:169]
	v_cvt_pk_bf16_f32 v168, v108, v109
	v_cvt_pk_bf16_f32 v169, v110, v111
	v_cvt_pk_bf16_f32 v170, v104, v105
	v_cvt_pk_bf16_f32 v171, v106, v107
	flat_store_dwordx4 v[172:173], v[168:171] sc1
	v_ashrrev_i32_e32 v145, 31, v144
	v_ashrrev_i32_e32 v143, 31, v142
	v_cvt_pk_bf16_f32 v168, v100, v101
	v_cvt_pk_bf16_f32 v169, v102, v103
	v_cvt_pk_bf16_f32 v170, v96, v97
	v_cvt_pk_bf16_f32 v171, v98, v99
	flat_store_dwordx4 v[172:173], v[168:171] offset:256 sc1
	v_ashrrev_i32_e32 v141, 31, v140
	s_nop 0
	v_lshlrev_b64 v[168:169], 12, v[152:153]
	v_lshl_add_u64 v[172:173], v[148:149], 0, v[168:169]
	v_cvt_pk_bf16_f32 v168, v92, v93
	v_cvt_pk_bf16_f32 v169, v94, v95
	v_cvt_pk_bf16_f32 v170, v88, v89
	v_cvt_pk_bf16_f32 v171, v90, v91
	flat_store_dwordx4 v[172:173], v[168:171] sc1
	s_nop 1
	v_cvt_pk_bf16_f32 v168, v84, v85
	v_cvt_pk_bf16_f32 v169, v86, v87
	v_cvt_pk_bf16_f32 v170, v80, v81
	v_cvt_pk_bf16_f32 v171, v82, v83
	flat_store_dwordx4 v[172:173], v[168:171] offset:256 sc1
	s_nop 1
	v_lshlrev_b64 v[168:169], 12, v[150:151]
	v_lshl_add_u64 v[172:173], v[148:149], 0, v[168:169]
	v_cvt_pk_bf16_f32 v168, v76, v77
	v_cvt_pk_bf16_f32 v169, v78, v79
	v_cvt_pk_bf16_f32 v170, v72, v73
	v_cvt_pk_bf16_f32 v171, v74, v75
	flat_store_dwordx4 v[172:173], v[168:171] sc1
	s_nop 1
	v_cvt_pk_bf16_f32 v168, v68, v69
	v_cvt_pk_bf16_f32 v169, v70, v71
	v_cvt_pk_bf16_f32 v170, v64, v65
	v_cvt_pk_bf16_f32 v171, v66, v67
	flat_store_dwordx4 v[172:173], v[168:171] offset:256 sc1
	s_nop 1
	v_lshlrev_b64 v[168:169], 12, v[146:147]
	v_lshl_add_u64 v[172:173], v[148:149], 0, v[168:169]
	v_cvt_pk_bf16_f32 v168, v60, v61
	v_cvt_pk_bf16_f32 v169, v62, v63
	v_cvt_pk_bf16_f32 v170, v56, v57
	v_cvt_pk_bf16_f32 v171, v58, v59
	flat_store_dwordx4 v[172:173], v[168:171] sc1
	s_nop 1
	v_cvt_pk_bf16_f32 v168, v52, v53
	v_cvt_pk_bf16_f32 v169, v54, v55
	v_cvt_pk_bf16_f32 v170, v48, v49
	v_cvt_pk_bf16_f32 v171, v50, v51
	flat_store_dwordx4 v[172:173], v[168:171] offset:256 sc1
	s_nop 1
	v_lshlrev_b64 v[168:169], 12, v[144:145]
	v_lshl_add_u64 v[172:173], v[148:149], 0, v[168:169]
	v_cvt_pk_bf16_f32 v168, v44, v45
	v_cvt_pk_bf16_f32 v169, v46, v47
	v_cvt_pk_bf16_f32 v170, v40, v41
	v_cvt_pk_bf16_f32 v171, v42, v43
	flat_store_dwordx4 v[172:173], v[168:171] sc1
	s_nop 1
	v_cvt_pk_bf16_f32 v168, v36, v37
	v_cvt_pk_bf16_f32 v169, v38, v39
	v_cvt_pk_bf16_f32 v170, v32, v33
	v_cvt_pk_bf16_f32 v171, v34, v35
	flat_store_dwordx4 v[172:173], v[168:171] offset:256 sc1
	s_nop 1
	v_lshlrev_b64 v[168:169], 12, v[142:143]
	v_lshl_add_u64 v[172:173], v[148:149], 0, v[168:169]
	v_cvt_pk_bf16_f32 v168, v28, v29
	v_cvt_pk_bf16_f32 v169, v30, v31
	v_cvt_pk_bf16_f32 v170, v24, v25
	v_cvt_pk_bf16_f32 v171, v26, v27
	flat_store_dwordx4 v[172:173], v[168:171] sc1
	s_nop 1
	v_cvt_pk_bf16_f32 v168, v20, v21
	v_cvt_pk_bf16_f32 v169, v22, v23
	v_cvt_pk_bf16_f32 v170, v16, v17
	v_cvt_pk_bf16_f32 v171, v18, v19
	flat_store_dwordx4 v[172:173], v[168:171] offset:256 sc1
	s_nop 1
	v_lshlrev_b64 v[168:169], 12, v[140:141]
	v_lshl_add_u64 v[148:149], v[148:149], 0, v[168:169]
	v_cvt_pk_bf16_f32 v168, v12, v13
	v_cvt_pk_bf16_f32 v169, v14, v15
	v_cvt_pk_bf16_f32 v170, v8, v9
	v_cvt_pk_bf16_f32 v171, v10, v11
	flat_store_dwordx4 v[148:149], v[168:171] sc1
	s_nop 1
	v_cvt_pk_bf16_f32 v168, v4, v5
	v_cvt_pk_bf16_f32 v169, v6, v7
	v_cvt_pk_bf16_f32 v170, v0, v1
	v_cvt_pk_bf16_f32 v171, v2, v3
	flat_store_dwordx4 v[148:149], v[168:171] offset:256 sc1
	s_cbranch_execnz .LBB0_567
.LBB0_566:
	s_add_i32 s8, s58, 0xffffe000
	s_ashr_i32 s59, s58, 31
	s_cmpk_lt_i32 s58, 0x2000
	s_cselect_b32 s13, s59, 0
	s_cselect_b32 s12, s58, s8
	s_waitcnt lgkmcnt(0)
	s_cselect_b32 s8, s5, s7
	s_cselect_b32 s41, s4, s6
	s_lshl_b64 s[12:13], s[12:13], 13
	v_lshl_add_u32 v148, v166, 3, s84
	s_add_u32 s60, s41, s12
	v_ashrrev_i32_e32 v149, 31, v148
	v_lshlrev_b64 v[156:157], 11, v[156:157]
	s_addc_u32 s61, s8, s13
	v_lshl_add_u64 v[156:157], v[156:157], 0, v[148:149]
	s_ashr_i32 s51, s50, 31
	v_lshl_add_u64 v[156:157], v[156:157], 0, s[50:51]
	v_lshl_add_u64 v[174:175], v[156:157], 2, s[60:61]
	global_load_dwordx4 v[166:169], v[174:175], off
	global_load_dwordx4 v[170:173], v[174:175], off offset:16
	s_lshl_b64 s[12:13], s[58:59], 12
	s_add_u32 s58, s75, s12
	s_addc_u32 s59, s76, s13
	v_lshl_add_u64 v[156:157], v[156:157], 1, s[58:59]
	v_ashrrev_i32_e32 v155, 31, v154
	v_lshlrev_b64 v[154:155], 11, v[154:155]
	v_lshl_add_u64 v[154:155], v[154:155], 0, v[148:149]
	v_lshl_add_u64 v[154:155], v[154:155], 0, s[50:51]
	v_ashrrev_i32_e32 v153, 31, v152
	v_ashrrev_i32_e32 v151, 31, v150
	v_ashrrev_i32_e32 v147, 31, v146
	v_ashrrev_i32_e32 v145, 31, v144
	v_ashrrev_i32_e32 v143, 31, v142
	v_ashrrev_i32_e32 v141, 31, v140
	s_waitcnt vmcnt(0)
	v_pk_add_f32 v[124:125], v[124:125], v[166:167]
	v_pk_add_f32 v[166:167], v[122:123], v[172:173]
	v_pk_add_f32 v[122:123], v[120:121], v[170:171]
	v_pk_add_f32 v[126:127], v[126:127], v[168:169]
	v_cvt_pk_bf16_f32 v120, v124, v125
	s_nop 0
	v_cvt_pk_bf16_f32 v121, v126, v127
	v_cvt_pk_bf16_f32 v122, v122, v123
	v_cvt_pk_bf16_f32 v123, v166, v167
	flat_store_dwordx4 v[156:157], v[120:123] sc1
	global_load_dwordx4 v[120:123], v[174:175], off offset:512
	s_nop 0
	global_load_dwordx4 v[124:127], v[174:175], off offset:528
	v_lshl_add_u64 v[166:167], v[154:155], 2, s[60:61]
	s_waitcnt vmcnt(0)
	v_pk_add_f32 v[116:117], v[116:117], v[120:121]
	v_pk_add_f32 v[120:121], v[114:115], v[126:127]
	v_pk_add_f32 v[114:115], v[112:113], v[124:125]
	v_pk_add_f32 v[118:119], v[118:119], v[122:123]
	v_cvt_pk_bf16_f32 v112, v116, v117
	s_nop 0
	v_cvt_pk_bf16_f32 v113, v118, v119
	v_cvt_pk_bf16_f32 v114, v114, v115
	v_cvt_pk_bf16_f32 v115, v120, v121
	flat_store_dwordx4 v[156:157], v[112:115] offset:256 sc1
	global_load_dwordx4 v[112:115], v[166:167], off
	s_nop 0
	global_load_dwordx4 v[116:119], v[166:167], off offset:16
	v_lshl_add_u64 v[120:121], v[154:155], 1, s[58:59]
	s_waitcnt vmcnt(0)
	v_pk_add_f32 v[108:109], v[108:109], v[112:113]
	v_pk_add_f32 v[112:113], v[106:107], v[118:119]
	v_pk_add_f32 v[106:107], v[104:105], v[116:117]
	v_pk_add_f32 v[110:111], v[110:111], v[114:115]
	v_cvt_pk_bf16_f32 v104, v108, v109
	s_nop 0
	v_cvt_pk_bf16_f32 v105, v110, v111
	v_cvt_pk_bf16_f32 v106, v106, v107
	v_cvt_pk_bf16_f32 v107, v112, v113
	flat_store_dwordx4 v[120:121], v[104:107] sc1
	global_load_dwordx4 v[104:107], v[166:167], off offset:512
	s_nop 0
	global_load_dwordx4 v[108:111], v[166:167], off offset:528
	v_lshlrev_b64 v[112:113], 11, v[152:153]
	v_lshl_add_u64 v[112:113], v[112:113], 0, v[148:149]
	v_lshl_add_u64 v[112:113], v[112:113], 0, s[50:51]
	v_lshl_add_u64 v[114:115], v[112:113], 2, s[60:61]
	s_waitcnt vmcnt(0)
	v_pk_add_f32 v[100:101], v[100:101], v[104:105]
	v_pk_add_f32 v[104:105], v[98:99], v[110:111]
	v_pk_add_f32 v[98:99], v[96:97], v[108:109]
	v_pk_add_f32 v[102:103], v[102:103], v[106:107]
	v_cvt_pk_bf16_f32 v96, v100, v101
	s_nop 0
	v_cvt_pk_bf16_f32 v97, v102, v103
	v_cvt_pk_bf16_f32 v98, v98, v99
	v_cvt_pk_bf16_f32 v99, v104, v105
	flat_store_dwordx4 v[120:121], v[96:99] offset:256 sc1
	global_load_dwordx4 v[96:99], v[114:115], off
	s_nop 0
	global_load_dwordx4 v[100:103], v[114:115], off offset:16
	v_lshl_add_u64 v[104:105], v[112:113], 1, s[58:59]
	s_waitcnt vmcnt(0)
	v_pk_add_f32 v[92:93], v[92:93], v[96:97]
	v_pk_add_f32 v[96:97], v[90:91], v[102:103]
	v_pk_add_f32 v[90:91], v[88:89], v[100:101]
	v_pk_add_f32 v[94:95], v[94:95], v[98:99]
	v_cvt_pk_bf16_f32 v88, v92, v93
	s_nop 0
	v_cvt_pk_bf16_f32 v89, v94, v95
	v_cvt_pk_bf16_f32 v90, v90, v91
	v_cvt_pk_bf16_f32 v91, v96, v97
	flat_store_dwordx4 v[104:105], v[88:91] sc1
	global_load_dwordx4 v[88:91], v[114:115], off offset:512
	s_nop 0
	global_load_dwordx4 v[92:95], v[114:115], off offset:528
	v_lshlrev_b64 v[96:97], 11, v[150:151]
	v_lshl_add_u64 v[96:97], v[96:97], 0, v[148:149]
	v_lshl_add_u64 v[96:97], v[96:97], 0, s[50:51]
	v_lshl_add_u64 v[98:99], v[96:97], 2, s[60:61]
	s_waitcnt vmcnt(0)
	v_pk_add_f32 v[84:85], v[84:85], v[88:89]
	v_pk_add_f32 v[88:89], v[82:83], v[94:95]
	v_pk_add_f32 v[82:83], v[80:81], v[92:93]
	v_pk_add_f32 v[86:87], v[86:87], v[90:91]
	v_cvt_pk_bf16_f32 v80, v84, v85
	s_nop 0
	v_cvt_pk_bf16_f32 v81, v86, v87
	v_cvt_pk_bf16_f32 v82, v82, v83
	v_cvt_pk_bf16_f32 v83, v88, v89
	flat_store_dwordx4 v[104:105], v[80:83] offset:256 sc1
	global_load_dwordx4 v[80:83], v[98:99], off
	s_nop 0
	global_load_dwordx4 v[84:87], v[98:99], off offset:16
	v_lshl_add_u64 v[88:89], v[96:97], 1, s[58:59]
	s_waitcnt vmcnt(0)
	v_pk_add_f32 v[76:77], v[76:77], v[80:81]
	v_pk_add_f32 v[80:81], v[74:75], v[86:87]
	v_pk_add_f32 v[74:75], v[72:73], v[84:85]
	v_pk_add_f32 v[78:79], v[78:79], v[82:83]
	v_cvt_pk_bf16_f32 v72, v76, v77
	s_nop 0
	v_cvt_pk_bf16_f32 v73, v78, v79
	v_cvt_pk_bf16_f32 v74, v74, v75
	v_cvt_pk_bf16_f32 v75, v80, v81
	flat_store_dwordx4 v[88:89], v[72:75] sc1
	global_load_dwordx4 v[72:75], v[98:99], off offset:512
	s_nop 0
	global_load_dwordx4 v[76:79], v[98:99], off offset:528
	v_lshlrev_b64 v[80:81], 11, v[146:147]
	v_lshl_add_u64 v[80:81], v[80:81], 0, v[148:149]
	v_lshl_add_u64 v[80:81], v[80:81], 0, s[50:51]
	v_lshl_add_u64 v[82:83], v[80:81], 2, s[60:61]
	s_waitcnt vmcnt(0)
	v_pk_add_f32 v[68:69], v[68:69], v[72:73]
	v_pk_add_f32 v[72:73], v[66:67], v[78:79]
	v_pk_add_f32 v[66:67], v[64:65], v[76:77]
	v_pk_add_f32 v[70:71], v[70:71], v[74:75]
	v_cvt_pk_bf16_f32 v64, v68, v69
	s_nop 0
	v_cvt_pk_bf16_f32 v65, v70, v71
	v_cvt_pk_bf16_f32 v66, v66, v67
	v_cvt_pk_bf16_f32 v67, v72, v73
	flat_store_dwordx4 v[88:89], v[64:67] offset:256 sc1
	global_load_dwordx4 v[64:67], v[82:83], off
	s_nop 0
	global_load_dwordx4 v[68:71], v[82:83], off offset:16
	v_lshl_add_u64 v[72:73], v[80:81], 1, s[58:59]
	s_waitcnt vmcnt(0)
	v_pk_add_f32 v[60:61], v[60:61], v[64:65]
	v_pk_add_f32 v[64:65], v[58:59], v[70:71]
	v_pk_add_f32 v[58:59], v[56:57], v[68:69]
	v_pk_add_f32 v[62:63], v[62:63], v[66:67]
	v_cvt_pk_bf16_f32 v56, v60, v61
	s_nop 0
	v_cvt_pk_bf16_f32 v57, v62, v63
	v_cvt_pk_bf16_f32 v58, v58, v59
	v_cvt_pk_bf16_f32 v59, v64, v65
	flat_store_dwordx4 v[72:73], v[56:59] sc1
	global_load_dwordx4 v[56:59], v[82:83], off offset:512
	s_nop 0
	global_load_dwordx4 v[60:63], v[82:83], off offset:528
	v_lshlrev_b64 v[64:65], 11, v[144:145]
	v_lshl_add_u64 v[64:65], v[64:65], 0, v[148:149]
	v_lshl_add_u64 v[64:65], v[64:65], 0, s[50:51]
	v_lshl_add_u64 v[66:67], v[64:65], 2, s[60:61]
	s_waitcnt vmcnt(0)
	v_pk_add_f32 v[52:53], v[52:53], v[56:57]
	v_pk_add_f32 v[56:57], v[50:51], v[62:63]
	v_pk_add_f32 v[50:51], v[48:49], v[60:61]
	v_pk_add_f32 v[54:55], v[54:55], v[58:59]
	v_cvt_pk_bf16_f32 v48, v52, v53
	s_nop 0
	v_cvt_pk_bf16_f32 v49, v54, v55
	v_cvt_pk_bf16_f32 v50, v50, v51
	v_cvt_pk_bf16_f32 v51, v56, v57
	flat_store_dwordx4 v[72:73], v[48:51] offset:256 sc1
	global_load_dwordx4 v[48:51], v[66:67], off
	s_nop 0
	global_load_dwordx4 v[52:55], v[66:67], off offset:16
	v_lshl_add_u64 v[56:57], v[64:65], 1, s[58:59]
	s_waitcnt vmcnt(0)
	v_pk_add_f32 v[44:45], v[44:45], v[48:49]
	v_pk_add_f32 v[48:49], v[42:43], v[54:55]
	v_pk_add_f32 v[42:43], v[40:41], v[52:53]
	v_pk_add_f32 v[46:47], v[46:47], v[50:51]
	v_cvt_pk_bf16_f32 v40, v44, v45
	s_nop 0
	v_cvt_pk_bf16_f32 v41, v46, v47
	v_cvt_pk_bf16_f32 v42, v42, v43
	v_cvt_pk_bf16_f32 v43, v48, v49
	flat_store_dwordx4 v[56:57], v[40:43] sc1
	global_load_dwordx4 v[40:43], v[66:67], off offset:512
	s_nop 0
	global_load_dwordx4 v[44:47], v[66:67], off offset:528
	v_lshlrev_b64 v[48:49], 11, v[142:143]
	v_lshl_add_u64 v[48:49], v[48:49], 0, v[148:149]
	v_lshl_add_u64 v[48:49], v[48:49], 0, s[50:51]
	v_lshl_add_u64 v[50:51], v[48:49], 2, s[60:61]
	s_waitcnt vmcnt(0)
	v_pk_add_f32 v[36:37], v[36:37], v[40:41]
	v_pk_add_f32 v[40:41], v[34:35], v[46:47]
	v_pk_add_f32 v[34:35], v[32:33], v[44:45]
	v_pk_add_f32 v[38:39], v[38:39], v[42:43]
	v_cvt_pk_bf16_f32 v32, v36, v37
	s_nop 0
	v_cvt_pk_bf16_f32 v33, v38, v39
	v_cvt_pk_bf16_f32 v34, v34, v35
	v_cvt_pk_bf16_f32 v35, v40, v41
	flat_store_dwordx4 v[56:57], v[32:35] offset:256 sc1
	global_load_dwordx4 v[32:35], v[50:51], off
	s_nop 0
	global_load_dwordx4 v[36:39], v[50:51], off offset:16
	v_lshl_add_u64 v[40:41], v[48:49], 1, s[58:59]
	s_waitcnt vmcnt(0)
	v_pk_add_f32 v[28:29], v[28:29], v[32:33]
	v_pk_add_f32 v[32:33], v[26:27], v[38:39]
	v_pk_add_f32 v[26:27], v[24:25], v[36:37]
	v_pk_add_f32 v[30:31], v[30:31], v[34:35]
	v_cvt_pk_bf16_f32 v24, v28, v29
	s_nop 0
	v_cvt_pk_bf16_f32 v25, v30, v31
	v_cvt_pk_bf16_f32 v26, v26, v27
	v_cvt_pk_bf16_f32 v27, v32, v33
	flat_store_dwordx4 v[40:41], v[24:27] sc1
	global_load_dwordx4 v[24:27], v[50:51], off offset:512
	s_nop 0
	global_load_dwordx4 v[28:31], v[50:51], off offset:528
	v_lshlrev_b64 v[32:33], 11, v[140:141]
	v_lshl_add_u64 v[32:33], v[32:33], 0, v[148:149]
	v_lshl_add_u64 v[32:33], v[32:33], 0, s[50:51]
	v_lshl_add_u64 v[34:35], v[32:33], 2, s[60:61]
	s_waitcnt vmcnt(0)
	v_pk_add_f32 v[20:21], v[20:21], v[24:25]
	v_pk_add_f32 v[24:25], v[18:19], v[30:31]
	v_pk_add_f32 v[18:19], v[16:17], v[28:29]
	v_pk_add_f32 v[22:23], v[22:23], v[26:27]
	v_cvt_pk_bf16_f32 v16, v20, v21
	s_nop 0
	v_cvt_pk_bf16_f32 v17, v22, v23
	v_cvt_pk_bf16_f32 v18, v18, v19
	v_cvt_pk_bf16_f32 v19, v24, v25
	flat_store_dwordx4 v[40:41], v[16:19] offset:256 sc1
	global_load_dwordx4 v[16:19], v[34:35], off
	s_nop 0
	global_load_dwordx4 v[20:23], v[34:35], off offset:16
	v_lshl_add_u64 v[24:25], v[32:33], 1, s[58:59]
	s_waitcnt vmcnt(0)
	v_pk_add_f32 v[12:13], v[12:13], v[16:17]
	v_pk_add_f32 v[16:17], v[10:11], v[22:23]
	v_pk_add_f32 v[10:11], v[8:9], v[20:21]
	v_pk_add_f32 v[14:15], v[14:15], v[18:19]
	v_cvt_pk_bf16_f32 v8, v12, v13
	s_nop 0
	v_cvt_pk_bf16_f32 v9, v14, v15
	v_cvt_pk_bf16_f32 v10, v10, v11
	v_cvt_pk_bf16_f32 v11, v16, v17
	flat_store_dwordx4 v[24:25], v[8:11] sc1
	global_load_dwordx4 v[8:11], v[34:35], off offset:512
	s_nop 0
	global_load_dwordx4 v[12:15], v[34:35], off offset:528
	s_waitcnt vmcnt(0)
	v_pk_add_f32 v[4:5], v[4:5], v[8:9]
	v_pk_add_f32 v[8:9], v[2:3], v[14:15]
	v_pk_add_f32 v[2:3], v[0:1], v[12:13]
	v_pk_add_f32 v[6:7], v[6:7], v[10:11]
	v_cvt_pk_bf16_f32 v0, v4, v5
	s_nop 0
	v_cvt_pk_bf16_f32 v1, v6, v7
	v_cvt_pk_bf16_f32 v2, v2, v3
	v_cvt_pk_bf16_f32 v3, v8, v9
	flat_store_dwordx4 v[24:25], v[0:3] offset:256 sc1

.LBB0_630:
	s_or_b64 exec, exec, s[4:5]
	s_waitcnt lgkmcnt(0)
	v_mov_b32_e32 v0, v164
	s_barrier
	s_add_u32 s8, s34, 0x20200000
	s_mov_b32 s4, 16
	s_addc_u32 s9, s35, 0
	s_ashr_i32 s5, s4, 31
	s_lshl_b64 s[4:5], s[4:5], 3
	s_add_u32 s4, s0, s4
	s_addc_u32 s5, s1, s5
	s_load_dwordx2 s[14:15], s[4:5], 0x0
	s_add_u32 s6, s34, 0x9800000
	s_mov_b32 s4, 1
	s_addc_u32 s7, s35, 0
	s_ashr_i32 s5, s4, 31
	s_lshl_b64 s[4:5], s[4:5], 3
	s_add_u32 s4, s0, s4
	s_addc_u32 s5, s1, s5
	s_load_dwordx2 s[10:11], s[4:5], 0x0
	v_readlane_b32 s12, v226, 3
	v_readlane_b32 s13, v226, 4
	v_and_b32_e32 v45, 63, v0
	s_andn2_b64 vcc, exec, s[12:13]
	v_cndmask_b32_e64 v0, 0, 1, s[12:13]
	v_cmp_ne_u32_e64 s[4:5], 1, v0
	v_lshlrev_b32_e32 v40, 4, v45
	v_lshlrev_b32_e32 v44, 5, v45
	s_mov_b32 s52, s24
	s_cbranch_vccnz .LBB0_632
	v_mov_b32_e32 v41, 0
	s_ashr_i32 s25, s24, 31
	v_lshl_add_u64 v[0:1], s[8:9], 0, v[40:41]
	s_lshl_b64 s[50:51], s[24:25], 12
	v_lshl_add_u64 v[2:3], v[0:1], 0, s[50:51]
	s_add_i32 s12, s24, s18
	flat_load_dwordx4 v[28:31], v[2:3] offset:1024
	flat_load_dwordx4 v[32:35], v[2:3] offset:2048
	flat_load_dwordx4 v[24:27], v[2:3] offset:3072
	flat_load_dwordx4 v[36:39], v[2:3]
	s_ashr_i32 s13, s12, 31
	s_lshl_b64 s[46:47], s[12:13], 12
	v_lshl_add_u64 v[2:3], v[0:1], 0, s[46:47]
	flat_load_dwordx4 v[46:49], v[2:3]
	flat_load_dwordx4 v[50:53], v[2:3] offset:1024
	flat_load_dwordx4 v[108:111], v[2:3] offset:2048
	flat_load_dwordx4 v[12:15], v[2:3] offset:3072
	v_readlane_b32 s28, v226, 1
	v_readlane_b32 s29, v226, 2
	s_add_i32 s40, s12, s18
	s_mov_b32 s12, s28
	s_ashr_i32 s29, s28, 31
	v_writelane_b32 v226, s12, 1
	s_ashr_i32 s41, s40, 31
	s_lshl_b64 s[44:45], s[40:41], 12
	v_writelane_b32 v226, s13, 2
	s_lshl_b64 s[12:13], s[28:29], 12
	v_lshl_add_u64 v[4:5], v[0:1], 0, s[12:13]
	v_lshl_add_u64 v[0:1], v[0:1], 0, s[44:45]
	flat_load_dwordx4 v[20:23], v[0:1]
	flat_load_dwordx4 v[16:19], v[0:1] offset:1024
	flat_load_dwordx4 v[8:11], v[0:1] offset:2048
	s_nop 0
	flat_load_dwordx4 v[0:3], v[0:1] offset:3072
	s_waitcnt lgkmcnt(0)
	global_load_dwordx4 v[112:115], v44, s[14:15] offset:16
	global_load_dwordx4 v[122:125], v44, s[14:15]
	s_mov_b32 s40, 0x358637bd
	s_mov_b32 s48, 0x3a000000
	s_mov_b32 s3, 0x800000
	v_mov_b32_e32 v105, v41
	s_waitcnt vmcnt(0)
	v_lshlrev_b32_e32 v87, 16, v30
	v_and_b32_e32 v93, 0xffff0000, v30
	v_lshlrev_b32_e32 v89, 16, v31
	v_and_b32_e32 v71, 0xffff0000, v36
	v_and_b32_e32 v70, 0xffff0000, v46
	v_lshlrev_b32_e32 v63, 16, v36
	v_and_b32_e32 v97, 0xffff0000, v31
	v_lshlrev_b32_e32 v62, 16, v46
	v_pk_mul_f32 v[30:31], v[70:71], v[70:71]
	v_lshlrev_b32_e32 v65, 16, v37
	v_and_b32_e32 v55, 0xffff0000, v33
	v_lshlrev_b32_e32 v59, 16, v32
	v_and_b32_e32 v67, 0xffff0000, v32
	v_lshlrev_b32_e32 v61, 16, v33
	v_lshlrev_b32_e32 v64, 16, v47
	v_pk_fma_f32 v[32:33], v[62:63], v[62:63], v[30:31]
	v_and_b32_e32 v77, 0xffff0000, v37
	v_and_b32_e32 v76, 0xffff0000, v47
	v_pk_fma_f32 v[32:33], v[64:65], v[64:65], v[32:33]
	v_lshlrev_b32_e32 v73, 16, v38
	v_lshlrev_b32_e32 v72, 16, v48
	v_pk_fma_f32 v[32:33], v[76:77], v[76:77], v[32:33]
	v_and_b32_e32 v85, 0xffff0000, v38
	v_and_b32_e32 v84, 0xffff0000, v48
	v_pk_fma_f32 v[32:33], v[72:73], v[72:73], v[32:33]
	v_lshlrev_b32_e32 v83, 16, v39
	v_lshlrev_b32_e32 v82, 16, v49
	v_pk_fma_f32 v[32:33], v[84:85], v[84:85], v[32:33]
	v_and_b32_e32 v95, 0xffff0000, v39
	v_and_b32_e32 v94, 0xffff0000, v49
	v_pk_fma_f32 v[32:33], v[82:83], v[82:83], v[32:33]
	v_lshlrev_b32_e32 v69, 16, v28
	v_lshlrev_b32_e32 v68, 16, v50
	v_pk_fma_f32 v[32:33], v[94:95], v[94:95], v[32:33]
	v_and_b32_e32 v57, 0xffff0000, v28
	v_and_b32_e32 v56, 0xffff0000, v50
	v_pk_fma_f32 v[32:33], v[68:69], v[68:69], v[32:33]
	v_lshlrev_b32_e32 v81, 16, v29
	v_lshlrev_b32_e32 v80, 16, v51
	v_pk_fma_f32 v[32:33], v[56:57], v[56:57], v[32:33]
	v_and_b32_e32 v91, 0xffff0000, v29
	v_and_b32_e32 v90, 0xffff0000, v51
	v_pk_fma_f32 v[32:33], v[80:81], v[80:81], v[32:33]
	v_lshlrev_b32_e32 v86, 16, v52
	v_pk_fma_f32 v[32:33], v[90:91], v[90:91], v[32:33]
	v_and_b32_e32 v92, 0xffff0000, v52
	v_pk_fma_f32 v[32:33], v[86:87], v[86:87], v[32:33]
	v_lshlrev_b32_e32 v88, 16, v53
	v_pk_fma_f32 v[32:33], v[92:93], v[92:93], v[32:33]
	v_and_b32_e32 v96, 0xffff0000, v53
	v_pk_fma_f32 v[32:33], v[88:89], v[88:89], v[32:33]
	v_lshlrev_b32_e32 v58, 16, v108
	v_pk_fma_f32 v[32:33], v[96:97], v[96:97], v[32:33]
	v_and_b32_e32 v66, 0xffff0000, v108
	v_pk_fma_f32 v[32:33], v[58:59], v[58:59], v[32:33]
	v_lshlrev_b32_e32 v60, 16, v109
	v_pk_fma_f32 v[32:33], v[66:67], v[66:67], v[32:33]
	v_and_b32_e32 v54, 0xffff0000, v109
	v_pk_fma_f32 v[32:33], v[60:61], v[60:61], v[32:33]
	v_lshlrev_b32_e32 v43, 16, v34
	v_lshlrev_b32_e32 v42, 16, v110
	v_pk_fma_f32 v[32:33], v[54:55], v[54:55], v[32:33]
	v_and_b32_e32 v79, 0xffff0000, v34
	v_and_b32_e32 v78, 0xffff0000, v110
	v_pk_fma_f32 v[32:33], v[42:43], v[42:43], v[32:33]
	v_lshlrev_b32_e32 v75, 16, v35
	v_lshlrev_b32_e32 v74, 16, v111
	v_pk_fma_f32 v[32:33], v[78:79], v[78:79], v[32:33]
	v_and_b32_e32 v99, 0xffff0000, v35
	v_and_b32_e32 v98, 0xffff0000, v111
	v_pk_fma_f32 v[32:33], v[74:75], v[74:75], v[32:33]
	v_lshlrev_b32_e32 v47, 16, v24
	v_pk_fma_f32 v[32:33], v[98:99], v[98:99], v[32:33]
	v_lshlrev_b32_e32 v46, 16, v12
	v_and_b32_e32 v100, 0xffff0000, v26
	v_lshlrev_b32_e32 v103, 16, v26
	v_and_b32_e32 v26, 0xffff0000, v14
	v_and_b32_e32 v49, 0xffff0000, v24
	v_and_b32_e32 v48, 0xffff0000, v12
	v_lshlrev_b32_e32 v50, 16, v13
	v_and_b32_e32 v24, 0xffff0000, v13
	v_pk_fma_f32 v[12:13], v[46:47], v[46:47], v[32:33]
	v_mov_b32_e32 v102, v100
	v_lshlrev_b32_e32 v53, 16, v14
	v_mov_b32_e32 v52, v26
	v_lshlrev_b32_e32 v51, 16, v25
	v_pk_fma_f32 v[12:13], v[48:49], v[48:49], v[12:13]
	v_pk_mul_f32 v[28:29], v[102:103], v[102:103]
	v_pk_mul_f32 v[30:31], v[52:53], v[52:53]
	v_and_b32_e32 v25, 0xffff0000, v25
	v_pk_fma_f32 v[12:13], v[50:51], v[50:51], v[12:13]
	v_mov_b32_e32 v32, v31
	v_pk_fma_f32 v[12:13], v[24:25], v[24:25], v[12:13]
	v_mov_b32_e32 v33, v29
	v_pk_add_f32 v[32:33], v[32:33], v[12:13]
	v_mbcnt_hi_u32_b32 v13, -1, v165
	v_and_b32_e32 v14, 64, v13
	v_and_b32_e32 v104, 0xffff0000, v27
	v_and_b32_e32 v12, 0xffff0000, v15
	v_add_u32_e32 v14, 64, v14
	v_xor_b32_e32 v29, 1, v13
	v_lshlrev_b32_e32 v107, 16, v27
	v_mov_b32_e32 v106, v104
	v_lshlrev_b32_e32 v111, 16, v15
	v_mov_b32_e32 v110, v12
	v_cmp_lt_i32_e32 vcc, v29, v14
	v_pk_mul_f32 v[6:7], v[106:107], v[106:107]
	v_pk_mul_f32 v[34:35], v[110:111], v[110:111]
	v_cndmask_b32_e32 v29, v13, v29, vcc
	v_mov_b32_e32 v31, v28
	v_lshlrev_b32_e32 v116, 2, v29
	v_pk_add_f32 v[28:29], v[30:31], v[32:33]
	v_mov_b32_e32 v30, v35
	v_mov_b32_e32 v31, v7
	v_pk_add_f32 v[28:29], v[30:31], v[28:29]
	v_mov_b32_e32 v35, v6
	v_pk_add_f32 v[6:7], v[34:35], v[28:29]
	ds_bpermute_b32 v29, v116, v7
	ds_bpermute_b32 v28, v116, v6
	v_xor_b32_e32 v30, 2, v13
	v_cmp_lt_i32_e32 vcc, v30, v14
	v_mov_b32_e32 v128, v65
	v_mov_b32_e32 v129, v77
	v_cndmask_b32_e32 v30, v13, v30, vcc
	v_lshlrev_b32_e32 v118, 2, v30
	s_waitcnt lgkmcnt(0)
	v_pk_add_f32 v[6:7], v[6:7], v[28:29]
	ds_bpermute_b32 v29, v118, v7
	ds_bpermute_b32 v28, v118, v6
	v_xor_b32_e32 v30, 4, v13
	v_cmp_lt_i32_e32 vcc, v30, v14
	v_mov_b32_e32 v134, v81
	v_mov_b32_e32 v135, v91
	v_cndmask_b32_e32 v30, v13, v30, vcc
	v_lshlrev_b32_e32 v119, 2, v30
	s_waitcnt lgkmcnt(0)
	v_pk_add_f32 v[6:7], v[6:7], v[28:29]
	ds_bpermute_b32 v29, v119, v7
	ds_bpermute_b32 v28, v119, v6
	v_xor_b32_e32 v30, 8, v13
	v_cmp_lt_i32_e32 vcc, v30, v14
	v_mov_b32_e32 v136, v87
	v_mov_b32_e32 v137, v93
	v_cndmask_b32_e32 v30, v13, v30, vcc
	v_lshlrev_b32_e32 v120, 2, v30
	s_waitcnt lgkmcnt(0)
	v_pk_add_f32 v[6:7], v[6:7], v[28:29]
	ds_bpermute_b32 v29, v120, v7
	ds_bpermute_b32 v28, v120, v6
	v_xor_b32_e32 v30, 16, v13
	v_cmp_lt_i32_e32 vcc, v30, v14
	v_mov_b32_e32 v138, v89
	v_mov_b32_e32 v139, v97
	v_cndmask_b32_e32 v30, v13, v30, vcc
	v_lshlrev_b32_e32 v121, 2, v30
	s_waitcnt lgkmcnt(0)
	v_pk_add_f32 v[6:7], v[6:7], v[28:29]
	ds_bpermute_b32 v29, v121, v7
	ds_bpermute_b32 v28, v121, v6
	v_xor_b32_e32 v30, 32, v13
	v_cmp_lt_i32_e32 vcc, v30, v14
	v_and_b32_e32 v101, s0, v27
	v_pk_mov_b32 v[100:101], v[102:103], v[100:101] op_sel:[1,0]
	v_cndmask_b32_e32 v13, v13, v30, vcc
	v_lshlrev_b32_e32 v117, 2, v13
	s_waitcnt lgkmcnt(0)
	v_pk_add_f32 v[108:109], v[6:7], v[28:29]
	ds_bpermute_b32 v127, v117, v109
	ds_bpermute_b32 v126, v117, v108
	flat_load_dwordx4 v[36:39], v[4:5]
	flat_load_dwordx4 v[32:35], v[4:5] offset:1024
	flat_load_dwordx4 v[28:31], v[4:5] offset:2048
	s_nop 0
	flat_load_dwordx4 v[4:7], v[4:5] offset:3072
	v_pk_mov_b32 v[102:103], v[106:107], v[104:105] op_sel:[1,0]
	v_mov_b32_e32 v65, v76
	v_mov_b32_e32 v81, v90
	s_waitcnt lgkmcnt(0)
	v_pk_add_f32 v[126:127], v[108:109], v[126:127]
	v_mov_b64_e32 v[108:109], s[40:41]
	v_pk_fma_f32 v[130:131], v[126:127], s[48:49], v[108:109] op_sel_hi:[1,0,0]
	v_mov_b32_e32 v126, v63
	v_mul_f32_e32 v13, 0x4b800000, v131
	v_cmp_gt_f32_e32 vcc, s3, v131
	v_mov_b32_e32 v127, v71
	s_add_u32 s40, s6, s50
	v_cndmask_b32_e32 v13, v131, v13, vcc
	v_rsq_f32_e32 v13, v13
	s_addc_u32 s41, s7, s51
	v_lshl_add_u64 v[132:133], s[40:41], 0, v[40:41]
	s_add_u32 s40, s6, s46
	v_mul_f32_e32 v14, 0x45800000, v13
	v_cndmask_b32_e32 v14, v13, v14, vcc
	v_pk_mul_f32 v[126:127], v[126:127], v[14:15] op_sel_hi:[1,0]
	v_pk_mul_f32 v[128:129], v[128:129], v[14:15] op_sel_hi:[1,0]
	v_pk_mul_f32 v[122:123], v[122:123], v[126:127]
	v_pk_mul_f32 v[124:125], v[124:125], v[128:129]
	v_mov_b32_e32 v126, v73
	v_mov_b32_e32 v127, v85
	v_mov_b32_e32 v128, v83
	v_mov_b32_e32 v129, v95
	v_pk_mul_f32 v[126:127], v[126:127], v[14:15] op_sel_hi:[1,0]
	v_pk_mul_f32 v[128:129], v[128:129], v[14:15] op_sel_hi:[1,0]
	v_pk_mul_f32 v[134:135], v[134:135], v[14:15] op_sel_hi:[1,0]
	v_pk_mul_f32 v[128:129], v[114:115], v[128:129]
	v_pk_mul_f32 v[114:115], v[112:113], v[126:127]
	v_cvt_pk_bf16_f32 v112, v122, v123
	v_cvt_pk_bf16_f32 v113, v124, v125
	v_pk_mul_f32 v[136:137], v[136:137], v[14:15] op_sel_hi:[1,0]
	v_cvt_pk_bf16_f32 v114, v114, v115
	v_cvt_pk_bf16_f32 v115, v128, v129
	flat_store_dwordx4 v[132:133], v[112:115] sc1
	global_load_dwordx4 v[122:125], v44, s[14:15] offset:2048
	global_load_dwordx4 v[126:129], v44, s[14:15] offset:2064
	v_mov_b32_e32 v112, v69
	v_mov_b32_e32 v113, v57
	v_pk_mul_f32 v[112:113], v[112:113], v[14:15] op_sel_hi:[1,0]
	v_pk_mul_f32 v[138:139], v[138:139], v[14:15] op_sel_hi:[1,0]
	v_or_b32_e32 v114, 0x1000, v44
	v_or_b32_e32 v115, 0x1800, v44
	v_pk_mul_f32 v[100:101], v[14:15], v[100:101] op_sel_hi:[0,1]
	v_pk_mul_f32 v[102:103], v[14:15], v[102:103] op_sel_hi:[0,1]
	v_mul_f32_e32 v13, 0x4b800000, v130
	v_cmp_gt_f32_e32 vcc, s3, v130
	v_mov_b32_e32 v63, v70
	s_addc_u32 s41, s7, s47
	v_cndmask_b32_e32 v13, v130, v13, vcc
	v_rsq_f32_e32 v13, v13
	v_mov_b32_e32 v73, v84
	v_mov_b32_e32 v83, v94
	v_mov_b32_e32 v69, v56
	v_mov_b32_e32 v87, v92
	v_mov_b32_e32 v89, v96
	v_lshlrev_b32_e32 v85, 16, v20
	v_and_b32_e32 v93, 0xffff0000, v21
	v_and_b32_e32 v95, 0xffff0000, v22
	v_lshlrev_b32_e32 v91, 16, v23
	v_and_b32_e32 v27, s0, v15
	v_and_b32_e32 v97, 0xffff0000, v23
	s_waitcnt vmcnt(0)
	v_and_b32_e32 v94, 0xffff0000, v38
	v_lshlrev_b32_e32 v90, 16, v39
	v_and_b32_e32 v96, 0xffff0000, v39
	v_lshlrev_b32_e32 v84, 16, v36
	v_and_b32_e32 v92, 0xffff0000, v37
	v_pk_mul_f32 v[124:125], v[124:125], v[134:135]
	v_pk_mul_f32 v[112:113], v[122:123], v[112:113]
	v_pk_mul_f32 v[128:129], v[128:129], v[138:139]
	v_pk_mul_f32 v[126:127], v[126:127], v[136:137]
	v_cvt_pk_bf16_f32 v122, v112, v113
	v_cvt_pk_bf16_f32 v123, v124, v125
	v_mov_b32_e32 v134, v61
	v_cvt_pk_bf16_f32 v124, v126, v127
	v_cvt_pk_bf16_f32 v125, v128, v129
	flat_store_dwordx4 v[132:133], v[122:125] offset:1024 sc1
	global_load_dwordx4 v[122:125], v114, s[14:15]
	s_nop 0
	global_load_dwordx4 v[126:129], v114, s[14:15] offset:16
	v_mov_b32_e32 v135, v55
	v_mov_b32_e32 v112, v59
	v_mov_b32_e32 v113, v67
	v_mov_b32_e32 v136, v43
	v_mov_b32_e32 v137, v79
	v_mov_b32_e32 v138, v75
	v_mov_b32_e32 v139, v99
	v_pk_mul_f32 v[134:135], v[134:135], v[14:15] op_sel_hi:[1,0]
	v_pk_mul_f32 v[112:113], v[112:113], v[14:15] op_sel_hi:[1,0]
	v_pk_mul_f32 v[136:137], v[136:137], v[14:15] op_sel_hi:[1,0]
	v_pk_mul_f32 v[138:139], v[138:139], v[14:15] op_sel_hi:[1,0]
	v_mov_b32_e32 v43, v78
	v_mov_b32_e32 v59, v66
	v_mov_b32_e32 v61, v54
	v_mov_b32_e32 v75, v98
	v_and_b32_e32 v98, 0xffff0000, v2
	v_and_b32_e32 v67, 0xffff0000, v10
	v_and_b32_e32 v78, 0xffff0000, v35
	v_and_b32_e32 v66, 0xffff0000, v30
	v_and_b32_e32 v79, 0xffff0000, v19
	v_and_b32_e32 v99, s0, v3
	s_waitcnt vmcnt(0)
	v_pk_mul_f32 v[124:125], v[134:135], v[124:125]
	v_pk_mul_f32 v[112:113], v[112:113], v[122:123]
	v_pk_mul_f32 v[128:129], v[138:139], v[128:129]
	v_pk_mul_f32 v[126:127], v[136:137], v[126:127]
	v_cvt_pk_bf16_f32 v122, v112, v113
	v_cvt_pk_bf16_f32 v123, v124, v125
	v_mov_b32_e32 v112, v47
	v_cvt_pk_bf16_f32 v124, v126, v127
	v_cvt_pk_bf16_f32 v125, v128, v129
	flat_store_dwordx4 v[132:133], v[122:125] offset:2048 sc1
	global_load_dwordx4 v[122:125], v115, s[14:15]
	s_nop 0
	global_load_dwordx4 v[126:129], v115, s[14:15] offset:16
	v_mov_b32_e32 v113, v49
	v_mov_b32_e32 v134, v51
	v_mov_b32_e32 v135, v25
	v_pk_mul_f32 v[104:105], v[112:113], v[14:15] op_sel_hi:[1,0]
	v_pk_mul_f32 v[106:107], v[134:135], v[14:15] op_sel_hi:[1,0]
	v_mul_f32_e32 v14, 0x45800000, v13
	v_cndmask_b32_e32 v130, v13, v14, vcc
	v_pk_mul_f32 v[62:63], v[62:63], v[130:131] op_sel_hi:[1,0]
	v_pk_mul_f32 v[64:65], v[64:65], v[130:131] op_sel_hi:[1,0]
	v_pk_mul_f32 v[70:71], v[72:73], v[130:131] op_sel_hi:[1,0]
	v_pk_mul_f32 v[72:73], v[82:83], v[130:131] op_sel_hi:[1,0]
	v_pk_mul_f32 v[56:57], v[68:69], v[130:131] op_sel_hi:[1,0]
	v_pk_mul_f32 v[68:69], v[80:81], v[130:131] op_sel_hi:[1,0]
	v_pk_mul_f32 v[76:77], v[86:87], v[130:131] op_sel_hi:[1,0]
	v_pk_mul_f32 v[80:81], v[88:89], v[130:131] op_sel_hi:[1,0]
	v_lshlrev_b32_e32 v88, 16, v38
	v_pk_mul_f32 v[38:39], v[42:43], v[130:131] op_sel_hi:[1,0]
	v_lshlrev_b32_e32 v86, 16, v37
	v_and_b32_e32 v82, 0xffff0000, v33
	v_pk_mul_f32 v[42:43], v[74:75], v[130:131] op_sel_hi:[1,0]
	v_and_b32_e32 v75, 0xffff0000, v8
	v_lshlrev_b32_e32 v87, 16, v21
	v_lshlrev_b32_e32 v89, 16, v22
	v_and_b32_e32 v14, 0xffff0000, v6
	v_mov_b32_e32 v13, v41
	v_mov_b32_e32 v47, v48
	v_and_b32_e32 v83, 0xffff0000, v17
	v_pk_mov_b32 v[12:13], v[110:111], v[12:13] op_sel:[1,0]
	v_mov_b32_e32 v51, v24
	v_pk_mul_f32 v[12:13], v[130:131], v[12:13] op_sel_hi:[0,1]
	v_and_b32_e32 v74, 0xffff0000, v28
	v_mov_b32_e32 v24, v87
	v_mov_b32_e32 v25, v93
	v_and_b32_e32 v15, s0, v7
	s_waitcnt vmcnt(0)
	v_pk_mul_f32 v[106:107], v[106:107], v[124:125]
	v_pk_mul_f32 v[112:113], v[102:103], v[128:129]
	v_pk_mul_f32 v[102:103], v[100:101], v[126:127]
	v_pk_mul_f32 v[104:105], v[104:105], v[122:123]
	s_nop 0
	v_cvt_pk_bf16_f32 v100, v104, v105
	v_cvt_pk_bf16_f32 v101, v106, v107
	v_cvt_pk_bf16_f32 v102, v102, v103
	v_cvt_pk_bf16_f32 v103, v112, v113
	flat_store_dwordx4 v[132:133], v[100:103] offset:3072 sc1
	global_load_dwordx4 v[100:103], v44, s[14:15]
	s_nop 0
	global_load_dwordx4 v[104:107], v44, s[14:15] offset:16
	v_lshl_add_u64 v[112:113], s[40:41], 0, v[40:41]
	s_add_u32 s40, s6, s44
	s_addc_u32 s41, s7, s45
	s_add_u32 s12, s6, s12
	s_addc_u32 s13, s7, s13
	s_waitcnt vmcnt(0)
	v_pk_mul_f32 v[64:65], v[64:65], v[102:103]
	v_pk_mul_f32 v[62:63], v[62:63], v[100:101]
	v_pk_mul_f32 v[72:73], v[72:73], v[106:107]
	v_pk_mul_f32 v[70:71], v[70:71], v[104:105]
	v_cvt_pk_bf16_f32 v62, v62, v63
	v_cvt_pk_bf16_f32 v63, v64, v65
	v_and_b32_e32 v100, 0xffff0000, v36
	v_cvt_pk_bf16_f32 v64, v70, v71
	v_cvt_pk_bf16_f32 v65, v72, v73
	flat_store_dwordx4 v[112:113], v[62:65] sc1
	global_load_dwordx4 v[62:65], v44, s[14:15] offset:2048
	s_nop 0
	global_load_dwordx4 v[70:73], v44, s[14:15] offset:2064
	v_pk_mul_f32 v[36:37], v[60:61], v[130:131] op_sel_hi:[1,0]
	v_and_b32_e32 v101, 0xffff0000, v20
	v_lshlrev_b32_e32 v107, 16, v2
	v_and_b32_e32 v61, 0xffff0000, v11
	v_mov_b32_e32 v106, v98
	v_and_b32_e32 v60, 0xffff0000, v31
	s_waitcnt vmcnt(0)
	v_pk_mul_f32 v[64:65], v[68:69], v[64:65]
	v_pk_mul_f32 v[56:57], v[56:57], v[62:63]
	v_pk_mul_f32 v[68:69], v[80:81], v[72:73]
	v_pk_mul_f32 v[70:71], v[76:77], v[70:71]
	v_cvt_pk_bf16_f32 v62, v56, v57
	v_cvt_pk_bf16_f32 v63, v64, v65
	v_and_b32_e32 v80, 0xffff0000, v32
	v_cvt_pk_bf16_f32 v64, v70, v71
	v_cvt_pk_bf16_f32 v65, v68, v69
	flat_store_dwordx4 v[112:113], v[62:65] offset:1024 sc1
	global_load_dwordx4 v[102:105], v114, s[14:15]
	global_load_dwordx4 v[122:125], v114, s[14:15] offset:16
	v_lshlrev_b32_e32 v64, 16, v32
	v_lshlrev_b32_e32 v68, 16, v33
	v_pk_mul_f32 v[32:33], v[58:59], v[130:131] op_sel_hi:[1,0]
	v_and_b32_e32 v63, 0xffff0000, v9
	v_lshlrev_b32_e32 v57, 16, v10
	v_lshlrev_b32_e32 v65, 16, v16
	v_lshlrev_b32_e32 v59, 16, v11
	v_pk_mov_b32 v[10:11], v[52:53], v[26:27] op_sel:[1,0]
	v_and_b32_e32 v81, 0xffff0000, v16
	v_lshlrev_b32_e32 v69, 16, v17
	v_pk_mul_f32 v[16:17], v[106:107], v[106:107]
	v_pk_mul_f32 v[10:11], v[130:131], v[10:11] op_sel_hi:[0,1]
	v_mov_b32_e32 v23, v17
	v_and_b32_e32 v62, 0xffff0000, v29
	v_lshlrev_b32_e32 v56, 16, v30
	v_lshlrev_b32_e32 v70, 16, v34
	v_and_b32_e32 v76, 0xffff0000, v34
	v_lshlrev_b32_e32 v72, 16, v35
	v_lshlrev_b32_e32 v58, 16, v31
	v_and_b32_e32 v30, 0xffff0000, v4
	v_and_b32_e32 v34, 0xffff0000, v5
	v_lshlrev_b32_e32 v71, 16, v18
	v_and_b32_e32 v77, 0xffff0000, v18
	v_lshlrev_b32_e32 v73, 16, v19
	v_and_b32_e32 v31, 0xffff0000, v0
	v_and_b32_e32 v35, 0xffff0000, v1
	s_waitcnt vmcnt(0)
	v_pk_mul_f32 v[54:55], v[36:37], v[104:105]
	v_pk_mul_f32 v[38:39], v[38:39], v[122:123]
	v_pk_mul_f32 v[32:33], v[32:33], v[102:103]
	v_pk_mul_f32 v[42:43], v[42:43], v[124:125]
	v_cvt_pk_bf16_f32 v36, v32, v33
	v_cvt_pk_bf16_f32 v37, v54, v55
	v_cvt_pk_bf16_f32 v38, v38, v39
	v_lshlrev_b32_e32 v55, 16, v9
	v_cvt_pk_bf16_f32 v39, v42, v43
	flat_store_dwordx4 v[112:113], v[36:39] offset:2048 sc1
	global_load_dwordx4 v[122:125], v115, s[14:15] offset:16
	global_load_dwordx4 v[126:129], v115, s[14:15]
	v_lshlrev_b32_e32 v43, 16, v8
	v_pk_mul_f32 v[8:9], v[100:101], v[100:101]
	v_lshlrev_b32_e32 v33, 16, v6
	v_pk_fma_f32 v[8:9], v[84:85], v[84:85], v[8:9]
	v_mov_b32_e32 v32, v14
	v_pk_fma_f32 v[8:9], v[86:87], v[86:87], v[8:9]
	v_and_b32_e32 v36, 0xffff0000, v7
	v_pk_fma_f32 v[8:9], v[92:93], v[92:93], v[8:9]
	v_and_b32_e32 v102, 0xffff0000, v3
	v_pk_fma_f32 v[8:9], v[88:89], v[88:89], v[8:9]
	v_pk_mul_f32 v[20:21], v[32:33], v[32:33]
	v_pk_fma_f32 v[8:9], v[94:95], v[94:95], v[8:9]
	v_lshlrev_b32_e32 v39, 16, v7
	v_pk_fma_f32 v[8:9], v[90:91], v[90:91], v[8:9]
	v_mov_b32_e32 v38, v36
	v_pk_fma_f32 v[8:9], v[96:97], v[96:97], v[8:9]
	v_lshlrev_b32_e32 v105, 16, v3
	v_pk_fma_f32 v[52:53], v[64:65], v[64:65], v[8:9]
	v_pk_mul_f32 v[8:9], v[46:47], v[130:131] op_sel_hi:[1,0]
	v_mov_b32_e32 v104, v102
	v_mov_b32_e32 v22, v21
	v_mov_b32_e32 v21, v16
	v_pk_mul_f32 v[16:17], v[50:51], v[130:131] op_sel_hi:[1,0]
	v_lshlrev_b32_e32 v42, 16, v28
	v_lshlrev_b32_e32 v54, 16, v29
	v_lshlrev_b32_e32 v28, 16, v4
	v_lshlrev_b32_e32 v4, 16, v5
	v_lshlrev_b32_e32 v29, 16, v0
	v_lshlrev_b32_e32 v5, 16, v1
	v_pk_mul_f32 v[0:1], v[38:39], v[38:39]
	v_pk_mul_f32 v[18:19], v[104:105], v[104:105]
	v_mov_b32_e32 v26, v1
	v_mov_b32_e32 v27, v19
	v_mov_b32_e32 v1, v18
	v_mov_b32_e32 v103, v41
	v_mov_b32_e32 v87, v92
	v_mov_b32_e32 v37, v41
	s_waitcnt vmcnt(0)
	v_pk_mul_f32 v[10:11], v[10:11], v[122:123]
	v_pk_mul_f32 v[8:9], v[8:9], v[126:127]
	v_pk_mul_f32 v[16:17], v[16:17], v[128:129]
	v_pk_mul_f32 v[12:13], v[12:13], v[124:125]
	v_cvt_pk_bf16_f32 v8, v8, v9
	v_cvt_pk_bf16_f32 v9, v16, v17
	v_cvt_pk_bf16_f32 v10, v10, v11
	s_nop 0
	v_cvt_pk_bf16_f32 v11, v12, v13
	flat_store_dwordx4 v[112:113], v[8:11] offset:3072 sc1
	global_load_dwordx4 v[8:11], v44, s[14:15] offset:16
	s_nop 0
	global_load_dwordx4 v[16:19], v44, s[14:15]
	v_pk_fma_f32 v[12:13], v[80:81], v[80:81], v[52:53]
	s_nop 0
	v_pk_fma_f32 v[12:13], v[68:69], v[68:69], v[12:13]
	s_nop 0
	v_pk_fma_f32 v[12:13], v[82:83], v[82:83], v[12:13]
	s_nop 0
	v_pk_fma_f32 v[12:13], v[70:71], v[70:71], v[12:13]
	s_nop 0
	v_pk_fma_f32 v[12:13], v[76:77], v[76:77], v[12:13]
	s_nop 0
	v_pk_fma_f32 v[12:13], v[72:73], v[72:73], v[12:13]
	s_nop 0
	v_pk_fma_f32 v[12:13], v[78:79], v[78:79], v[12:13]
	s_nop 0
	v_pk_fma_f32 v[12:13], v[42:43], v[42:43], v[12:13]
	s_nop 0
	v_pk_fma_f32 v[12:13], v[74:75], v[74:75], v[12:13]
	s_nop 0
	v_pk_fma_f32 v[12:13], v[54:55], v[54:55], v[12:13]
	s_nop 0
	v_pk_fma_f32 v[12:13], v[62:63], v[62:63], v[12:13]
	s_nop 0
	v_pk_fma_f32 v[12:13], v[56:57], v[56:57], v[12:13]
	s_nop 0
	v_pk_fma_f32 v[12:13], v[66:67], v[66:67], v[12:13]
	s_nop 0
	v_pk_fma_f32 v[12:13], v[58:59], v[58:59], v[12:13]
	s_nop 0
	v_pk_fma_f32 v[12:13], v[60:61], v[60:61], v[12:13]
	s_nop 0
	v_pk_fma_f32 v[12:13], v[28:29], v[28:29], v[12:13]
	s_nop 0
	v_pk_fma_f32 v[12:13], v[30:31], v[30:31], v[12:13]
	s_nop 0
	v_pk_fma_f32 v[12:13], v[4:5], v[4:5], v[12:13]
	s_nop 0
	v_pk_fma_f32 v[12:13], v[34:35], v[34:35], v[12:13]
	s_nop 0
	v_pk_add_f32 v[12:13], v[22:23], v[12:13]
	v_mov_b32_e32 v22, v85
	v_pk_add_f32 v[12:13], v[20:21], v[12:13]
	v_mov_b32_e32 v23, v101
	v_pk_add_f32 v[12:13], v[26:27], v[12:13]
	v_mov_b32_e32 v26, v89
	v_pk_add_f32 v[0:1], v[0:1], v[12:13]
	ds_bpermute_b32 v13, v116, v1
	ds_bpermute_b32 v12, v116, v0
	v_mov_b32_e32 v27, v95
	v_lshl_add_u64 v[20:21], s[40:41], 0, v[40:41]
	v_mov_b32_e32 v85, v100
	v_mov_b32_e32 v89, v94
	s_waitcnt lgkmcnt(0)
	v_pk_add_f32 v[0:1], v[0:1], v[12:13]
	ds_bpermute_b32 v13, v118, v1
	ds_bpermute_b32 v12, v118, v0
	s_waitcnt lgkmcnt(0)
	v_pk_add_f32 v[0:1], v[0:1], v[12:13]
	ds_bpermute_b32 v13, v119, v1
	ds_bpermute_b32 v12, v119, v0
	s_waitcnt lgkmcnt(0)
	v_pk_add_f32 v[0:1], v[0:1], v[12:13]
	ds_bpermute_b32 v13, v120, v1
	ds_bpermute_b32 v12, v120, v0
	s_waitcnt lgkmcnt(0)
	v_pk_add_f32 v[0:1], v[0:1], v[12:13]
	ds_bpermute_b32 v13, v121, v1
	ds_bpermute_b32 v12, v121, v0
	s_waitcnt lgkmcnt(0)
	v_pk_add_f32 v[0:1], v[0:1], v[12:13]
	ds_bpermute_b32 v13, v117, v1
	ds_bpermute_b32 v12, v117, v0
	s_waitcnt lgkmcnt(0)
	v_pk_add_f32 v[0:1], v[0:1], v[12:13]
	s_nop 0
	v_pk_fma_f32 v[12:13], v[0:1], s[48:49], v[108:109] op_sel_hi:[1,0,0]
	v_mov_b32_e32 v1, v97
	v_mul_f32_e32 v0, 0x4b800000, v13
	v_cmp_gt_f32_e32 vcc, s3, v13
	s_nop 1
	v_cndmask_b32_e32 v0, v13, v0, vcc
	v_rsq_f32_e32 v2, v0
	v_mov_b32_e32 v0, v91
	v_mov_b32_e32 v91, v96
	v_mul_f32_e32 v6, 0x45800000, v2
	v_cndmask_b32_e32 v2, v2, v6, vcc
	v_pk_mul_f32 v[26:27], v[26:27], v[2:3] op_sel_hi:[1,0]
	v_pk_mul_f32 v[0:1], v[0:1], v[2:3] op_sel_hi:[1,0]
	v_pk_mul_f32 v[22:23], v[22:23], v[2:3] op_sel_hi:[1,0]
	v_pk_mul_f32 v[24:25], v[24:25], v[2:3] op_sel_hi:[1,0]
	s_waitcnt vmcnt(0)
	v_pk_mul_f32 v[0:1], v[0:1], v[10:11]
	v_pk_mul_f32 v[10:11], v[26:27], v[8:9]
	v_pk_mul_f32 v[18:19], v[24:25], v[18:19]
	v_pk_mul_f32 v[16:17], v[22:23], v[16:17]
	v_mov_b32_e32 v22, v69
	v_cvt_pk_bf16_f32 v8, v16, v17
	v_cvt_pk_bf16_f32 v9, v18, v19
	v_cvt_pk_bf16_f32 v10, v10, v11
	v_cvt_pk_bf16_f32 v11, v0, v1
	flat_store_dwordx4 v[20:21], v[8:11] sc1
	global_load_dwordx4 v[8:11], v44, s[14:15] offset:2048
	s_nop 0
	global_load_dwordx4 v[16:19], v44, s[14:15] offset:2064
	v_mov_b32_e32 v23, v83
	v_mov_b32_e32 v0, v65
	v_mov_b32_e32 v1, v81
	v_mov_b32_e32 v24, v71
	v_mov_b32_e32 v25, v77
	v_mov_b32_e32 v26, v73
	v_mov_b32_e32 v27, v79
	v_pk_mul_f32 v[22:23], v[22:23], v[2:3] op_sel_hi:[1,0]
	v_pk_mul_f32 v[0:1], v[0:1], v[2:3] op_sel_hi:[1,0]
	v_pk_mul_f32 v[24:25], v[24:25], v[2:3] op_sel_hi:[1,0]
	v_pk_mul_f32 v[26:27], v[26:27], v[2:3] op_sel_hi:[1,0]
	v_cmp_gt_f32_e32 vcc, s3, v12
	v_mov_b32_e32 v65, v80
	v_mov_b32_e32 v69, v82
	v_mov_b32_e32 v71, v76
	v_mov_b32_e32 v73, v78
	s_lshl_b32 s3, s26, 5
	s_add_i32 s52, s24, s3
	s_waitcnt vmcnt(0)
	v_pk_mul_f32 v[10:11], v[22:23], v[10:11]
	v_pk_mul_f32 v[0:1], v[0:1], v[8:9]
	v_pk_mul_f32 v[18:19], v[26:27], v[18:19]
	v_pk_mul_f32 v[16:17], v[24:25], v[16:17]
	v_cvt_pk_bf16_f32 v8, v0, v1
	v_cvt_pk_bf16_f32 v9, v10, v11
	v_mov_b32_e32 v22, v55
	v_cvt_pk_bf16_f32 v10, v16, v17
	v_cvt_pk_bf16_f32 v11, v18, v19
	flat_store_dwordx4 v[20:21], v[8:11] offset:1024 sc1
	global_load_dwordx4 v[8:11], v114, s[14:15]
	s_nop 0
	global_load_dwordx4 v[16:19], v114, s[14:15] offset:16
	v_mov_b32_e32 v23, v63
	v_mov_b32_e32 v0, v43
	v_mov_b32_e32 v1, v75
	v_mov_b32_e32 v24, v57
	v_mov_b32_e32 v25, v67
	v_mov_b32_e32 v26, v59
	v_mov_b32_e32 v27, v61
	v_pk_mul_f32 v[22:23], v[22:23], v[2:3] op_sel_hi:[1,0]
	v_pk_mul_f32 v[0:1], v[0:1], v[2:3] op_sel_hi:[1,0]
	v_pk_mul_f32 v[24:25], v[24:25], v[2:3] op_sel_hi:[1,0]
	v_pk_mul_f32 v[26:27], v[26:27], v[2:3] op_sel_hi:[1,0]
	v_mov_b32_e32 v43, v74
	v_mov_b32_e32 v55, v62
	v_mov_b32_e32 v57, v66
	v_mov_b32_e32 v59, v60
	s_waitcnt vmcnt(0)
	v_pk_mul_f32 v[10:11], v[22:23], v[10:11]
	v_pk_mul_f32 v[0:1], v[0:1], v[8:9]
	v_pk_mul_f32 v[18:19], v[26:27], v[18:19]
	v_pk_mul_f32 v[16:17], v[24:25], v[16:17]
	v_cvt_pk_bf16_f32 v8, v0, v1
	v_cvt_pk_bf16_f32 v9, v10, v11
	v_mov_b32_e32 v0, v29
	v_cvt_pk_bf16_f32 v10, v16, v17
	v_cvt_pk_bf16_f32 v11, v18, v19
	flat_store_dwordx4 v[20:21], v[8:11] offset:2048 sc1
	global_load_dwordx4 v[8:11], v115, s[14:15]
	s_nop 0
	global_load_dwordx4 v[16:19], v115, s[14:15] offset:16
	v_mov_b32_e32 v1, v31
	v_mov_b32_e32 v22, v5
	v_mov_b32_e32 v23, v35
	v_pk_mov_b32 v[24:25], v[106:107], v[98:99] op_sel:[1,0]
	v_pk_mov_b32 v[26:27], v[104:105], v[102:103] op_sel:[1,0]
	v_pk_mul_f32 v[0:1], v[0:1], v[2:3] op_sel_hi:[1,0]
	v_pk_mul_f32 v[22:23], v[22:23], v[2:3] op_sel_hi:[1,0]
	v_pk_mul_f32 v[24:25], v[2:3], v[24:25] op_sel_hi:[0,1]
	v_pk_mul_f32 v[2:3], v[2:3], v[26:27] op_sel_hi:[0,1]
	v_mul_f32_e32 v5, 0x4b800000, v12
	v_cndmask_b32_e32 v5, v12, v5, vcc
	v_rsq_f32_e32 v5, v5
	v_mov_b32_e32 v29, v30
	v_mul_f32_e32 v6, 0x45800000, v5
	v_cndmask_b32_e32 v6, v5, v6, vcc
	v_pk_mul_f32 v[12:13], v[84:85], v[6:7] op_sel_hi:[1,0]
	v_mov_b32_e32 v5, v34
	v_pk_mul_f32 v[4:5], v[4:5], v[6:7] op_sel_hi:[1,0]
	s_waitcnt vmcnt(0)
	v_pk_mul_f32 v[0:1], v[0:1], v[8:9]
	v_pk_mul_f32 v[8:9], v[2:3], v[18:19]
	v_pk_mul_f32 v[2:3], v[24:25], v[16:17]
	v_pk_mul_f32 v[10:11], v[22:23], v[10:11]
	v_cvt_pk_bf16_f32 v0, v0, v1
	v_pk_mul_f32 v[18:19], v[86:87], v[6:7] op_sel_hi:[1,0]
	v_cvt_pk_bf16_f32 v1, v10, v11
	v_cvt_pk_bf16_f32 v2, v2, v3
	v_cvt_pk_bf16_f32 v3, v8, v9
	flat_store_dwordx4 v[20:21], v[0:3] offset:3072 sc1
	global_load_dwordx4 v[0:3], v44, s[14:15]
	s_nop 0
	global_load_dwordx4 v[8:11], v44, s[14:15] offset:16
	v_lshl_add_u64 v[16:17], s[12:13], 0, v[40:41]
	v_pk_mul_f32 v[20:21], v[88:89], v[6:7] op_sel_hi:[1,0]
	v_pk_mul_f32 v[22:23], v[90:91], v[6:7] op_sel_hi:[1,0]
	s_waitcnt vmcnt(0)
	v_pk_mul_f32 v[2:3], v[18:19], v[2:3]
	v_pk_mul_f32 v[0:1], v[12:13], v[0:1]
	v_pk_mul_f32 v[10:11], v[22:23], v[10:11]
	v_pk_mul_f32 v[8:9], v[20:21], v[8:9]
	v_cvt_pk_bf16_f32 v0, v0, v1
	v_cvt_pk_bf16_f32 v1, v2, v3
	v_pk_mul_f32 v[12:13], v[64:65], v[6:7] op_sel_hi:[1,0]
	v_cvt_pk_bf16_f32 v2, v8, v9
	v_cvt_pk_bf16_f32 v3, v10, v11
	flat_store_dwordx4 v[16:17], v[0:3] sc1
	global_load_dwordx4 v[0:3], v44, s[14:15] offset:2048
	s_nop 0
	global_load_dwordx4 v[8:11], v44, s[14:15] offset:2064
	v_pk_mul_f32 v[18:19], v[68:69], v[6:7] op_sel_hi:[1,0]
	v_pk_mul_f32 v[20:21], v[70:71], v[6:7] op_sel_hi:[1,0]
	v_pk_mul_f32 v[22:23], v[72:73], v[6:7] op_sel_hi:[1,0]
	s_waitcnt vmcnt(0)
	v_pk_mul_f32 v[2:3], v[18:19], v[2:3]
	v_pk_mul_f32 v[0:1], v[12:13], v[0:1]
	v_pk_mul_f32 v[10:11], v[22:23], v[10:11]
	v_pk_mul_f32 v[8:9], v[20:21], v[8:9]
	v_cvt_pk_bf16_f32 v0, v0, v1
	v_cvt_pk_bf16_f32 v1, v2, v3
	v_pk_mul_f32 v[12:13], v[42:43], v[6:7] op_sel_hi:[1,0]
	v_cvt_pk_bf16_f32 v2, v8, v9
	v_cvt_pk_bf16_f32 v3, v10, v11
	flat_store_dwordx4 v[16:17], v[0:3] offset:1024 sc1
	global_load_dwordx4 v[0:3], v114, s[14:15]
	s_nop 0
	global_load_dwordx4 v[8:11], v114, s[14:15] offset:16
	v_pk_mul_f32 v[18:19], v[54:55], v[6:7] op_sel_hi:[1,0]
	v_pk_mul_f32 v[20:21], v[56:57], v[6:7] op_sel_hi:[1,0]
	v_pk_mul_f32 v[22:23], v[58:59], v[6:7] op_sel_hi:[1,0]
	s_waitcnt vmcnt(0)
	v_pk_mul_f32 v[2:3], v[18:19], v[2:3]
	v_pk_mul_f32 v[0:1], v[12:13], v[0:1]
	v_pk_mul_f32 v[10:11], v[22:23], v[10:11]
	v_pk_mul_f32 v[8:9], v[20:21], v[8:9]
	v_cvt_pk_bf16_f32 v0, v0, v1
	v_cvt_pk_bf16_f32 v1, v2, v3
	v_pk_mov_b32 v[12:13], v[32:33], v[14:15] op_sel:[1,0]
	v_cvt_pk_bf16_f32 v2, v8, v9
	v_cvt_pk_bf16_f32 v3, v10, v11
	flat_store_dwordx4 v[16:17], v[0:3] offset:2048 sc1
	global_load_dwordx4 v[0:3], v115, s[14:15]
	s_nop 0
	global_load_dwordx4 v[8:11], v115, s[14:15] offset:16
	v_pk_mov_b32 v[14:15], v[38:39], v[36:37] op_sel:[1,0]
	v_pk_mul_f32 v[18:19], v[28:29], v[6:7] op_sel_hi:[1,0]
	v_pk_mul_f32 v[12:13], v[6:7], v[12:13] op_sel_hi:[0,1]
	v_pk_mul_f32 v[6:7], v[6:7], v[14:15] op_sel_hi:[0,1]
	s_waitcnt vmcnt(0)
	v_pk_mul_f32 v[2:3], v[4:5], v[2:3]
	v_pk_mul_f32 v[0:1], v[18:19], v[0:1]
	v_pk_mul_f32 v[4:5], v[6:7], v[10:11]
	v_pk_mul_f32 v[6:7], v[12:13], v[8:9]
	v_cvt_pk_bf16_f32 v0, v0, v1
	v_cvt_pk_bf16_f32 v1, v2, v3
	s_nop 0
	v_cvt_pk_bf16_f32 v2, v6, v7
	v_cvt_pk_bf16_f32 v3, v4, v5
	flat_store_dwordx4 v[16:17], v[0:3] offset:3072 sc1

.LBB0_638:
	v_mul_f32_e32 v64, v25, v25
	v_fmac_f32_e32 v64, v24, v24
	v_fmac_f32_e32 v64, v26, v26
	v_fmac_f32_e32 v64, v27, v27
	v_fmac_f32_e32 v64, v28, v28
	v_fmac_f32_e32 v64, v29, v29
	v_fmac_f32_e32 v64, v30, v30
	v_fmac_f32_e32 v64, v31, v31
	v_fmac_f32_e32 v64, v16, v16
	v_fmac_f32_e32 v64, v17, v17
	v_fmac_f32_e32 v64, v18, v18
	v_fmac_f32_e32 v64, v19, v19
	v_fmac_f32_e32 v64, v20, v20
	v_fmac_f32_e32 v64, v21, v21
	v_fmac_f32_e32 v64, v22, v22
	v_fmac_f32_e32 v64, v23, v23
	v_fmac_f32_e32 v64, v8, v8
	v_lshlrev_b32_e32 v7, 16, v35
	v_and_b32_e32 v6, 0xffff0000, v35
	v_fmac_f32_e32 v64, v9, v9
	global_load_dwordx4 v[32:35], v[44:45], off offset:16
	global_load_dwordx4 v[58:61], v[44:45], off
	v_fmac_f32_e32 v64, v10, v10
	v_fmac_f32_e32 v64, v11, v11
	v_fmac_f32_e32 v64, v12, v12
	v_fmac_f32_e32 v64, v13, v13
	v_fmac_f32_e32 v64, v14, v14
	v_fmac_f32_e32 v64, v15, v15
	v_fmac_f32_e32 v64, v0, v0
	v_fmac_f32_e32 v64, v1, v1
	v_fmac_f32_e32 v64, v2, v2
	v_fmac_f32_e32 v64, v3, v3
	v_pk_mul_f32 v[62:63], v[4:5], v[4:5]
	s_add_i32 s12, s49, s18
	v_add_f32_e32 v62, v62, v64
	v_add_f32_e32 v64, v63, v62
	v_pk_mul_f32 v[62:63], v[6:7], v[6:7]
	s_cmp_le_i32 s49, s52
	v_add_f32_e32 v63, v63, v64
	v_add_f32_e32 v62, v62, v63
	v_and_b32_e32 v63, 64, v96
	v_add_u32_e32 v63, 64, v63
	v_xor_b32_e32 v64, 1, v96
	v_cmp_lt_i32_e32 vcc, v64, v63
	s_cselect_b64 s[40:41], -1, 0
	s_cmpk_lt_i32 s12, 0x2400
	v_cndmask_b32_e32 v64, v96, v64, vcc
	v_lshlrev_b32_e32 v64, 2, v64
	ds_bpermute_b32 v64, v64, v62
	s_cselect_b64 s[54:55], -1, 0
	s_and_b64 s[40:41], s[40:41], s[54:55]
	s_mov_b32 s49, s12
	s_waitcnt lgkmcnt(0)
	v_add_f32_e32 v62, v62, v64
	v_xor_b32_e32 v64, 2, v96
	v_cmp_lt_i32_e32 vcc, v64, v63
	s_nop 1
	v_cndmask_b32_e32 v64, v96, v64, vcc
	v_lshlrev_b32_e32 v64, 2, v64
	ds_bpermute_b32 v64, v64, v62
	s_waitcnt lgkmcnt(0)
	v_add_f32_e32 v62, v62, v64
	v_xor_b32_e32 v64, 4, v96
	v_cmp_lt_i32_e32 vcc, v64, v63
	s_nop 1
	v_cndmask_b32_e32 v64, v96, v64, vcc
	v_lshlrev_b32_e32 v64, 2, v64
	ds_bpermute_b32 v64, v64, v62
	s_waitcnt lgkmcnt(0)
	v_add_f32_e32 v62, v62, v64
	v_xor_b32_e32 v64, 8, v96
	v_cmp_lt_i32_e32 vcc, v64, v63
	s_nop 1
	v_cndmask_b32_e32 v64, v96, v64, vcc
	v_lshlrev_b32_e32 v64, 2, v64
	ds_bpermute_b32 v64, v64, v62
	s_waitcnt lgkmcnt(0)
	v_add_f32_e32 v62, v62, v64
	v_xor_b32_e32 v64, 16, v96
	v_cmp_lt_i32_e32 vcc, v64, v63
	s_nop 1
	v_cndmask_b32_e32 v64, v96, v64, vcc
	v_lshlrev_b32_e32 v64, 2, v64
	ds_bpermute_b32 v64, v64, v62
	s_waitcnt lgkmcnt(0)
	v_add_f32_e32 v62, v62, v64
	v_xor_b32_e32 v64, 32, v96
	v_cmp_lt_i32_e32 vcc, v64, v63
	s_nop 1
	v_cndmask_b32_e32 v63, v96, v64, vcc
	v_lshlrev_b32_e32 v63, 2, v63
	ds_bpermute_b32 v63, v63, v62
	s_waitcnt lgkmcnt(0)
	v_add_f32_e32 v62, v62, v63
	v_fmamk_f32 v62, v62, 0x3a000000, v54
	v_mul_f32_e32 v63, 0x4b800000, v62
	v_cmp_gt_f32_e32 vcc, s19, v62
	s_nop 1
	v_cndmask_b32_e32 v62, v62, v63, vcc
	v_rsq_f32_e32 v62, v62
	s_nop 0
	v_mul_f32_e32 v63, 0x45800000, v62
	v_cndmask_b32_e32 v62, v62, v63, vcc
	v_pk_mul_f32 v[24:25], v[62:63], v[24:25] op_sel_hi:[0,1]
	v_pk_mul_f32 v[26:27], v[62:63], v[26:27] op_sel_hi:[0,1]
	v_pk_mul_f32 v[28:29], v[62:63], v[28:29] op_sel_hi:[0,1]
	s_waitcnt vmcnt(0)
	v_pk_mul_f32 v[26:27], v[60:61], v[26:27]
	v_pk_mul_f32 v[24:25], v[58:59], v[24:25]
	v_pk_mul_f32 v[28:29], v[32:33], v[28:29]
	v_cvt_pk_bf16_f32 v24, v24, v25
	v_cvt_pk_bf16_f32 v25, v26, v27
	v_pk_mul_f32 v[30:31], v[62:63], v[30:31] op_sel_hi:[0,1]
	v_cvt_pk_bf16_f32 v26, v28, v29
	v_add_co_u32_e32 v28, vcc, s62, v56
	v_pk_mul_f32 v[30:31], v[34:35], v[30:31]
	s_nop 0
	v_addc_co_u32_e32 v29, vcc, -1, v57, vcc
	v_cvt_pk_bf16_f32 v27, v30, v31
	flat_store_dwordx4 v[28:29], v[24:27] sc1
	global_load_dwordx4 v[24:27], v[44:45], off offset:2048
	s_nop 0
	global_load_dwordx4 v[28:31], v[44:45], off offset:2064
	v_add_co_u32_e32 v32, vcc, s63, v56
	v_pk_mul_f32 v[16:17], v[62:63], v[16:17] op_sel_hi:[0,1]
	v_pk_mul_f32 v[18:19], v[62:63], v[18:19] op_sel_hi:[0,1]
	v_addc_co_u32_e32 v33, vcc, -1, v57, vcc
	v_pk_mul_f32 v[20:21], v[62:63], v[20:21] op_sel_hi:[0,1]
	v_pk_mul_f32 v[22:23], v[62:63], v[22:23] op_sel_hi:[0,1]
	v_pk_mul_f32 v[8:9], v[62:63], v[8:9] op_sel_hi:[0,1]
	v_pk_mul_f32 v[10:11], v[62:63], v[10:11] op_sel_hi:[0,1]
	v_pk_mul_f32 v[12:13], v[62:63], v[12:13] op_sel_hi:[0,1]
	v_pk_mul_f32 v[14:15], v[62:63], v[14:15] op_sel_hi:[0,1]
	v_pk_mul_f32 v[0:1], v[62:63], v[0:1] op_sel_hi:[0,1]
	v_pk_mul_f32 v[2:3], v[62:63], v[2:3] op_sel_hi:[0,1]
	v_pk_mul_f32 v[4:5], v[62:63], v[4:5] op_sel_hi:[0,1]
	s_waitcnt vmcnt(0)
	v_pk_mul_f32 v[18:19], v[26:27], v[18:19]
	v_pk_mul_f32 v[16:17], v[24:25], v[16:17]
	v_pk_mul_f32 v[22:23], v[30:31], v[22:23]
	v_pk_mul_f32 v[20:21], v[28:29], v[20:21]
	v_cvt_pk_bf16_f32 v16, v16, v17
	v_cvt_pk_bf16_f32 v17, v18, v19
	v_add_co_u32_e32 v24, vcc, s64, v56
	v_cvt_pk_bf16_f32 v18, v20, v21
	v_cvt_pk_bf16_f32 v19, v22, v23
	flat_store_dwordx4 v[32:33], v[16:19] sc1
	global_load_dwordx4 v[16:19], v[46:47], off
	s_nop 0
	global_load_dwordx4 v[20:23], v[46:47], off offset:16
	v_addc_co_u32_e32 v25, vcc, -1, v57, vcc
	s_waitcnt vmcnt(0)
	v_pk_mul_f32 v[10:11], v[18:19], v[10:11]
	v_pk_mul_f32 v[8:9], v[16:17], v[8:9]
	v_pk_mul_f32 v[14:15], v[22:23], v[14:15]
	v_pk_mul_f32 v[12:13], v[20:21], v[12:13]
	v_cvt_pk_bf16_f32 v8, v8, v9
	v_cvt_pk_bf16_f32 v9, v10, v11
	v_add_co_u32_e32 v16, vcc, 0xe9600c00, v56
	v_cvt_pk_bf16_f32 v10, v12, v13
	v_cvt_pk_bf16_f32 v11, v14, v15
	flat_store_dwordx4 v[24:25], v[8:11] sc1
	global_load_dwordx4 v[8:11], v[48:49], off
	s_nop 0
	global_load_dwordx4 v[12:15], v[48:49], off offset:16
	v_mov_b32_e32 v18, v7
	v_mov_b32_e32 v19, v6
	v_addc_co_u32_e32 v17, vcc, -1, v57, vcc
	v_lshl_add_u64 v[56:57], v[56:57], 0, s[14:15]
	s_and_b64 vcc, exec, s[40:41]
	v_pk_mul_f32 v[6:7], v[62:63], v[18:19] op_sel_hi:[0,1]
	s_waitcnt vmcnt(0)
	v_pk_mul_f32 v[2:3], v[10:11], v[2:3]
	v_pk_mul_f32 v[0:1], v[8:9], v[0:1]
	v_pk_mul_f32 v[6:7], v[14:15], v[6:7]
	v_pk_mul_f32 v[4:5], v[12:13], v[4:5]
	v_cvt_pk_bf16_f32 v0, v0, v1
	v_cvt_pk_bf16_f32 v1, v2, v3
	s_nop 0
	v_cvt_pk_bf16_f32 v2, v4, v5
	v_cvt_pk_bf16_f32 v3, v6, v7
	flat_store_dwordx4 v[16:17], v[0:3] sc1
	s_cbranch_vccz .LBB0_660

.LBB0_652:
	v_lshl_add_u64 v[32:33], v[36:37], 0, s[54:55]
	v_add_co_u32_e32 v34, vcc, s3, v32
	flat_load_dwordx4 v[58:61], v[32:33]
	flat_load_dwordx4 v[62:65], v[32:33] offset:1024
	flat_load_dwordx4 v[66:69], v[32:33] offset:2048
	flat_load_dwordx4 v[70:73], v[32:33] offset:3072
	v_addc_co_u32_e32 v35, vcc, 0, v33, vcc
	flat_load_dwordx4 v[74:77], v[34:35]
	v_add_co_u32_e32 v98, vcc, s19, v32
	s_waitcnt vmcnt(0) lgkmcnt(0)
	v_lshlrev_b32_e32 v97, 16, v60
	v_addc_co_u32_e32 v99, vcc, 0, v33, vcc
	flat_load_dwordx4 v[78:81], v[34:35] offset:1024
	flat_load_dwordx4 v[82:85], v[34:35] offset:2048
	flat_load_dwordx4 v[86:89], v[34:35] offset:3072
	flat_load_dwordx4 v[90:93], v[98:99]
	v_lshlrev_b32_e32 v34, 16, v58
	v_and_b32_e32 v35, 0xffff0000, v58
	v_lshlrev_b32_e32 v58, 16, v59
	v_and_b32_e32 v59, 0xffff0000, v59
	v_lshlrev_b32_e32 v101, 16, v62
	v_and_b32_e32 v62, 0xffff0000, v62
	v_and_b32_e32 v60, 0xffff0000, v60
	v_lshlrev_b32_e32 v100, 16, v61
	v_and_b32_e32 v61, 0xffff0000, v61
	v_lshlrev_b32_e32 v102, 16, v63
	v_and_b32_e32 v63, 0xffff0000, v63
	v_lshlrev_b32_e32 v103, 16, v64
	v_and_b32_e32 v64, 0xffff0000, v64
	v_lshlrev_b32_e32 v104, 16, v65
	v_and_b32_e32 v65, 0xffff0000, v65
	v_lshlrev_b32_e32 v105, 16, v66
	v_and_b32_e32 v66, 0xffff0000, v66
	v_add_f32_e32 v0, v0, v34
	v_add_f32_e32 v34, v1, v35
	v_add_f32_e32 v35, v2, v58
	v_add_f32_e32 v58, v3, v59
	v_add_f32_e32 v4, v4, v97
	v_add_f32_e32 v9, v9, v62
	v_lshlrev_b32_e32 v1, 16, v74
	v_and_b32_e32 v59, 0xffff0000, v74
	v_lshlrev_b32_e32 v62, 16, v76
	v_lshlrev_b32_e32 v110, 16, v71
	v_and_b32_e32 v71, 0xffff0000, v71
	v_add_f32_e32 v5, v5, v60
	v_add_f32_e32 v6, v6, v100
	v_add_f32_e32 v7, v7, v61
	v_add_f32_e32 v8, v8, v101
	v_add_f32_e32 v11, v11, v63
	v_add_f32_e32 v13, v13, v64
	v_add_f32_e32 v15, v15, v65
	v_add_f32_e32 v17, v17, v66
	v_lshlrev_b32_e32 v60, 16, v75
	v_and_b32_e32 v61, 0xffff0000, v75
	v_and_b32_e32 v63, 0xffff0000, v76
	v_lshlrev_b32_e32 v64, 16, v77
	v_and_b32_e32 v65, 0xffff0000, v77
	v_add_f32_e32 v66, v0, v1
	flat_load_dwordx4 v[0:3], v[98:99] offset:1024
	v_add_f32_e32 v34, v34, v59
	v_add_f32_e32 v59, v4, v62
	v_add_f32_e32 v27, v27, v71
	v_add_f32_e32 v35, v35, v60
	v_add_f32_e32 v58, v58, v61
	v_add_f32_e32 v60, v5, v63
	v_add_f32_e32 v61, v6, v64
	v_add_f32_e32 v62, v7, v65
	v_lshlrev_b32_e32 v109, 16, v70
	v_and_b32_e32 v70, 0xffff0000, v70
	v_lshlrev_b32_e32 v106, 16, v67
	v_and_b32_e32 v67, 0xffff0000, v67
	v_lshlrev_b32_e32 v107, 16, v68
	v_add_f32_e32 v10, v10, v102
	v_add_f32_e32 v16, v16, v105
	v_add_f32_e32 v25, v25, v70
	v_and_b32_e32 v68, 0xffff0000, v68
	v_lshlrev_b32_e32 v108, 16, v69
	v_and_b32_e32 v69, 0xffff0000, v69
	v_lshlrev_b32_e32 v111, 16, v72
	v_and_b32_e32 v72, 0xffff0000, v72
	v_add_f32_e32 v12, v12, v103
	v_add_f32_e32 v19, v19, v67
	v_add_f32_e32 v20, v20, v107
	v_lshlrev_b32_e32 v112, 16, v73
	v_and_b32_e32 v73, 0xffff0000, v73
	v_add_f32_e32 v14, v14, v104
	v_add_f32_e32 v21, v21, v68
	v_add_f32_e32 v23, v23, v69
	v_add_f32_e32 v29, v29, v72
	v_add_f32_e32 v18, v18, v106
	v_add_f32_e32 v22, v22, v108
	v_add_f32_e32 v24, v24, v109
	s_waitcnt vmcnt(0) lgkmcnt(0)
	v_lshlrev_b32_e32 v4, 16, v78
	v_add_f32_e32 v71, v8, v4
	flat_load_dwordx4 v[4:7], v[98:99] offset:2048
	v_and_b32_e32 v63, 0xffff0000, v78
	v_lshlrev_b32_e32 v64, 16, v79
	v_and_b32_e32 v65, 0xffff0000, v79
	v_and_b32_e32 v70, 0xffff0000, v81
	v_lshlrev_b32_e32 v8, 16, v82
	v_lshlrev_b32_e32 v67, 16, v80
	v_add_f32_e32 v63, v9, v63
	v_add_f32_e32 v64, v10, v64
	v_add_f32_e32 v65, v11, v65
	v_add_f32_e32 v70, v15, v70
	v_lshlrev_b32_e32 v15, 16, v84
	v_add_f32_e32 v75, v16, v8
	flat_load_dwordx4 v[8:11], v[98:99] offset:3072
	v_and_b32_e32 v68, 0xffff0000, v80
	v_lshlrev_b32_e32 v69, 16, v81
	v_add_f32_e32 v67, v12, v67
	v_and_b32_e32 v12, 0xffff0000, v82
	v_and_b32_e32 v72, 0xffff0000, v84
	v_add_f32_e32 v79, v20, v15
	v_add_co_u32_e32 v20, vcc, s25, v32
	v_add_f32_e32 v31, v31, v73
	v_add_f32_e32 v68, v13, v68
	v_add_f32_e32 v69, v14, v69
	v_lshlrev_b32_e32 v13, 16, v83
	v_and_b32_e32 v14, 0xffff0000, v83
	v_lshlrev_b32_e32 v73, 16, v85
	v_and_b32_e32 v74, 0xffff0000, v85
	v_add_f32_e32 v76, v17, v12
	v_add_f32_e32 v72, v21, v72
	v_lshlrev_b32_e32 v12, 16, v86
	v_and_b32_e32 v16, 0xffff0000, v86
	v_addc_co_u32_e32 v21, vcc, 0, v33, vcc
	v_add_f32_e32 v26, v26, v110
	v_add_f32_e32 v28, v28, v111
	v_add_f32_e32 v30, v30, v112
	v_add_f32_e32 v77, v18, v13
	v_add_f32_e32 v78, v19, v14
	v_add_f32_e32 v22, v22, v73
	v_add_f32_e32 v23, v23, v74
	v_lshlrev_b32_e32 v17, 16, v87
	v_and_b32_e32 v18, 0xffff0000, v87
	v_lshlrev_b32_e32 v19, 16, v88
	v_and_b32_e32 v73, 0xffff0000, v88
	v_lshlrev_b32_e32 v74, 16, v89
	v_and_b32_e32 v80, 0xffff0000, v89
	v_add_f32_e32 v24, v24, v12
	flat_load_dwordx4 v[12:15], v[20:21]
	v_add_f32_e32 v25, v25, v16
	v_lshlrev_b32_e32 v16, 16, v90
	v_add_f32_e32 v26, v26, v17
	v_add_f32_e32 v27, v27, v18
	v_add_f32_e32 v28, v28, v19
	v_add_f32_e32 v29, v29, v73
	v_add_f32_e32 v30, v30, v74
	v_add_f32_e32 v31, v31, v80
	v_and_b32_e32 v73, 0xffff0000, v90
	v_lshlrev_b32_e32 v74, 16, v91
	v_and_b32_e32 v80, 0xffff0000, v91
	v_lshlrev_b32_e32 v81, 16, v92
	v_and_b32_e32 v82, 0xffff0000, v92
	v_lshlrev_b32_e32 v83, 16, v93
	v_and_b32_e32 v84, 0xffff0000, v93
	v_add_f32_e32 v66, v66, v16
	flat_load_dwordx4 v[16:19], v[20:21] offset:1024
	v_add_f32_e32 v34, v34, v73
	v_add_f32_e32 v35, v35, v74
	v_add_f32_e32 v58, v58, v80
	v_add_f32_e32 v59, v59, v81
	v_add_f32_e32 v60, v60, v82
	v_add_f32_e32 v61, v61, v83
	v_add_f32_e32 v62, v62, v84
	v_lshlrev_b32_e32 v73, 16, v0
	v_and_b32_e32 v74, 0xffff0000, v0
	v_lshlrev_b32_e32 v80, 16, v1
	v_and_b32_e32 v81, 0xffff0000, v1
	v_lshlrev_b32_e32 v82, 16, v2
	v_and_b32_e32 v83, 0xffff0000, v2
	v_lshlrev_b32_e32 v84, 16, v3
	v_and_b32_e32 v85, 0xffff0000, v3
	flat_load_dwordx4 v[0:3], v[20:21] offset:2048
	v_add_f32_e32 v71, v71, v73
	v_add_f32_e32 v63, v63, v74
	v_add_f32_e32 v64, v64, v80
	v_add_f32_e32 v65, v65, v81
	v_add_f32_e32 v67, v67, v82
	v_add_f32_e32 v68, v68, v83
	v_add_f32_e32 v69, v69, v84
	v_add_f32_e32 v70, v70, v85
	s_waitcnt vmcnt(0) lgkmcnt(0)
	v_lshlrev_b32_e32 v73, 16, v4
	v_and_b32_e32 v74, 0xffff0000, v4
	v_lshlrev_b32_e32 v80, 16, v5
	v_and_b32_e32 v81, 0xffff0000, v5
	v_lshlrev_b32_e32 v82, 16, v6
	v_and_b32_e32 v83, 0xffff0000, v6
	v_lshlrev_b32_e32 v84, 16, v7
	v_and_b32_e32 v85, 0xffff0000, v7
	flat_load_dwordx4 v[4:7], v[20:21] offset:3072
	v_lshlrev_b32_e32 v20, 16, v8
	v_add_f32_e32 v24, v24, v20
	v_add_co_u32_e32 v20, vcc, s29, v32
	v_add_f32_e32 v73, v75, v73
	v_add_f32_e32 v74, v76, v74
	v_add_f32_e32 v75, v77, v80
	v_add_f32_e32 v76, v78, v81
	v_add_f32_e32 v77, v79, v82
	v_add_f32_e32 v72, v72, v83
	v_add_f32_e32 v22, v22, v84
	v_and_b32_e32 v78, 0xffff0000, v8
	v_lshlrev_b32_e32 v79, 16, v9
	v_and_b32_e32 v80, 0xffff0000, v9
	v_lshlrev_b32_e32 v81, 16, v10
	v_and_b32_e32 v82, 0xffff0000, v10
	v_lshlrev_b32_e32 v83, 16, v11
	v_and_b32_e32 v84, 0xffff0000, v11
	v_addc_co_u32_e32 v21, vcc, 0, v33, vcc
	v_add_f32_e32 v23, v23, v85
	flat_load_dwordx4 v[8:11], v[20:21]
	v_add_f32_e32 v25, v25, v78
	v_add_f32_e32 v26, v26, v79
	v_add_f32_e32 v27, v27, v80
	v_add_f32_e32 v28, v28, v81
	v_add_f32_e32 v29, v29, v82
	v_add_f32_e32 v30, v30, v83
	v_add_f32_e32 v31, v31, v84
	v_lshlrev_b32_e32 v78, 16, v12
	v_and_b32_e32 v79, 0xffff0000, v12
	v_lshlrev_b32_e32 v80, 16, v13
	v_and_b32_e32 v81, 0xffff0000, v13
	v_lshlrev_b32_e32 v82, 16, v14
	v_and_b32_e32 v83, 0xffff0000, v14
	v_lshlrev_b32_e32 v84, 16, v15
	v_and_b32_e32 v85, 0xffff0000, v15
	v_add_f32_e32 v66, v66, v78
	flat_load_dwordx4 v[12:15], v[20:21] offset:1024
	v_add_f32_e32 v34, v34, v79
	v_add_f32_e32 v35, v35, v80
	v_add_f32_e32 v58, v58, v81
	v_add_f32_e32 v59, v59, v82
	v_add_f32_e32 v60, v60, v83
	v_add_f32_e32 v61, v61, v84
	v_add_f32_e32 v62, v62, v85
	v_lshlrev_b32_e32 v78, 16, v16
	v_and_b32_e32 v79, 0xffff0000, v16
	v_lshlrev_b32_e32 v80, 16, v17
	v_and_b32_e32 v81, 0xffff0000, v17
	v_lshlrev_b32_e32 v82, 16, v18
	v_and_b32_e32 v83, 0xffff0000, v18
	v_lshlrev_b32_e32 v84, 16, v19
	v_and_b32_e32 v85, 0xffff0000, v19
	v_add_f32_e32 v71, v71, v78
	flat_load_dwordx4 v[16:19], v[20:21] offset:2048
	v_add_f32_e32 v63, v63, v79
	v_add_f32_e32 v64, v64, v80
	v_add_f32_e32 v65, v65, v81
	v_add_f32_e32 v67, v67, v82
	v_add_f32_e32 v68, v68, v83
	v_add_f32_e32 v69, v69, v84
	v_add_f32_e32 v70, v70, v85
	v_lshlrev_b32_e32 v78, 16, v0
	v_and_b32_e32 v79, 0xffff0000, v0
	v_lshlrev_b32_e32 v80, 16, v1
	v_and_b32_e32 v81, 0xffff0000, v1
	v_lshlrev_b32_e32 v82, 16, v2
	v_and_b32_e32 v83, 0xffff0000, v2
	v_lshlrev_b32_e32 v84, 16, v3
	v_and_b32_e32 v85, 0xffff0000, v3
	flat_load_dwordx4 v[0:3], v[20:21] offset:3072
	v_add_f32_e32 v73, v73, v78
	v_add_f32_e32 v74, v74, v79
	v_add_f32_e32 v75, v75, v80
	v_add_f32_e32 v76, v76, v81
	v_add_f32_e32 v77, v77, v82
	v_add_f32_e32 v72, v72, v83
	v_add_f32_e32 v22, v22, v84
	s_waitcnt vmcnt(0) lgkmcnt(0)
	v_lshlrev_b32_e32 v20, 16, v4
	v_add_f32_e32 v24, v24, v20
	v_add_co_u32_e32 v20, vcc, s45, v32
	v_and_b32_e32 v78, 0xffff0000, v4
	s_nop 0
	v_addc_co_u32_e32 v21, vcc, 0, v33, vcc
	v_lshlrev_b32_e32 v79, 16, v5
	v_and_b32_e32 v80, 0xffff0000, v5
	v_lshlrev_b32_e32 v81, 16, v6
	v_and_b32_e32 v82, 0xffff0000, v6
	v_lshlrev_b32_e32 v83, 16, v7
	v_and_b32_e32 v84, 0xffff0000, v7
	flat_load_dwordx4 v[4:7], v[20:21]
	v_add_f32_e32 v23, v23, v85
	v_add_f32_e32 v25, v25, v78
	v_add_f32_e32 v26, v26, v79
	v_add_f32_e32 v27, v27, v80
	v_add_f32_e32 v28, v28, v81
	v_add_f32_e32 v29, v29, v82
	v_add_f32_e32 v30, v30, v83
	v_add_f32_e32 v31, v31, v84
	v_lshlrev_b32_e32 v78, 16, v8
	v_and_b32_e32 v79, 0xffff0000, v8
	v_lshlrev_b32_e32 v80, 16, v9
	v_and_b32_e32 v81, 0xffff0000, v9
	v_lshlrev_b32_e32 v82, 16, v10
	v_and_b32_e32 v83, 0xffff0000, v10
	v_lshlrev_b32_e32 v84, 16, v11
	v_and_b32_e32 v85, 0xffff0000, v11
	flat_load_dwordx4 v[8:11], v[20:21] offset:1024
	v_add_f32_e32 v66, v66, v78
	v_add_f32_e32 v34, v34, v79
	v_add_f32_e32 v35, v35, v80
	v_add_f32_e32 v58, v58, v81
	v_add_f32_e32 v59, v59, v82
	v_add_f32_e32 v60, v60, v83
	v_add_f32_e32 v61, v61, v84
	v_add_f32_e32 v62, v62, v85
	v_lshlrev_b32_e32 v78, 16, v12
	v_and_b32_e32 v79, 0xffff0000, v12
	v_lshlrev_b32_e32 v80, 16, v13
	v_and_b32_e32 v81, 0xffff0000, v13
	v_lshlrev_b32_e32 v82, 16, v14
	v_and_b32_e32 v83, 0xffff0000, v14
	v_lshlrev_b32_e32 v84, 16, v15
	v_and_b32_e32 v85, 0xffff0000, v15
	flat_load_dwordx4 v[12:15], v[20:21] offset:2048
	v_add_f32_e32 v71, v71, v78
	v_add_f32_e32 v63, v63, v79
	v_add_f32_e32 v64, v64, v80
	v_add_f32_e32 v65, v65, v81
	v_add_f32_e32 v67, v67, v82
	v_add_f32_e32 v68, v68, v83
	v_add_f32_e32 v69, v69, v84
	v_add_f32_e32 v70, v70, v85
	v_lshlrev_b32_e32 v78, 16, v16
	v_and_b32_e32 v79, 0xffff0000, v16
	v_lshlrev_b32_e32 v80, 16, v17
	v_and_b32_e32 v81, 0xffff0000, v17
	v_lshlrev_b32_e32 v82, 16, v18
	v_and_b32_e32 v83, 0xffff0000, v18
	v_lshlrev_b32_e32 v84, 16, v19
	v_and_b32_e32 v85, 0xffff0000, v19
	flat_load_dwordx4 v[16:19], v[20:21] offset:3072
	v_add_f32_e32 v23, v23, v85
	v_add_f32_e32 v73, v73, v78
	v_add_f32_e32 v74, v74, v79
	v_add_f32_e32 v75, v75, v80
	v_add_f32_e32 v76, v76, v81
	v_add_f32_e32 v77, v77, v82
	v_add_f32_e32 v72, v72, v83
	v_lshlrev_b32_e32 v20, 16, v0
	v_add_f32_e32 v85, v24, v20
	v_add_co_u32_e32 v20, vcc, s60, v32
	v_add_f32_e32 v22, v22, v84
	s_nop 0
	v_addc_co_u32_e32 v21, vcc, 0, v33, vcc
	v_and_b32_e32 v78, 0xffff0000, v0
	v_lshlrev_b32_e32 v79, 16, v1
	v_and_b32_e32 v80, 0xffff0000, v1
	v_lshlrev_b32_e32 v81, 16, v2
	v_and_b32_e32 v82, 0xffff0000, v2
	v_lshlrev_b32_e32 v83, 16, v3
	v_and_b32_e32 v84, 0xffff0000, v3
	flat_load_dwordx4 v[0:3], v[20:21]
	v_add_f32_e32 v78, v25, v78
	v_add_f32_e32 v26, v26, v79
	v_add_f32_e32 v27, v27, v80
	v_add_f32_e32 v28, v28, v81
	v_add_f32_e32 v29, v29, v82
	v_add_f32_e32 v30, v30, v83
	v_add_f32_e32 v31, v31, v84
	s_waitcnt vmcnt(0) lgkmcnt(0)
	v_lshlrev_b32_e32 v24, 16, v4
	v_and_b32_e32 v25, 0xffff0000, v4
	v_lshlrev_b32_e32 v79, 16, v5
	v_and_b32_e32 v80, 0xffff0000, v5
	v_lshlrev_b32_e32 v81, 16, v6
	v_and_b32_e32 v82, 0xffff0000, v6
	v_lshlrev_b32_e32 v83, 16, v7
	v_and_b32_e32 v84, 0xffff0000, v7
	flat_load_dwordx4 v[4:7], v[20:21] offset:1024
	v_add_f32_e32 v66, v66, v24
	v_add_f32_e32 v34, v34, v25
	v_add_f32_e32 v35, v35, v79
	v_add_f32_e32 v58, v58, v80
	v_add_f32_e32 v59, v59, v81
	v_add_f32_e32 v60, v60, v82
	v_add_f32_e32 v61, v61, v83
	v_lshlrev_b32_e32 v24, 16, v8
	v_and_b32_e32 v25, 0xffff0000, v8
	v_add_f32_e32 v71, v71, v24
	v_add_f32_e32 v62, v62, v84
	v_lshlrev_b32_e32 v79, 16, v9
	v_and_b32_e32 v80, 0xffff0000, v9
	v_lshlrev_b32_e32 v81, 16, v10
	v_and_b32_e32 v82, 0xffff0000, v10
	v_lshlrev_b32_e32 v83, 16, v11
	v_and_b32_e32 v84, 0xffff0000, v11
	flat_load_dwordx4 v[8:11], v[20:21] offset:2048
	v_add_f32_e32 v63, v63, v25
	v_add_f32_e32 v64, v64, v79
	v_add_f32_e32 v65, v65, v80
	v_add_f32_e32 v67, v67, v81
	v_add_f32_e32 v68, v68, v82
	v_add_f32_e32 v69, v69, v83
	v_lshlrev_b32_e32 v24, 16, v12
	v_and_b32_e32 v25, 0xffff0000, v12
	v_add_f32_e32 v73, v73, v24
	v_add_co_u32_e32 v24, vcc, s61, v32
	v_add_f32_e32 v70, v70, v84
	v_lshlrev_b32_e32 v79, 16, v13
	v_and_b32_e32 v80, 0xffff0000, v13
	v_lshlrev_b32_e32 v81, 16, v14
	v_and_b32_e32 v82, 0xffff0000, v14
	v_lshlrev_b32_e32 v83, 16, v15
	v_and_b32_e32 v84, 0xffff0000, v15
	flat_load_dwordx4 v[12:15], v[20:21] offset:3072
	v_add_f32_e32 v74, v74, v25
	v_addc_co_u32_e32 v25, vcc, 0, v33, vcc
	v_add_f32_e32 v75, v75, v79
	v_add_f32_e32 v76, v76, v80
	v_add_f32_e32 v77, v77, v81
	v_add_f32_e32 v72, v72, v82
	v_add_f32_e32 v79, v22, v83
	v_add_f32_e32 v80, v23, v84
	v_lshlrev_b32_e32 v81, 16, v16
	v_and_b32_e32 v16, 0xffff0000, v16
	v_lshlrev_b32_e32 v82, 16, v17
	v_and_b32_e32 v17, 0xffff0000, v17
	flat_load_dwordx4 v[20:23], v[24:25]
	v_lshlrev_b32_e32 v32, 16, v18
	v_and_b32_e32 v18, 0xffff0000, v18
	v_lshlrev_b32_e32 v33, 16, v19
	v_and_b32_e32 v19, 0xffff0000, v19
	v_add_f32_e32 v78, v78, v16
	v_add_f32_e32 v26, v26, v82
	v_add_f32_e32 v27, v27, v17
	v_add_f32_e32 v28, v28, v32
	v_add_f32_e32 v29, v29, v18
	v_add_f32_e32 v30, v30, v33
	v_add_f32_e32 v31, v31, v19
	flat_load_dwordx4 v[16:19], v[24:25] offset:1024
	v_lshlrev_b32_e32 v32, 16, v0
	v_and_b32_e32 v0, 0xffff0000, v0
	v_lshlrev_b32_e32 v33, 16, v1
	v_and_b32_e32 v1, 0xffff0000, v1
	v_lshlrev_b32_e32 v82, 16, v2
	v_and_b32_e32 v2, 0xffff0000, v2
	v_lshlrev_b32_e32 v83, 16, v3
	v_and_b32_e32 v3, 0xffff0000, v3
	v_add_f32_e32 v32, v66, v32
	v_add_f32_e32 v34, v34, v0
	v_add_f32_e32 v33, v35, v33
	v_add_f32_e32 v35, v58, v1
	v_add_f32_e32 v58, v59, v82
	v_add_f32_e32 v59, v60, v2
	v_add_f32_e32 v60, v61, v83
	v_add_f32_e32 v61, v62, v3
	s_waitcnt vmcnt(0) lgkmcnt(0)
	v_lshlrev_b32_e32 v62, 16, v4
	v_and_b32_e32 v4, 0xffff0000, v4
	flat_load_dwordx4 v[0:3], v[24:25] offset:2048
	v_lshlrev_b32_e32 v66, 16, v5
	v_and_b32_e32 v5, 0xffff0000, v5
	v_lshlrev_b32_e32 v82, 16, v6
	v_and_b32_e32 v6, 0xffff0000, v6
	v_lshlrev_b32_e32 v83, 16, v7
	v_and_b32_e32 v7, 0xffff0000, v7
	v_add_f32_e32 v63, v63, v4
	v_add_f32_e32 v64, v64, v66
	v_add_f32_e32 v65, v65, v5
	v_add_f32_e32 v66, v67, v82
	v_add_f32_e32 v67, v68, v6
	v_add_f32_e32 v68, v69, v83
	v_add_f32_e32 v69, v70, v7
	flat_load_dwordx4 v[4:7], v[24:25] offset:3072
	v_add_f32_e32 v62, v71, v62
	v_lshlrev_b32_e32 v70, 16, v8
	v_and_b32_e32 v8, 0xffff0000, v8
	v_lshlrev_b32_e32 v24, 16, v9
	v_add_f32_e32 v70, v73, v70
	v_add_f32_e32 v8, v74, v8
	v_add_f32_e32 v24, v75, v24
	v_and_b32_e32 v9, 0xffff0000, v9
	v_lshlrev_b32_e32 v25, 16, v10
	v_and_b32_e32 v10, 0xffff0000, v10
	v_lshlrev_b32_e32 v71, 16, v11
	v_and_b32_e32 v11, 0xffff0000, v11
	v_add_f32_e32 v81, v85, v81
	v_add_f32_e32 v9, v76, v9
	v_add_f32_e32 v10, v72, v10
	v_add_f32_e32 v11, v80, v11
	v_add_f32_e32 v25, v77, v25
	v_add_f32_e32 v71, v79, v71
	v_lshlrev_b32_e32 v73, 16, v13
	v_and_b32_e32 v13, 0xffff0000, v13
	v_lshlrev_b32_e32 v74, 16, v14
	v_lshlrev_b32_e32 v75, 16, v15
	v_and_b32_e32 v14, 0xffff0000, v14
	v_and_b32_e32 v15, 0xffff0000, v15
	v_add_f32_e32 v13, v27, v13
	v_add_f32_e32 v27, v28, v74
	v_add_f32_e32 v28, v30, v75
	v_add_f32_e32 v26, v26, v73
	v_add_f32_e32 v14, v29, v14
	v_add_f32_e32 v15, v31, v15
	v_lshlrev_b32_e32 v72, 16, v12
	v_and_b32_e32 v12, 0xffff0000, v12
	v_lshlrev_b32_e32 v30, 16, v21
	v_lshlrev_b32_e32 v29, 16, v20
	v_lshlrev_b32_e32 v31, 16, v22
	v_and_b32_e32 v22, 0xffff0000, v22
	v_lshlrev_b32_e32 v73, 16, v23
	v_and_b32_e32 v23, 0xffff0000, v23
	v_add_f32_e32 v30, v33, v30
	v_and_b32_e32 v20, 0xffff0000, v20
	v_and_b32_e32 v21, 0xffff0000, v21
	v_add_f32_e32 v29, v32, v29
	v_add_f32_e32 v22, v59, v22
	v_add_f32_e32 v32, v60, v73
	v_lshlrev_b32_e32 v33, 16, v16
	v_add_f32_e32 v23, v61, v23
	v_add_f32_e32 v33, v62, v33
	v_add_f32_e32 v72, v81, v72
	v_add_f32_e32 v12, v78, v12
	v_add_f32_e32 v20, v34, v20
	v_add_f32_e32 v21, v35, v21
	v_add_f32_e32 v31, v58, v31
	v_and_b32_e32 v16, 0xffff0000, v16
	v_lshlrev_b32_e32 v34, 16, v17
	v_and_b32_e32 v17, 0xffff0000, v17
	v_lshlrev_b32_e32 v35, 16, v18
	v_and_b32_e32 v18, 0xffff0000, v18
	v_lshlrev_b32_e32 v58, 16, v19
	v_and_b32_e32 v19, 0xffff0000, v19
	v_add_f32_e32 v16, v63, v16
	v_add_f32_e32 v34, v64, v34
	v_add_f32_e32 v17, v65, v17
	v_add_f32_e32 v35, v66, v35
	s_waitcnt vmcnt(0) lgkmcnt(0)
	v_lshlrev_b32_e32 v59, 16, v0
	v_and_b32_e32 v0, 0xffff0000, v0
	v_lshlrev_b32_e32 v60, 16, v1
	v_and_b32_e32 v1, 0xffff0000, v1
	v_lshlrev_b32_e32 v61, 16, v2
	v_and_b32_e32 v2, 0xffff0000, v2
	v_lshlrev_b32_e32 v62, 16, v3
	v_and_b32_e32 v3, 0xffff0000, v3
	v_add_f32_e32 v8, v8, v0
	v_add_f32_e32 v9, v9, v1
	v_add_f32_e32 v10, v10, v2
	v_add_f32_e32 v11, v11, v3
	v_add_f32_e32 v18, v67, v18
	v_add_f32_e32 v58, v68, v58
	v_lshlrev_b32_e32 v0, 16, v4
	v_and_b32_e32 v1, 0xffff0000, v4
	v_lshlrev_b32_e32 v2, 16, v5
	v_and_b32_e32 v3, 0xffff0000, v5
	v_lshlrev_b32_e32 v4, 16, v6
	v_and_b32_e32 v5, 0xffff0000, v6
	v_lshlrev_b32_e32 v6, 16, v7
	v_add_f32_e32 v63, v72, v0
	v_add_f32_e32 v64, v12, v1
	v_add_f32_e32 v65, v26, v2
	v_add_f32_e32 v66, v13, v3
	v_add_f32_e32 v67, v27, v4
	v_add_f32_e32 v68, v14, v5
	v_lshl_add_u64 v[4:5], v[38:39], 0, s[54:55]
	v_cvt_pk_bf16_f32 v0, v29, v20
	v_cvt_pk_bf16_f32 v1, v30, v21
	v_cvt_pk_bf16_f32 v2, v31, v22
	v_cvt_pk_bf16_f32 v3, v32, v23
	v_add_f32_e32 v19, v69, v19
	v_add_f32_e32 v60, v24, v60
	v_add_f32_e32 v61, v25, v61
	v_add_f32_e32 v6, v28, v6
	flat_store_dwordx4 v[4:5], v[0:3] sc1
	v_lshlrev_b32_e32 v24, 16, v0
	v_and_b32_e32 v25, 0xffff0000, v0
	v_lshlrev_b32_e32 v26, 16, v1
	v_and_b32_e32 v27, 0xffff0000, v1
	v_lshlrev_b32_e32 v28, 16, v2
	v_and_b32_e32 v29, 0xffff0000, v2
	v_lshlrev_b32_e32 v30, 16, v3
	v_and_b32_e32 v31, 0xffff0000, v3
	v_cvt_pk_bf16_f32 v0, v33, v16
	v_cvt_pk_bf16_f32 v1, v34, v17
	v_cvt_pk_bf16_f32 v2, v35, v18
	v_cvt_pk_bf16_f32 v3, v58, v19
	v_add_f32_e32 v59, v70, v59
	v_add_f32_e32 v62, v71, v62
	v_and_b32_e32 v7, 0xffff0000, v7
	flat_store_dwordx4 v[4:5], v[0:3] offset:1024 sc1
	v_lshlrev_b32_e32 v16, 16, v0
	v_and_b32_e32 v17, 0xffff0000, v0
	v_lshlrev_b32_e32 v18, 16, v1
	v_and_b32_e32 v19, 0xffff0000, v1
	v_lshlrev_b32_e32 v20, 16, v2
	v_and_b32_e32 v21, 0xffff0000, v2
	v_lshlrev_b32_e32 v22, 16, v3
	v_and_b32_e32 v23, 0xffff0000, v3
	v_cvt_pk_bf16_f32 v0, v59, v8
	v_cvt_pk_bf16_f32 v1, v60, v9
	v_cvt_pk_bf16_f32 v2, v61, v10
	v_cvt_pk_bf16_f32 v3, v62, v11
	v_add_f32_e32 v7, v15, v7
	flat_store_dwordx4 v[4:5], v[0:3] offset:2048 sc1
	v_lshlrev_b32_e32 v8, 16, v0
	v_and_b32_e32 v9, 0xffff0000, v0
	v_lshlrev_b32_e32 v10, 16, v1
	v_and_b32_e32 v11, 0xffff0000, v1
	v_lshlrev_b32_e32 v12, 16, v2
	v_and_b32_e32 v13, 0xffff0000, v2
	v_lshlrev_b32_e32 v14, 16, v3
	v_and_b32_e32 v15, 0xffff0000, v3
	v_cvt_pk_bf16_f32 v32, v63, v64
	v_cvt_pk_bf16_f32 v33, v65, v66
	v_cvt_pk_bf16_f32 v34, v67, v68
	v_cvt_pk_bf16_f32 v35, v6, v7
	flat_store_dwordx4 v[4:5], v[32:35] offset:3072 sc1
	v_lshlrev_b32_e32 v0, 16, v32
	v_and_b32_e32 v1, 0xffff0000, v32
	v_lshlrev_b32_e32 v2, 16, v33
	v_and_b32_e32 v3, 0xffff0000, v33
	v_lshlrev_b32_e32 v4, 16, v34
	v_and_b32_e32 v5, 0xffff0000, v34
	s_mov_b64 s[54:55], 0

.LBB0_661:
	v_lshl_add_u64 v[0:1], v[42:43], 0, s[50:51]
	s_ashr_i32 s49, s48, 31
	flat_load_dwordx4 v[12:15], v[0:1] offset:1024
	flat_load_dwordx4 v[26:29], v[0:1] offset:2048
	flat_load_dwordx4 v[22:25], v[0:1]
	flat_load_dwordx4 v[4:7], v[0:1] offset:3072
	s_lshl_b64 s[52:53], s[48:49], 12
	v_lshl_add_u64 v[0:1], v[42:43], 0, s[52:53]
	flat_load_dwordx4 v[98:101], v[0:1] offset:1024
	flat_load_dwordx4 v[8:11], v[0:1] offset:2048
	flat_load_dwordx4 v[102:105], v[0:1]
	s_nop 0
	flat_load_dwordx4 v[0:3], v[0:1] offset:3072
	s_nop 0
	global_load_dwordx4 v[106:109], v[44:45], off offset:16
	global_load_dwordx4 v[110:113], v[44:45], off
	v_lshl_add_u64 v[116:117], v[50:51], 0, s[50:51]
	v_mov_b32_e32 v91, v41
	s_waitcnt vmcnt(0) lgkmcnt(0)
	v_and_b32_e32 v63, 0xffff0000, v12
	v_lshlrev_b32_e32 v35, 16, v12
	v_and_b32_e32 v85, 0xffff0000, v22
	v_and_b32_e32 v84, 0xffff0000, v102
	v_lshlrev_b32_e32 v71, 16, v22
	v_lshlrev_b32_e32 v57, 16, v13
	v_and_b32_e32 v69, 0xffff0000, v13
	v_lshlrev_b32_e32 v59, 16, v14
	v_and_b32_e32 v67, 0xffff0000, v14
	v_lshlrev_b32_e32 v13, 16, v4
	v_and_b32_e32 v17, 0xffff0000, v4
	v_lshlrev_b32_e32 v70, 16, v102
	v_lshlrev_b32_e32 v12, 16, v0
	v_and_b32_e32 v16, 0xffff0000, v0
	v_lshlrev_b32_e32 v14, 16, v1
	v_and_b32_e32 v4, 0xffff0000, v1
	v_pk_mul_f32 v[0:1], v[84:85], v[84:85]
	v_lshlrev_b32_e32 v73, 16, v23
	v_lshlrev_b32_e32 v72, 16, v103
	v_pk_fma_f32 v[0:1], v[70:71], v[70:71], v[0:1]
	v_and_b32_e32 v79, 0xffff0000, v23
	v_and_b32_e32 v78, 0xffff0000, v103
	v_pk_fma_f32 v[0:1], v[72:73], v[72:73], v[0:1]
	v_lshlrev_b32_e32 v75, 16, v24
	v_lshlrev_b32_e32 v74, 16, v104
	v_pk_fma_f32 v[0:1], v[78:79], v[78:79], v[0:1]
	v_and_b32_e32 v81, 0xffff0000, v24
	v_and_b32_e32 v80, 0xffff0000, v104
	v_pk_fma_f32 v[0:1], v[74:75], v[74:75], v[0:1]
	v_lshlrev_b32_e32 v77, 16, v25
	v_lshlrev_b32_e32 v76, 16, v105
	v_pk_fma_f32 v[0:1], v[80:81], v[80:81], v[0:1]
	v_and_b32_e32 v83, 0xffff0000, v25
	v_and_b32_e32 v82, 0xffff0000, v105
	v_pk_fma_f32 v[0:1], v[76:77], v[76:77], v[0:1]
	v_lshlrev_b32_e32 v34, 16, v98
	v_pk_fma_f32 v[0:1], v[82:83], v[82:83], v[0:1]
	v_and_b32_e32 v62, 0xffff0000, v98
	v_pk_fma_f32 v[0:1], v[34:35], v[34:35], v[0:1]
	v_lshlrev_b32_e32 v56, 16, v99
	v_pk_fma_f32 v[0:1], v[62:63], v[62:63], v[0:1]
	v_and_b32_e32 v68, 0xffff0000, v99
	v_pk_fma_f32 v[0:1], v[56:57], v[56:57], v[0:1]
	v_lshlrev_b32_e32 v58, 16, v100
	v_pk_fma_f32 v[0:1], v[68:69], v[68:69], v[0:1]
	v_and_b32_e32 v66, 0xffff0000, v100
	v_pk_fma_f32 v[0:1], v[58:59], v[58:59], v[0:1]
	v_lshlrev_b32_e32 v61, 16, v15
	v_lshlrev_b32_e32 v60, 16, v101
	v_pk_fma_f32 v[0:1], v[66:67], v[66:67], v[0:1]
	v_and_b32_e32 v65, 0xffff0000, v15
	v_and_b32_e32 v64, 0xffff0000, v101
	v_pk_fma_f32 v[0:1], v[60:61], v[60:61], v[0:1]
	v_lshlrev_b32_e32 v23, 16, v26
	v_lshlrev_b32_e32 v22, 16, v8
	v_pk_fma_f32 v[0:1], v[64:65], v[64:65], v[0:1]
	v_and_b32_e32 v33, 0xffff0000, v26
	v_and_b32_e32 v32, 0xffff0000, v8
	v_pk_fma_f32 v[0:1], v[22:23], v[22:23], v[0:1]
	v_lshlrev_b32_e32 v25, 16, v27
	v_lshlrev_b32_e32 v24, 16, v9
	v_pk_fma_f32 v[0:1], v[32:33], v[32:33], v[0:1]
	v_and_b32_e32 v21, 0xffff0000, v27
	v_and_b32_e32 v20, 0xffff0000, v9
	v_pk_fma_f32 v[0:1], v[24:25], v[24:25], v[0:1]
	v_lshlrev_b32_e32 v19, 16, v28
	v_lshlrev_b32_e32 v18, 16, v10
	v_pk_fma_f32 v[0:1], v[20:21], v[20:21], v[0:1]
	v_and_b32_e32 v31, 0xffff0000, v28
	v_and_b32_e32 v30, 0xffff0000, v10
	v_pk_fma_f32 v[0:1], v[18:19], v[18:19], v[0:1]
	v_lshlrev_b32_e32 v27, 16, v29
	v_lshlrev_b32_e32 v26, 16, v11
	v_pk_fma_f32 v[0:1], v[30:31], v[30:31], v[0:1]
	v_and_b32_e32 v29, 0xffff0000, v29
	v_and_b32_e32 v28, 0xffff0000, v11
	v_pk_fma_f32 v[0:1], v[26:27], v[26:27], v[0:1]
	v_and_b32_e32 v86, 0xffff0000, v6
	v_pk_fma_f32 v[0:1], v[28:29], v[28:29], v[0:1]
	v_lshlrev_b32_e32 v89, 16, v6
	v_and_b32_e32 v6, 0xffff0000, v2
	v_pk_fma_f32 v[0:1], v[12:13], v[12:13], v[0:1]
	v_lshlrev_b32_e32 v15, 16, v5
	v_mov_b32_e32 v88, v86
	v_lshlrev_b32_e32 v9, 16, v2
	v_mov_b32_e32 v8, v6
	v_pk_fma_f32 v[0:1], v[16:17], v[16:17], v[0:1]
	v_and_b32_e32 v5, 0xffff0000, v5
	v_pk_mul_f32 v[98:99], v[88:89], v[88:89]
	v_pk_mul_f32 v[102:103], v[8:9], v[8:9]
	v_pk_fma_f32 v[0:1], v[14:15], v[14:15], v[0:1]
	v_mov_b32_e32 v11, v99
	v_mov_b32_e32 v10, v103
	v_pk_fma_f32 v[0:1], v[4:5], v[4:5], v[0:1]
	v_and_b32_e32 v90, 0xffff0000, v7
	v_pk_add_f32 v[104:105], v[10:11], v[0:1]
	v_and_b32_e32 v0, 0xffff0000, v3
	v_lshlrev_b32_e32 v93, 16, v7
	v_mov_b32_e32 v92, v90
	v_lshlrev_b32_e32 v11, 16, v3
	v_mov_b32_e32 v10, v0
	v_and_b32_e32 v1, 64, v96
	v_pk_mul_f32 v[100:101], v[92:93], v[92:93]
	v_pk_mul_f32 v[114:115], v[10:11], v[10:11]
	v_add_u32_e32 v1, 64, v1
	v_xor_b32_e32 v2, 1, v96
	v_mov_b32_e32 v103, v98
	v_cmp_lt_i32_e32 vcc, v2, v1
	v_pk_add_f32 v[98:99], v[102:103], v[104:105]
	v_mov_b32_e32 v102, v115
	v_mov_b32_e32 v103, v101
	v_cndmask_b32_e32 v2, v96, v2, vcc
	v_pk_add_f32 v[98:99], v[102:103], v[98:99]
	v_mov_b32_e32 v115, v100
	v_lshlrev_b32_e32 v2, 2, v2
	v_pk_add_f32 v[98:99], v[114:115], v[98:99]
	ds_bpermute_b32 v101, v2, v99
	ds_bpermute_b32 v100, v2, v98
	v_xor_b32_e32 v2, 2, v96
	v_cmp_lt_i32_e32 vcc, v2, v1
	v_mov_b32_e32 v102, v75
	v_mov_b32_e32 v103, v81
	v_cndmask_b32_e32 v2, v96, v2, vcc
	v_lshlrev_b32_e32 v2, 2, v2
	s_waitcnt lgkmcnt(0)
	v_pk_add_f32 v[98:99], v[98:99], v[100:101]
	ds_bpermute_b32 v101, v2, v99
	ds_bpermute_b32 v100, v2, v98
	v_xor_b32_e32 v2, 4, v96
	v_cmp_lt_i32_e32 vcc, v2, v1
	v_mov_b32_e32 v104, v77
	v_mov_b32_e32 v105, v83
	v_cndmask_b32_e32 v2, v96, v2, vcc
	v_lshlrev_b32_e32 v2, 2, v2
	s_waitcnt lgkmcnt(0)
	v_pk_add_f32 v[98:99], v[98:99], v[100:101]
	ds_bpermute_b32 v101, v2, v99
	ds_bpermute_b32 v100, v2, v98
	v_xor_b32_e32 v2, 8, v96
	v_cmp_lt_i32_e32 vcc, v2, v1
	v_and_b32_e32 v87, s0, v7
	v_pk_mov_b32 v[86:87], v[88:89], v[86:87] op_sel:[1,0]
	v_cndmask_b32_e32 v2, v96, v2, vcc
	v_lshlrev_b32_e32 v2, 2, v2
	s_waitcnt lgkmcnt(0)
	v_pk_add_f32 v[98:99], v[98:99], v[100:101]
	ds_bpermute_b32 v101, v2, v99
	ds_bpermute_b32 v100, v2, v98
	v_xor_b32_e32 v2, 16, v96
	v_cmp_lt_i32_e32 vcc, v2, v1
	v_pk_mov_b32 v[88:89], v[92:93], v[90:91] op_sel:[1,0]
	v_mov_b32_e32 v75, v80
	v_cndmask_b32_e32 v2, v96, v2, vcc
	v_lshlrev_b32_e32 v2, 2, v2
	s_waitcnt lgkmcnt(0)
	v_pk_add_f32 v[98:99], v[98:99], v[100:101]
	ds_bpermute_b32 v101, v2, v99
	ds_bpermute_b32 v100, v2, v98
	v_xor_b32_e32 v2, 32, v96
	v_cmp_lt_i32_e32 vcc, v2, v1
	v_mov_b32_e32 v77, v82
	v_and_b32_e32 v7, s0, v3
	v_cndmask_b32_e32 v1, v96, v2, vcc
	v_lshlrev_b32_e32 v1, 2, v1
	s_waitcnt lgkmcnt(0)
	v_pk_add_f32 v[98:99], v[98:99], v[100:101]
	ds_bpermute_b32 v101, v1, v99
	ds_bpermute_b32 v100, v1, v98
	v_pk_mov_b32 v[6:7], v[8:9], v[6:7] op_sel:[1,0]
	s_waitcnt lgkmcnt(0)
	v_pk_add_f32 v[98:99], v[98:99], v[100:101]
	s_nop 0
	v_pk_fma_f32 v[114:115], v[98:99], s[44:45], v[54:55] op_sel_hi:[1,0,0]
	v_mov_b32_e32 v98, v71
	v_mul_f32_e32 v1, 0x4b800000, v115
	v_cmp_gt_f32_e32 vcc, s19, v115
	v_mov_b32_e32 v99, v85
	v_mov_b32_e32 v100, v73
	v_cndmask_b32_e32 v1, v115, v1, vcc
	v_rsq_f32_e32 v1, v1
	v_mov_b32_e32 v101, v79
	v_mov_b32_e32 v71, v84
	v_mov_b32_e32 v73, v78
	v_mul_f32_e32 v2, 0x45800000, v1
	v_cndmask_b32_e32 v2, v1, v2, vcc
	v_pk_mul_f32 v[98:99], v[98:99], v[2:3] op_sel_hi:[1,0]
	v_pk_mul_f32 v[100:101], v[100:101], v[2:3] op_sel_hi:[1,0]
	v_pk_mul_f32 v[98:99], v[110:111], v[98:99]
	v_pk_mul_f32 v[100:101], v[112:113], v[100:101]
	v_pk_mul_f32 v[102:103], v[102:103], v[2:3] op_sel_hi:[1,0]
	v_pk_mul_f32 v[104:105], v[104:105], v[2:3] op_sel_hi:[1,0]
	v_pk_mul_f32 v[102:103], v[106:107], v[102:103]
	v_pk_mul_f32 v[104:105], v[108:109], v[104:105]
	v_cvt_pk_bf16_f32 v98, v98, v99
	v_cvt_pk_bf16_f32 v99, v100, v101
	v_cvt_pk_bf16_f32 v100, v102, v103
	v_mov_b32_e32 v106, v35
	v_cvt_pk_bf16_f32 v101, v104, v105
	flat_store_dwordx4 v[116:117], v[98:101] sc1
	global_load_dwordx4 v[98:101], v[44:45], off offset:2048
	s_nop 0
	global_load_dwordx4 v[102:105], v[44:45], off offset:2064
	v_mov_b32_e32 v107, v63
	v_mov_b32_e32 v108, v57
	v_mov_b32_e32 v109, v69
	v_mov_b32_e32 v110, v59
	v_mov_b32_e32 v111, v67
	v_mov_b32_e32 v112, v61
	v_mov_b32_e32 v113, v65
	v_pk_mul_f32 v[106:107], v[106:107], v[2:3] op_sel_hi:[1,0]
	v_pk_mul_f32 v[108:109], v[108:109], v[2:3] op_sel_hi:[1,0]
	v_pk_mul_f32 v[110:111], v[110:111], v[2:3] op_sel_hi:[1,0]
	v_pk_mul_f32 v[112:113], v[112:113], v[2:3] op_sel_hi:[1,0]
	v_pk_mul_f32 v[86:87], v[2:3], v[86:87] op_sel_hi:[0,1]
	v_pk_mul_f32 v[88:89], v[2:3], v[88:89] op_sel_hi:[0,1]
	v_mul_f32_e32 v1, 0x4b800000, v114
	v_cmp_gt_f32_e32 vcc, s19, v114
	v_mov_b32_e32 v59, v66
	v_mov_b32_e32 v35, v62
	v_cndmask_b32_e32 v1, v114, v1, vcc
	v_rsq_f32_e32 v1, v1
	v_mov_b32_e32 v57, v68
	v_mov_b32_e32 v61, v64
	s_waitcnt vmcnt(0)
	v_pk_mul_f32 v[100:101], v[100:101], v[108:109]
	v_pk_mul_f32 v[98:99], v[98:99], v[106:107]
	v_pk_mul_f32 v[104:105], v[104:105], v[112:113]
	v_pk_mul_f32 v[102:103], v[102:103], v[110:111]
	v_cvt_pk_bf16_f32 v98, v98, v99
	v_cvt_pk_bf16_f32 v99, v100, v101
	v_mov_b32_e32 v106, v23
	v_cvt_pk_bf16_f32 v100, v102, v103
	v_cvt_pk_bf16_f32 v101, v104, v105
	flat_store_dwordx4 v[116:117], v[98:101] offset:1024 sc1
	global_load_dwordx4 v[98:101], v[46:47], off
	s_nop 0
	global_load_dwordx4 v[102:105], v[46:47], off offset:16
	v_mov_b32_e32 v107, v33
	v_mov_b32_e32 v108, v25
	v_mov_b32_e32 v109, v21
	v_mov_b32_e32 v110, v19
	v_mov_b32_e32 v111, v31
	v_mov_b32_e32 v112, v27
	v_mov_b32_e32 v113, v29
	v_pk_mul_f32 v[106:107], v[106:107], v[2:3] op_sel_hi:[1,0]
	v_pk_mul_f32 v[108:109], v[108:109], v[2:3] op_sel_hi:[1,0]
	v_pk_mul_f32 v[110:111], v[110:111], v[2:3] op_sel_hi:[1,0]
	v_pk_mul_f32 v[112:113], v[112:113], v[2:3] op_sel_hi:[1,0]
	v_mov_b32_e32 v23, v32
	v_mov_b32_e32 v25, v20
	v_mov_b32_e32 v19, v30
	v_mov_b32_e32 v27, v28
	s_waitcnt vmcnt(0)
	v_pk_mul_f32 v[100:101], v[100:101], v[108:109]
	v_pk_mul_f32 v[98:99], v[98:99], v[106:107]
	v_pk_mul_f32 v[104:105], v[104:105], v[112:113]
	v_pk_mul_f32 v[102:103], v[102:103], v[110:111]
	v_cvt_pk_bf16_f32 v98, v98, v99
	v_cvt_pk_bf16_f32 v99, v100, v101
	v_mov_b32_e32 v106, v13
	v_cvt_pk_bf16_f32 v100, v102, v103
	v_cvt_pk_bf16_f32 v101, v104, v105
	flat_store_dwordx4 v[116:117], v[98:101] offset:2048 sc1
	global_load_dwordx4 v[98:101], v[48:49], off
	s_nop 0
	global_load_dwordx4 v[102:105], v[48:49], off offset:16
	v_mov_b32_e32 v107, v17
	v_mov_b32_e32 v108, v15
	v_mov_b32_e32 v109, v5
	v_pk_mul_f32 v[90:91], v[106:107], v[2:3] op_sel_hi:[1,0]
	v_pk_mul_f32 v[92:93], v[108:109], v[2:3] op_sel_hi:[1,0]
	v_mul_f32_e32 v2, 0x45800000, v1
	v_cndmask_b32_e32 v2, v1, v2, vcc
	v_pk_mul_f32 v[70:71], v[70:71], v[2:3] op_sel_hi:[1,0]
	v_pk_mul_f32 v[72:73], v[72:73], v[2:3] op_sel_hi:[1,0]
	v_pk_mul_f32 v[74:75], v[74:75], v[2:3] op_sel_hi:[1,0]
	v_pk_mul_f32 v[76:77], v[76:77], v[2:3] op_sel_hi:[1,0]
	v_pk_mul_f32 v[58:59], v[58:59], v[2:3] op_sel_hi:[1,0]
	v_pk_mul_f32 v[34:35], v[34:35], v[2:3] op_sel_hi:[1,0]
	v_pk_mul_f32 v[56:57], v[56:57], v[2:3] op_sel_hi:[1,0]
	v_pk_mul_f32 v[60:61], v[60:61], v[2:3] op_sel_hi:[1,0]
	v_pk_mul_f32 v[20:21], v[22:23], v[2:3] op_sel_hi:[1,0]
	v_pk_mul_f32 v[22:23], v[24:25], v[2:3] op_sel_hi:[1,0]
	v_pk_mul_f32 v[18:19], v[18:19], v[2:3] op_sel_hi:[1,0]
	v_pk_mul_f32 v[24:25], v[26:27], v[2:3] op_sel_hi:[1,0]
	v_mov_b32_e32 v1, v41
	v_mov_b32_e32 v15, v4
	v_pk_mov_b32 v[0:1], v[10:11], v[0:1] op_sel:[1,0]
	v_mov_b32_e32 v13, v16
	v_pk_mul_f32 v[8:9], v[14:15], v[2:3] op_sel_hi:[1,0]
	v_pk_mul_f32 v[4:5], v[12:13], v[2:3] op_sel_hi:[1,0]
	v_pk_mul_f32 v[6:7], v[2:3], v[6:7] op_sel_hi:[0,1]
	v_pk_mul_f32 v[0:1], v[2:3], v[0:1] op_sel_hi:[0,1]
	s_waitcnt vmcnt(0)
	v_pk_mul_f32 v[90:91], v[98:99], v[90:91]
	v_pk_mul_f32 v[98:99], v[104:105], v[88:89]
	v_pk_mul_f32 v[88:89], v[102:103], v[86:87]
	v_pk_mul_f32 v[92:93], v[100:101], v[92:93]
	v_cvt_pk_bf16_f32 v86, v90, v91
	s_nop 0
	v_cvt_pk_bf16_f32 v87, v92, v93
	v_cvt_pk_bf16_f32 v88, v88, v89
	v_cvt_pk_bf16_f32 v89, v98, v99
	flat_store_dwordx4 v[116:117], v[86:89] offset:3072 sc1
	global_load_dwordx4 v[86:89], v[44:45], off
	s_nop 0
	global_load_dwordx4 v[90:93], v[44:45], off offset:16
	v_lshl_add_u64 v[98:99], v[50:51], 0, s[52:53]
	s_waitcnt vmcnt(0)
	v_pk_mul_f32 v[72:73], v[88:89], v[72:73]
	v_pk_mul_f32 v[70:71], v[86:87], v[70:71]
	v_pk_mul_f32 v[76:77], v[92:93], v[76:77]
	v_pk_mul_f32 v[74:75], v[90:91], v[74:75]
	v_cvt_pk_bf16_f32 v70, v70, v71
	v_cvt_pk_bf16_f32 v71, v72, v73
	s_nop 0
	v_cvt_pk_bf16_f32 v72, v74, v75
	v_cvt_pk_bf16_f32 v73, v76, v77
	flat_store_dwordx4 v[98:99], v[70:73] sc1
	global_load_dwordx4 v[70:73], v[44:45], off offset:2048
	s_nop 0
	global_load_dwordx4 v[74:77], v[44:45], off offset:2064
	s_waitcnt vmcnt(0)
	v_pk_mul_f32 v[62:63], v[56:57], v[72:73]
	v_pk_mul_f32 v[58:59], v[58:59], v[74:75]
	v_pk_mul_f32 v[34:35], v[34:35], v[70:71]
	v_pk_mul_f32 v[60:61], v[60:61], v[76:77]
	v_cvt_pk_bf16_f32 v56, v34, v35
	v_cvt_pk_bf16_f32 v57, v62, v63
	v_cvt_pk_bf16_f32 v58, v58, v59
	s_nop 0
	v_cvt_pk_bf16_f32 v59, v60, v61
	flat_store_dwordx4 v[98:99], v[56:59] offset:1024 sc1
	global_load_dwordx4 v[56:59], v[46:47], off
	s_nop 0
	global_load_dwordx4 v[60:63], v[46:47], off offset:16
	s_waitcnt vmcnt(0)
	v_pk_mul_f32 v[20:21], v[20:21], v[56:57]
	v_pk_mul_f32 v[22:23], v[22:23], v[58:59]
	v_pk_mul_f32 v[24:25], v[24:25], v[62:63]
	v_pk_mul_f32 v[26:27], v[18:19], v[60:61]
	v_cvt_pk_bf16_f32 v18, v20, v21
	v_cvt_pk_bf16_f32 v19, v22, v23
	s_nop 0
	v_cvt_pk_bf16_f32 v20, v26, v27
	v_cvt_pk_bf16_f32 v21, v24, v25
	flat_store_dwordx4 v[98:99], v[18:21] offset:2048 sc1
	global_load_dwordx4 v[18:21], v[48:49], off
	s_nop 0
	global_load_dwordx4 v[22:25], v[48:49], off offset:16
	s_waitcnt vmcnt(0)
	v_pk_mul_f32 v[2:3], v[8:9], v[20:21]
	v_pk_mul_f32 v[4:5], v[4:5], v[18:19]
	v_pk_mul_f32 v[8:9], v[0:1], v[24:25]
	v_pk_mul_f32 v[6:7], v[6:7], v[22:23]
	v_cvt_pk_bf16_f32 v0, v4, v5
	v_cvt_pk_bf16_f32 v1, v2, v3
	s_nop 0
	v_cvt_pk_bf16_f32 v2, v6, v7
	v_cvt_pk_bf16_f32 v3, v8, v9
	flat_store_dwordx4 v[98:99], v[0:3] offset:3072 sc1
	s_branch .LBB0_634

.LBB0_733:
	v_mov_b32_e32 v152, v146
	v_mov_b32_e32 v153, v147
	s_cmp_lg_u32 s6, 0
	s_cbranch_scc0 .LBB0_740
	s_add_i32 s6, s6, -1
	s_lshl_b64 s[40:41], s[6:7], 22
	s_add_u32 s6, s72, s40
	s_addc_u32 s57, s73, s41
	s_ashr_i32 s59, s58, 31
	s_lshl_b64 s[40:41], s[58:59], 12
	s_add_u32 s6, s6, s40
	s_addc_u32 s59, s57, s41
	s_ashr_i32 s57, s56, 31
	s_lshl_b64 s[40:41], s[56:57], 1
	s_add_u32 s6, s6, s40
	s_addc_u32 s41, s59, s41
	v_add_u32_e32 v128, s74, v152
	s_add_u32 s40, s6, s87
	v_lshlrev_b32_e32 v130, 3, v153
	s_addc_u32 s41, s41, 0
	v_ashrrev_i32_e32 v131, 31, v130
	v_ashrrev_i32_e32 v129, 31, v128
	v_lshl_add_u64 v[130:131], v[130:131], 1, s[40:41]
	v_lshlrev_b64 v[144:145], 12, v[128:129]
	v_lshl_add_u64 v[144:145], v[130:131], 0, v[144:145]
	v_cvt_pk_bf16_f32 v154, v124, v125
	v_cvt_pk_bf16_f32 v155, v126, v127
	v_cvt_pk_bf16_f32 v156, v120, v121
	v_cvt_pk_bf16_f32 v157, v122, v123
	flat_store_dwordx4 v[144:145], v[154:157] sc1
	s_nop 1
	v_cvt_pk_bf16_f32 v154, v116, v117
	v_cvt_pk_bf16_f32 v155, v118, v119
	v_cvt_pk_bf16_f32 v156, v112, v113
	v_cvt_pk_bf16_f32 v157, v114, v115
	flat_store_dwordx4 v[144:145], v[154:157] offset:256 sc1
	v_add_u32_e32 v144, 16, v128
	v_ashrrev_i32_e32 v145, 31, v144
	v_lshlrev_b64 v[144:145], 12, v[144:145]
	v_lshl_add_u64 v[144:145], v[130:131], 0, v[144:145]
	v_cvt_pk_bf16_f32 v154, v108, v109
	v_cvt_pk_bf16_f32 v155, v110, v111
	v_cvt_pk_bf16_f32 v156, v104, v105
	v_cvt_pk_bf16_f32 v157, v106, v107
	flat_store_dwordx4 v[144:145], v[154:157] sc1
	s_nop 1
	v_cvt_pk_bf16_f32 v154, v100, v101
	v_cvt_pk_bf16_f32 v155, v102, v103
	v_cvt_pk_bf16_f32 v156, v96, v97
	v_cvt_pk_bf16_f32 v157, v98, v99
	flat_store_dwordx4 v[144:145], v[154:157] offset:256 sc1
	v_add_u32_e32 v144, 32, v128
	v_ashrrev_i32_e32 v145, 31, v144
	v_lshlrev_b64 v[144:145], 12, v[144:145]
	v_lshl_add_u64 v[144:145], v[130:131], 0, v[144:145]
	v_cvt_pk_bf16_f32 v154, v92, v93
	v_cvt_pk_bf16_f32 v155, v94, v95
	v_cvt_pk_bf16_f32 v156, v88, v89
	v_cvt_pk_bf16_f32 v157, v90, v91
	flat_store_dwordx4 v[144:145], v[154:157] sc1
	s_nop 1
	v_cvt_pk_bf16_f32 v154, v84, v85
	v_cvt_pk_bf16_f32 v155, v86, v87
	v_cvt_pk_bf16_f32 v156, v80, v81
	v_cvt_pk_bf16_f32 v157, v82, v83
	flat_store_dwordx4 v[144:145], v[154:157] offset:256 sc1
	v_add_u32_e32 v144, 48, v128
	v_ashrrev_i32_e32 v145, 31, v144
	v_lshlrev_b64 v[144:145], 12, v[144:145]
	v_lshl_add_u64 v[144:145], v[130:131], 0, v[144:145]
	v_cvt_pk_bf16_f32 v154, v76, v77
	v_cvt_pk_bf16_f32 v155, v78, v79
	v_cvt_pk_bf16_f32 v156, v72, v73
	v_cvt_pk_bf16_f32 v157, v74, v75
	flat_store_dwordx4 v[144:145], v[154:157] sc1
	s_nop 1
	v_cvt_pk_bf16_f32 v154, v68, v69
	v_cvt_pk_bf16_f32 v155, v70, v71
	v_cvt_pk_bf16_f32 v156, v64, v65
	v_cvt_pk_bf16_f32 v157, v66, v67
	flat_store_dwordx4 v[144:145], v[154:157] offset:256 sc1
	v_add_u32_e32 v144, 0x80, v128
	v_ashrrev_i32_e32 v145, 31, v144
	v_lshlrev_b64 v[144:145], 12, v[144:145]
	v_lshl_add_u64 v[144:145], v[130:131], 0, v[144:145]
	v_cvt_pk_bf16_f32 v154, v60, v61
	v_cvt_pk_bf16_f32 v155, v62, v63
	v_cvt_pk_bf16_f32 v156, v56, v57
	v_cvt_pk_bf16_f32 v157, v58, v59
	flat_store_dwordx4 v[144:145], v[154:157] sc1
	s_nop 1
	v_cvt_pk_bf16_f32 v154, v52, v53
	v_cvt_pk_bf16_f32 v155, v54, v55
	v_cvt_pk_bf16_f32 v156, v48, v49
	v_cvt_pk_bf16_f32 v157, v50, v51
	flat_store_dwordx4 v[144:145], v[154:157] offset:256 sc1
	v_add_u32_e32 v144, 0x90, v128
	v_ashrrev_i32_e32 v145, 31, v144
	v_lshlrev_b64 v[144:145], 12, v[144:145]
	v_lshl_add_u64 v[144:145], v[130:131], 0, v[144:145]
	v_cvt_pk_bf16_f32 v154, v44, v45
	v_cvt_pk_bf16_f32 v155, v46, v47
	v_cvt_pk_bf16_f32 v156, v40, v41
	v_cvt_pk_bf16_f32 v157, v42, v43
	flat_store_dwordx4 v[144:145], v[154:157] sc1
	s_nop 1
	v_cvt_pk_bf16_f32 v154, v36, v37
	v_cvt_pk_bf16_f32 v155, v38, v39
	v_cvt_pk_bf16_f32 v156, v32, v33
	v_cvt_pk_bf16_f32 v157, v34, v35
	flat_store_dwordx4 v[144:145], v[154:157] offset:256 sc1
	v_add_u32_e32 v144, 0xa0, v128
	v_ashrrev_i32_e32 v145, 31, v144
	v_add_u32_e32 v128, 0xb0, v128
	v_lshlrev_b64 v[144:145], 12, v[144:145]
	v_ashrrev_i32_e32 v129, 31, v128
	v_lshl_add_u64 v[144:145], v[130:131], 0, v[144:145]
	v_cvt_pk_bf16_f32 v154, v28, v29
	v_cvt_pk_bf16_f32 v155, v30, v31
	v_cvt_pk_bf16_f32 v156, v24, v25
	v_cvt_pk_bf16_f32 v157, v26, v27
	v_lshlrev_b64 v[128:129], 12, v[128:129]
	flat_store_dwordx4 v[144:145], v[154:157] sc1
	s_nop 1
	v_cvt_pk_bf16_f32 v154, v20, v21
	v_cvt_pk_bf16_f32 v155, v22, v23
	v_cvt_pk_bf16_f32 v156, v16, v17
	v_cvt_pk_bf16_f32 v157, v18, v19
	flat_store_dwordx4 v[144:145], v[154:157] offset:256 sc1
	v_lshl_add_u64 v[144:145], v[130:131], 0, v[128:129]
	v_cvt_pk_bf16_f32 v128, v12, v13
	v_cvt_pk_bf16_f32 v129, v14, v15
	v_cvt_pk_bf16_f32 v130, v8, v9
	v_cvt_pk_bf16_f32 v131, v10, v11
	flat_store_dwordx4 v[144:145], v[128:131] sc1
	s_nop 1
	v_cvt_pk_bf16_f32 v128, v4, v5
	v_cvt_pk_bf16_f32 v129, v6, v7
	v_cvt_pk_bf16_f32 v130, v0, v1
	v_cvt_pk_bf16_f32 v131, v2, v3
	s_cbranch_execnz .LBB0_736
.LBB0_735:
	s_add_i32 s6, s58, s74
	v_add_u32_e32 v128, s6, v152
	v_ashrrev_i32_e32 v129, 31, v128
	v_lshl_add_u32 v130, v153, 3, s75
	v_lshlrev_b64 v[144:145], 12, v[128:129]
	s_ashr_i32 s57, s56, 31
	v_ashrrev_i32_e32 v131, 31, v130
	v_lshl_add_u64 v[144:145], s[10:11], 0, v[144:145]
	s_lshl_b64 s[56:57], s[56:57], 1
	v_lshl_add_u64 v[144:145], v[144:145], 0, s[56:57]
	v_lshlrev_b64 v[130:131], 1, v[130:131]
	v_lshl_add_u64 v[144:145], v[144:145], 0, v[130:131]
	v_pk_mul_f32 v[126:127], v[126:127], s[48:49] op_sel_hi:[1,0]
	v_pk_mul_f32 v[124:125], v[124:125], s[48:49] op_sel_hi:[1,0]
	v_pk_mul_f32 v[152:153], v[122:123], s[48:49] op_sel_hi:[1,0]
	v_pk_mul_f32 v[122:123], v[120:121], s[48:49] op_sel_hi:[1,0]
	v_cvt_pk_bf16_f32 v120, v124, v125
	v_cvt_pk_bf16_f32 v121, v126, v127
	v_pk_mul_f32 v[116:117], v[116:117], s[48:49] op_sel_hi:[1,0]
	v_cvt_pk_bf16_f32 v122, v122, v123
	v_cvt_pk_bf16_f32 v123, v152, v153
	flat_store_dwordx4 v[144:145], v[120:123] sc1
	v_pk_mul_f32 v[118:119], v[118:119], s[48:49] op_sel_hi:[1,0]
	v_pk_mul_f32 v[110:111], v[110:111], s[48:49] op_sel_hi:[1,0]
	v_pk_mul_f32 v[120:121], v[114:115], s[48:49] op_sel_hi:[1,0]
	v_pk_mul_f32 v[114:115], v[112:113], s[48:49] op_sel_hi:[1,0]
	v_cvt_pk_bf16_f32 v112, v116, v117
	v_cvt_pk_bf16_f32 v113, v118, v119
	v_pk_mul_f32 v[108:109], v[108:109], s[48:49] op_sel_hi:[1,0]
	v_cvt_pk_bf16_f32 v114, v114, v115
	v_cvt_pk_bf16_f32 v115, v120, v121
	flat_store_dwordx4 v[144:145], v[112:115] offset:256 sc1
	v_pk_mul_f32 v[100:101], v[100:101], s[48:49] op_sel_hi:[1,0]
	v_pk_mul_f32 v[102:103], v[102:103], s[48:49] op_sel_hi:[1,0]
	v_add_u32_e32 v112, 16, v128
	v_ashrrev_i32_e32 v113, 31, v112
	v_lshlrev_b64 v[112:113], 12, v[112:113]
	v_lshl_add_u64 v[112:113], s[10:11], 0, v[112:113]
	v_lshl_add_u64 v[112:113], v[112:113], 0, s[56:57]
	v_lshl_add_u64 v[112:113], v[112:113], 0, v[130:131]
	v_pk_mul_f32 v[114:115], v[106:107], s[48:49] op_sel_hi:[1,0]
	v_pk_mul_f32 v[106:107], v[104:105], s[48:49] op_sel_hi:[1,0]
	v_cvt_pk_bf16_f32 v104, v108, v109
	v_cvt_pk_bf16_f32 v105, v110, v111
	v_pk_mul_f32 v[94:95], v[94:95], s[48:49] op_sel_hi:[1,0]
	v_cvt_pk_bf16_f32 v106, v106, v107
	v_cvt_pk_bf16_f32 v107, v114, v115
	flat_store_dwordx4 v[112:113], v[104:107] sc1
	v_pk_mul_f32 v[92:93], v[92:93], s[48:49] op_sel_hi:[1,0]
	v_pk_mul_f32 v[84:85], v[84:85], s[48:49] op_sel_hi:[1,0]
	v_pk_mul_f32 v[104:105], v[98:99], s[48:49] op_sel_hi:[1,0]
	v_pk_mul_f32 v[98:99], v[96:97], s[48:49] op_sel_hi:[1,0]
	v_cvt_pk_bf16_f32 v96, v100, v101
	v_cvt_pk_bf16_f32 v97, v102, v103
	v_pk_mul_f32 v[86:87], v[86:87], s[48:49] op_sel_hi:[1,0]
	v_cvt_pk_bf16_f32 v98, v98, v99
	v_cvt_pk_bf16_f32 v99, v104, v105
	flat_store_dwordx4 v[112:113], v[96:99] offset:256 sc1
	v_pk_mul_f32 v[78:79], v[78:79], s[48:49] op_sel_hi:[1,0]
	v_pk_mul_f32 v[76:77], v[76:77], s[48:49] op_sel_hi:[1,0]
	v_add_u32_e32 v96, 32, v128
	v_ashrrev_i32_e32 v97, 31, v96
	v_lshlrev_b64 v[96:97], 12, v[96:97]
	v_lshl_add_u64 v[96:97], s[10:11], 0, v[96:97]
	v_lshl_add_u64 v[96:97], v[96:97], 0, s[56:57]
	v_lshl_add_u64 v[96:97], v[96:97], 0, v[130:131]
	v_pk_mul_f32 v[98:99], v[90:91], s[48:49] op_sel_hi:[1,0]
	v_pk_mul_f32 v[90:91], v[88:89], s[48:49] op_sel_hi:[1,0]
	v_cvt_pk_bf16_f32 v88, v92, v93
	v_cvt_pk_bf16_f32 v89, v94, v95
	v_pk_mul_f32 v[68:69], v[68:69], s[48:49] op_sel_hi:[1,0]
	v_cvt_pk_bf16_f32 v90, v90, v91
	v_cvt_pk_bf16_f32 v91, v98, v99
	flat_store_dwordx4 v[96:97], v[88:91] sc1
	v_pk_mul_f32 v[70:71], v[70:71], s[48:49] op_sel_hi:[1,0]
	v_pk_mul_f32 v[62:63], v[62:63], s[48:49] op_sel_hi:[1,0]
	v_pk_mul_f32 v[88:89], v[82:83], s[48:49] op_sel_hi:[1,0]
	v_pk_mul_f32 v[82:83], v[80:81], s[48:49] op_sel_hi:[1,0]
	v_cvt_pk_bf16_f32 v80, v84, v85
	v_cvt_pk_bf16_f32 v81, v86, v87
	v_pk_mul_f32 v[60:61], v[60:61], s[48:49] op_sel_hi:[1,0]
	v_cvt_pk_bf16_f32 v82, v82, v83
	v_cvt_pk_bf16_f32 v83, v88, v89
	flat_store_dwordx4 v[96:97], v[80:83] offset:256 sc1
	v_pk_mul_f32 v[52:53], v[52:53], s[48:49] op_sel_hi:[1,0]
	v_pk_mul_f32 v[54:55], v[54:55], s[48:49] op_sel_hi:[1,0]
	v_add_u32_e32 v80, 48, v128
	v_ashrrev_i32_e32 v81, 31, v80
	v_lshlrev_b64 v[80:81], 12, v[80:81]
	v_lshl_add_u64 v[80:81], s[10:11], 0, v[80:81]
	v_lshl_add_u64 v[80:81], v[80:81], 0, s[56:57]
	v_lshl_add_u64 v[80:81], v[80:81], 0, v[130:131]
	v_pk_mul_f32 v[82:83], v[74:75], s[48:49] op_sel_hi:[1,0]
	v_pk_mul_f32 v[74:75], v[72:73], s[48:49] op_sel_hi:[1,0]
	v_cvt_pk_bf16_f32 v72, v76, v77
	v_cvt_pk_bf16_f32 v73, v78, v79
	v_pk_mul_f32 v[46:47], v[46:47], s[48:49] op_sel_hi:[1,0]
	v_cvt_pk_bf16_f32 v74, v74, v75
	v_cvt_pk_bf16_f32 v75, v82, v83
	flat_store_dwordx4 v[80:81], v[72:75] sc1
	v_pk_mul_f32 v[44:45], v[44:45], s[48:49] op_sel_hi:[1,0]
	v_pk_mul_f32 v[36:37], v[36:37], s[48:49] op_sel_hi:[1,0]
	v_pk_mul_f32 v[72:73], v[66:67], s[48:49] op_sel_hi:[1,0]
	v_pk_mul_f32 v[66:67], v[64:65], s[48:49] op_sel_hi:[1,0]
	v_cvt_pk_bf16_f32 v64, v68, v69
	v_cvt_pk_bf16_f32 v65, v70, v71
	v_pk_mul_f32 v[38:39], v[38:39], s[48:49] op_sel_hi:[1,0]
	v_cvt_pk_bf16_f32 v66, v66, v67
	v_cvt_pk_bf16_f32 v67, v72, v73
	flat_store_dwordx4 v[80:81], v[64:67] offset:256 sc1
	v_pk_mul_f32 v[30:31], v[30:31], s[48:49] op_sel_hi:[1,0]
	v_pk_mul_f32 v[28:29], v[28:29], s[48:49] op_sel_hi:[1,0]
	v_add_u32_e32 v64, 0x80, v128
	v_ashrrev_i32_e32 v65, 31, v64
	v_lshlrev_b64 v[64:65], 12, v[64:65]
	v_lshl_add_u64 v[64:65], s[10:11], 0, v[64:65]
	v_lshl_add_u64 v[64:65], v[64:65], 0, s[56:57]
	v_lshl_add_u64 v[64:65], v[64:65], 0, v[130:131]
	v_pk_mul_f32 v[66:67], v[58:59], s[48:49] op_sel_hi:[1,0]
	v_pk_mul_f32 v[58:59], v[56:57], s[48:49] op_sel_hi:[1,0]
	v_cvt_pk_bf16_f32 v56, v60, v61
	v_cvt_pk_bf16_f32 v57, v62, v63
	v_pk_mul_f32 v[20:21], v[20:21], s[48:49] op_sel_hi:[1,0]
	v_cvt_pk_bf16_f32 v58, v58, v59
	v_cvt_pk_bf16_f32 v59, v66, v67
	flat_store_dwordx4 v[64:65], v[56:59] sc1
	v_pk_mul_f32 v[22:23], v[22:23], s[48:49] op_sel_hi:[1,0]
	v_pk_mul_f32 v[14:15], v[14:15], s[48:49] op_sel_hi:[1,0]
	v_pk_mul_f32 v[56:57], v[50:51], s[48:49] op_sel_hi:[1,0]
	v_pk_mul_f32 v[50:51], v[48:49], s[48:49] op_sel_hi:[1,0]
	v_cvt_pk_bf16_f32 v48, v52, v53
	v_cvt_pk_bf16_f32 v49, v54, v55
	v_pk_mul_f32 v[12:13], v[12:13], s[48:49] op_sel_hi:[1,0]
	v_cvt_pk_bf16_f32 v50, v50, v51
	v_cvt_pk_bf16_f32 v51, v56, v57
	flat_store_dwordx4 v[64:65], v[48:51] offset:256 sc1
	v_pk_mul_f32 v[6:7], v[6:7], s[48:49] op_sel_hi:[1,0]
	v_pk_mul_f32 v[4:5], v[4:5], s[48:49] op_sel_hi:[1,0]
	v_add_u32_e32 v48, 0x90, v128
	v_ashrrev_i32_e32 v49, 31, v48
	v_lshlrev_b64 v[48:49], 12, v[48:49]
	v_lshl_add_u64 v[48:49], s[10:11], 0, v[48:49]
	v_lshl_add_u64 v[48:49], v[48:49], 0, s[56:57]
	v_lshl_add_u64 v[48:49], v[48:49], 0, v[130:131]
	v_pk_mul_f32 v[50:51], v[42:43], s[48:49] op_sel_hi:[1,0]
	v_pk_mul_f32 v[42:43], v[40:41], s[48:49] op_sel_hi:[1,0]
	v_cvt_pk_bf16_f32 v40, v44, v45
	v_cvt_pk_bf16_f32 v41, v46, v47
	v_pk_mul_f32 v[2:3], v[2:3], s[48:49] op_sel_hi:[1,0]
	v_cvt_pk_bf16_f32 v42, v42, v43
	v_cvt_pk_bf16_f32 v43, v50, v51
	flat_store_dwordx4 v[48:49], v[40:43] sc1
	v_pk_mul_f32 v[0:1], v[0:1], s[48:49] op_sel_hi:[1,0]
	s_nop 0
	v_pk_mul_f32 v[40:41], v[34:35], s[48:49] op_sel_hi:[1,0]
	v_pk_mul_f32 v[34:35], v[32:33], s[48:49] op_sel_hi:[1,0]
	v_cvt_pk_bf16_f32 v32, v36, v37
	v_cvt_pk_bf16_f32 v33, v38, v39
	s_nop 0
	v_cvt_pk_bf16_f32 v34, v34, v35
	v_cvt_pk_bf16_f32 v35, v40, v41
	flat_store_dwordx4 v[48:49], v[32:35] offset:256 sc1
	s_nop 1
	v_add_u32_e32 v32, 0xa0, v128
	v_ashrrev_i32_e32 v33, 31, v32
	v_lshlrev_b64 v[32:33], 12, v[32:33]
	v_lshl_add_u64 v[32:33], s[10:11], 0, v[32:33]
	v_lshl_add_u64 v[32:33], v[32:33], 0, s[56:57]
	v_lshl_add_u64 v[32:33], v[32:33], 0, v[130:131]
	v_pk_mul_f32 v[34:35], v[26:27], s[48:49] op_sel_hi:[1,0]
	v_pk_mul_f32 v[26:27], v[24:25], s[48:49] op_sel_hi:[1,0]
	v_cvt_pk_bf16_f32 v24, v28, v29
	v_cvt_pk_bf16_f32 v25, v30, v31
	s_nop 0
	v_cvt_pk_bf16_f32 v26, v26, v27
	v_cvt_pk_bf16_f32 v27, v34, v35
	flat_store_dwordx4 v[32:33], v[24:27] sc1
	s_nop 1
	v_pk_mul_f32 v[24:25], v[18:19], s[48:49] op_sel_hi:[1,0]
	v_pk_mul_f32 v[18:19], v[16:17], s[48:49] op_sel_hi:[1,0]
	v_cvt_pk_bf16_f32 v16, v20, v21
	v_cvt_pk_bf16_f32 v17, v22, v23
	s_nop 0
	v_cvt_pk_bf16_f32 v18, v18, v19
	v_cvt_pk_bf16_f32 v19, v24, v25
	flat_store_dwordx4 v[32:33], v[16:19] offset:256 sc1
	s_nop 1
	v_add_u32_e32 v16, 0xb0, v128
	v_ashrrev_i32_e32 v17, 31, v16
	v_lshlrev_b64 v[16:17], 12, v[16:17]
	v_lshl_add_u64 v[16:17], s[10:11], 0, v[16:17]
	v_lshl_add_u64 v[16:17], v[16:17], 0, s[56:57]
	v_lshl_add_u64 v[144:145], v[16:17], 0, v[130:131]
	v_pk_mul_f32 v[16:17], v[10:11], s[48:49] op_sel_hi:[1,0]
	v_pk_mul_f32 v[10:11], v[8:9], s[48:49] op_sel_hi:[1,0]
	v_cvt_pk_bf16_f32 v8, v12, v13
	v_cvt_pk_bf16_f32 v9, v14, v15
	s_nop 0
	v_cvt_pk_bf16_f32 v10, v10, v11
	v_cvt_pk_bf16_f32 v11, v16, v17
	flat_store_dwordx4 v[144:145], v[8:11] sc1
	v_cvt_pk_bf16_f32 v128, v4, v5
	v_cvt_pk_bf16_f32 v129, v6, v7
	v_cvt_pk_bf16_f32 v130, v0, v1
	v_cvt_pk_bf16_f32 v131, v2, v3
.LBB0_736:
	s_andn2_b64 vcc, exec, s[50:51]
	s_mov_b64 s[50:51], -1
	flat_store_dwordx4 v[144:145], v[128:131] offset:256 sc1
	s_cbranch_vccnz .LBB0_721
	s_andn2_b64 vcc, exec, s[8:9]
	s_cbranch_vccnz .LBB0_720
	s_barrier
	s_branch .LBB0_720

.LBB0_960:
	v_mov_b32_e32 v140, v158
	v_mov_b32_e32 v165, v159
	s_ashr_i32 s47, s46, 31
	v_add_u32_e32 v156, s79, v140
	s_cmp_lg_u32 s6, 0
	v_ashrrev_i32_e32 v157, 31, v156
	v_add_u32_e32 v154, 16, v156
	v_add_u32_e32 v152, 32, v156
	v_add_u32_e32 v150, 48, v156
	v_add_u32_e32 v148, 0x80, v156
	v_add_u32_e32 v144, 0x90, v156
	v_add_u32_e32 v142, 0xa0, v156
	v_add_u32_e32 v140, 0xb0, v156
	s_cbranch_scc0 .LBB0_967
	s_add_i32 s6, s6, -1
	s_lshl_b64 s[40:41], s[6:7], 22
	s_add_u32 s6, s75, s40
	s_addc_u32 s56, s76, s41
	s_ashr_i32 s55, s54, 31
	s_lshl_b64 s[40:41], s[54:55], 12
	s_add_u32 s6, s6, s40
	s_addc_u32 s55, s56, s41
	s_lshl_b64 s[40:41], s[46:47], 1
	s_add_u32 s6, s6, s40
	s_addc_u32 s41, s55, s41
	s_add_u32 s40, s6, s89
	v_lshlrev_b32_e32 v146, 3, v165
	s_addc_u32 s41, s41, 0
	v_ashrrev_i32_e32 v147, 31, v146
	v_lshl_add_u64 v[146:147], v[146:147], 1, s[40:41]
	v_lshlrev_b64 v[166:167], 12, v[156:157]
	v_lshl_add_u64 v[170:171], v[146:147], 0, v[166:167]
	v_cvt_pk_bf16_f32 v166, v124, v125
	v_cvt_pk_bf16_f32 v167, v126, v127
	v_cvt_pk_bf16_f32 v168, v120, v121
	v_cvt_pk_bf16_f32 v169, v122, v123
	flat_store_dwordx4 v[170:171], v[166:169] sc1
	v_ashrrev_i32_e32 v155, 31, v154
	v_ashrrev_i32_e32 v153, 31, v152
	v_cvt_pk_bf16_f32 v166, v116, v117
	v_cvt_pk_bf16_f32 v167, v118, v119
	v_cvt_pk_bf16_f32 v168, v112, v113
	v_cvt_pk_bf16_f32 v169, v114, v115
	flat_store_dwordx4 v[170:171], v[166:169] offset:256 sc1
	v_ashrrev_i32_e32 v151, 31, v150
	v_ashrrev_i32_e32 v149, 31, v148
	v_lshlrev_b64 v[166:167], 12, v[154:155]
	v_lshl_add_u64 v[170:171], v[146:147], 0, v[166:167]
	v_cvt_pk_bf16_f32 v166, v108, v109
	v_cvt_pk_bf16_f32 v167, v110, v111
	v_cvt_pk_bf16_f32 v168, v104, v105
	v_cvt_pk_bf16_f32 v169, v106, v107
	flat_store_dwordx4 v[170:171], v[166:169] sc1
	v_ashrrev_i32_e32 v145, 31, v144
	v_ashrrev_i32_e32 v143, 31, v142
	v_cvt_pk_bf16_f32 v166, v100, v101
	v_cvt_pk_bf16_f32 v167, v102, v103
	v_cvt_pk_bf16_f32 v168, v96, v97
	v_cvt_pk_bf16_f32 v169, v98, v99
	flat_store_dwordx4 v[170:171], v[166:169] offset:256 sc1
	v_ashrrev_i32_e32 v141, 31, v140
	s_nop 0
	v_lshlrev_b64 v[166:167], 12, v[152:153]
	v_lshl_add_u64 v[170:171], v[146:147], 0, v[166:167]
	v_cvt_pk_bf16_f32 v166, v92, v93
	v_cvt_pk_bf16_f32 v167, v94, v95
	v_cvt_pk_bf16_f32 v168, v88, v89
	v_cvt_pk_bf16_f32 v169, v90, v91
	flat_store_dwordx4 v[170:171], v[166:169] sc1
	s_nop 1
	v_cvt_pk_bf16_f32 v166, v84, v85
	v_cvt_pk_bf16_f32 v167, v86, v87
	v_cvt_pk_bf16_f32 v168, v80, v81
	v_cvt_pk_bf16_f32 v169, v82, v83
	flat_store_dwordx4 v[170:171], v[166:169] offset:256 sc1
	s_nop 1
	v_lshlrev_b64 v[166:167], 12, v[150:151]
	v_lshl_add_u64 v[170:171], v[146:147], 0, v[166:167]
	v_cvt_pk_bf16_f32 v166, v76, v77
	v_cvt_pk_bf16_f32 v167, v78, v79
	v_cvt_pk_bf16_f32 v168, v72, v73
	v_cvt_pk_bf16_f32 v169, v74, v75
	flat_store_dwordx4 v[170:171], v[166:169] sc1
	s_nop 1
	v_cvt_pk_bf16_f32 v166, v68, v69
	v_cvt_pk_bf16_f32 v167, v70, v71
	v_cvt_pk_bf16_f32 v168, v64, v65
	v_cvt_pk_bf16_f32 v169, v66, v67
	flat_store_dwordx4 v[170:171], v[166:169] offset:256 sc1
	s_nop 1
	v_lshlrev_b64 v[166:167], 12, v[148:149]
	v_lshl_add_u64 v[170:171], v[146:147], 0, v[166:167]
	v_cvt_pk_bf16_f32 v166, v60, v61
	v_cvt_pk_bf16_f32 v167, v62, v63
	v_cvt_pk_bf16_f32 v168, v56, v57
	v_cvt_pk_bf16_f32 v169, v58, v59
	flat_store_dwordx4 v[170:171], v[166:169] sc1
	s_nop 1
	v_cvt_pk_bf16_f32 v166, v52, v53
	v_cvt_pk_bf16_f32 v167, v54, v55
	v_cvt_pk_bf16_f32 v168, v48, v49
	v_cvt_pk_bf16_f32 v169, v50, v51
	flat_store_dwordx4 v[170:171], v[166:169] offset:256 sc1
	s_nop 1
	v_lshlrev_b64 v[166:167], 12, v[144:145]
	v_lshl_add_u64 v[170:171], v[146:147], 0, v[166:167]
	v_cvt_pk_bf16_f32 v166, v44, v45
	v_cvt_pk_bf16_f32 v167, v46, v47
	v_cvt_pk_bf16_f32 v168, v40, v41
	v_cvt_pk_bf16_f32 v169, v42, v43
	flat_store_dwordx4 v[170:171], v[166:169] sc1
	s_nop 1
	v_cvt_pk_bf16_f32 v166, v36, v37
	v_cvt_pk_bf16_f32 v167, v38, v39
	v_cvt_pk_bf16_f32 v168, v32, v33
	v_cvt_pk_bf16_f32 v169, v34, v35
	flat_store_dwordx4 v[170:171], v[166:169] offset:256 sc1
	s_nop 1
	v_lshlrev_b64 v[166:167], 12, v[142:143]
	v_lshl_add_u64 v[170:171], v[146:147], 0, v[166:167]
	v_cvt_pk_bf16_f32 v166, v28, v29
	v_cvt_pk_bf16_f32 v167, v30, v31
	v_cvt_pk_bf16_f32 v168, v24, v25
	v_cvt_pk_bf16_f32 v169, v26, v27
	flat_store_dwordx4 v[170:171], v[166:169] sc1
	s_nop 1
	v_cvt_pk_bf16_f32 v166, v20, v21
	v_cvt_pk_bf16_f32 v167, v22, v23
	v_cvt_pk_bf16_f32 v168, v16, v17
	v_cvt_pk_bf16_f32 v169, v18, v19
	flat_store_dwordx4 v[170:171], v[166:169] offset:256 sc1
	s_nop 1
	v_lshlrev_b64 v[166:167], 12, v[140:141]
	v_lshl_add_u64 v[146:147], v[146:147], 0, v[166:167]
	v_cvt_pk_bf16_f32 v166, v12, v13
	v_cvt_pk_bf16_f32 v167, v14, v15
	v_cvt_pk_bf16_f32 v168, v8, v9
	v_cvt_pk_bf16_f32 v169, v10, v11
	flat_store_dwordx4 v[146:147], v[166:169] sc1
	s_nop 1
	v_cvt_pk_bf16_f32 v166, v4, v5
	v_cvt_pk_bf16_f32 v167, v6, v7
	v_cvt_pk_bf16_f32 v168, v0, v1
	v_cvt_pk_bf16_f32 v169, v2, v3
	flat_store_dwordx4 v[146:147], v[166:169] offset:256 sc1
	s_cbranch_execnz .LBB0_963
.LBB0_962:
	v_lshl_add_u32 v146, v165, 3, s81
	v_ashrrev_i32_e32 v147, 31, v146
	v_lshlrev_b64 v[156:157], 11, v[156:157]
	s_ashr_i32 s55, s54, 31
	v_lshl_add_u64 v[156:157], v[156:157], 0, v[146:147]
	s_lshl_b64 s[56:57], s[54:55], 12
	v_lshl_add_u64 v[156:157], v[156:157], 0, s[46:47]
	s_add_u32 s54, s71, s56
	s_addc_u32 s55, s72, s57
	v_lshlrev_b64 v[156:157], 1, v[156:157]
	v_lshl_add_u64 v[170:171], s[54:55], 0, v[156:157]
	flat_load_dwordx4 v[166:169], v[170:171]
	v_ashrrev_i32_e32 v155, 31, v154
	s_add_u32 s56, s73, s56
	v_lshlrev_b64 v[154:155], 11, v[154:155]
	s_addc_u32 s57, s74, s57
	v_lshl_add_u64 v[154:155], v[154:155], 0, v[146:147]
	v_lshl_add_u64 v[156:157], s[56:57], 0, v[156:157]
	v_lshl_add_u64 v[154:155], v[154:155], 0, s[46:47]
	v_lshlrev_b64 v[154:155], 1, v[154:155]
	v_ashrrev_i32_e32 v153, 31, v152
	v_ashrrev_i32_e32 v151, 31, v150
	v_ashrrev_i32_e32 v149, 31, v148
	v_ashrrev_i32_e32 v145, 31, v144
	v_ashrrev_i32_e32 v143, 31, v142
	v_ashrrev_i32_e32 v141, 31, v140
	s_waitcnt vmcnt(0) lgkmcnt(0)
	v_lshlrev_b32_e32 v172, 16, v166
	v_and_b32_e32 v173, 0xffff0000, v166
	v_lshlrev_b32_e32 v166, 16, v167
	v_and_b32_e32 v167, 0xffff0000, v167
	v_lshlrev_b32_e32 v174, 16, v168
	v_and_b32_e32 v175, 0xffff0000, v168
	v_lshlrev_b32_e32 v168, 16, v169
	v_and_b32_e32 v169, 0xffff0000, v169
	v_pk_add_f32 v[126:127], v[126:127], v[166:167]
	v_pk_add_f32 v[124:125], v[124:125], v[172:173]
	v_pk_add_f32 v[166:167], v[122:123], v[168:169]
	v_pk_add_f32 v[122:123], v[120:121], v[174:175]
	v_cvt_pk_bf16_f32 v120, v124, v125
	v_cvt_pk_bf16_f32 v121, v126, v127
	s_nop 0
	v_cvt_pk_bf16_f32 v122, v122, v123
	v_cvt_pk_bf16_f32 v123, v166, v167
	flat_load_dwordx4 v[124:127], v[170:171] offset:256
	v_lshl_add_u64 v[166:167], s[54:55], 0, v[154:155]
	flat_store_dwordx4 v[156:157], v[120:123] sc1
	s_waitcnt vmcnt(0) lgkmcnt(0)
	s_nop 0
	v_lshlrev_b32_e32 v120, 16, v124
	v_and_b32_e32 v121, 0xffff0000, v124
	v_lshlrev_b32_e32 v122, 16, v125
	v_and_b32_e32 v123, 0xffff0000, v125
	v_lshlrev_b32_e32 v124, 16, v126
	v_and_b32_e32 v125, 0xffff0000, v126
	v_lshlrev_b32_e32 v126, 16, v127
	v_and_b32_e32 v127, 0xffff0000, v127
	v_pk_add_f32 v[116:117], v[116:117], v[120:121]
	v_pk_add_f32 v[120:121], v[114:115], v[126:127]
	v_pk_add_f32 v[114:115], v[112:113], v[124:125]
	v_pk_add_f32 v[118:119], v[118:119], v[122:123]
	v_cvt_pk_bf16_f32 v112, v116, v117
	s_nop 0
	v_cvt_pk_bf16_f32 v113, v118, v119
	v_cvt_pk_bf16_f32 v114, v114, v115
	v_cvt_pk_bf16_f32 v115, v120, v121
	flat_store_dwordx4 v[156:157], v[112:115] offset:256 sc1
	flat_load_dwordx4 v[112:115], v[166:167]
	s_waitcnt vmcnt(0) lgkmcnt(0)
	v_lshlrev_b32_e32 v116, 16, v112
	v_and_b32_e32 v117, 0xffff0000, v112
	v_lshlrev_b32_e32 v112, 16, v113
	v_and_b32_e32 v113, 0xffff0000, v113
	v_lshlrev_b32_e32 v118, 16, v114
	v_and_b32_e32 v119, 0xffff0000, v114
	v_lshlrev_b32_e32 v114, 16, v115
	v_and_b32_e32 v115, 0xffff0000, v115
	v_pk_add_f32 v[110:111], v[110:111], v[112:113]
	v_pk_add_f32 v[108:109], v[108:109], v[116:117]
	v_pk_add_f32 v[112:113], v[106:107], v[114:115]
	v_pk_add_f32 v[106:107], v[104:105], v[118:119]
	v_cvt_pk_bf16_f32 v104, v108, v109
	v_cvt_pk_bf16_f32 v105, v110, v111
	v_lshl_add_u64 v[116:117], s[56:57], 0, v[154:155]
	v_cvt_pk_bf16_f32 v106, v106, v107
	v_cvt_pk_bf16_f32 v107, v112, v113
	flat_load_dwordx4 v[108:111], v[166:167] offset:256
	v_lshlrev_b64 v[112:113], 11, v[152:153]
	v_lshl_add_u64 v[112:113], v[112:113], 0, v[146:147]
	v_lshl_add_u64 v[112:113], v[112:113], 0, s[46:47]
	flat_store_dwordx4 v[116:117], v[104:107] sc1
	v_lshlrev_b64 v[112:113], 1, v[112:113]
	v_lshl_add_u64 v[114:115], s[54:55], 0, v[112:113]
	s_waitcnt vmcnt(0) lgkmcnt(0)
	v_lshlrev_b32_e32 v104, 16, v108
	v_and_b32_e32 v105, 0xffff0000, v108
	v_lshlrev_b32_e32 v106, 16, v109
	v_and_b32_e32 v107, 0xffff0000, v109
	v_lshlrev_b32_e32 v108, 16, v110
	v_and_b32_e32 v109, 0xffff0000, v110
	v_lshlrev_b32_e32 v110, 16, v111
	v_and_b32_e32 v111, 0xffff0000, v111
	v_pk_add_f32 v[100:101], v[100:101], v[104:105]
	v_pk_add_f32 v[104:105], v[98:99], v[110:111]
	v_pk_add_f32 v[98:99], v[96:97], v[108:109]
	v_pk_add_f32 v[102:103], v[102:103], v[106:107]
	v_cvt_pk_bf16_f32 v96, v100, v101
	s_nop 0
	v_cvt_pk_bf16_f32 v97, v102, v103
	v_cvt_pk_bf16_f32 v98, v98, v99
	v_cvt_pk_bf16_f32 v99, v104, v105
	flat_store_dwordx4 v[116:117], v[96:99] offset:256 sc1
	flat_load_dwordx4 v[96:99], v[114:115]
	s_waitcnt vmcnt(0) lgkmcnt(0)
	v_lshlrev_b32_e32 v100, 16, v96
	v_and_b32_e32 v101, 0xffff0000, v96
	v_lshlrev_b32_e32 v96, 16, v97
	v_and_b32_e32 v97, 0xffff0000, v97
	v_lshlrev_b32_e32 v102, 16, v98
	v_and_b32_e32 v103, 0xffff0000, v98
	v_lshlrev_b32_e32 v98, 16, v99
	v_and_b32_e32 v99, 0xffff0000, v99
	v_pk_add_f32 v[94:95], v[94:95], v[96:97]
	v_pk_add_f32 v[92:93], v[92:93], v[100:101]
	v_pk_add_f32 v[96:97], v[90:91], v[98:99]
	v_pk_add_f32 v[90:91], v[88:89], v[102:103]
	v_cvt_pk_bf16_f32 v88, v92, v93
	v_cvt_pk_bf16_f32 v89, v94, v95
	v_lshl_add_u64 v[100:101], s[56:57], 0, v[112:113]
	v_cvt_pk_bf16_f32 v90, v90, v91
	v_cvt_pk_bf16_f32 v91, v96, v97
	flat_load_dwordx4 v[92:95], v[114:115] offset:256
	v_lshlrev_b64 v[96:97], 11, v[150:151]
	v_lshl_add_u64 v[96:97], v[96:97], 0, v[146:147]
	v_lshl_add_u64 v[96:97], v[96:97], 0, s[46:47]
	flat_store_dwordx4 v[100:101], v[88:91] sc1
	v_lshlrev_b64 v[96:97], 1, v[96:97]
	v_lshl_add_u64 v[98:99], s[54:55], 0, v[96:97]
	s_waitcnt vmcnt(0) lgkmcnt(0)
	v_lshlrev_b32_e32 v88, 16, v92
	v_and_b32_e32 v89, 0xffff0000, v92
	v_lshlrev_b32_e32 v90, 16, v93
	v_and_b32_e32 v91, 0xffff0000, v93
	v_lshlrev_b32_e32 v92, 16, v94
	v_and_b32_e32 v93, 0xffff0000, v94
	v_lshlrev_b32_e32 v94, 16, v95
	v_and_b32_e32 v95, 0xffff0000, v95
	v_pk_add_f32 v[84:85], v[84:85], v[88:89]
	v_pk_add_f32 v[88:89], v[82:83], v[94:95]
	v_pk_add_f32 v[82:83], v[80:81], v[92:93]
	v_pk_add_f32 v[86:87], v[86:87], v[90:91]
	v_cvt_pk_bf16_f32 v80, v84, v85
	s_nop 0
	v_cvt_pk_bf16_f32 v81, v86, v87
	v_cvt_pk_bf16_f32 v82, v82, v83
	v_cvt_pk_bf16_f32 v83, v88, v89
	flat_store_dwordx4 v[100:101], v[80:83] offset:256 sc1
	flat_load_dwordx4 v[80:83], v[98:99]
	s_waitcnt vmcnt(0) lgkmcnt(0)
	v_lshlrev_b32_e32 v84, 16, v80
	v_and_b32_e32 v85, 0xffff0000, v80
	v_lshlrev_b32_e32 v80, 16, v81
	v_and_b32_e32 v81, 0xffff0000, v81
	v_lshlrev_b32_e32 v86, 16, v82
	v_and_b32_e32 v87, 0xffff0000, v82
	v_lshlrev_b32_e32 v82, 16, v83
	v_and_b32_e32 v83, 0xffff0000, v83
	v_pk_add_f32 v[78:79], v[78:79], v[80:81]
	v_pk_add_f32 v[76:77], v[76:77], v[84:85]
	v_pk_add_f32 v[80:81], v[74:75], v[82:83]
	v_pk_add_f32 v[74:75], v[72:73], v[86:87]
	v_cvt_pk_bf16_f32 v72, v76, v77
	v_cvt_pk_bf16_f32 v73, v78, v79
	v_lshl_add_u64 v[84:85], s[56:57], 0, v[96:97]
	v_cvt_pk_bf16_f32 v74, v74, v75
	v_cvt_pk_bf16_f32 v75, v80, v81
	flat_load_dwordx4 v[76:79], v[98:99] offset:256
	v_lshlrev_b64 v[80:81], 11, v[148:149]
	v_lshl_add_u64 v[80:81], v[80:81], 0, v[146:147]
	v_lshl_add_u64 v[80:81], v[80:81], 0, s[46:47]
	flat_store_dwordx4 v[84:85], v[72:75] sc1
	v_lshlrev_b64 v[80:81], 1, v[80:81]
	v_lshl_add_u64 v[82:83], s[54:55], 0, v[80:81]
	s_waitcnt vmcnt(0) lgkmcnt(0)
	v_lshlrev_b32_e32 v72, 16, v76
	v_and_b32_e32 v73, 0xffff0000, v76
	v_lshlrev_b32_e32 v74, 16, v77
	v_and_b32_e32 v75, 0xffff0000, v77
	v_lshlrev_b32_e32 v76, 16, v78
	v_and_b32_e32 v77, 0xffff0000, v78
	v_lshlrev_b32_e32 v78, 16, v79
	v_and_b32_e32 v79, 0xffff0000, v79
	v_pk_add_f32 v[68:69], v[68:69], v[72:73]
	v_pk_add_f32 v[72:73], v[66:67], v[78:79]
	v_pk_add_f32 v[66:67], v[64:65], v[76:77]
	v_pk_add_f32 v[70:71], v[70:71], v[74:75]
	v_cvt_pk_bf16_f32 v64, v68, v69
	s_nop 0
	v_cvt_pk_bf16_f32 v65, v70, v71
	v_cvt_pk_bf16_f32 v66, v66, v67
	v_cvt_pk_bf16_f32 v67, v72, v73
	flat_store_dwordx4 v[84:85], v[64:67] offset:256 sc1
	flat_load_dwordx4 v[64:67], v[82:83]
	s_waitcnt vmcnt(0) lgkmcnt(0)
	v_lshlrev_b32_e32 v68, 16, v64
	v_and_b32_e32 v69, 0xffff0000, v64
	v_lshlrev_b32_e32 v64, 16, v65
	v_and_b32_e32 v65, 0xffff0000, v65
	v_lshlrev_b32_e32 v70, 16, v66
	v_and_b32_e32 v71, 0xffff0000, v66
	v_lshlrev_b32_e32 v66, 16, v67
	v_and_b32_e32 v67, 0xffff0000, v67
	v_pk_add_f32 v[62:63], v[62:63], v[64:65]
	v_pk_add_f32 v[60:61], v[60:61], v[68:69]
	v_pk_add_f32 v[64:65], v[58:59], v[66:67]
	v_pk_add_f32 v[58:59], v[56:57], v[70:71]
	v_cvt_pk_bf16_f32 v56, v60, v61
	v_cvt_pk_bf16_f32 v57, v62, v63
	v_lshl_add_u64 v[68:69], s[56:57], 0, v[80:81]
	v_cvt_pk_bf16_f32 v58, v58, v59
	v_cvt_pk_bf16_f32 v59, v64, v65
	flat_load_dwordx4 v[60:63], v[82:83] offset:256
	v_lshlrev_b64 v[64:65], 11, v[144:145]
	v_lshl_add_u64 v[64:65], v[64:65], 0, v[146:147]
	v_lshl_add_u64 v[64:65], v[64:65], 0, s[46:47]
	flat_store_dwordx4 v[68:69], v[56:59] sc1
	v_lshlrev_b64 v[64:65], 1, v[64:65]
	v_lshl_add_u64 v[66:67], s[54:55], 0, v[64:65]
	s_waitcnt vmcnt(0) lgkmcnt(0)
	v_lshlrev_b32_e32 v56, 16, v60
	v_and_b32_e32 v57, 0xffff0000, v60
	v_lshlrev_b32_e32 v58, 16, v61
	v_and_b32_e32 v59, 0xffff0000, v61
	v_lshlrev_b32_e32 v60, 16, v62
	v_and_b32_e32 v61, 0xffff0000, v62
	v_lshlrev_b32_e32 v62, 16, v63
	v_and_b32_e32 v63, 0xffff0000, v63
	v_pk_add_f32 v[52:53], v[52:53], v[56:57]
	v_pk_add_f32 v[56:57], v[50:51], v[62:63]
	v_pk_add_f32 v[50:51], v[48:49], v[60:61]
	v_pk_add_f32 v[54:55], v[54:55], v[58:59]
	v_cvt_pk_bf16_f32 v48, v52, v53
	s_nop 0
	v_cvt_pk_bf16_f32 v49, v54, v55
	v_cvt_pk_bf16_f32 v50, v50, v51
	v_cvt_pk_bf16_f32 v51, v56, v57
	flat_store_dwordx4 v[68:69], v[48:51] offset:256 sc1
	flat_load_dwordx4 v[48:51], v[66:67]
	s_waitcnt vmcnt(0) lgkmcnt(0)
	v_lshlrev_b32_e32 v52, 16, v48
	v_and_b32_e32 v53, 0xffff0000, v48
	v_lshlrev_b32_e32 v48, 16, v49
	v_and_b32_e32 v49, 0xffff0000, v49
	v_lshlrev_b32_e32 v54, 16, v50
	v_and_b32_e32 v55, 0xffff0000, v50
	v_lshlrev_b32_e32 v50, 16, v51
	v_and_b32_e32 v51, 0xffff0000, v51
	v_pk_add_f32 v[46:47], v[46:47], v[48:49]
	v_pk_add_f32 v[44:45], v[44:45], v[52:53]
	v_pk_add_f32 v[48:49], v[42:43], v[50:51]
	v_pk_add_f32 v[42:43], v[40:41], v[54:55]
	v_cvt_pk_bf16_f32 v40, v44, v45
	v_cvt_pk_bf16_f32 v41, v46, v47
	v_lshl_add_u64 v[52:53], s[56:57], 0, v[64:65]
	v_cvt_pk_bf16_f32 v42, v42, v43
	v_cvt_pk_bf16_f32 v43, v48, v49
	flat_load_dwordx4 v[44:47], v[66:67] offset:256
	v_lshlrev_b64 v[48:49], 11, v[142:143]
	v_lshl_add_u64 v[48:49], v[48:49], 0, v[146:147]
	v_lshl_add_u64 v[48:49], v[48:49], 0, s[46:47]
	flat_store_dwordx4 v[52:53], v[40:43] sc1
	v_lshlrev_b64 v[48:49], 1, v[48:49]
	v_lshl_add_u64 v[50:51], s[54:55], 0, v[48:49]
	s_waitcnt vmcnt(0) lgkmcnt(0)
	v_lshlrev_b32_e32 v40, 16, v44
	v_and_b32_e32 v41, 0xffff0000, v44
	v_lshlrev_b32_e32 v42, 16, v45
	v_and_b32_e32 v43, 0xffff0000, v45
	v_lshlrev_b32_e32 v44, 16, v46
	v_and_b32_e32 v45, 0xffff0000, v46
	v_lshlrev_b32_e32 v46, 16, v47
	v_and_b32_e32 v47, 0xffff0000, v47
	v_pk_add_f32 v[36:37], v[36:37], v[40:41]
	v_pk_add_f32 v[40:41], v[34:35], v[46:47]
	v_pk_add_f32 v[34:35], v[32:33], v[44:45]
	v_pk_add_f32 v[38:39], v[38:39], v[42:43]
	v_cvt_pk_bf16_f32 v32, v36, v37
	s_nop 0
	v_cvt_pk_bf16_f32 v33, v38, v39
	v_cvt_pk_bf16_f32 v34, v34, v35
	v_cvt_pk_bf16_f32 v35, v40, v41
	flat_store_dwordx4 v[52:53], v[32:35] offset:256 sc1
	flat_load_dwordx4 v[32:35], v[50:51]
	s_waitcnt vmcnt(0) lgkmcnt(0)
	v_lshlrev_b32_e32 v36, 16, v32
	v_and_b32_e32 v37, 0xffff0000, v32
	v_lshlrev_b32_e32 v32, 16, v33
	v_and_b32_e32 v33, 0xffff0000, v33
	v_lshlrev_b32_e32 v38, 16, v34
	v_and_b32_e32 v39, 0xffff0000, v34
	v_lshlrev_b32_e32 v34, 16, v35
	v_and_b32_e32 v35, 0xffff0000, v35
	v_pk_add_f32 v[30:31], v[30:31], v[32:33]
	v_pk_add_f32 v[28:29], v[28:29], v[36:37]
	v_pk_add_f32 v[32:33], v[26:27], v[34:35]
	v_pk_add_f32 v[26:27], v[24:25], v[38:39]
	v_cvt_pk_bf16_f32 v24, v28, v29
	v_cvt_pk_bf16_f32 v25, v30, v31
	v_lshl_add_u64 v[36:37], s[56:57], 0, v[48:49]
	v_cvt_pk_bf16_f32 v26, v26, v27
	v_cvt_pk_bf16_f32 v27, v32, v33
	flat_load_dwordx4 v[28:31], v[50:51] offset:256
	v_lshlrev_b64 v[32:33], 11, v[140:141]
	v_lshl_add_u64 v[32:33], v[32:33], 0, v[146:147]
	v_lshl_add_u64 v[32:33], v[32:33], 0, s[46:47]
	flat_store_dwordx4 v[36:37], v[24:27] sc1
	v_lshlrev_b64 v[32:33], 1, v[32:33]
	v_lshl_add_u64 v[34:35], s[54:55], 0, v[32:33]
	s_waitcnt vmcnt(0) lgkmcnt(0)
	v_lshlrev_b32_e32 v24, 16, v28
	v_and_b32_e32 v25, 0xffff0000, v28
	v_lshlrev_b32_e32 v26, 16, v29
	v_and_b32_e32 v27, 0xffff0000, v29
	v_lshlrev_b32_e32 v28, 16, v30
	v_and_b32_e32 v29, 0xffff0000, v30
	v_lshlrev_b32_e32 v30, 16, v31
	v_and_b32_e32 v31, 0xffff0000, v31
	v_pk_add_f32 v[20:21], v[20:21], v[24:25]
	v_pk_add_f32 v[24:25], v[18:19], v[30:31]
	v_pk_add_f32 v[18:19], v[16:17], v[28:29]
	v_pk_add_f32 v[22:23], v[22:23], v[26:27]
	v_cvt_pk_bf16_f32 v16, v20, v21
	s_nop 0
	v_cvt_pk_bf16_f32 v17, v22, v23
	v_cvt_pk_bf16_f32 v18, v18, v19
	v_cvt_pk_bf16_f32 v19, v24, v25
	flat_store_dwordx4 v[36:37], v[16:19] offset:256 sc1
	flat_load_dwordx4 v[16:19], v[34:35]
	s_waitcnt vmcnt(0) lgkmcnt(0)
	v_lshlrev_b32_e32 v20, 16, v16
	v_and_b32_e32 v21, 0xffff0000, v16
	v_lshlrev_b32_e32 v16, 16, v17
	v_and_b32_e32 v17, 0xffff0000, v17
	v_lshlrev_b32_e32 v22, 16, v18
	v_and_b32_e32 v23, 0xffff0000, v18
	v_lshlrev_b32_e32 v18, 16, v19
	v_and_b32_e32 v19, 0xffff0000, v19
	v_pk_add_f32 v[14:15], v[14:15], v[16:17]
	v_pk_add_f32 v[12:13], v[12:13], v[20:21]
	v_pk_add_f32 v[16:17], v[10:11], v[18:19]
	v_pk_add_f32 v[10:11], v[8:9], v[22:23]
	v_cvt_pk_bf16_f32 v8, v12, v13
	v_cvt_pk_bf16_f32 v9, v14, v15
	s_nop 0
	v_cvt_pk_bf16_f32 v10, v10, v11
	v_cvt_pk_bf16_f32 v11, v16, v17
	flat_load_dwordx4 v[12:15], v[34:35] offset:256
	v_lshl_add_u64 v[16:17], s[56:57], 0, v[32:33]
	flat_store_dwordx4 v[16:17], v[8:11] sc1
	s_waitcnt vmcnt(0) lgkmcnt(0)
	s_nop 0
	v_lshlrev_b32_e32 v8, 16, v12
	v_and_b32_e32 v9, 0xffff0000, v12
	v_lshlrev_b32_e32 v10, 16, v13
	v_and_b32_e32 v11, 0xffff0000, v13
	v_lshlrev_b32_e32 v12, 16, v14
	v_and_b32_e32 v13, 0xffff0000, v14
	v_lshlrev_b32_e32 v14, 16, v15
	v_and_b32_e32 v15, 0xffff0000, v15
	v_pk_add_f32 v[4:5], v[4:5], v[8:9]
	v_pk_add_f32 v[8:9], v[2:3], v[14:15]
	v_pk_add_f32 v[2:3], v[0:1], v[12:13]
	v_pk_add_f32 v[6:7], v[6:7], v[10:11]
	v_cvt_pk_bf16_f32 v0, v4, v5
	s_nop 0
	v_cvt_pk_bf16_f32 v1, v6, v7
	v_cvt_pk_bf16_f32 v2, v2, v3
	v_cvt_pk_bf16_f32 v3, v8, v9
	flat_store_dwordx4 v[16:17], v[0:3] offset:256 sc1

.LBB0_1026:
	s_or_b64 exec, exec, s[6:7]
	s_waitcnt lgkmcnt(0)
	v_mov_b32_e32 v0, v164
	s_barrier
	s_add_u32 s6, s34, 0x2aa00000
	s_mov_b32 s8, 22
	s_addc_u32 s7, s35, 0
	s_ashr_i32 s9, s8, 31
	s_lshl_b64 s[8:9], s[8:9], 3
	s_add_u32 s8, s0, s8
	s_addc_u32 s9, s1, s9
	s_load_dwordx2 s[12:13], s[8:9], 0x0
	v_and_b32_e32 v0, 63, v0
	s_add_u32 s10, s34, 0x9800000
	s_addc_u32 s11, s35, 0
	s_and_b64 vcc, exec, s[4:5]
	v_lshlrev_b32_e32 v40, 4, v0
	v_lshlrev_b32_e32 v48, 5, v0
	s_mov_b32 s48, s24
	s_cbranch_vccnz .LBB0_1028
	v_mov_b32_e32 v41, 0
	s_ashr_i32 s25, s24, 31
	v_lshl_add_u64 v[0:1], s[6:7], 0, v[40:41]
	s_lshl_b64 s[48:49], s[24:25], 12
	v_lshl_add_u64 v[2:3], v[0:1], 0, s[48:49]
	s_add_i32 s8, s24, s18
	flat_load_dwordx4 v[4:7], v[2:3] offset:1024
	flat_load_dwordx4 v[28:31], v[2:3] offset:2048
	flat_load_dwordx4 v[24:27], v[2:3] offset:3072
	flat_load_dwordx4 v[32:35], v[2:3]
	s_ashr_i32 s9, s8, 31
	s_lshl_b64 s[44:45], s[8:9], 12
	v_lshl_add_u64 v[2:3], v[0:1], 0, s[44:45]
	flat_load_dwordx4 v[36:39], v[2:3]
	flat_load_dwordx4 v[44:47], v[2:3] offset:1024
	flat_load_dwordx4 v[110:113], v[2:3] offset:2048
	flat_load_dwordx4 v[12:15], v[2:3] offset:3072
	v_readlane_b32 s14, v226, 1
	v_readlane_b32 s15, v226, 2
	s_mov_b32 s28, s14
	s_ashr_i32 s29, s14, 31
	s_add_i32 s14, s8, s18
	s_mov_b32 s8, s28
	s_ashr_i32 s15, s14, 31
	v_writelane_b32 v226, s8, 1
	s_lshl_b64 s[14:15], s[14:15], 12
	v_lshl_add_u64 v[42:43], v[0:1], 0, s[14:15]
	v_writelane_b32 v226, s9, 2
	s_lshl_b64 s[8:9], s[28:29], 12
	v_lshl_add_u64 v[108:109], v[0:1], 0, s[8:9]
	flat_load_dwordx4 v[20:23], v[42:43]
	flat_load_dwordx4 v[16:19], v[42:43] offset:1024
	flat_load_dwordx4 v[8:11], v[42:43] offset:2048
	flat_load_dwordx4 v[0:3], v[42:43] offset:3072
	s_waitcnt lgkmcnt(0)
	global_load_dwordx4 v[120:123], v48, s[12:13] offset:16
	global_load_dwordx4 v[124:127], v48, s[12:13]
	s_mov_b32 s40, 0x358637bd
	s_mov_b32 s46, 0x3a000000
	s_mov_b32 s3, 0x800000
	v_or_b32_e32 v49, 0x1800, v48
	v_mov_b32_e32 v105, v41
	s_waitcnt vmcnt(0)
	v_lshlrev_b32_e32 v69, 16, v4
	v_and_b32_e32 v55, 0xffff0000, v29
	v_lshlrev_b32_e32 v59, 16, v28
	v_and_b32_e32 v71, 0xffff0000, v32
	v_and_b32_e32 v70, 0xffff0000, v36
	v_lshlrev_b32_e32 v63, 16, v32
	v_and_b32_e32 v67, 0xffff0000, v28
	v_lshlrev_b32_e32 v61, 16, v29
	v_lshlrev_b32_e32 v62, 16, v36
	v_pk_mul_f32 v[28:29], v[70:71], v[70:71]
	v_lshlrev_b32_e32 v65, 16, v33
	v_and_b32_e32 v77, 0xffff0000, v33
	v_lshlrev_b32_e32 v64, 16, v37
	v_pk_fma_f32 v[32:33], v[62:63], v[62:63], v[28:29]
	v_and_b32_e32 v76, 0xffff0000, v37
	v_pk_fma_f32 v[32:33], v[64:65], v[64:65], v[32:33]
	v_lshlrev_b32_e32 v73, 16, v34
	v_lshlrev_b32_e32 v72, 16, v38
	v_pk_fma_f32 v[32:33], v[76:77], v[76:77], v[32:33]
	v_and_b32_e32 v85, 0xffff0000, v34
	v_and_b32_e32 v84, 0xffff0000, v38
	v_pk_fma_f32 v[32:33], v[72:73], v[72:73], v[32:33]
	v_lshlrev_b32_e32 v83, 16, v35
	v_lshlrev_b32_e32 v82, 16, v39
	v_pk_fma_f32 v[32:33], v[84:85], v[84:85], v[32:33]
	v_and_b32_e32 v95, 0xffff0000, v35
	v_and_b32_e32 v94, 0xffff0000, v39
	v_pk_fma_f32 v[32:33], v[82:83], v[82:83], v[32:33]
	v_lshlrev_b32_e32 v68, 16, v44
	v_pk_fma_f32 v[32:33], v[94:95], v[94:95], v[32:33]
	v_and_b32_e32 v57, 0xffff0000, v4
	v_and_b32_e32 v56, 0xffff0000, v44
	v_pk_fma_f32 v[32:33], v[68:69], v[68:69], v[32:33]
	v_lshlrev_b32_e32 v81, 16, v5
	v_lshlrev_b32_e32 v80, 16, v45
	v_pk_fma_f32 v[32:33], v[56:57], v[56:57], v[32:33]
	v_and_b32_e32 v91, 0xffff0000, v5
	v_and_b32_e32 v90, 0xffff0000, v45
	v_pk_fma_f32 v[32:33], v[80:81], v[80:81], v[32:33]
	v_lshlrev_b32_e32 v87, 16, v6
	v_lshlrev_b32_e32 v86, 16, v46
	v_pk_fma_f32 v[32:33], v[90:91], v[90:91], v[32:33]
	v_and_b32_e32 v93, 0xffff0000, v6
	v_and_b32_e32 v92, 0xffff0000, v46
	v_pk_fma_f32 v[32:33], v[86:87], v[86:87], v[32:33]
	v_lshlrev_b32_e32 v89, 16, v7
	v_lshlrev_b32_e32 v88, 16, v47
	v_pk_fma_f32 v[32:33], v[92:93], v[92:93], v[32:33]
	v_and_b32_e32 v97, 0xffff0000, v7
	v_and_b32_e32 v96, 0xffff0000, v47
	v_pk_fma_f32 v[32:33], v[88:89], v[88:89], v[32:33]
	v_lshlrev_b32_e32 v58, 16, v110
	v_pk_fma_f32 v[32:33], v[96:97], v[96:97], v[32:33]
	v_and_b32_e32 v66, 0xffff0000, v110
	v_pk_fma_f32 v[32:33], v[58:59], v[58:59], v[32:33]
	v_lshlrev_b32_e32 v60, 16, v111
	v_pk_fma_f32 v[32:33], v[66:67], v[66:67], v[32:33]
	v_lshlrev_b32_e32 v43, 16, v30
	v_and_b32_e32 v79, 0xffff0000, v30
	v_lshlrev_b32_e32 v75, 16, v31
	v_and_b32_e32 v54, 0xffff0000, v111
	v_and_b32_e32 v99, 0xffff0000, v31
	v_pk_fma_f32 v[30:31], v[60:61], v[60:61], v[32:33]
	v_lshlrev_b32_e32 v42, 16, v112
	v_pk_fma_f32 v[30:31], v[54:55], v[54:55], v[30:31]
	v_and_b32_e32 v78, 0xffff0000, v112
	v_pk_fma_f32 v[30:31], v[42:43], v[42:43], v[30:31]
	v_lshlrev_b32_e32 v74, 16, v113
	v_pk_fma_f32 v[30:31], v[78:79], v[78:79], v[30:31]
	v_and_b32_e32 v100, 0xffff0000, v26
	v_and_b32_e32 v98, 0xffff0000, v113
	v_pk_fma_f32 v[30:31], v[74:75], v[74:75], v[30:31]
	v_lshlrev_b32_e32 v103, 16, v26
	v_mov_b32_e32 v102, v100
	v_pk_fma_f32 v[30:31], v[98:99], v[98:99], v[30:31]
	v_lshlrev_b32_e32 v45, 16, v24
	v_lshlrev_b32_e32 v44, 16, v12
	v_and_b32_e32 v26, 0xffff0000, v14
	v_pk_mul_f32 v[6:7], v[102:103], v[102:103]
	v_and_b32_e32 v47, 0xffff0000, v24
	v_and_b32_e32 v46, 0xffff0000, v12
	v_lshlrev_b32_e32 v50, 16, v13
	v_and_b32_e32 v24, 0xffff0000, v13
	v_pk_fma_f32 v[12:13], v[44:45], v[44:45], v[30:31]
	v_lshlrev_b32_e32 v53, 16, v14
	v_mov_b32_e32 v52, v26
	v_lshlrev_b32_e32 v51, 16, v25
	v_pk_fma_f32 v[12:13], v[46:47], v[46:47], v[12:13]
	v_mov_b32_e32 v31, v7
	v_and_b32_e32 v7, 64, v196
	v_and_b32_e32 v104, 0xffff0000, v27
	v_pk_mul_f32 v[28:29], v[52:53], v[52:53]
	v_and_b32_e32 v25, 0xffff0000, v25
	v_pk_fma_f32 v[12:13], v[50:51], v[50:51], v[12:13]
	v_and_b32_e32 v110, 0xffff0000, v15
	v_add_u32_e32 v14, 64, v7
	v_xor_b32_e32 v7, 1, v196
	v_lshlrev_b32_e32 v107, 16, v27
	v_mov_b32_e32 v106, v104
	v_pk_fma_f32 v[12:13], v[24:25], v[24:25], v[12:13]
	v_mov_b32_e32 v30, v29
	v_lshlrev_b32_e32 v113, 16, v15
	v_mov_b32_e32 v112, v110
	v_cmp_lt_i32_e32 vcc, v7, v14
	v_pk_mul_f32 v[4:5], v[106:107], v[106:107]
	v_pk_add_f32 v[12:13], v[30:31], v[12:13]
	v_pk_mul_f32 v[30:31], v[112:113], v[112:113]
	v_cndmask_b32_e32 v7, v196, v7, vcc
	v_mov_b32_e32 v29, v6
	v_lshlrev_b32_e32 v114, 2, v7
	v_pk_add_f32 v[6:7], v[28:29], v[12:13]
	v_mov_b32_e32 v12, v31
	v_mov_b32_e32 v13, v5
	v_pk_add_f32 v[6:7], v[12:13], v[6:7]
	v_mov_b32_e32 v31, v4
	v_pk_add_f32 v[4:5], v[30:31], v[6:7]
	ds_bpermute_b32 v7, v114, v5
	ds_bpermute_b32 v6, v114, v4
	v_xor_b32_e32 v12, 2, v196
	v_cmp_lt_i32_e32 vcc, v12, v14
	v_mov_b32_e32 v130, v63
	v_mov_b32_e32 v131, v71
	v_cndmask_b32_e32 v12, v196, v12, vcc
	v_lshlrev_b32_e32 v116, 2, v12
	s_waitcnt lgkmcnt(0)
	v_pk_add_f32 v[4:5], v[4:5], v[6:7]
	ds_bpermute_b32 v7, v116, v5
	ds_bpermute_b32 v6, v116, v4
	v_xor_b32_e32 v12, 4, v196
	v_cmp_lt_i32_e32 vcc, v12, v14
	v_mov_b32_e32 v132, v65
	v_mov_b32_e32 v133, v77
	v_cndmask_b32_e32 v12, v196, v12, vcc
	v_lshlrev_b32_e32 v117, 2, v12
	s_waitcnt lgkmcnt(0)
	v_pk_add_f32 v[4:5], v[4:5], v[6:7]
	ds_bpermute_b32 v7, v117, v5
	ds_bpermute_b32 v6, v117, v4
	v_xor_b32_e32 v12, 8, v196
	v_cmp_lt_i32_e32 vcc, v12, v14
	v_mov_b32_e32 v134, v87
	v_mov_b32_e32 v135, v93
	v_cndmask_b32_e32 v12, v196, v12, vcc
	v_lshlrev_b32_e32 v118, 2, v12
	s_waitcnt lgkmcnt(0)
	v_pk_add_f32 v[4:5], v[4:5], v[6:7]
	ds_bpermute_b32 v7, v118, v5
	ds_bpermute_b32 v6, v118, v4
	v_xor_b32_e32 v12, 16, v196
	v_cmp_lt_i32_e32 vcc, v12, v14
	v_mov_b32_e32 v136, v89
	v_mov_b32_e32 v137, v97
	v_cndmask_b32_e32 v12, v196, v12, vcc
	v_lshlrev_b32_e32 v119, 2, v12
	s_waitcnt lgkmcnt(0)
	v_pk_add_f32 v[4:5], v[4:5], v[6:7]
	ds_bpermute_b32 v7, v119, v5
	ds_bpermute_b32 v6, v119, v4
	v_xor_b32_e32 v12, 32, v196
	v_cmp_lt_i32_e32 vcc, v12, v14
	v_and_b32_e32 v101, s0, v27
	v_pk_mov_b32 v[100:101], v[102:103], v[100:101] op_sel:[1,0]
	v_cndmask_b32_e32 v12, v196, v12, vcc
	v_lshlrev_b32_e32 v115, 2, v12
	s_waitcnt lgkmcnt(0)
	v_pk_add_f32 v[12:13], v[4:5], v[6:7]
	ds_bpermute_b32 v129, v115, v13
	ds_bpermute_b32 v128, v115, v12
	flat_load_dwordx4 v[36:39], v[108:109]
	flat_load_dwordx4 v[32:35], v[108:109] offset:1024
	flat_load_dwordx4 v[28:31], v[108:109] offset:2048
	flat_load_dwordx4 v[4:7], v[108:109] offset:3072
	v_mov_b64_e32 v[108:109], s[40:41]
	s_add_u32 s40, s10, s48
	s_addc_u32 s41, s11, s49
	s_waitcnt lgkmcnt(0)
	v_pk_add_f32 v[12:13], v[12:13], v[128:129]
	v_lshl_add_u64 v[128:129], s[40:41], 0, v[40:41]
	v_pk_fma_f32 v[12:13], v[12:13], s[46:47], v[108:109] op_sel_hi:[1,0,0]
	v_pk_mov_b32 v[102:103], v[106:107], v[104:105] op_sel:[1,0]
	v_mul_f32_e32 v14, 0x4b800000, v13
	v_cmp_gt_f32_e32 vcc, s3, v13
	s_add_u32 s40, s10, s44
	v_mov_b32_e32 v63, v70
	v_cndmask_b32_e32 v13, v13, v14, vcc
	v_rsq_f32_e32 v13, v13
	v_mov_b32_e32 v65, v76
	s_addc_u32 s41, s11, s45
	v_mov_b32_e32 v87, v92
	v_mul_f32_e32 v14, 0x45800000, v13
	v_cndmask_b32_e32 v14, v13, v14, vcc
	v_pk_mul_f32 v[130:131], v[130:131], v[14:15] op_sel_hi:[1,0]
	v_pk_mul_f32 v[132:133], v[132:133], v[14:15] op_sel_hi:[1,0]
	v_pk_mul_f32 v[124:125], v[124:125], v[130:131]
	v_pk_mul_f32 v[126:127], v[126:127], v[132:133]
	v_mov_b32_e32 v130, v73
	v_mov_b32_e32 v131, v85
	v_mov_b32_e32 v132, v83
	v_mov_b32_e32 v133, v95
	v_pk_mul_f32 v[130:131], v[130:131], v[14:15] op_sel_hi:[1,0]
	v_pk_mul_f32 v[132:133], v[132:133], v[14:15] op_sel_hi:[1,0]
	v_pk_mul_f32 v[134:135], v[134:135], v[14:15] op_sel_hi:[1,0]
	v_pk_mul_f32 v[132:133], v[122:123], v[132:133]
	v_pk_mul_f32 v[122:123], v[120:121], v[130:131]
	v_cvt_pk_bf16_f32 v120, v124, v125
	v_cvt_pk_bf16_f32 v121, v126, v127
	v_mov_b32_e32 v130, v69
	v_cvt_pk_bf16_f32 v122, v122, v123
	v_cvt_pk_bf16_f32 v123, v132, v133
	flat_store_dwordx4 v[128:129], v[120:123] sc1
	global_load_dwordx4 v[120:123], v48, s[12:13] offset:2048
	s_nop 0
	global_load_dwordx4 v[124:127], v48, s[12:13] offset:2064
	v_mov_b32_e32 v131, v57
	v_mov_b32_e32 v132, v81
	v_mov_b32_e32 v133, v91
	v_pk_mul_f32 v[130:131], v[130:131], v[14:15] op_sel_hi:[1,0]
	v_pk_mul_f32 v[132:133], v[132:133], v[14:15] op_sel_hi:[1,0]
	v_pk_mul_f32 v[136:137], v[136:137], v[14:15] op_sel_hi:[1,0]
	v_or_b32_e32 v13, 0x1000, v48
	v_pk_mul_f32 v[100:101], v[14:15], v[100:101] op_sel_hi:[0,1]
	v_pk_mul_f32 v[102:103], v[14:15], v[102:103] op_sel_hi:[0,1]
	v_cmp_gt_f32_e32 vcc, s3, v12
	v_mov_b32_e32 v73, v84
	v_mov_b32_e32 v83, v94
	v_mov_b32_e32 v69, v56
	v_mov_b32_e32 v81, v90
	v_mov_b32_e32 v89, v96
	v_and_b32_e32 v97, 0xffff0000, v20
	v_lshlrev_b32_e32 v85, 16, v21
	v_and_b32_e32 v91, 0xffff0000, v21
	v_and_b32_e32 v93, 0xffff0000, v22
	v_and_b32_e32 v27, s0, v15
	v_and_b32_e32 v95, 0xffff0000, v23
	v_mov_b32_e32 v111, v41
	s_add_u32 s14, s10, s14
	s_addc_u32 s15, s11, s15
	s_add_u32 s8, s10, s8
	s_addc_u32 s9, s11, s9
	s_waitcnt vmcnt(0)
	v_and_b32_e32 v96, 0xffff0000, v36
	v_lshlrev_b32_e32 v84, 16, v37
	v_and_b32_e32 v90, 0xffff0000, v37
	v_and_b32_e32 v92, 0xffff0000, v38
	v_and_b32_e32 v94, 0xffff0000, v39
	v_pk_mul_f32 v[122:123], v[122:123], v[132:133]
	v_pk_mul_f32 v[120:121], v[120:121], v[130:131]
	v_pk_mul_f32 v[126:127], v[126:127], v[136:137]
	v_pk_mul_f32 v[124:125], v[124:125], v[134:135]
	v_cvt_pk_bf16_f32 v120, v120, v121
	v_cvt_pk_bf16_f32 v121, v122, v123
	v_mov_b32_e32 v130, v59
	v_cvt_pk_bf16_f32 v122, v124, v125
	v_cvt_pk_bf16_f32 v123, v126, v127
	flat_store_dwordx4 v[128:129], v[120:123] offset:1024 sc1
	global_load_dwordx4 v[120:123], v13, s[12:13]
	s_nop 0
	global_load_dwordx4 v[124:127], v13, s[12:13] offset:16
	v_mov_b32_e32 v131, v67
	v_mov_b32_e32 v132, v61
	v_mov_b32_e32 v133, v55
	v_mov_b32_e32 v134, v43
	v_mov_b32_e32 v135, v79
	v_mov_b32_e32 v136, v75
	v_mov_b32_e32 v137, v99
	v_pk_mul_f32 v[130:131], v[130:131], v[14:15] op_sel_hi:[1,0]
	v_pk_mul_f32 v[132:133], v[132:133], v[14:15] op_sel_hi:[1,0]
	v_pk_mul_f32 v[134:135], v[134:135], v[14:15] op_sel_hi:[1,0]
	v_pk_mul_f32 v[136:137], v[136:137], v[14:15] op_sel_hi:[1,0]
	v_mov_b32_e32 v59, v66
	v_mov_b32_e32 v61, v54
	v_mov_b32_e32 v43, v78
	v_mov_b32_e32 v75, v98
	v_and_b32_e32 v98, 0xffff0000, v2
	v_and_b32_e32 v66, 0xffff0000, v30
	v_and_b32_e32 v67, 0xffff0000, v10
	v_and_b32_e32 v79, 0xffff0000, v19
	v_and_b32_e32 v78, 0xffff0000, v35
	v_and_b32_e32 v99, s0, v3
	s_waitcnt vmcnt(0)
	v_pk_mul_f32 v[122:123], v[132:133], v[122:123]
	v_pk_mul_f32 v[120:121], v[130:131], v[120:121]
	v_pk_mul_f32 v[126:127], v[136:137], v[126:127]
	v_pk_mul_f32 v[124:125], v[134:135], v[124:125]
	v_cvt_pk_bf16_f32 v120, v120, v121
	v_cvt_pk_bf16_f32 v121, v122, v123
	v_mov_b32_e32 v130, v45
	v_cvt_pk_bf16_f32 v122, v124, v125
	v_cvt_pk_bf16_f32 v123, v126, v127
	flat_store_dwordx4 v[128:129], v[120:123] offset:2048 sc1
	global_load_dwordx4 v[120:123], v49, s[12:13]
	s_nop 0
	global_load_dwordx4 v[124:127], v49, s[12:13] offset:16
	v_mov_b32_e32 v131, v47
	v_mov_b32_e32 v132, v51
	v_mov_b32_e32 v133, v25
	v_pk_mul_f32 v[104:105], v[130:131], v[14:15] op_sel_hi:[1,0]
	v_pk_mul_f32 v[106:107], v[132:133], v[14:15] op_sel_hi:[1,0]
	v_mul_f32_e32 v14, 0x4b800000, v12
	v_cndmask_b32_e32 v12, v12, v14, vcc
	v_rsq_f32_e32 v12, v12
	v_lshlrev_b32_e32 v15, 16, v0
	v_mov_b32_e32 v45, v46
	v_mov_b32_e32 v51, v24
	v_mul_f32_e32 v14, 0x45800000, v12
	s_waitcnt vmcnt(0)
	v_pk_mul_f32 v[104:105], v[104:105], v[120:121]
	v_pk_mul_f32 v[120:121], v[102:103], v[126:127]
	v_pk_mul_f32 v[102:103], v[100:101], v[124:125]
	v_pk_mul_f32 v[106:107], v[106:107], v[122:123]
	v_cvt_pk_bf16_f32 v100, v104, v105
	v_lshlrev_b32_e32 v105, 16, v2
	v_cvt_pk_bf16_f32 v101, v106, v107
	v_cvt_pk_bf16_f32 v102, v102, v103
	v_cvt_pk_bf16_f32 v103, v120, v121
	flat_store_dwordx4 v[128:129], v[100:103] offset:3072 sc1
	global_load_dwordx4 v[100:103], v48, s[12:13]
	s_nop 0
	global_load_dwordx4 v[120:123], v48, s[12:13] offset:16
	v_cndmask_b32_e32 v128, v12, v14, vcc
	v_pk_mul_f32 v[62:63], v[62:63], v[128:129] op_sel_hi:[1,0]
	v_pk_mul_f32 v[64:65], v[64:65], v[128:129] op_sel_hi:[1,0]
	v_lshl_add_u64 v[106:107], s[40:41], 0, v[40:41]
	v_pk_mul_f32 v[70:71], v[72:73], v[128:129] op_sel_hi:[1,0]
	v_pk_mul_f32 v[72:73], v[82:83], v[128:129] op_sel_hi:[1,0]
	v_pk_mul_f32 v[56:57], v[68:69], v[128:129] op_sel_hi:[1,0]
	v_pk_mul_f32 v[68:69], v[80:81], v[128:129] op_sel_hi:[1,0]
	v_pk_mul_f32 v[76:77], v[86:87], v[128:129] op_sel_hi:[1,0]
	v_pk_mul_f32 v[80:81], v[88:89], v[128:129] op_sel_hi:[1,0]
	v_lshlrev_b32_e32 v82, 16, v36
	v_pk_mul_f32 v[36:37], v[60:61], v[128:129] op_sel_hi:[1,0]
	v_pk_mul_f32 v[42:43], v[42:43], v[128:129] op_sel_hi:[1,0]
	v_pk_mul_f32 v[54:55], v[74:75], v[128:129] op_sel_hi:[1,0]
	v_lshlrev_b32_e32 v83, 16, v20
	v_and_b32_e32 v75, 0xffff0000, v8
	v_lshlrev_b32_e32 v86, 16, v38
	v_lshlrev_b32_e32 v87, 16, v22
	v_lshlrev_b32_e32 v88, 16, v39
	v_lshlrev_b32_e32 v89, 16, v23
	v_and_b32_e32 v12, 0xffff0000, v6
	v_lshlrev_b32_e32 v38, 16, v30
	v_and_b32_e32 v74, 0xffff0000, v28
	v_lshlrev_b32_e32 v14, 16, v4
	v_and_b32_e32 v30, 0xffff0000, v4
	v_lshlrev_b32_e32 v4, 16, v5
	v_lshlrev_b32_e32 v39, 16, v10
	v_mov_b32_e32 v104, v98
	s_waitcnt vmcnt(0)
	v_pk_mul_f32 v[64:65], v[64:65], v[102:103]
	v_pk_mul_f32 v[62:63], v[62:63], v[100:101]
	v_pk_mul_f32 v[72:73], v[72:73], v[122:123]
	v_pk_mul_f32 v[70:71], v[70:71], v[120:121]
	v_cvt_pk_bf16_f32 v62, v62, v63
	v_cvt_pk_bf16_f32 v63, v64, v65
	s_nop 0
	v_cvt_pk_bf16_f32 v64, v70, v71
	v_cvt_pk_bf16_f32 v65, v72, v73
	flat_store_dwordx4 v[106:107], v[62:65] sc1
	global_load_dwordx4 v[62:65], v48, s[12:13] offset:2048
	s_nop 0
	global_load_dwordx4 v[70:73], v48, s[12:13] offset:2064
	s_waitcnt vmcnt(0)
	v_pk_mul_f32 v[64:65], v[68:69], v[64:65]
	v_pk_mul_f32 v[56:57], v[56:57], v[62:63]
	v_pk_mul_f32 v[68:69], v[80:81], v[72:73]
	v_pk_mul_f32 v[70:71], v[76:77], v[70:71]
	v_cvt_pk_bf16_f32 v62, v56, v57
	v_cvt_pk_bf16_f32 v63, v64, v65
	v_and_b32_e32 v76, 0xffff0000, v32
	v_cvt_pk_bf16_f32 v64, v70, v71
	v_cvt_pk_bf16_f32 v65, v68, v69
	flat_store_dwordx4 v[106:107], v[62:65] offset:1024 sc1
	global_load_dwordx4 v[100:103], v13, s[12:13]
	global_load_dwordx4 v[120:123], v13, s[12:13] offset:16
	v_lshlrev_b32_e32 v62, 16, v32
	v_lshlrev_b32_e32 v64, 16, v33
	v_and_b32_e32 v80, 0xffff0000, v33
	v_pk_mul_f32 v[32:33], v[58:59], v[128:129] op_sel_hi:[1,0]
	v_and_b32_e32 v57, 0xffff0000, v9
	v_lshlrev_b32_e32 v68, 16, v34
	v_and_b32_e32 v72, 0xffff0000, v34
	v_and_b32_e32 v34, 0xffff0000, v7
	v_and_b32_e32 v56, 0xffff0000, v29
	v_lshlrev_b32_e32 v63, 16, v16
	v_and_b32_e32 v77, 0xffff0000, v16
	v_lshlrev_b32_e32 v65, 16, v17
	v_and_b32_e32 v81, 0xffff0000, v17
	v_lshlrev_b32_e32 v69, 16, v18
	v_and_b32_e32 v73, 0xffff0000, v18
	v_lshlrev_b32_e32 v71, 16, v19
	v_pk_mov_b32 v[16:17], v[112:113], v[110:111] op_sel:[1,0]
	v_pk_mul_f32 v[18:19], v[104:105], v[104:105]
	v_pk_mul_f32 v[16:17], v[128:129], v[16:17] op_sel_hi:[0,1]
	v_mov_b32_e32 v23, v19
	v_lshlrev_b32_e32 v70, 16, v35
	v_mov_b32_e32 v35, v41
	s_waitcnt vmcnt(0)
	v_pk_mul_f32 v[36:37], v[36:37], v[102:103]
	v_pk_mul_f32 v[32:33], v[32:33], v[100:101]
	v_pk_mul_f32 v[54:55], v[54:55], v[122:123]
	v_pk_mul_f32 v[42:43], v[42:43], v[120:121]
	v_cvt_pk_bf16_f32 v58, v32, v33
	v_cvt_pk_bf16_f32 v59, v36, v37
	v_and_b32_e32 v100, 0xffff0000, v3
	v_cvt_pk_bf16_f32 v60, v42, v43
	v_cvt_pk_bf16_f32 v61, v54, v55
	flat_store_dwordx4 v[106:107], v[58:61] offset:2048 sc1
	global_load_dwordx4 v[120:123], v49, s[12:13] offset:16
	global_load_dwordx4 v[124:127], v49, s[12:13]
	v_lshlrev_b32_e32 v43, 16, v8
	v_lshlrev_b32_e32 v55, 16, v9
	v_pk_mul_f32 v[8:9], v[96:97], v[96:97]
	v_lshlrev_b32_e32 v37, 16, v7
	v_pk_fma_f32 v[8:9], v[82:83], v[82:83], v[8:9]
	v_mov_b32_e32 v36, v34
	v_pk_fma_f32 v[8:9], v[84:85], v[84:85], v[8:9]
	v_lshlrev_b32_e32 v103, 16, v3
	v_pk_fma_f32 v[8:9], v[90:91], v[90:91], v[8:9]
	v_mov_b32_e32 v102, v100
	v_pk_fma_f32 v[8:9], v[86:87], v[86:87], v[8:9]
	v_lshlrev_b32_e32 v42, 16, v28
	v_pk_fma_f32 v[8:9], v[92:93], v[92:93], v[8:9]
	v_lshlrev_b32_e32 v54, 16, v29
	v_pk_fma_f32 v[8:9], v[88:89], v[88:89], v[8:9]
	v_lshlrev_b32_e32 v29, 16, v6
	v_lshlrev_b32_e32 v58, 16, v31
	v_and_b32_e32 v60, 0xffff0000, v31
	v_and_b32_e32 v32, 0xffff0000, v5
	v_mov_b32_e32 v28, v12
	v_lshlrev_b32_e32 v59, 16, v11
	v_and_b32_e32 v61, 0xffff0000, v11
	v_and_b32_e32 v31, 0xffff0000, v0
	v_lshlrev_b32_e32 v5, 16, v1
	v_and_b32_e32 v33, 0xffff0000, v1
	v_pk_mul_f32 v[0:1], v[36:37], v[36:37]
	v_pk_mov_b32 v[10:11], v[52:53], v[26:27] op_sel:[1,0]
	v_pk_mul_f32 v[52:53], v[102:103], v[102:103]
	v_pk_fma_f32 v[8:9], v[94:95], v[94:95], v[8:9]
	v_pk_mul_f32 v[20:21], v[28:29], v[28:29]
	v_mov_b32_e32 v26, v1
	v_mov_b32_e32 v27, v53
	v_mov_b32_e32 v1, v52
	v_pk_fma_f32 v[52:53], v[62:63], v[62:63], v[8:9]
	v_pk_mul_f32 v[8:9], v[44:45], v[128:129] op_sel_hi:[1,0]
	v_pk_mul_f32 v[10:11], v[128:129], v[10:11] op_sel_hi:[0,1]
	v_mov_b32_e32 v22, v21
	v_mov_b32_e32 v21, v18
	v_pk_mul_f32 v[18:19], v[50:51], v[128:129] op_sel_hi:[1,0]
	v_pk_fma_f32 v[24:25], v[76:77], v[76:77], v[52:53]
	v_mov_b32_e32 v44, v87
	v_pk_fma_f32 v[24:25], v[64:65], v[64:65], v[24:25]
	v_mov_b32_e32 v45, v93
	v_pk_fma_f32 v[24:25], v[80:81], v[80:81], v[24:25]
	v_mov_b32_e32 v101, v41
	v_pk_fma_f32 v[24:25], v[68:69], v[68:69], v[24:25]
	v_mov_b32_e32 v87, v92
	v_pk_fma_f32 v[24:25], v[72:73], v[72:73], v[24:25]
	s_waitcnt vmcnt(0)
	v_pk_mul_f32 v[10:11], v[10:11], v[120:121]
	v_pk_mul_f32 v[8:9], v[8:9], v[124:125]
	v_pk_mul_f32 v[18:19], v[18:19], v[126:127]
	v_pk_mul_f32 v[16:17], v[16:17], v[122:123]
	v_cvt_pk_bf16_f32 v8, v8, v9
	v_cvt_pk_bf16_f32 v9, v18, v19
	v_cvt_pk_bf16_f32 v10, v10, v11
	v_pk_fma_f32 v[24:25], v[70:71], v[70:71], v[24:25]
	v_cvt_pk_bf16_f32 v11, v16, v17
	flat_store_dwordx4 v[106:107], v[8:11] offset:3072 sc1
	global_load_dwordx4 v[8:11], v48, s[12:13] offset:16
	s_nop 0
	global_load_dwordx4 v[16:19], v48, s[12:13]
	v_pk_fma_f32 v[24:25], v[78:79], v[78:79], v[24:25]
	s_nop 0
	v_pk_fma_f32 v[24:25], v[42:43], v[42:43], v[24:25]
	s_nop 0
	v_pk_fma_f32 v[24:25], v[74:75], v[74:75], v[24:25]
	s_nop 0
	v_pk_fma_f32 v[24:25], v[54:55], v[54:55], v[24:25]
	s_nop 0
	v_pk_fma_f32 v[24:25], v[56:57], v[56:57], v[24:25]
	s_nop 0
	v_pk_fma_f32 v[24:25], v[38:39], v[38:39], v[24:25]
	s_nop 0
	v_pk_fma_f32 v[24:25], v[66:67], v[66:67], v[24:25]
	s_nop 0
	v_pk_fma_f32 v[24:25], v[58:59], v[58:59], v[24:25]
	s_nop 0
	v_pk_fma_f32 v[24:25], v[60:61], v[60:61], v[24:25]
	s_nop 0
	v_pk_fma_f32 v[24:25], v[14:15], v[14:15], v[24:25]
	s_nop 0
	v_pk_fma_f32 v[24:25], v[30:31], v[30:31], v[24:25]
	s_nop 0
	v_pk_fma_f32 v[24:25], v[4:5], v[4:5], v[24:25]
	s_nop 0
	v_pk_fma_f32 v[24:25], v[32:33], v[32:33], v[24:25]
	s_nop 0
	v_pk_add_f32 v[22:23], v[22:23], v[24:25]
	v_mov_b32_e32 v24, v83
	v_pk_add_f32 v[20:21], v[20:21], v[22:23]
	v_mov_b32_e32 v25, v97
	v_pk_add_f32 v[20:21], v[26:27], v[20:21]
	v_mov_b32_e32 v26, v85
	v_pk_add_f32 v[0:1], v[0:1], v[20:21]
	ds_bpermute_b32 v21, v114, v1
	ds_bpermute_b32 v20, v114, v0
	v_mov_b32_e32 v27, v91
	v_lshl_add_u64 v[22:23], s[14:15], 0, v[40:41]
	v_mov_b32_e32 v83, v96
	v_mov_b32_e32 v85, v90
	s_waitcnt lgkmcnt(0)
	v_pk_add_f32 v[0:1], v[0:1], v[20:21]
	ds_bpermute_b32 v21, v116, v1
	ds_bpermute_b32 v20, v116, v0
	s_waitcnt lgkmcnt(0)
	v_pk_add_f32 v[0:1], v[0:1], v[20:21]
	ds_bpermute_b32 v21, v117, v1
	ds_bpermute_b32 v20, v117, v0
	s_waitcnt lgkmcnt(0)
	v_pk_add_f32 v[0:1], v[0:1], v[20:21]
	ds_bpermute_b32 v21, v118, v1
	ds_bpermute_b32 v20, v118, v0
	s_waitcnt lgkmcnt(0)
	v_pk_add_f32 v[0:1], v[0:1], v[20:21]
	ds_bpermute_b32 v21, v119, v1
	ds_bpermute_b32 v20, v119, v0
	s_waitcnt lgkmcnt(0)
	v_pk_add_f32 v[0:1], v[0:1], v[20:21]
	ds_bpermute_b32 v21, v115, v1
	ds_bpermute_b32 v20, v115, v0
	s_waitcnt lgkmcnt(0)
	v_pk_add_f32 v[0:1], v[0:1], v[20:21]
	s_nop 0
	v_pk_fma_f32 v[20:21], v[0:1], s[46:47], v[108:109] op_sel_hi:[1,0,0]
	v_mov_b32_e32 v1, v95
	v_mul_f32_e32 v0, 0x4b800000, v21
	v_cmp_gt_f32_e32 vcc, s3, v21
	s_nop 1
	v_cndmask_b32_e32 v0, v21, v0, vcc
	v_rsq_f32_e32 v2, v0
	v_mov_b32_e32 v0, v89
	v_mov_b32_e32 v89, v94
	v_mul_f32_e32 v6, 0x45800000, v2
	v_cndmask_b32_e32 v2, v2, v6, vcc
	v_pk_mul_f32 v[44:45], v[44:45], v[2:3] op_sel_hi:[1,0]
	v_pk_mul_f32 v[0:1], v[0:1], v[2:3] op_sel_hi:[1,0]
	v_pk_mul_f32 v[24:25], v[24:25], v[2:3] op_sel_hi:[1,0]
	v_pk_mul_f32 v[26:27], v[26:27], v[2:3] op_sel_hi:[1,0]
	s_waitcnt vmcnt(0)
	v_pk_mul_f32 v[0:1], v[0:1], v[10:11]
	v_pk_mul_f32 v[10:11], v[44:45], v[8:9]
	v_pk_mul_f32 v[18:19], v[26:27], v[18:19]
	v_pk_mul_f32 v[16:17], v[24:25], v[16:17]
	v_mov_b32_e32 v24, v65
	v_cvt_pk_bf16_f32 v8, v16, v17
	v_cvt_pk_bf16_f32 v9, v18, v19
	v_cvt_pk_bf16_f32 v10, v10, v11
	v_cvt_pk_bf16_f32 v11, v0, v1
	flat_store_dwordx4 v[22:23], v[8:11] sc1
	global_load_dwordx4 v[8:11], v48, s[12:13] offset:2048
	s_nop 0
	global_load_dwordx4 v[16:19], v48, s[12:13] offset:2064
	v_mov_b32_e32 v25, v81
	v_mov_b32_e32 v0, v63
	v_mov_b32_e32 v1, v77
	v_mov_b32_e32 v26, v69
	v_mov_b32_e32 v27, v73
	v_mov_b32_e32 v44, v71
	v_mov_b32_e32 v45, v79
	v_pk_mul_f32 v[24:25], v[24:25], v[2:3] op_sel_hi:[1,0]
	v_pk_mul_f32 v[0:1], v[0:1], v[2:3] op_sel_hi:[1,0]
	v_pk_mul_f32 v[26:27], v[26:27], v[2:3] op_sel_hi:[1,0]
	v_pk_mul_f32 v[44:45], v[44:45], v[2:3] op_sel_hi:[1,0]
	v_cmp_gt_f32_e32 vcc, s3, v20
	v_mov_b32_e32 v63, v76
	v_mov_b32_e32 v65, v80
	v_mov_b32_e32 v69, v72
	v_mov_b32_e32 v71, v78
	s_lshl_b32 s3, s26, 5
	s_add_i32 s48, s24, s3
	s_waitcnt vmcnt(0)
	v_pk_mul_f32 v[10:11], v[24:25], v[10:11]
	v_pk_mul_f32 v[0:1], v[0:1], v[8:9]
	v_pk_mul_f32 v[18:19], v[44:45], v[18:19]
	v_pk_mul_f32 v[16:17], v[26:27], v[16:17]
	v_cvt_pk_bf16_f32 v8, v0, v1
	v_cvt_pk_bf16_f32 v9, v10, v11
	v_mov_b32_e32 v24, v55
	v_cvt_pk_bf16_f32 v10, v16, v17
	v_cvt_pk_bf16_f32 v11, v18, v19
	flat_store_dwordx4 v[22:23], v[8:11] offset:1024 sc1
	global_load_dwordx4 v[8:11], v13, s[12:13]
	s_nop 0
	global_load_dwordx4 v[16:19], v13, s[12:13] offset:16
	v_mov_b32_e32 v25, v57
	v_mov_b32_e32 v0, v43
	v_mov_b32_e32 v1, v75
	v_mov_b32_e32 v26, v39
	v_mov_b32_e32 v27, v67
	v_mov_b32_e32 v44, v59
	v_mov_b32_e32 v45, v61
	v_pk_mul_f32 v[24:25], v[24:25], v[2:3] op_sel_hi:[1,0]
	v_pk_mul_f32 v[0:1], v[0:1], v[2:3] op_sel_hi:[1,0]
	v_pk_mul_f32 v[26:27], v[26:27], v[2:3] op_sel_hi:[1,0]
	v_pk_mul_f32 v[44:45], v[44:45], v[2:3] op_sel_hi:[1,0]
	v_mov_b32_e32 v43, v74
	v_mov_b32_e32 v55, v56
	v_mov_b32_e32 v39, v66
	v_mov_b32_e32 v59, v60
	s_waitcnt vmcnt(0)
	v_pk_mul_f32 v[10:11], v[24:25], v[10:11]
	v_pk_mul_f32 v[0:1], v[0:1], v[8:9]
	v_pk_mul_f32 v[18:19], v[44:45], v[18:19]
	v_pk_mul_f32 v[16:17], v[26:27], v[16:17]
	v_cvt_pk_bf16_f32 v8, v0, v1
	v_cvt_pk_bf16_f32 v9, v10, v11
	v_mov_b32_e32 v0, v15
	v_cvt_pk_bf16_f32 v10, v16, v17
	v_cvt_pk_bf16_f32 v11, v18, v19
	flat_store_dwordx4 v[22:23], v[8:11] offset:2048 sc1
	global_load_dwordx4 v[8:11], v49, s[12:13]
	s_nop 0
	global_load_dwordx4 v[16:19], v49, s[12:13] offset:16
	v_mov_b32_e32 v1, v31
	v_mov_b32_e32 v24, v5
	v_mov_b32_e32 v25, v33
	v_pk_mov_b32 v[26:27], v[104:105], v[98:99] op_sel:[1,0]
	v_pk_mov_b32 v[44:45], v[102:103], v[100:101] op_sel:[1,0]
	v_pk_mul_f32 v[0:1], v[0:1], v[2:3] op_sel_hi:[1,0]
	v_pk_mul_f32 v[24:25], v[24:25], v[2:3] op_sel_hi:[1,0]
	v_pk_mul_f32 v[26:27], v[2:3], v[26:27] op_sel_hi:[0,1]
	v_pk_mul_f32 v[2:3], v[2:3], v[44:45] op_sel_hi:[0,1]
	v_mul_f32_e32 v5, 0x4b800000, v20
	v_cndmask_b32_e32 v5, v20, v5, vcc
	v_rsq_f32_e32 v5, v5
	v_mov_b32_e32 v15, v30
	v_mul_f32_e32 v6, 0x45800000, v5
	v_cndmask_b32_e32 v6, v5, v6, vcc
	v_pk_mul_f32 v[20:21], v[84:85], v[6:7] op_sel_hi:[1,0]
	v_mov_b32_e32 v5, v32
	v_pk_mul_f32 v[14:15], v[14:15], v[6:7] op_sel_hi:[1,0]
	v_pk_mul_f32 v[4:5], v[4:5], v[6:7] op_sel_hi:[1,0]
	s_waitcnt vmcnt(0)
	v_pk_mul_f32 v[0:1], v[0:1], v[8:9]
	v_pk_mul_f32 v[8:9], v[2:3], v[18:19]
	v_pk_mul_f32 v[2:3], v[26:27], v[16:17]
	v_pk_mul_f32 v[10:11], v[24:25], v[10:11]
	v_cvt_pk_bf16_f32 v0, v0, v1
	v_pk_mul_f32 v[18:19], v[82:83], v[6:7] op_sel_hi:[1,0]
	v_cvt_pk_bf16_f32 v1, v10, v11
	v_cvt_pk_bf16_f32 v2, v2, v3
	v_cvt_pk_bf16_f32 v3, v8, v9
	flat_store_dwordx4 v[22:23], v[0:3] offset:3072 sc1
	global_load_dwordx4 v[0:3], v48, s[12:13]
	s_nop 0
	global_load_dwordx4 v[8:11], v48, s[12:13] offset:16
	v_lshl_add_u64 v[16:17], s[8:9], 0, v[40:41]
	v_pk_mul_f32 v[22:23], v[86:87], v[6:7] op_sel_hi:[1,0]
	v_pk_mul_f32 v[24:25], v[88:89], v[6:7] op_sel_hi:[1,0]
	s_waitcnt vmcnt(0)
	v_pk_mul_f32 v[2:3], v[20:21], v[2:3]
	v_pk_mul_f32 v[0:1], v[18:19], v[0:1]
	v_pk_mul_f32 v[10:11], v[24:25], v[10:11]
	v_pk_mul_f32 v[8:9], v[22:23], v[8:9]
	v_cvt_pk_bf16_f32 v0, v0, v1
	v_cvt_pk_bf16_f32 v1, v2, v3
	v_pk_mul_f32 v[18:19], v[62:63], v[6:7] op_sel_hi:[1,0]
	v_cvt_pk_bf16_f32 v2, v8, v9
	v_cvt_pk_bf16_f32 v3, v10, v11
	flat_store_dwordx4 v[16:17], v[0:3] sc1
	global_load_dwordx4 v[0:3], v48, s[12:13] offset:2048
	s_nop 0
	global_load_dwordx4 v[8:11], v48, s[12:13] offset:2064
	v_pk_mul_f32 v[20:21], v[64:65], v[6:7] op_sel_hi:[1,0]
	v_pk_mul_f32 v[22:23], v[68:69], v[6:7] op_sel_hi:[1,0]
	v_pk_mul_f32 v[24:25], v[70:71], v[6:7] op_sel_hi:[1,0]
	s_waitcnt vmcnt(0)
	v_pk_mul_f32 v[2:3], v[20:21], v[2:3]
	v_pk_mul_f32 v[0:1], v[18:19], v[0:1]
	v_pk_mul_f32 v[10:11], v[24:25], v[10:11]
	v_pk_mul_f32 v[8:9], v[22:23], v[8:9]
	v_cvt_pk_bf16_f32 v0, v0, v1
	v_cvt_pk_bf16_f32 v1, v2, v3
	v_pk_mul_f32 v[18:19], v[42:43], v[6:7] op_sel_hi:[1,0]
	v_cvt_pk_bf16_f32 v2, v8, v9
	v_cvt_pk_bf16_f32 v3, v10, v11
	flat_store_dwordx4 v[16:17], v[0:3] offset:1024 sc1
	global_load_dwordx4 v[0:3], v13, s[12:13]
	s_nop 0
	global_load_dwordx4 v[8:11], v13, s[12:13] offset:16
	v_pk_mul_f32 v[20:21], v[54:55], v[6:7] op_sel_hi:[1,0]
	v_pk_mul_f32 v[22:23], v[38:39], v[6:7] op_sel_hi:[1,0]
	v_pk_mul_f32 v[24:25], v[58:59], v[6:7] op_sel_hi:[1,0]
	v_and_b32_e32 v13, s0, v7
	v_pk_mov_b32 v[12:13], v[28:29], v[12:13] op_sel:[1,0]
	s_waitcnt vmcnt(0)
	v_pk_mul_f32 v[2:3], v[20:21], v[2:3]
	v_pk_mul_f32 v[0:1], v[18:19], v[0:1]
	v_pk_mul_f32 v[10:11], v[24:25], v[10:11]
	v_pk_mul_f32 v[8:9], v[22:23], v[8:9]
	v_cvt_pk_bf16_f32 v0, v0, v1
	v_cvt_pk_bf16_f32 v1, v2, v3
	v_pk_mov_b32 v[18:19], v[36:37], v[34:35] op_sel:[1,0]
	v_cvt_pk_bf16_f32 v2, v8, v9
	v_cvt_pk_bf16_f32 v3, v10, v11
	flat_store_dwordx4 v[16:17], v[0:3] offset:2048 sc1
	global_load_dwordx4 v[0:3], v49, s[12:13]
	s_nop 0
	global_load_dwordx4 v[8:11], v49, s[12:13] offset:16
	v_pk_mul_f32 v[12:13], v[6:7], v[12:13] op_sel_hi:[0,1]
	v_pk_mul_f32 v[6:7], v[6:7], v[18:19] op_sel_hi:[0,1]
	s_waitcnt vmcnt(0)
	v_pk_mul_f32 v[2:3], v[4:5], v[2:3]
	v_pk_mul_f32 v[0:1], v[14:15], v[0:1]
	v_pk_mul_f32 v[4:5], v[6:7], v[10:11]
	v_pk_mul_f32 v[6:7], v[12:13], v[8:9]
	v_cvt_pk_bf16_f32 v0, v0, v1
	v_cvt_pk_bf16_f32 v1, v2, v3
	s_nop 0
	v_cvt_pk_bf16_f32 v2, v6, v7
	v_cvt_pk_bf16_f32 v3, v4, v5
	flat_store_dwordx4 v[16:17], v[0:3] offset:3072 sc1

.LBB0_1034:
	v_mul_f32_e32 v40, v25, v25
	v_fmac_f32_e32 v40, v24, v24
	v_fmac_f32_e32 v40, v26, v26
	v_fmac_f32_e32 v40, v27, v27
	v_fmac_f32_e32 v40, v28, v28
	v_fmac_f32_e32 v40, v29, v29
	v_fmac_f32_e32 v40, v30, v30
	v_fmac_f32_e32 v40, v31, v31
	v_fmac_f32_e32 v40, v16, v16
	v_fmac_f32_e32 v40, v17, v17
	v_fmac_f32_e32 v40, v18, v18
	v_fmac_f32_e32 v40, v19, v19
	v_fmac_f32_e32 v40, v20, v20
	v_fmac_f32_e32 v40, v21, v21
	v_fmac_f32_e32 v40, v22, v22
	v_fmac_f32_e32 v40, v23, v23
	v_lshlrev_b32_e32 v7, 16, v35
	v_and_b32_e32 v6, 0xffff0000, v35
	v_fmac_f32_e32 v40, v8, v8
	global_load_dwordx4 v[32:35], v[44:45], off offset:16
	global_load_dwordx4 v[60:63], v[44:45], off
	v_fmac_f32_e32 v40, v9, v9
	v_fmac_f32_e32 v40, v10, v10
	v_fmac_f32_e32 v40, v11, v11
	v_fmac_f32_e32 v40, v12, v12
	v_fmac_f32_e32 v40, v13, v13
	v_fmac_f32_e32 v40, v14, v14
	v_fmac_f32_e32 v40, v15, v15
	v_fmac_f32_e32 v40, v0, v0
	v_fmac_f32_e32 v40, v1, v1
	v_fmac_f32_e32 v40, v2, v2
	v_fmac_f32_e32 v40, v3, v3
	v_pk_mul_f32 v[64:65], v[4:5], v[4:5]
	v_and_b32_e32 v57, 64, v196
	v_add_f32_e32 v40, v64, v40
	v_add_f32_e32 v40, v65, v40
	v_pk_mul_f32 v[64:65], v[6:7], v[6:7]
	v_add_u32_e32 v57, 64, v57
	v_add_f32_e32 v40, v65, v40
	v_add_f32_e32 v40, v64, v40
	v_xor_b32_e32 v64, 1, v196
	v_cmp_lt_i32_e32 vcc, v64, v57
	s_add_i32 s8, s45, s18
	s_cmp_le_i32 s45, s48
	v_cndmask_b32_e32 v64, v196, v64, vcc
	v_lshlrev_b32_e32 v64, 2, v64
	ds_bpermute_b32 v64, v64, v40
	s_cselect_b64 s[40:41], -1, 0
	s_cmpk_lt_i32 s8, 0x2400
	s_cselect_b64 s[50:51], -1, 0
	s_and_b64 s[40:41], s[40:41], s[50:51]
	s_waitcnt lgkmcnt(0)
	v_add_f32_e32 v40, v40, v64
	v_xor_b32_e32 v64, 2, v196
	v_cmp_lt_i32_e32 vcc, v64, v57
	s_mov_b32 s45, s8
	s_nop 0
	v_cndmask_b32_e32 v64, v196, v64, vcc
	v_lshlrev_b32_e32 v64, 2, v64
	ds_bpermute_b32 v64, v64, v40
	s_waitcnt lgkmcnt(0)
	v_add_f32_e32 v40, v40, v64
	v_xor_b32_e32 v64, 4, v196
	v_cmp_lt_i32_e32 vcc, v64, v57
	s_nop 1
	v_cndmask_b32_e32 v64, v196, v64, vcc
	v_lshlrev_b32_e32 v64, 2, v64
	ds_bpermute_b32 v64, v64, v40
	s_waitcnt lgkmcnt(0)
	v_add_f32_e32 v40, v40, v64
	v_xor_b32_e32 v64, 8, v196
	v_cmp_lt_i32_e32 vcc, v64, v57
	s_nop 1
	v_cndmask_b32_e32 v64, v196, v64, vcc
	v_lshlrev_b32_e32 v64, 2, v64
	ds_bpermute_b32 v64, v64, v40
	s_waitcnt lgkmcnt(0)
	v_add_f32_e32 v40, v40, v64
	v_xor_b32_e32 v64, 16, v196
	v_cmp_lt_i32_e32 vcc, v64, v57
	s_nop 1
	v_cndmask_b32_e32 v64, v196, v64, vcc
	v_lshlrev_b32_e32 v64, 2, v64
	ds_bpermute_b32 v64, v64, v40
	s_waitcnt lgkmcnt(0)
	v_add_f32_e32 v40, v40, v64
	v_xor_b32_e32 v64, 32, v196
	v_cmp_lt_i32_e32 vcc, v64, v57
	s_nop 1
	v_cndmask_b32_e32 v57, v196, v64, vcc
	v_lshlrev_b32_e32 v57, 2, v57
	ds_bpermute_b32 v57, v57, v40
	s_waitcnt lgkmcnt(0)
	v_add_f32_e32 v40, v40, v57
	v_fmamk_f32 v40, v40, 0x3a000000, v56
	v_mul_f32_e32 v57, 0x4b800000, v40
	v_cmp_gt_f32_e32 vcc, s13, v40
	s_nop 1
	v_cndmask_b32_e32 v40, v40, v57, vcc
	v_rsq_f32_e32 v40, v40
	s_nop 0
	v_mul_f32_e32 v57, 0x45800000, v40
	v_cndmask_b32_e32 v40, v40, v57, vcc
	v_pk_mul_f32 v[24:25], v[40:41], v[24:25] op_sel_hi:[0,1]
	v_pk_mul_f32 v[26:27], v[40:41], v[26:27] op_sel_hi:[0,1]
	v_pk_mul_f32 v[28:29], v[40:41], v[28:29] op_sel_hi:[0,1]
	s_waitcnt vmcnt(0)
	v_pk_mul_f32 v[26:27], v[62:63], v[26:27]
	v_pk_mul_f32 v[24:25], v[60:61], v[24:25]
	v_pk_mul_f32 v[28:29], v[32:33], v[28:29]
	v_cvt_pk_bf16_f32 v24, v24, v25
	v_cvt_pk_bf16_f32 v25, v26, v27
	v_pk_mul_f32 v[30:31], v[40:41], v[30:31] op_sel_hi:[0,1]
	v_cvt_pk_bf16_f32 v26, v28, v29
	v_add_co_u32_e32 v28, vcc, s54, v58
	v_pk_mul_f32 v[30:31], v[34:35], v[30:31]
	s_nop 0
	v_addc_co_u32_e32 v29, vcc, -1, v59, vcc
	v_cvt_pk_bf16_f32 v27, v30, v31
	flat_store_dwordx4 v[28:29], v[24:27] sc1
	global_load_dwordx4 v[24:27], v[44:45], off offset:2048
	s_nop 0
	global_load_dwordx4 v[28:31], v[44:45], off offset:2064
	v_add_co_u32_e32 v32, vcc, s55, v58
	v_pk_mul_f32 v[16:17], v[40:41], v[16:17] op_sel_hi:[0,1]
	v_pk_mul_f32 v[18:19], v[40:41], v[18:19] op_sel_hi:[0,1]
	v_addc_co_u32_e32 v33, vcc, -1, v59, vcc
	v_pk_mul_f32 v[20:21], v[40:41], v[20:21] op_sel_hi:[0,1]
	v_pk_mul_f32 v[22:23], v[40:41], v[22:23] op_sel_hi:[0,1]
	v_pk_mul_f32 v[8:9], v[40:41], v[8:9] op_sel_hi:[0,1]
	v_pk_mul_f32 v[10:11], v[40:41], v[10:11] op_sel_hi:[0,1]
	v_pk_mul_f32 v[12:13], v[40:41], v[12:13] op_sel_hi:[0,1]
	v_pk_mul_f32 v[14:15], v[40:41], v[14:15] op_sel_hi:[0,1]
	v_pk_mul_f32 v[0:1], v[40:41], v[0:1] op_sel_hi:[0,1]
	v_pk_mul_f32 v[2:3], v[40:41], v[2:3] op_sel_hi:[0,1]
	v_pk_mul_f32 v[4:5], v[40:41], v[4:5] op_sel_hi:[0,1]
	s_waitcnt vmcnt(0)
	v_pk_mul_f32 v[18:19], v[26:27], v[18:19]
	v_pk_mul_f32 v[16:17], v[24:25], v[16:17]
	v_pk_mul_f32 v[22:23], v[30:31], v[22:23]
	v_pk_mul_f32 v[20:21], v[28:29], v[20:21]
	v_cvt_pk_bf16_f32 v16, v16, v17
	v_cvt_pk_bf16_f32 v17, v18, v19
	v_add_co_u32_e32 v24, vcc, s56, v58
	v_cvt_pk_bf16_f32 v18, v20, v21
	v_cvt_pk_bf16_f32 v19, v22, v23
	flat_store_dwordx4 v[32:33], v[16:19] sc1
	global_load_dwordx4 v[16:19], v[46:47], off
	s_nop 0
	global_load_dwordx4 v[20:23], v[46:47], off offset:16
	v_addc_co_u32_e32 v25, vcc, -1, v59, vcc
	s_waitcnt vmcnt(0)
	v_pk_mul_f32 v[10:11], v[18:19], v[10:11]
	v_pk_mul_f32 v[8:9], v[16:17], v[8:9]
	v_pk_mul_f32 v[14:15], v[22:23], v[14:15]
	v_pk_mul_f32 v[12:13], v[20:21], v[12:13]
	v_cvt_pk_bf16_f32 v8, v8, v9
	v_cvt_pk_bf16_f32 v9, v10, v11
	v_add_co_u32_e32 v16, vcc, 0xdee00c00, v58
	v_cvt_pk_bf16_f32 v10, v12, v13
	v_cvt_pk_bf16_f32 v11, v14, v15
	flat_store_dwordx4 v[24:25], v[8:11] sc1
	global_load_dwordx4 v[8:11], v[48:49], off
	s_nop 0
	global_load_dwordx4 v[12:15], v[48:49], off offset:16
	v_mov_b32_e32 v18, v7
	v_mov_b32_e32 v19, v6
	v_addc_co_u32_e32 v17, vcc, -1, v59, vcc
	v_lshl_add_u64 v[58:59], v[58:59], 0, s[10:11]
	s_and_b64 vcc, exec, s[40:41]
	v_pk_mul_f32 v[6:7], v[40:41], v[18:19] op_sel_hi:[0,1]
	s_waitcnt vmcnt(0)
	v_pk_mul_f32 v[2:3], v[10:11], v[2:3]
	v_pk_mul_f32 v[0:1], v[8:9], v[0:1]
	v_pk_mul_f32 v[6:7], v[14:15], v[6:7]
	v_pk_mul_f32 v[4:5], v[12:13], v[4:5]
	v_cvt_pk_bf16_f32 v0, v0, v1
	v_cvt_pk_bf16_f32 v1, v2, v3
	s_nop 0
	v_cvt_pk_bf16_f32 v2, v4, v5
	v_cvt_pk_bf16_f32 v3, v6, v7
	flat_store_dwordx4 v[16:17], v[0:3] sc1
	s_cbranch_vccz .LBB0_1040
.LBB0_1035:
	s_cmpk_gt_i32 s45, 0x1fff
	s_cselect_b64 s[40:41], -1, 0
	s_and_b64 s[40:41], s[14:15], s[40:41]
	s_mov_b64 s[50:51], -1
	s_and_b64 vcc, exec, s[40:41]
	s_cbranch_vccz .LBB0_1037
	s_add_i32 s8, s45, 0xffffe000
	s_lshl_b64 s[50:51], s[8:9], 12
	v_lshl_add_u64 v[26:27], v[50:51], 0, s[50:51]
	flat_load_dwordx4 v[2:5], v[26:27]
	v_lshl_add_u64 v[0:1], v[36:37], 0, s[50:51]
	flat_load_dwordx4 v[6:9], v[0:1]
	flat_load_dwordx4 v[10:13], v[26:27] offset:1024
	flat_load_dwordx4 v[14:17], v[0:1] offset:1024
	flat_load_dwordx4 v[18:21], v[26:27] offset:2048
	flat_load_dwordx4 v[22:25], v[0:1] offset:2048
	s_nop 0
	flat_load_dwordx4 v[26:29], v[26:27] offset:3072
	s_nop 0
	flat_load_dwordx4 v[30:33], v[0:1] offset:3072
	v_add_co_u32_e32 v34, vcc, s3, v0
	s_waitcnt vmcnt(0) lgkmcnt(0)
	v_lshlrev_b32_e32 v57, 16, v6
	v_addc_co_u32_e32 v35, vcc, 0, v1, vcc
	flat_load_dwordx4 v[60:63], v[34:35]
	flat_load_dwordx4 v[64:67], v[34:35] offset:1024
	flat_load_dwordx4 v[68:71], v[34:35] offset:2048
	v_lshlrev_b32_e32 v40, 16, v2
	v_and_b32_e32 v6, 0xffff0000, v6
	v_and_b32_e32 v2, 0xffff0000, v2
	v_lshlrev_b32_e32 v72, 16, v3
	v_lshlrev_b32_e32 v73, 16, v7
	v_and_b32_e32 v7, 0xffff0000, v7
	v_and_b32_e32 v3, 0xffff0000, v3
	v_lshlrev_b32_e32 v86, 16, v18
	v_lshlrev_b32_e32 v87, 16, v22
	v_lshlrev_b32_e32 v88, 16, v19
	v_lshlrev_b32_e32 v89, 16, v23
	v_add_f32_e32 v40, v57, v40
	v_add_f32_e32 v57, v6, v2
	v_add_f32_e32 v72, v73, v72
	v_add_f32_e32 v73, v7, v3
	v_lshlrev_b32_e32 v2, 16, v21
	v_lshlrev_b32_e32 v3, 16, v25
	v_lshlrev_b32_e32 v74, 16, v4
	v_lshlrev_b32_e32 v75, 16, v8
	v_and_b32_e32 v8, 0xffff0000, v8
	v_and_b32_e32 v4, 0xffff0000, v4
	v_lshlrev_b32_e32 v76, 16, v5
	v_lshlrev_b32_e32 v77, 16, v9
	v_and_b32_e32 v9, 0xffff0000, v9
	v_and_b32_e32 v5, 0xffff0000, v5
	v_add_f32_e32 v86, v87, v86
	v_add_f32_e32 v87, v89, v88
	v_add_f32_e32 v89, v3, v2
	v_and_b32_e32 v2, 0xffff0000, v25
	v_and_b32_e32 v3, 0xffff0000, v21
	v_add_f32_e32 v74, v75, v74
	v_add_f32_e32 v75, v8, v4
	v_add_f32_e32 v76, v77, v76
	v_add_f32_e32 v77, v9, v5
	v_add_f32_e32 v25, v2, v3
	flat_load_dwordx4 v[2:5], v[34:35] offset:3072
	v_lshlrev_b32_e32 v6, 16, v26
	v_lshlrev_b32_e32 v7, 16, v30
	v_add_f32_e32 v34, v7, v6
	v_and_b32_e32 v6, 0xffff0000, v30
	v_and_b32_e32 v7, 0xffff0000, v26
	v_lshlrev_b32_e32 v78, 16, v10
	v_lshlrev_b32_e32 v79, 16, v14
	v_and_b32_e32 v14, 0xffff0000, v14
	v_and_b32_e32 v10, 0xffff0000, v10
	v_lshlrev_b32_e32 v80, 16, v11
	v_lshlrev_b32_e32 v81, 16, v15
	v_and_b32_e32 v15, 0xffff0000, v15
	v_and_b32_e32 v11, 0xffff0000, v11
	v_add_f32_e32 v26, v6, v7
	v_lshlrev_b32_e32 v6, 16, v27
	v_lshlrev_b32_e32 v7, 16, v31
	v_and_b32_e32 v22, 0xffff0000, v22
	v_and_b32_e32 v18, 0xffff0000, v18
	v_add_f32_e32 v78, v79, v78
	v_add_f32_e32 v79, v14, v10
	v_add_f32_e32 v80, v81, v80
	v_add_f32_e32 v81, v15, v11
	v_add_f32_e32 v30, v7, v6
	v_and_b32_e32 v6, 0xffff0000, v31
	v_and_b32_e32 v7, 0xffff0000, v27
	v_and_b32_e32 v10, 0xffff0000, v32
	v_and_b32_e32 v11, 0xffff0000, v28
	v_and_b32_e32 v23, 0xffff0000, v23
	v_and_b32_e32 v19, 0xffff0000, v19
	v_add_f32_e32 v22, v22, v18
	v_add_f32_e32 v27, v6, v7
	v_lshlrev_b32_e32 v6, 16, v28
	v_add_co_u32_e32 v18, vcc, s13, v0
	v_add_f32_e32 v28, v10, v11
	v_lshlrev_b32_e32 v10, 16, v29
	v_lshlrev_b32_e32 v11, 16, v33
	v_add_f32_e32 v23, v23, v19
	v_lshlrev_b32_e32 v7, 16, v32
	v_addc_co_u32_e32 v19, vcc, 0, v1, vcc
	v_add_f32_e32 v32, v11, v10
	v_and_b32_e32 v10, 0xffff0000, v33
	v_and_b32_e32 v11, 0xffff0000, v29
	v_lshlrev_b32_e32 v82, 16, v12
	v_lshlrev_b32_e32 v83, 16, v16
	v_and_b32_e32 v16, 0xffff0000, v16
	v_and_b32_e32 v12, 0xffff0000, v12
	v_lshlrev_b32_e32 v84, 16, v13
	v_lshlrev_b32_e32 v85, 16, v17
	v_and_b32_e32 v17, 0xffff0000, v17
	v_and_b32_e32 v13, 0xffff0000, v13
	v_add_f32_e32 v31, v7, v6
	flat_load_dwordx4 v[6:9], v[18:19]
	v_add_f32_e32 v29, v10, v11
	s_waitcnt vmcnt(0) lgkmcnt(0)
	v_lshlrev_b32_e32 v10, 16, v60
	v_and_b32_e32 v14, 0xffff0000, v60
	v_add_f32_e32 v82, v83, v82
	v_add_f32_e32 v83, v16, v12
	v_add_f32_e32 v84, v85, v84
	v_add_f32_e32 v85, v17, v13
	v_lshlrev_b32_e32 v15, 16, v61
	v_and_b32_e32 v16, 0xffff0000, v61
	v_lshlrev_b32_e32 v17, 16, v62
	v_add_f32_e32 v35, v40, v10
	flat_load_dwordx4 v[10:13], v[18:19] offset:1024
	v_add_f32_e32 v40, v57, v14
	v_lshlrev_b32_e32 v14, 16, v64
	v_add_f32_e32 v57, v72, v15
	v_add_f32_e32 v60, v73, v16
	v_add_f32_e32 v61, v74, v17
	v_add_f32_e32 v73, v78, v14
	flat_load_dwordx4 v[14:17], v[18:19] offset:2048
	v_lshlrev_b32_e32 v90, 16, v20
	v_lshlrev_b32_e32 v91, 16, v24
	v_and_b32_e32 v24, 0xffff0000, v24
	v_and_b32_e32 v20, 0xffff0000, v20
	v_add_f32_e32 v24, v24, v20
	v_and_b32_e32 v20, 0xffff0000, v62
	v_add_f32_e32 v62, v75, v20
	v_and_b32_e32 v20, 0xffff0000, v64
	v_add_f32_e32 v74, v79, v20
	v_lshlrev_b32_e32 v20, 16, v68
	v_and_b32_e32 v68, 0xffff0000, v68
	v_lshlrev_b32_e32 v21, 16, v63
	v_add_f32_e32 v68, v22, v68
	v_lshlrev_b32_e32 v22, 16, v2
	v_and_b32_e32 v33, 0xffff0000, v63
	v_add_f32_e32 v63, v76, v21
	v_lshlrev_b32_e32 v76, 16, v69
	v_and_b32_e32 v69, 0xffff0000, v69
	v_add_f32_e32 v34, v34, v22
	v_add_co_u32_e32 v22, vcc, s19, v0
	v_add_f32_e32 v33, v77, v33
	v_lshlrev_b32_e32 v21, 16, v65
	v_and_b32_e32 v64, 0xffff0000, v65
	v_lshlrev_b32_e32 v65, 16, v66
	v_and_b32_e32 v66, 0xffff0000, v66
	v_lshlrev_b32_e32 v72, 16, v67
	v_lshlrev_b32_e32 v77, 16, v70
	v_and_b32_e32 v70, 0xffff0000, v70
	v_lshlrev_b32_e32 v78, 16, v71
	v_and_b32_e32 v71, 0xffff0000, v71
	v_add_f32_e32 v69, v23, v69
	v_addc_co_u32_e32 v23, vcc, 0, v1, vcc
	v_add_f32_e32 v75, v80, v21
	v_add_f32_e32 v64, v81, v64
	v_add_f32_e32 v65, v82, v65
	v_add_f32_e32 v66, v83, v66
	v_add_f32_e32 v72, v84, v72
	v_add_f32_e32 v79, v86, v20
	v_add_f32_e32 v24, v24, v70
	v_add_f32_e32 v70, v89, v78
	v_add_f32_e32 v25, v25, v71
	v_and_b32_e32 v71, 0xffff0000, v2
	v_lshlrev_b32_e32 v78, 16, v3
	v_and_b32_e32 v80, 0xffff0000, v3
	v_lshlrev_b32_e32 v81, 16, v4
	v_and_b32_e32 v82, 0xffff0000, v4
	v_lshlrev_b32_e32 v83, 16, v5
	v_and_b32_e32 v84, 0xffff0000, v5
	flat_load_dwordx4 v[2:5], v[22:23]
	v_and_b32_e32 v67, 0xffff0000, v67
	flat_load_dwordx4 v[18:21], v[18:19] offset:3072
	v_add_f32_e32 v67, v85, v67
	v_add_f32_e32 v26, v26, v71
	v_add_f32_e32 v30, v30, v78
	v_add_f32_e32 v27, v27, v80
	v_add_f32_e32 v31, v31, v81
	v_add_f32_e32 v28, v28, v82
	v_add_f32_e32 v32, v32, v83
	v_add_f32_e32 v29, v29, v84
	v_lshlrev_b32_e32 v71, 16, v6
	v_and_b32_e32 v78, 0xffff0000, v6
	v_lshlrev_b32_e32 v80, 16, v7
	v_and_b32_e32 v81, 0xffff0000, v7
	v_lshlrev_b32_e32 v82, 16, v8
	v_and_b32_e32 v83, 0xffff0000, v8
	v_lshlrev_b32_e32 v84, 16, v9
	v_and_b32_e32 v85, 0xffff0000, v9
	flat_load_dwordx4 v[6:9], v[22:23] offset:1024
	v_add_f32_e32 v35, v35, v71
	v_add_f32_e32 v40, v40, v78
	v_add_f32_e32 v57, v57, v80
	v_add_f32_e32 v60, v60, v81
	v_add_f32_e32 v61, v61, v82
	v_add_f32_e32 v62, v62, v83
	v_add_f32_e32 v63, v63, v84
	v_add_f32_e32 v33, v33, v85
	s_waitcnt vmcnt(0) lgkmcnt(0)
	v_lshlrev_b32_e32 v71, 16, v10
	v_and_b32_e32 v78, 0xffff0000, v10
	v_lshlrev_b32_e32 v80, 16, v11
	v_and_b32_e32 v81, 0xffff0000, v11
	v_lshlrev_b32_e32 v82, 16, v12
	v_and_b32_e32 v83, 0xffff0000, v12
	v_lshlrev_b32_e32 v84, 16, v13
	v_and_b32_e32 v85, 0xffff0000, v13
	flat_load_dwordx4 v[10:13], v[22:23] offset:2048
	v_add_f32_e32 v71, v73, v71
	v_add_f32_e32 v73, v74, v78
	v_add_f32_e32 v74, v75, v80
	v_add_f32_e32 v64, v64, v81
	v_add_f32_e32 v65, v65, v82
	v_add_f32_e32 v66, v66, v83
	v_add_f32_e32 v72, v72, v84
	v_add_f32_e32 v67, v67, v85
	v_lshlrev_b32_e32 v75, 16, v14
	v_and_b32_e32 v78, 0xffff0000, v14
	v_lshlrev_b32_e32 v80, 16, v15
	v_and_b32_e32 v81, 0xffff0000, v15
	v_lshlrev_b32_e32 v82, 16, v16
	v_and_b32_e32 v83, 0xffff0000, v16
	v_lshlrev_b32_e32 v84, 16, v17
	v_and_b32_e32 v85, 0xffff0000, v17
	flat_load_dwordx4 v[14:17], v[22:23] offset:3072
	v_add_f32_e32 v88, v91, v90
	v_add_f32_e32 v76, v87, v76
	v_add_f32_e32 v77, v88, v77
	v_add_f32_e32 v75, v79, v75
	v_add_f32_e32 v68, v68, v78
	v_add_f32_e32 v76, v76, v80
	v_add_f32_e32 v69, v69, v81
	v_add_f32_e32 v77, v77, v82
	v_add_f32_e32 v24, v24, v83
	v_add_f32_e32 v70, v70, v84
	v_add_f32_e32 v25, v25, v85
	v_and_b32_e32 v85, 0xffff0000, v5
	v_add_f32_e32 v33, v33, v85
	v_lshlrev_b32_e32 v22, 16, v18
	v_add_f32_e32 v34, v34, v22
	v_add_co_u32_e32 v22, vcc, s25, v0
	v_and_b32_e32 v78, 0xffff0000, v18
	v_lshlrev_b32_e32 v79, 16, v19
	v_and_b32_e32 v80, 0xffff0000, v19
	v_lshlrev_b32_e32 v81, 16, v20
	v_and_b32_e32 v82, 0xffff0000, v20
	v_lshlrev_b32_e32 v83, 16, v21
	v_and_b32_e32 v84, 0xffff0000, v21
	v_addc_co_u32_e32 v23, vcc, 0, v1, vcc
	flat_load_dwordx4 v[18:21], v[22:23]
	v_add_f32_e32 v26, v26, v78
	v_add_f32_e32 v30, v30, v79
	v_add_f32_e32 v27, v27, v80
	v_add_f32_e32 v31, v31, v81
	v_add_f32_e32 v28, v28, v82
	v_add_f32_e32 v32, v32, v83
	v_add_f32_e32 v29, v29, v84
	v_lshlrev_b32_e32 v78, 16, v2
	v_and_b32_e32 v79, 0xffff0000, v2
	v_lshlrev_b32_e32 v80, 16, v3
	v_and_b32_e32 v81, 0xffff0000, v3
	v_lshlrev_b32_e32 v82, 16, v4
	v_and_b32_e32 v83, 0xffff0000, v4
	v_lshlrev_b32_e32 v84, 16, v5
	v_add_f32_e32 v35, v35, v78
	flat_load_dwordx4 v[2:5], v[22:23] offset:1024
	v_add_f32_e32 v40, v40, v79
	v_add_f32_e32 v57, v57, v80
	v_add_f32_e32 v60, v60, v81
	v_add_f32_e32 v61, v61, v82
	v_add_f32_e32 v62, v62, v83
	v_add_f32_e32 v63, v63, v84
	v_lshlrev_b32_e32 v78, 16, v6
	v_and_b32_e32 v79, 0xffff0000, v6
	v_lshlrev_b32_e32 v80, 16, v7
	v_and_b32_e32 v81, 0xffff0000, v7
	v_lshlrev_b32_e32 v82, 16, v8
	v_and_b32_e32 v83, 0xffff0000, v8
	v_lshlrev_b32_e32 v84, 16, v9
	v_and_b32_e32 v85, 0xffff0000, v9
	v_add_f32_e32 v71, v71, v78
	flat_load_dwordx4 v[6:9], v[22:23] offset:2048
	v_add_f32_e32 v73, v73, v79
	v_add_f32_e32 v74, v74, v80
	v_add_f32_e32 v64, v64, v81
	v_add_f32_e32 v65, v65, v82
	v_add_f32_e32 v66, v66, v83
	v_add_f32_e32 v72, v72, v84
	v_add_f32_e32 v67, v67, v85
	s_waitcnt vmcnt(0) lgkmcnt(0)
	v_lshlrev_b32_e32 v78, 16, v10
	v_and_b32_e32 v79, 0xffff0000, v10
	v_lshlrev_b32_e32 v80, 16, v11
	v_and_b32_e32 v81, 0xffff0000, v11
	v_lshlrev_b32_e32 v82, 16, v12
	v_and_b32_e32 v83, 0xffff0000, v12
	v_lshlrev_b32_e32 v84, 16, v13
	v_and_b32_e32 v85, 0xffff0000, v13
	flat_load_dwordx4 v[10:13], v[22:23] offset:3072
	v_lshlrev_b32_e32 v22, 16, v14
	v_add_f32_e32 v34, v34, v22
	v_add_co_u32_e32 v22, vcc, s29, v0
	v_add_f32_e32 v75, v75, v78
	s_nop 0
	v_addc_co_u32_e32 v23, vcc, 0, v1, vcc
	v_add_f32_e32 v68, v68, v79
	v_add_f32_e32 v76, v76, v80
	v_add_f32_e32 v69, v69, v81
	v_add_f32_e32 v77, v77, v82
	v_add_f32_e32 v24, v24, v83
	v_add_f32_e32 v70, v70, v84
	v_and_b32_e32 v78, 0xffff0000, v14
	v_lshlrev_b32_e32 v79, 16, v15
	v_and_b32_e32 v80, 0xffff0000, v15
	v_lshlrev_b32_e32 v81, 16, v16
	v_and_b32_e32 v82, 0xffff0000, v16
	v_lshlrev_b32_e32 v83, 16, v17
	v_and_b32_e32 v84, 0xffff0000, v17
	flat_load_dwordx4 v[14:17], v[22:23]
	v_add_f32_e32 v25, v25, v85
	v_add_f32_e32 v26, v26, v78
	v_add_f32_e32 v30, v30, v79
	v_add_f32_e32 v27, v27, v80
	v_add_f32_e32 v31, v31, v81
	v_add_f32_e32 v28, v28, v82
	v_add_f32_e32 v32, v32, v83
	v_add_f32_e32 v29, v29, v84
	v_lshlrev_b32_e32 v78, 16, v18
	v_and_b32_e32 v79, 0xffff0000, v18
	v_lshlrev_b32_e32 v80, 16, v19
	v_and_b32_e32 v81, 0xffff0000, v19
	v_lshlrev_b32_e32 v82, 16, v20
	v_and_b32_e32 v83, 0xffff0000, v20
	v_lshlrev_b32_e32 v84, 16, v21
	v_and_b32_e32 v85, 0xffff0000, v21
	v_add_f32_e32 v35, v35, v78
	v_add_f32_e32 v40, v40, v79
	v_add_f32_e32 v57, v57, v80
	v_add_f32_e32 v60, v60, v81
	v_add_f32_e32 v61, v61, v82
	v_add_f32_e32 v62, v62, v83
	v_add_f32_e32 v63, v63, v84
	v_add_f32_e32 v33, v33, v85
	v_lshlrev_b32_e32 v78, 16, v2
	v_and_b32_e32 v79, 0xffff0000, v2
	v_lshlrev_b32_e32 v80, 16, v3
	v_and_b32_e32 v81, 0xffff0000, v3
	v_lshlrev_b32_e32 v82, 16, v4
	v_and_b32_e32 v83, 0xffff0000, v4
	v_lshlrev_b32_e32 v84, 16, v5
	v_and_b32_e32 v85, 0xffff0000, v5
	flat_load_dwordx4 v[18:21], v[22:23] offset:1024
	v_add_f32_e32 v71, v71, v78
	flat_load_dwordx4 v[2:5], v[22:23] offset:2048
	v_add_f32_e32 v73, v73, v79
	v_add_f32_e32 v74, v74, v80
	v_add_f32_e32 v64, v64, v81
	v_add_f32_e32 v65, v65, v82
	v_add_f32_e32 v66, v66, v83
	v_add_f32_e32 v72, v72, v84
	v_add_f32_e32 v67, v67, v85
	v_lshlrev_b32_e32 v78, 16, v6
	v_and_b32_e32 v79, 0xffff0000, v6
	v_lshlrev_b32_e32 v80, 16, v7
	v_and_b32_e32 v81, 0xffff0000, v7
	v_lshlrev_b32_e32 v82, 16, v8
	v_and_b32_e32 v83, 0xffff0000, v8
	v_lshlrev_b32_e32 v84, 16, v9
	v_and_b32_e32 v85, 0xffff0000, v9
	flat_load_dwordx4 v[6:9], v[22:23] offset:3072
	v_add_f32_e32 v75, v75, v78
	v_add_f32_e32 v68, v68, v79
	v_add_f32_e32 v76, v76, v80
	v_add_f32_e32 v69, v69, v81
	v_add_f32_e32 v77, v77, v82
	s_waitcnt vmcnt(0) lgkmcnt(0)
	v_lshlrev_b32_e32 v22, 16, v10
	v_add_f32_e32 v34, v34, v22
	v_add_co_u32_e32 v22, vcc, s52, v0
	v_add_f32_e32 v24, v24, v83
	s_nop 0
	v_addc_co_u32_e32 v23, vcc, 0, v1, vcc
	v_add_f32_e32 v70, v70, v84
	v_and_b32_e32 v78, 0xffff0000, v10
	v_lshlrev_b32_e32 v79, 16, v11
	v_and_b32_e32 v80, 0xffff0000, v11
	v_lshlrev_b32_e32 v81, 16, v12
	v_and_b32_e32 v82, 0xffff0000, v12
	v_lshlrev_b32_e32 v83, 16, v13
	v_and_b32_e32 v84, 0xffff0000, v13
	flat_load_dwordx4 v[10:13], v[22:23]
	v_add_f32_e32 v25, v25, v85
	v_add_f32_e32 v26, v26, v78
	v_add_f32_e32 v30, v30, v79
	v_add_f32_e32 v27, v27, v80
	v_add_f32_e32 v31, v31, v81
	v_add_f32_e32 v28, v28, v82
	v_add_f32_e32 v32, v32, v83
	v_add_f32_e32 v29, v29, v84
	v_lshlrev_b32_e32 v78, 16, v14
	v_and_b32_e32 v79, 0xffff0000, v14
	v_lshlrev_b32_e32 v80, 16, v15
	v_and_b32_e32 v81, 0xffff0000, v15
	v_lshlrev_b32_e32 v82, 16, v16
	v_and_b32_e32 v83, 0xffff0000, v16
	v_lshlrev_b32_e32 v84, 16, v17
	v_and_b32_e32 v85, 0xffff0000, v17
	flat_load_dwordx4 v[14:17], v[22:23] offset:1024
	v_add_f32_e32 v35, v35, v78
	v_add_f32_e32 v57, v57, v80
	v_add_f32_e32 v60, v60, v81
	v_add_f32_e32 v61, v61, v82
	v_add_f32_e32 v62, v62, v83
	v_add_f32_e32 v40, v40, v79
	v_add_f32_e32 v63, v63, v84
	v_add_f32_e32 v33, v33, v85
	v_add_co_u32_e32 v0, vcc, s53, v0
	v_lshlrev_b32_e32 v78, 16, v18
	v_lshlrev_b32_e32 v80, 16, v19
	v_and_b32_e32 v81, 0xffff0000, v19
	v_lshlrev_b32_e32 v82, 16, v20
	v_and_b32_e32 v83, 0xffff0000, v20
	v_and_b32_e32 v79, 0xffff0000, v18
	v_lshlrev_b32_e32 v84, 16, v21
	v_and_b32_e32 v85, 0xffff0000, v21
	v_add_f32_e32 v71, v71, v78
	flat_load_dwordx4 v[18:21], v[22:23] offset:2048
	v_add_f32_e32 v74, v74, v80
	v_add_f32_e32 v64, v64, v81
	v_add_f32_e32 v65, v65, v82
	v_add_f32_e32 v66, v66, v83
	v_lshlrev_b32_e32 v78, 16, v2
	v_lshlrev_b32_e32 v80, 16, v3
	v_and_b32_e32 v81, 0xffff0000, v3
	v_lshlrev_b32_e32 v82, 16, v4
	v_and_b32_e32 v83, 0xffff0000, v4
	v_add_f32_e32 v73, v73, v79
	v_add_f32_e32 v72, v72, v84
	v_add_f32_e32 v67, v67, v85
	v_and_b32_e32 v79, 0xffff0000, v2
	v_lshlrev_b32_e32 v84, 16, v5
	v_and_b32_e32 v85, 0xffff0000, v5
	v_add_f32_e32 v75, v75, v78
	flat_load_dwordx4 v[2:5], v[22:23] offset:3072
	v_add_f32_e32 v76, v76, v80
	v_add_f32_e32 v69, v69, v81
	v_add_f32_e32 v77, v77, v82
	v_add_f32_e32 v78, v24, v83
	v_lshlrev_b32_e32 v80, 16, v6
	v_lshlrev_b32_e32 v81, 16, v7
	v_addc_co_u32_e32 v1, vcc, 0, v1, vcc
	v_lshlrev_b32_e32 v82, 16, v8
	v_lshlrev_b32_e32 v83, 16, v9
	v_add_f32_e32 v68, v68, v79
	v_add_f32_e32 v79, v25, v85
	flat_load_dwordx4 v[22:25], v[0:1]
	v_add_f32_e32 v34, v34, v80
	v_add_f32_e32 v30, v30, v81
	v_add_f32_e32 v31, v31, v82
	v_add_f32_e32 v32, v32, v83
	s_waitcnt vmcnt(0) lgkmcnt(0)
	v_lshlrev_b32_e32 v80, 16, v10
	v_and_b32_e32 v10, 0xffff0000, v10
	v_lshlrev_b32_e32 v81, 16, v11
	v_and_b32_e32 v11, 0xffff0000, v11
	v_lshlrev_b32_e32 v82, 16, v12
	v_and_b32_e32 v12, 0xffff0000, v12
	v_lshlrev_b32_e32 v83, 16, v13
	v_and_b32_e32 v13, 0xffff0000, v13
	v_and_b32_e32 v6, 0xffff0000, v6
	v_and_b32_e32 v7, 0xffff0000, v7
	v_and_b32_e32 v8, 0xffff0000, v8
	v_and_b32_e32 v9, 0xffff0000, v9
	v_add_f32_e32 v35, v35, v80
	v_add_f32_e32 v40, v40, v10
	v_add_f32_e32 v57, v57, v81
	v_add_f32_e32 v60, v60, v11
	v_add_f32_e32 v61, v61, v82
	v_add_f32_e32 v62, v62, v12
	v_add_f32_e32 v63, v63, v83
	v_add_f32_e32 v33, v33, v13
	v_lshlrev_b32_e32 v80, 16, v14
	v_and_b32_e32 v14, 0xffff0000, v14
	flat_load_dwordx4 v[10:13], v[0:1] offset:2048
	v_lshlrev_b32_e32 v81, 16, v15
	v_and_b32_e32 v15, 0xffff0000, v15
	v_lshlrev_b32_e32 v82, 16, v16
	v_and_b32_e32 v16, 0xffff0000, v16
	v_lshlrev_b32_e32 v83, 16, v17
	v_and_b32_e32 v17, 0xffff0000, v17
	v_add_f32_e32 v26, v26, v6
	v_add_f32_e32 v27, v27, v7
	v_add_f32_e32 v28, v28, v8
	v_add_f32_e32 v29, v29, v9
	flat_load_dwordx4 v[6:9], v[0:1] offset:1024
	v_add_f32_e32 v73, v73, v14
	v_add_f32_e32 v64, v64, v15
	v_add_f32_e32 v66, v66, v16
	v_add_f32_e32 v67, v67, v17
	flat_load_dwordx4 v[14:17], v[0:1] offset:3072
	v_add_f32_e32 v70, v70, v84
	v_add_f32_e32 v71, v71, v80
	v_add_f32_e32 v74, v74, v81
	v_add_f32_e32 v65, v65, v82
	v_add_f32_e32 v72, v72, v83
	v_lshlrev_b32_e32 v80, 16, v18
	v_and_b32_e32 v0, 0xffff0000, v18
	v_lshlrev_b32_e32 v1, 16, v19
	v_and_b32_e32 v18, 0xffff0000, v19
	v_lshlrev_b32_e32 v81, 16, v21
	v_lshlrev_b32_e32 v19, 16, v20
	v_add_f32_e32 v0, v68, v0
	v_add_f32_e32 v1, v76, v1
	v_add_f32_e32 v18, v69, v18
	v_add_f32_e32 v68, v70, v81
	v_add_f32_e32 v19, v77, v19
	v_and_b32_e32 v20, 0xffff0000, v20
	v_and_b32_e32 v21, 0xffff0000, v21
	v_add_f32_e32 v75, v75, v80
	v_add_f32_e32 v20, v78, v20
	v_add_f32_e32 v21, v79, v21
	v_lshlrev_b32_e32 v69, 16, v2
	v_and_b32_e32 v2, 0xffff0000, v2
	v_lshlrev_b32_e32 v70, 16, v3
	v_and_b32_e32 v3, 0xffff0000, v3
	v_lshlrev_b32_e32 v76, 16, v4
	v_and_b32_e32 v4, 0xffff0000, v4
	v_lshlrev_b32_e32 v77, 16, v5
	v_and_b32_e32 v5, 0xffff0000, v5
	v_add_f32_e32 v2, v26, v2
	v_add_f32_e32 v26, v30, v70
	v_add_f32_e32 v3, v27, v3
	v_add_f32_e32 v27, v31, v76
	v_add_f32_e32 v4, v28, v4
	v_lshlrev_b32_e32 v30, 16, v23
	v_and_b32_e32 v23, 0xffff0000, v23
	v_lshlrev_b32_e32 v31, 16, v24
	v_and_b32_e32 v24, 0xffff0000, v24
	v_add_f32_e32 v28, v32, v77
	v_add_f32_e32 v5, v29, v5
	v_lshlrev_b32_e32 v29, 16, v22
	v_and_b32_e32 v22, 0xffff0000, v22
	v_lshlrev_b32_e32 v32, 16, v25
	v_add_f32_e32 v23, v60, v23
	v_add_f32_e32 v31, v61, v31
	v_add_f32_e32 v24, v62, v24
	v_add_f32_e32 v34, v34, v69
	v_and_b32_e32 v25, 0xffff0000, v25
	v_add_f32_e32 v29, v35, v29
	v_add_f32_e32 v22, v40, v22
	v_add_f32_e32 v32, v63, v32
	v_add_f32_e32 v30, v57, v30
	v_add_f32_e32 v25, v33, v25
	s_waitcnt vmcnt(0) lgkmcnt(0)
	v_lshlrev_b32_e32 v60, 16, v10
	v_and_b32_e32 v10, 0xffff0000, v10
	v_lshlrev_b32_e32 v61, 16, v11
	v_and_b32_e32 v11, 0xffff0000, v11
	v_lshlrev_b32_e32 v62, 16, v12
	v_lshlrev_b32_e32 v63, 16, v13
	v_add_f32_e32 v10, v0, v10
	v_add_f32_e32 v61, v1, v61
	v_add_f32_e32 v11, v18, v11
	v_add_f32_e32 v62, v19, v62
	v_add_f32_e32 v63, v68, v63
	v_lshlrev_b32_e32 v35, 16, v7
	v_and_b32_e32 v7, 0xffff0000, v7
	v_lshlrev_b32_e32 v40, 16, v8
	v_and_b32_e32 v8, 0xffff0000, v8
	v_lshlrev_b32_e32 v33, 16, v6
	v_lshlrev_b32_e32 v0, 16, v14
	v_and_b32_e32 v1, 0xffff0000, v14
	v_lshlrev_b32_e32 v14, 16, v15
	v_and_b32_e32 v15, 0xffff0000, v15
	v_lshlrev_b32_e32 v18, 16, v16
	v_and_b32_e32 v16, 0xffff0000, v16
	v_lshlrev_b32_e32 v19, 16, v17
	v_and_b32_e32 v17, 0xffff0000, v17
	v_and_b32_e32 v6, 0xffff0000, v6
	v_lshlrev_b32_e32 v57, 16, v9
	v_and_b32_e32 v9, 0xffff0000, v9
	v_add_f32_e32 v7, v64, v7
	v_add_f32_e32 v8, v66, v8
	v_add_f32_e32 v34, v34, v0
	v_add_f32_e32 v64, v2, v1
	v_add_f32_e32 v66, v3, v15
	v_add_f32_e32 v68, v4, v16
	v_add_f32_e32 v70, v5, v17
	v_lshl_add_u64 v[4:5], v[38:39], 0, s[50:51]
	v_cvt_pk_bf16_f32 v0, v29, v22
	v_cvt_pk_bf16_f32 v1, v30, v23
	v_cvt_pk_bf16_f32 v2, v31, v24
	v_cvt_pk_bf16_f32 v3, v32, v25
	v_add_f32_e32 v33, v71, v33
	v_add_f32_e32 v6, v73, v6
	v_add_f32_e32 v35, v74, v35
	v_add_f32_e32 v40, v65, v40
	v_add_f32_e32 v57, v72, v57
	v_add_f32_e32 v9, v67, v9
	v_and_b32_e32 v12, 0xffff0000, v12
	v_and_b32_e32 v13, 0xffff0000, v13
	v_add_f32_e32 v65, v26, v14
	v_add_f32_e32 v67, v27, v18
	v_add_f32_e32 v69, v28, v19
	flat_store_dwordx4 v[4:5], v[0:3] sc1
	v_lshlrev_b32_e32 v24, 16, v0
	v_and_b32_e32 v25, 0xffff0000, v0
	v_lshlrev_b32_e32 v26, 16, v1
	v_and_b32_e32 v27, 0xffff0000, v1
	v_lshlrev_b32_e32 v28, 16, v2
	v_and_b32_e32 v29, 0xffff0000, v2
	v_lshlrev_b32_e32 v30, 16, v3
	v_and_b32_e32 v31, 0xffff0000, v3
	v_cvt_pk_bf16_f32 v0, v33, v6
	v_cvt_pk_bf16_f32 v1, v35, v7
	v_cvt_pk_bf16_f32 v2, v40, v8
	v_cvt_pk_bf16_f32 v3, v57, v9
	v_add_f32_e32 v60, v75, v60
	v_add_f32_e32 v12, v20, v12
	v_add_f32_e32 v13, v21, v13
	flat_store_dwordx4 v[4:5], v[0:3] offset:1024 sc1
	v_lshlrev_b32_e32 v16, 16, v0
	v_and_b32_e32 v17, 0xffff0000, v0
	v_lshlrev_b32_e32 v18, 16, v1
	v_and_b32_e32 v19, 0xffff0000, v1
	v_lshlrev_b32_e32 v20, 16, v2
	v_and_b32_e32 v21, 0xffff0000, v2
	v_lshlrev_b32_e32 v22, 16, v3
	v_and_b32_e32 v23, 0xffff0000, v3
	v_cvt_pk_bf16_f32 v0, v60, v10
	v_cvt_pk_bf16_f32 v1, v61, v11
	v_cvt_pk_bf16_f32 v2, v62, v12
	v_cvt_pk_bf16_f32 v3, v63, v13
	flat_store_dwordx4 v[4:5], v[0:3] offset:2048 sc1
	v_lshlrev_b32_e32 v8, 16, v0
	v_and_b32_e32 v9, 0xffff0000, v0
	v_lshlrev_b32_e32 v10, 16, v1
	v_and_b32_e32 v11, 0xffff0000, v1
	v_lshlrev_b32_e32 v12, 16, v2
	v_and_b32_e32 v13, 0xffff0000, v2
	v_lshlrev_b32_e32 v14, 16, v3
	v_and_b32_e32 v15, 0xffff0000, v3
	v_cvt_pk_bf16_f32 v32, v34, v64
	v_cvt_pk_bf16_f32 v33, v65, v66
	v_cvt_pk_bf16_f32 v34, v67, v68
	v_cvt_pk_bf16_f32 v35, v69, v70
	flat_store_dwordx4 v[4:5], v[32:35] offset:3072 sc1
	v_lshlrev_b32_e32 v0, 16, v32
	v_and_b32_e32 v1, 0xffff0000, v32
	v_lshlrev_b32_e32 v2, 16, v33
	v_and_b32_e32 v3, 0xffff0000, v33
	v_lshlrev_b32_e32 v4, 16, v34
	v_and_b32_e32 v5, 0xffff0000, v34
	s_mov_b64 s[50:51], 0

.LBB0_1041:
	v_lshl_add_u64 v[0:1], v[42:43], 0, s[46:47]
	s_ashr_i32 s45, s44, 31
	flat_load_dwordx4 v[12:15], v[0:1] offset:1024
	flat_load_dwordx4 v[26:29], v[0:1] offset:2048
	flat_load_dwordx4 v[22:25], v[0:1]
	flat_load_dwordx4 v[4:7], v[0:1] offset:3072
	s_lshl_b64 s[48:49], s[44:45], 12
	v_lshl_add_u64 v[0:1], v[42:43], 0, s[48:49]
	flat_load_dwordx4 v[94:97], v[0:1] offset:1024
	flat_load_dwordx4 v[8:11], v[0:1] offset:2048
	flat_load_dwordx4 v[98:101], v[0:1]
	s_nop 0
	flat_load_dwordx4 v[0:3], v[0:1] offset:3072
	s_nop 0
	global_load_dwordx4 v[102:105], v[44:45], off offset:16
	global_load_dwordx4 v[106:109], v[44:45], off
	v_lshl_add_u64 v[112:113], v[52:53], 0, s[46:47]
	s_waitcnt vmcnt(0) lgkmcnt(0)
	v_and_b32_e32 v65, 0xffff0000, v12
	v_lshlrev_b32_e32 v35, 16, v12
	v_and_b32_e32 v87, 0xffff0000, v22
	v_and_b32_e32 v86, 0xffff0000, v98
	v_lshlrev_b32_e32 v73, 16, v22
	v_lshlrev_b32_e32 v59, 16, v13
	v_and_b32_e32 v71, 0xffff0000, v13
	v_lshlrev_b32_e32 v61, 16, v14
	v_and_b32_e32 v69, 0xffff0000, v14
	v_lshlrev_b32_e32 v13, 16, v4
	v_and_b32_e32 v17, 0xffff0000, v4
	v_lshlrev_b32_e32 v72, 16, v98
	v_lshlrev_b32_e32 v12, 16, v0
	v_and_b32_e32 v16, 0xffff0000, v0
	v_lshlrev_b32_e32 v14, 16, v1
	v_and_b32_e32 v4, 0xffff0000, v1
	v_pk_mul_f32 v[0:1], v[86:87], v[86:87]
	v_lshlrev_b32_e32 v75, 16, v23
	v_lshlrev_b32_e32 v74, 16, v99
	v_pk_fma_f32 v[0:1], v[72:73], v[72:73], v[0:1]
	v_and_b32_e32 v81, 0xffff0000, v23
	v_and_b32_e32 v80, 0xffff0000, v99
	v_pk_fma_f32 v[0:1], v[74:75], v[74:75], v[0:1]
	v_lshlrev_b32_e32 v77, 16, v24
	v_lshlrev_b32_e32 v76, 16, v100
	v_pk_fma_f32 v[0:1], v[80:81], v[80:81], v[0:1]
	v_and_b32_e32 v83, 0xffff0000, v24
	v_and_b32_e32 v82, 0xffff0000, v100
	v_pk_fma_f32 v[0:1], v[76:77], v[76:77], v[0:1]
	v_lshlrev_b32_e32 v79, 16, v25
	v_lshlrev_b32_e32 v78, 16, v101
	v_pk_fma_f32 v[0:1], v[82:83], v[82:83], v[0:1]
	v_and_b32_e32 v85, 0xffff0000, v25
	v_and_b32_e32 v84, 0xffff0000, v101
	v_pk_fma_f32 v[0:1], v[78:79], v[78:79], v[0:1]
	v_lshlrev_b32_e32 v34, 16, v94
	v_pk_fma_f32 v[0:1], v[84:85], v[84:85], v[0:1]
	v_and_b32_e32 v64, 0xffff0000, v94
	v_pk_fma_f32 v[0:1], v[34:35], v[34:35], v[0:1]
	v_lshlrev_b32_e32 v58, 16, v95
	v_pk_fma_f32 v[0:1], v[64:65], v[64:65], v[0:1]
	v_and_b32_e32 v70, 0xffff0000, v95
	v_pk_fma_f32 v[0:1], v[58:59], v[58:59], v[0:1]
	v_lshlrev_b32_e32 v60, 16, v96
	v_pk_fma_f32 v[0:1], v[70:71], v[70:71], v[0:1]
	v_and_b32_e32 v68, 0xffff0000, v96
	v_pk_fma_f32 v[0:1], v[60:61], v[60:61], v[0:1]
	v_lshlrev_b32_e32 v63, 16, v15
	v_lshlrev_b32_e32 v62, 16, v97
	v_pk_fma_f32 v[0:1], v[68:69], v[68:69], v[0:1]
	v_and_b32_e32 v67, 0xffff0000, v15
	v_and_b32_e32 v66, 0xffff0000, v97
	v_pk_fma_f32 v[0:1], v[62:63], v[62:63], v[0:1]
	v_lshlrev_b32_e32 v23, 16, v26
	v_lshlrev_b32_e32 v22, 16, v8
	v_pk_fma_f32 v[0:1], v[66:67], v[66:67], v[0:1]
	v_and_b32_e32 v33, 0xffff0000, v26
	v_and_b32_e32 v32, 0xffff0000, v8
	v_pk_fma_f32 v[0:1], v[22:23], v[22:23], v[0:1]
	v_lshlrev_b32_e32 v25, 16, v27
	v_lshlrev_b32_e32 v24, 16, v9
	v_pk_fma_f32 v[0:1], v[32:33], v[32:33], v[0:1]
	v_and_b32_e32 v21, 0xffff0000, v27
	v_and_b32_e32 v20, 0xffff0000, v9
	v_pk_fma_f32 v[0:1], v[24:25], v[24:25], v[0:1]
	v_lshlrev_b32_e32 v19, 16, v28
	v_lshlrev_b32_e32 v18, 16, v10
	v_pk_fma_f32 v[0:1], v[20:21], v[20:21], v[0:1]
	v_and_b32_e32 v31, 0xffff0000, v28
	v_and_b32_e32 v30, 0xffff0000, v10
	v_pk_fma_f32 v[0:1], v[18:19], v[18:19], v[0:1]
	v_lshlrev_b32_e32 v27, 16, v29
	v_lshlrev_b32_e32 v26, 16, v11
	v_pk_fma_f32 v[0:1], v[30:31], v[30:31], v[0:1]
	v_and_b32_e32 v29, 0xffff0000, v29
	v_and_b32_e32 v28, 0xffff0000, v11
	v_pk_fma_f32 v[0:1], v[26:27], v[26:27], v[0:1]
	v_and_b32_e32 v88, 0xffff0000, v6
	v_pk_fma_f32 v[0:1], v[28:29], v[28:29], v[0:1]
	v_lshlrev_b32_e32 v91, 16, v6
	v_and_b32_e32 v6, 0xffff0000, v2
	v_pk_fma_f32 v[0:1], v[12:13], v[12:13], v[0:1]
	v_lshlrev_b32_e32 v15, 16, v5
	v_mov_b32_e32 v90, v88
	v_lshlrev_b32_e32 v9, 16, v2
	v_mov_b32_e32 v8, v6
	v_pk_fma_f32 v[0:1], v[16:17], v[16:17], v[0:1]
	v_and_b32_e32 v5, 0xffff0000, v5
	v_pk_mul_f32 v[94:95], v[90:91], v[90:91]
	v_pk_mul_f32 v[98:99], v[8:9], v[8:9]
	v_pk_fma_f32 v[0:1], v[14:15], v[14:15], v[0:1]
	v_mov_b32_e32 v11, v95
	v_mov_b32_e32 v10, v99
	v_pk_fma_f32 v[0:1], v[4:5], v[4:5], v[0:1]
	v_and_b32_e32 v40, 0xffff0000, v7
	v_pk_add_f32 v[100:101], v[10:11], v[0:1]
	v_and_b32_e32 v0, 0xffff0000, v3
	v_lshlrev_b32_e32 v93, 16, v7
	v_mov_b32_e32 v92, v40
	v_lshlrev_b32_e32 v11, 16, v3
	v_mov_b32_e32 v10, v0
	v_and_b32_e32 v1, 64, v196
	v_pk_mul_f32 v[96:97], v[92:93], v[92:93]
	v_pk_mul_f32 v[110:111], v[10:11], v[10:11]
	v_add_u32_e32 v1, 64, v1
	v_xor_b32_e32 v2, 1, v196
	v_mov_b32_e32 v99, v94
	v_cmp_lt_i32_e32 vcc, v2, v1
	v_pk_add_f32 v[94:95], v[98:99], v[100:101]
	v_mov_b32_e32 v98, v111
	v_mov_b32_e32 v99, v97
	v_cndmask_b32_e32 v2, v196, v2, vcc
	v_pk_add_f32 v[94:95], v[98:99], v[94:95]
	v_mov_b32_e32 v111, v96
	v_lshlrev_b32_e32 v2, 2, v2
	v_pk_add_f32 v[94:95], v[110:111], v[94:95]
	ds_bpermute_b32 v97, v2, v95
	ds_bpermute_b32 v96, v2, v94
	v_xor_b32_e32 v2, 2, v196
	v_cmp_lt_i32_e32 vcc, v2, v1
	v_mov_b32_e32 v98, v77
	v_mov_b32_e32 v99, v83
	v_cndmask_b32_e32 v2, v196, v2, vcc
	v_lshlrev_b32_e32 v2, 2, v2
	s_waitcnt lgkmcnt(0)
	v_pk_add_f32 v[94:95], v[94:95], v[96:97]
	ds_bpermute_b32 v97, v2, v95
	ds_bpermute_b32 v96, v2, v94
	v_xor_b32_e32 v2, 4, v196
	v_cmp_lt_i32_e32 vcc, v2, v1
	v_mov_b32_e32 v100, v79
	v_mov_b32_e32 v101, v85
	v_cndmask_b32_e32 v2, v196, v2, vcc
	v_lshlrev_b32_e32 v2, 2, v2
	s_waitcnt lgkmcnt(0)
	v_pk_add_f32 v[94:95], v[94:95], v[96:97]
	ds_bpermute_b32 v97, v2, v95
	ds_bpermute_b32 v96, v2, v94
	v_xor_b32_e32 v2, 8, v196
	v_cmp_lt_i32_e32 vcc, v2, v1
	v_and_b32_e32 v89, s0, v7
	v_pk_mov_b32 v[88:89], v[90:91], v[88:89] op_sel:[1,0]
	v_cndmask_b32_e32 v2, v196, v2, vcc
	v_lshlrev_b32_e32 v2, 2, v2
	s_waitcnt lgkmcnt(0)
	v_pk_add_f32 v[94:95], v[94:95], v[96:97]
	ds_bpermute_b32 v97, v2, v95
	ds_bpermute_b32 v96, v2, v94
	v_xor_b32_e32 v2, 16, v196
	v_cmp_lt_i32_e32 vcc, v2, v1
	v_pk_mov_b32 v[90:91], v[92:93], v[40:41] op_sel:[1,0]
	v_mov_b32_e32 v77, v82
	v_cndmask_b32_e32 v2, v196, v2, vcc
	v_lshlrev_b32_e32 v2, 2, v2
	s_waitcnt lgkmcnt(0)
	v_pk_add_f32 v[94:95], v[94:95], v[96:97]
	ds_bpermute_b32 v97, v2, v95
	ds_bpermute_b32 v96, v2, v94
	v_xor_b32_e32 v2, 32, v196
	v_cmp_lt_i32_e32 vcc, v2, v1
	v_mov_b32_e32 v79, v84
	v_and_b32_e32 v7, s0, v3
	v_cndmask_b32_e32 v1, v196, v2, vcc
	v_lshlrev_b32_e32 v1, 2, v1
	s_waitcnt lgkmcnt(0)
	v_pk_add_f32 v[94:95], v[94:95], v[96:97]
	ds_bpermute_b32 v97, v1, v95
	ds_bpermute_b32 v96, v1, v94
	v_pk_mov_b32 v[6:7], v[8:9], v[6:7] op_sel:[1,0]
	s_waitcnt lgkmcnt(0)
	v_pk_add_f32 v[94:95], v[94:95], v[96:97]
	s_nop 0
	v_pk_fma_f32 v[110:111], v[94:95], s[12:13], v[56:57] op_sel_hi:[1,0,0]
	v_mov_b32_e32 v94, v73
	v_mul_f32_e32 v1, 0x4b800000, v111
	v_cmp_gt_f32_e32 vcc, s13, v111
	v_mov_b32_e32 v95, v87
	v_mov_b32_e32 v96, v75
	v_cndmask_b32_e32 v1, v111, v1, vcc
	v_rsq_f32_e32 v1, v1
	v_mov_b32_e32 v97, v81
	v_mov_b32_e32 v73, v86
	v_mov_b32_e32 v75, v80
	v_mul_f32_e32 v2, 0x45800000, v1
	v_cndmask_b32_e32 v2, v1, v2, vcc
	v_pk_mul_f32 v[94:95], v[94:95], v[2:3] op_sel_hi:[1,0]
	v_pk_mul_f32 v[96:97], v[96:97], v[2:3] op_sel_hi:[1,0]
	v_pk_mul_f32 v[94:95], v[106:107], v[94:95]
	v_pk_mul_f32 v[96:97], v[108:109], v[96:97]
	v_pk_mul_f32 v[98:99], v[98:99], v[2:3] op_sel_hi:[1,0]
	v_pk_mul_f32 v[100:101], v[100:101], v[2:3] op_sel_hi:[1,0]
	v_pk_mul_f32 v[98:99], v[102:103], v[98:99]
	v_pk_mul_f32 v[100:101], v[104:105], v[100:101]
	v_cvt_pk_bf16_f32 v94, v94, v95
	v_cvt_pk_bf16_f32 v95, v96, v97
	v_cvt_pk_bf16_f32 v96, v98, v99
	v_mov_b32_e32 v102, v35
	v_cvt_pk_bf16_f32 v97, v100, v101
	flat_store_dwordx4 v[112:113], v[94:97] sc1
	global_load_dwordx4 v[94:97], v[44:45], off offset:2048
	s_nop 0
	global_load_dwordx4 v[98:101], v[44:45], off offset:2064
	v_mov_b32_e32 v103, v65
	v_mov_b32_e32 v104, v59
	v_mov_b32_e32 v105, v71
	v_mov_b32_e32 v106, v61
	v_mov_b32_e32 v107, v69
	v_mov_b32_e32 v108, v63
	v_mov_b32_e32 v109, v67
	v_pk_mul_f32 v[102:103], v[102:103], v[2:3] op_sel_hi:[1,0]
	v_pk_mul_f32 v[104:105], v[104:105], v[2:3] op_sel_hi:[1,0]
	v_pk_mul_f32 v[106:107], v[106:107], v[2:3] op_sel_hi:[1,0]
	v_pk_mul_f32 v[108:109], v[108:109], v[2:3] op_sel_hi:[1,0]
	v_pk_mul_f32 v[88:89], v[2:3], v[88:89] op_sel_hi:[0,1]
	v_pk_mul_f32 v[90:91], v[2:3], v[90:91] op_sel_hi:[0,1]
	v_mul_f32_e32 v1, 0x4b800000, v110
	v_cmp_gt_f32_e32 vcc, s13, v110
	v_mov_b32_e32 v61, v68
	v_mov_b32_e32 v35, v64
	v_cndmask_b32_e32 v1, v110, v1, vcc
	v_rsq_f32_e32 v1, v1
	v_mov_b32_e32 v59, v70
	v_mov_b32_e32 v63, v66
	s_waitcnt vmcnt(0)
	v_pk_mul_f32 v[96:97], v[96:97], v[104:105]
	v_pk_mul_f32 v[94:95], v[94:95], v[102:103]
	v_pk_mul_f32 v[100:101], v[100:101], v[108:109]
	v_pk_mul_f32 v[98:99], v[98:99], v[106:107]
	v_cvt_pk_bf16_f32 v94, v94, v95
	v_cvt_pk_bf16_f32 v95, v96, v97
	v_mov_b32_e32 v102, v23
	v_cvt_pk_bf16_f32 v96, v98, v99
	v_cvt_pk_bf16_f32 v97, v100, v101
	flat_store_dwordx4 v[112:113], v[94:97] offset:1024 sc1
	global_load_dwordx4 v[94:97], v[46:47], off
	s_nop 0
	global_load_dwordx4 v[98:101], v[46:47], off offset:16
	v_mov_b32_e32 v103, v33
	v_mov_b32_e32 v104, v25
	v_mov_b32_e32 v105, v21
	v_mov_b32_e32 v106, v19
	v_mov_b32_e32 v107, v31
	v_mov_b32_e32 v108, v27
	v_mov_b32_e32 v109, v29
	v_pk_mul_f32 v[102:103], v[102:103], v[2:3] op_sel_hi:[1,0]
	v_pk_mul_f32 v[104:105], v[104:105], v[2:3] op_sel_hi:[1,0]
	v_pk_mul_f32 v[106:107], v[106:107], v[2:3] op_sel_hi:[1,0]
	v_pk_mul_f32 v[108:109], v[108:109], v[2:3] op_sel_hi:[1,0]
	v_mov_b32_e32 v23, v32
	v_mov_b32_e32 v25, v20
	v_mov_b32_e32 v19, v30
	v_mov_b32_e32 v27, v28
	s_waitcnt vmcnt(0)
	v_pk_mul_f32 v[96:97], v[96:97], v[104:105]
	v_pk_mul_f32 v[94:95], v[94:95], v[102:103]
	v_pk_mul_f32 v[100:101], v[100:101], v[108:109]
	v_pk_mul_f32 v[98:99], v[98:99], v[106:107]
	v_cvt_pk_bf16_f32 v94, v94, v95
	v_cvt_pk_bf16_f32 v95, v96, v97
	v_mov_b32_e32 v102, v13
	v_cvt_pk_bf16_f32 v96, v98, v99
	v_cvt_pk_bf16_f32 v97, v100, v101
	flat_store_dwordx4 v[112:113], v[94:97] offset:2048 sc1
	global_load_dwordx4 v[94:97], v[48:49], off
	s_nop 0
	global_load_dwordx4 v[98:101], v[48:49], off offset:16
	v_mov_b32_e32 v103, v17
	v_mov_b32_e32 v104, v15
	v_mov_b32_e32 v105, v5
	v_pk_mul_f32 v[92:93], v[102:103], v[2:3] op_sel_hi:[1,0]
	v_pk_mul_f32 v[102:103], v[104:105], v[2:3] op_sel_hi:[1,0]
	v_mul_f32_e32 v2, 0x45800000, v1
	v_cndmask_b32_e32 v2, v1, v2, vcc
	v_pk_mul_f32 v[72:73], v[72:73], v[2:3] op_sel_hi:[1,0]
	v_pk_mul_f32 v[74:75], v[74:75], v[2:3] op_sel_hi:[1,0]
	v_pk_mul_f32 v[76:77], v[76:77], v[2:3] op_sel_hi:[1,0]
	v_pk_mul_f32 v[78:79], v[78:79], v[2:3] op_sel_hi:[1,0]
	v_pk_mul_f32 v[60:61], v[60:61], v[2:3] op_sel_hi:[1,0]
	v_pk_mul_f32 v[34:35], v[34:35], v[2:3] op_sel_hi:[1,0]
	v_pk_mul_f32 v[58:59], v[58:59], v[2:3] op_sel_hi:[1,0]
	v_pk_mul_f32 v[62:63], v[62:63], v[2:3] op_sel_hi:[1,0]
	v_pk_mul_f32 v[20:21], v[22:23], v[2:3] op_sel_hi:[1,0]
	v_pk_mul_f32 v[22:23], v[24:25], v[2:3] op_sel_hi:[1,0]
	v_pk_mul_f32 v[18:19], v[18:19], v[2:3] op_sel_hi:[1,0]
	v_pk_mul_f32 v[24:25], v[26:27], v[2:3] op_sel_hi:[1,0]
	v_mov_b32_e32 v1, v41
	v_mov_b32_e32 v15, v4
	v_pk_mov_b32 v[0:1], v[10:11], v[0:1] op_sel:[1,0]
	v_mov_b32_e32 v13, v16
	v_pk_mul_f32 v[8:9], v[14:15], v[2:3] op_sel_hi:[1,0]
	v_pk_mul_f32 v[4:5], v[12:13], v[2:3] op_sel_hi:[1,0]
	v_pk_mul_f32 v[6:7], v[2:3], v[6:7] op_sel_hi:[0,1]
	v_pk_mul_f32 v[0:1], v[2:3], v[0:1] op_sel_hi:[0,1]
	s_waitcnt vmcnt(0)
	v_pk_mul_f32 v[92:93], v[94:95], v[92:93]
	v_pk_mul_f32 v[94:95], v[100:101], v[90:91]
	v_pk_mul_f32 v[90:91], v[98:99], v[88:89]
	v_pk_mul_f32 v[96:97], v[96:97], v[102:103]
	v_cvt_pk_bf16_f32 v88, v92, v93
	s_nop 0
	v_cvt_pk_bf16_f32 v89, v96, v97
	v_cvt_pk_bf16_f32 v90, v90, v91
	v_cvt_pk_bf16_f32 v91, v94, v95
	flat_store_dwordx4 v[112:113], v[88:91] offset:3072 sc1
	global_load_dwordx4 v[88:91], v[44:45], off
	s_nop 0
	global_load_dwordx4 v[92:95], v[44:45], off offset:16
	v_lshl_add_u64 v[96:97], v[52:53], 0, s[48:49]
	s_waitcnt vmcnt(0)
	v_pk_mul_f32 v[74:75], v[90:91], v[74:75]
	v_pk_mul_f32 v[72:73], v[88:89], v[72:73]
	v_pk_mul_f32 v[78:79], v[94:95], v[78:79]
	v_pk_mul_f32 v[76:77], v[92:93], v[76:77]
	v_cvt_pk_bf16_f32 v72, v72, v73
	v_cvt_pk_bf16_f32 v73, v74, v75
	s_nop 0
	v_cvt_pk_bf16_f32 v74, v76, v77
	v_cvt_pk_bf16_f32 v75, v78, v79
	flat_store_dwordx4 v[96:97], v[72:75] sc1
	global_load_dwordx4 v[72:75], v[44:45], off offset:2048
	s_nop 0
	global_load_dwordx4 v[76:79], v[44:45], off offset:2064
	s_waitcnt vmcnt(0)
	v_pk_mul_f32 v[64:65], v[58:59], v[74:75]
	v_pk_mul_f32 v[60:61], v[60:61], v[76:77]
	v_pk_mul_f32 v[34:35], v[34:35], v[72:73]
	v_pk_mul_f32 v[62:63], v[62:63], v[78:79]
	v_cvt_pk_bf16_f32 v58, v34, v35
	v_cvt_pk_bf16_f32 v59, v64, v65
	v_cvt_pk_bf16_f32 v60, v60, v61
	s_nop 0
	v_cvt_pk_bf16_f32 v61, v62, v63
	flat_store_dwordx4 v[96:97], v[58:61] offset:1024 sc1
	global_load_dwordx4 v[58:61], v[46:47], off
	s_nop 0
	global_load_dwordx4 v[62:65], v[46:47], off offset:16
	s_waitcnt vmcnt(0)
	v_pk_mul_f32 v[20:21], v[20:21], v[58:59]
	v_pk_mul_f32 v[22:23], v[22:23], v[60:61]
	v_pk_mul_f32 v[24:25], v[24:25], v[64:65]
	v_pk_mul_f32 v[26:27], v[18:19], v[62:63]
	v_cvt_pk_bf16_f32 v18, v20, v21
	v_cvt_pk_bf16_f32 v19, v22, v23
	s_nop 0
	v_cvt_pk_bf16_f32 v20, v26, v27
	v_cvt_pk_bf16_f32 v21, v24, v25
	flat_store_dwordx4 v[96:97], v[18:21] offset:2048 sc1
	global_load_dwordx4 v[18:21], v[48:49], off
	s_nop 0
	global_load_dwordx4 v[22:25], v[48:49], off offset:16
	s_waitcnt vmcnt(0)
	v_pk_mul_f32 v[2:3], v[8:9], v[20:21]
	v_pk_mul_f32 v[4:5], v[4:5], v[18:19]
	v_pk_mul_f32 v[8:9], v[0:1], v[24:25]
	v_pk_mul_f32 v[6:7], v[6:7], v[22:23]
	v_cvt_pk_bf16_f32 v0, v4, v5
	v_cvt_pk_bf16_f32 v1, v2, v3
	s_nop 0
	v_cvt_pk_bf16_f32 v2, v6, v7
	v_cvt_pk_bf16_f32 v3, v8, v9
	flat_store_dwordx4 v[96:97], v[0:3] offset:3072 sc1
	s_branch .LBB0_1030

.LBB0_1099:
	v_mov_b32_e32 v140, v145
	v_mov_b32_e32 v141, v146
	s_add_i32 s40, s45, s58
	v_add_u32_e32 v140, s40, v140
	v_max_f32_e32 v120, v120, v120
	v_lshl_add_u32 v142, v141, 3, s59
	v_ashrrev_i32_e32 v141, 31, v140
	v_max_f32_e32 v120, 0, v120
	v_max_f32_e32 v121, v121, v121
	v_max_f32_e32 v122, v122, v122
	s_ashr_i32 s45, s44, 31
	v_lshlrev_b64 v[152:153], 14, v[140:141]
	v_mul_f32_e32 v141, v120, v120
	v_max_f32_e32 v120, v125, v125
	v_max_f32_e32 v121, 0, v121
	v_max_f32_e32 v122, 0, v122
	v_ashrrev_i32_e32 v143, 31, v142
	v_lshl_add_u64 v[152:153], s[6:7], 0, v[152:153]
	s_lshl_b64 s[44:45], s[44:45], 1
	v_max_f32_e32 v124, v124, v124
	v_max_f32_e32 v120, 0, v120
	v_mul_f32_e32 v125, v121, v121
	v_max_f32_e32 v121, v126, v126
	v_mul_f32_e32 v126, v122, v122
	v_max_f32_e32 v122, v127, v127
	v_max_f32_e32 v123, v123, v123
	v_lshl_add_u64 v[152:153], v[152:153], 0, s[44:45]
	v_lshlrev_b64 v[142:143], 1, v[142:143]
	v_max_f32_e32 v124, 0, v124
	v_mul_f32_e32 v120, v120, v120
	v_max_f32_e32 v121, 0, v121
	v_max_f32_e32 v122, 0, v122
	v_max_f32_e32 v123, 0, v123
	v_max_f32_e32 v112, v112, v112
	v_lshl_add_u64 v[152:153], v[152:153], 0, v[142:143]
	v_mul_f32_e32 v124, v124, v124
	v_mul_f32_e32 v121, v121, v121
	v_mul_f32_e32 v122, v122, v122
	v_mul_f32_e32 v123, v123, v123
	v_cvt_pk_bf16_f32 v120, v124, v120
	v_max_f32_e32 v112, 0, v112
	v_max_f32_e32 v113, v113, v113
	v_max_f32_e32 v114, v114, v114
	v_cvt_pk_bf16_f32 v121, v121, v122
	v_cvt_pk_bf16_f32 v122, v141, v125
	v_cvt_pk_bf16_f32 v123, v126, v123
	flat_store_dwordx4 v[152:153], v[120:123] sc1
	v_max_f32_e32 v113, 0, v113
	v_max_f32_e32 v114, 0, v114
	v_mul_f32_e32 v120, v112, v112
	v_max_f32_e32 v112, v117, v117
	v_max_f32_e32 v116, v116, v116
	v_max_f32_e32 v112, 0, v112
	v_mul_f32_e32 v117, v113, v113
	v_max_f32_e32 v113, v118, v118
	v_mul_f32_e32 v118, v114, v114
	v_max_f32_e32 v114, v119, v119
	v_max_f32_e32 v115, v115, v115
	v_max_f32_e32 v116, 0, v116
	v_mul_f32_e32 v112, v112, v112
	v_max_f32_e32 v113, 0, v113
	v_max_f32_e32 v114, 0, v114
	v_max_f32_e32 v115, 0, v115
	v_mul_f32_e32 v116, v116, v116
	v_mul_f32_e32 v113, v113, v113
	v_mul_f32_e32 v114, v114, v114
	v_mul_f32_e32 v115, v115, v115
	v_cvt_pk_bf16_f32 v112, v116, v112
	v_cvt_pk_bf16_f32 v113, v113, v114
	v_cvt_pk_bf16_f32 v114, v120, v117
	v_cvt_pk_bf16_f32 v115, v118, v115
	flat_store_dwordx4 v[152:153], v[112:115] offset:256 sc1
	v_max_f32_e32 v104, v104, v104
	v_max_f32_e32 v104, 0, v104
	v_add_u32_e32 v112, 16, v140
	v_ashrrev_i32_e32 v113, 31, v112
	v_max_f32_e32 v105, v105, v105
	v_max_f32_e32 v106, v106, v106
	v_lshlrev_b64 v[112:113], 14, v[112:113]
	v_mul_f32_e32 v114, v104, v104
	v_max_f32_e32 v104, v109, v109
	v_max_f32_e32 v105, 0, v105
	v_max_f32_e32 v106, 0, v106
	v_lshl_add_u64 v[112:113], s[6:7], 0, v[112:113]
	v_max_f32_e32 v108, v108, v108
	v_max_f32_e32 v104, 0, v104
	v_mul_f32_e32 v109, v105, v105
	v_max_f32_e32 v105, v110, v110
	v_mul_f32_e32 v110, v106, v106
	v_max_f32_e32 v106, v111, v111
	v_max_f32_e32 v107, v107, v107
	v_lshl_add_u64 v[112:113], v[112:113], 0, s[44:45]
	v_max_f32_e32 v108, 0, v108
	v_mul_f32_e32 v104, v104, v104
	v_max_f32_e32 v105, 0, v105
	v_max_f32_e32 v106, 0, v106
	v_max_f32_e32 v107, 0, v107
	v_max_f32_e32 v96, v96, v96
	v_lshl_add_u64 v[112:113], v[112:113], 0, v[142:143]
	v_mul_f32_e32 v108, v108, v108
	v_mul_f32_e32 v105, v105, v105
	v_mul_f32_e32 v106, v106, v106
	v_mul_f32_e32 v107, v107, v107
	v_cvt_pk_bf16_f32 v104, v108, v104
	v_max_f32_e32 v96, 0, v96
	v_max_f32_e32 v97, v97, v97
	v_max_f32_e32 v98, v98, v98
	v_cvt_pk_bf16_f32 v105, v105, v106
	v_cvt_pk_bf16_f32 v106, v114, v109
	v_cvt_pk_bf16_f32 v107, v110, v107
	flat_store_dwordx4 v[112:113], v[104:107] sc1
	v_max_f32_e32 v97, 0, v97
	v_max_f32_e32 v98, 0, v98
	v_mul_f32_e32 v104, v96, v96
	v_max_f32_e32 v96, v101, v101
	v_max_f32_e32 v100, v100, v100
	v_max_f32_e32 v96, 0, v96
	v_mul_f32_e32 v101, v97, v97
	v_max_f32_e32 v97, v102, v102
	v_mul_f32_e32 v102, v98, v98
	v_max_f32_e32 v98, v103, v103
	v_max_f32_e32 v99, v99, v99
	v_max_f32_e32 v100, 0, v100
	v_mul_f32_e32 v96, v96, v96
	v_max_f32_e32 v97, 0, v97
	v_max_f32_e32 v98, 0, v98
	v_max_f32_e32 v99, 0, v99
	v_mul_f32_e32 v100, v100, v100
	v_mul_f32_e32 v97, v97, v97
	v_mul_f32_e32 v98, v98, v98
	v_mul_f32_e32 v99, v99, v99
	v_cvt_pk_bf16_f32 v96, v100, v96
	v_cvt_pk_bf16_f32 v97, v97, v98
	v_cvt_pk_bf16_f32 v98, v104, v101
	v_cvt_pk_bf16_f32 v99, v102, v99
	flat_store_dwordx4 v[112:113], v[96:99] offset:256 sc1
	v_max_f32_e32 v88, v88, v88
	v_max_f32_e32 v88, 0, v88
	v_add_u32_e32 v96, 32, v140
	v_ashrrev_i32_e32 v97, 31, v96
	v_max_f32_e32 v89, v89, v89
	v_max_f32_e32 v90, v90, v90
	v_lshlrev_b64 v[96:97], 14, v[96:97]
	v_mul_f32_e32 v98, v88, v88
	v_max_f32_e32 v88, v93, v93
	v_max_f32_e32 v89, 0, v89
	v_max_f32_e32 v90, 0, v90
	v_lshl_add_u64 v[96:97], s[6:7], 0, v[96:97]
	v_max_f32_e32 v92, v92, v92
	v_max_f32_e32 v88, 0, v88
	v_mul_f32_e32 v93, v89, v89
	v_max_f32_e32 v89, v94, v94
	v_mul_f32_e32 v94, v90, v90
	v_max_f32_e32 v90, v95, v95
	v_max_f32_e32 v91, v91, v91
	v_lshl_add_u64 v[96:97], v[96:97], 0, s[44:45]
	v_max_f32_e32 v92, 0, v92
	v_mul_f32_e32 v88, v88, v88
	v_max_f32_e32 v89, 0, v89
	v_max_f32_e32 v90, 0, v90
	v_max_f32_e32 v91, 0, v91
	v_max_f32_e32 v80, v80, v80
	v_lshl_add_u64 v[96:97], v[96:97], 0, v[142:143]
	v_mul_f32_e32 v92, v92, v92
	v_mul_f32_e32 v89, v89, v89
	v_mul_f32_e32 v90, v90, v90
	v_mul_f32_e32 v91, v91, v91
	v_cvt_pk_bf16_f32 v88, v92, v88
	v_max_f32_e32 v80, 0, v80
	v_max_f32_e32 v81, v81, v81
	v_max_f32_e32 v82, v82, v82
	v_cvt_pk_bf16_f32 v89, v89, v90
	v_cvt_pk_bf16_f32 v90, v98, v93
	v_cvt_pk_bf16_f32 v91, v94, v91
	flat_store_dwordx4 v[96:97], v[88:91] sc1
	v_max_f32_e32 v81, 0, v81
	v_max_f32_e32 v82, 0, v82
	v_mul_f32_e32 v88, v80, v80
	v_max_f32_e32 v80, v85, v85
	v_max_f32_e32 v84, v84, v84
	v_max_f32_e32 v80, 0, v80
	v_mul_f32_e32 v85, v81, v81
	v_max_f32_e32 v81, v86, v86
	v_mul_f32_e32 v86, v82, v82
	v_max_f32_e32 v82, v87, v87
	v_max_f32_e32 v83, v83, v83
	v_max_f32_e32 v84, 0, v84
	v_mul_f32_e32 v80, v80, v80
	v_max_f32_e32 v81, 0, v81
	v_max_f32_e32 v82, 0, v82
	v_max_f32_e32 v83, 0, v83
	v_mul_f32_e32 v84, v84, v84
	v_mul_f32_e32 v81, v81, v81
	v_mul_f32_e32 v82, v82, v82
	v_mul_f32_e32 v83, v83, v83
	v_cvt_pk_bf16_f32 v80, v84, v80
	v_cvt_pk_bf16_f32 v81, v81, v82
	v_cvt_pk_bf16_f32 v82, v88, v85
	v_cvt_pk_bf16_f32 v83, v86, v83
	flat_store_dwordx4 v[96:97], v[80:83] offset:256 sc1
	v_max_f32_e32 v72, v72, v72
	v_max_f32_e32 v72, 0, v72
	v_add_u32_e32 v80, 48, v140
	v_ashrrev_i32_e32 v81, 31, v80
	v_max_f32_e32 v73, v73, v73
	v_max_f32_e32 v74, v74, v74
	v_lshlrev_b64 v[80:81], 14, v[80:81]
	v_mul_f32_e32 v82, v72, v72
	v_max_f32_e32 v72, v77, v77
	v_max_f32_e32 v73, 0, v73
	v_max_f32_e32 v74, 0, v74
	v_lshl_add_u64 v[80:81], s[6:7], 0, v[80:81]
	v_max_f32_e32 v76, v76, v76
	v_max_f32_e32 v72, 0, v72
	v_mul_f32_e32 v77, v73, v73
	v_max_f32_e32 v73, v78, v78
	v_mul_f32_e32 v78, v74, v74
	v_max_f32_e32 v74, v79, v79
	v_max_f32_e32 v75, v75, v75
	v_lshl_add_u64 v[80:81], v[80:81], 0, s[44:45]
	v_max_f32_e32 v76, 0, v76
	v_mul_f32_e32 v72, v72, v72
	v_max_f32_e32 v73, 0, v73
	v_max_f32_e32 v74, 0, v74
	v_max_f32_e32 v75, 0, v75
	v_max_f32_e32 v64, v64, v64
	v_lshl_add_u64 v[80:81], v[80:81], 0, v[142:143]
	v_mul_f32_e32 v76, v76, v76
	v_mul_f32_e32 v73, v73, v73
	v_mul_f32_e32 v74, v74, v74
	v_mul_f32_e32 v75, v75, v75
	v_cvt_pk_bf16_f32 v72, v76, v72
	v_max_f32_e32 v64, 0, v64
	v_max_f32_e32 v65, v65, v65
	v_max_f32_e32 v66, v66, v66
	v_cvt_pk_bf16_f32 v73, v73, v74
	v_cvt_pk_bf16_f32 v74, v82, v77
	v_cvt_pk_bf16_f32 v75, v78, v75
	flat_store_dwordx4 v[80:81], v[72:75] sc1
	v_max_f32_e32 v65, 0, v65
	v_max_f32_e32 v66, 0, v66
	v_mul_f32_e32 v72, v64, v64
	v_max_f32_e32 v64, v69, v69
	v_max_f32_e32 v68, v68, v68
	v_max_f32_e32 v64, 0, v64
	v_mul_f32_e32 v69, v65, v65
	v_max_f32_e32 v65, v70, v70
	v_mul_f32_e32 v70, v66, v66
	v_max_f32_e32 v66, v71, v71
	v_max_f32_e32 v67, v67, v67
	v_max_f32_e32 v68, 0, v68
	v_mul_f32_e32 v64, v64, v64
	v_max_f32_e32 v65, 0, v65
	v_max_f32_e32 v66, 0, v66
	v_max_f32_e32 v67, 0, v67
	v_mul_f32_e32 v68, v68, v68
	v_mul_f32_e32 v65, v65, v65
	v_mul_f32_e32 v66, v66, v66
	v_mul_f32_e32 v67, v67, v67
	v_cvt_pk_bf16_f32 v64, v68, v64
	v_cvt_pk_bf16_f32 v65, v65, v66
	v_cvt_pk_bf16_f32 v66, v72, v69
	v_cvt_pk_bf16_f32 v67, v70, v67
	flat_store_dwordx4 v[80:81], v[64:67] offset:256 sc1
	v_max_f32_e32 v56, v56, v56
	v_max_f32_e32 v56, 0, v56
	v_add_u32_e32 v64, 0x80, v140
	v_ashrrev_i32_e32 v65, 31, v64
	v_max_f32_e32 v57, v57, v57
	v_max_f32_e32 v58, v58, v58
	v_lshlrev_b64 v[64:65], 14, v[64:65]
	v_mul_f32_e32 v66, v56, v56
	v_max_f32_e32 v56, v61, v61
	v_max_f32_e32 v57, 0, v57
	v_max_f32_e32 v58, 0, v58
	v_lshl_add_u64 v[64:65], s[6:7], 0, v[64:65]
	v_max_f32_e32 v60, v60, v60
	v_max_f32_e32 v56, 0, v56
	v_mul_f32_e32 v61, v57, v57
	v_max_f32_e32 v57, v62, v62
	v_mul_f32_e32 v62, v58, v58
	v_max_f32_e32 v58, v63, v63
	v_max_f32_e32 v59, v59, v59
	v_lshl_add_u64 v[64:65], v[64:65], 0, s[44:45]
	v_max_f32_e32 v60, 0, v60
	v_mul_f32_e32 v56, v56, v56
	v_max_f32_e32 v57, 0, v57
	v_max_f32_e32 v58, 0, v58
	v_max_f32_e32 v59, 0, v59
	v_max_f32_e32 v48, v48, v48
	v_lshl_add_u64 v[64:65], v[64:65], 0, v[142:143]
	v_mul_f32_e32 v60, v60, v60
	v_mul_f32_e32 v57, v57, v57
	v_mul_f32_e32 v58, v58, v58
	v_mul_f32_e32 v59, v59, v59
	v_cvt_pk_bf16_f32 v56, v60, v56
	v_max_f32_e32 v48, 0, v48
	v_max_f32_e32 v49, v49, v49
	v_max_f32_e32 v50, v50, v50
	v_cvt_pk_bf16_f32 v57, v57, v58
	v_cvt_pk_bf16_f32 v58, v66, v61
	v_cvt_pk_bf16_f32 v59, v62, v59
	flat_store_dwordx4 v[64:65], v[56:59] sc1
	v_max_f32_e32 v49, 0, v49
	v_max_f32_e32 v50, 0, v50
	v_mul_f32_e32 v56, v48, v48
	v_max_f32_e32 v48, v53, v53
	v_max_f32_e32 v52, v52, v52
	v_max_f32_e32 v48, 0, v48
	v_mul_f32_e32 v53, v49, v49
	v_max_f32_e32 v49, v54, v54
	v_mul_f32_e32 v54, v50, v50
	v_max_f32_e32 v50, v55, v55
	v_max_f32_e32 v51, v51, v51
	v_max_f32_e32 v52, 0, v52
	v_mul_f32_e32 v48, v48, v48
	v_max_f32_e32 v49, 0, v49
	v_max_f32_e32 v50, 0, v50
	v_max_f32_e32 v51, 0, v51
	v_mul_f32_e32 v52, v52, v52
	v_mul_f32_e32 v49, v49, v49
	v_mul_f32_e32 v50, v50, v50
	v_mul_f32_e32 v51, v51, v51
	v_cvt_pk_bf16_f32 v48, v52, v48
	v_cvt_pk_bf16_f32 v49, v49, v50
	v_cvt_pk_bf16_f32 v50, v56, v53
	v_cvt_pk_bf16_f32 v51, v54, v51
	flat_store_dwordx4 v[64:65], v[48:51] offset:256 sc1
	v_max_f32_e32 v40, v40, v40
	v_max_f32_e32 v40, 0, v40
	v_add_u32_e32 v48, 0x90, v140
	v_ashrrev_i32_e32 v49, 31, v48
	v_max_f32_e32 v41, v41, v41
	v_max_f32_e32 v42, v42, v42
	v_lshlrev_b64 v[48:49], 14, v[48:49]
	v_mul_f32_e32 v50, v40, v40
	v_max_f32_e32 v40, v45, v45
	v_max_f32_e32 v41, 0, v41
	v_max_f32_e32 v42, 0, v42
	v_lshl_add_u64 v[48:49], s[6:7], 0, v[48:49]
	v_max_f32_e32 v44, v44, v44
	v_max_f32_e32 v40, 0, v40
	v_mul_f32_e32 v45, v41, v41
	v_max_f32_e32 v41, v46, v46
	v_mul_f32_e32 v46, v42, v42
	v_max_f32_e32 v42, v47, v47
	v_max_f32_e32 v43, v43, v43
	v_lshl_add_u64 v[48:49], v[48:49], 0, s[44:45]
	v_max_f32_e32 v44, 0, v44
	v_mul_f32_e32 v40, v40, v40
	v_max_f32_e32 v41, 0, v41
	v_max_f32_e32 v42, 0, v42
	v_max_f32_e32 v43, 0, v43
	v_max_f32_e32 v32, v32, v32
	v_lshl_add_u64 v[48:49], v[48:49], 0, v[142:143]
	v_mul_f32_e32 v44, v44, v44
	v_mul_f32_e32 v41, v41, v41
	v_mul_f32_e32 v42, v42, v42
	v_mul_f32_e32 v43, v43, v43
	v_cvt_pk_bf16_f32 v40, v44, v40
	v_max_f32_e32 v32, 0, v32
	v_max_f32_e32 v33, v33, v33
	v_max_f32_e32 v34, v34, v34
	v_cvt_pk_bf16_f32 v41, v41, v42
	v_cvt_pk_bf16_f32 v42, v50, v45
	v_cvt_pk_bf16_f32 v43, v46, v43
	flat_store_dwordx4 v[48:49], v[40:43] sc1
	v_max_f32_e32 v33, 0, v33
	v_max_f32_e32 v34, 0, v34
	v_mul_f32_e32 v40, v32, v32
	v_max_f32_e32 v32, v37, v37
	v_max_f32_e32 v36, v36, v36
	v_max_f32_e32 v32, 0, v32
	v_mul_f32_e32 v37, v33, v33
	v_max_f32_e32 v33, v38, v38
	v_mul_f32_e32 v38, v34, v34
	v_max_f32_e32 v34, v39, v39
	v_max_f32_e32 v35, v35, v35
	v_max_f32_e32 v36, 0, v36
	v_mul_f32_e32 v32, v32, v32
	v_max_f32_e32 v33, 0, v33
	v_max_f32_e32 v34, 0, v34
	v_max_f32_e32 v35, 0, v35
	v_mul_f32_e32 v36, v36, v36
	v_mul_f32_e32 v33, v33, v33
	v_mul_f32_e32 v34, v34, v34
	v_mul_f32_e32 v35, v35, v35
	v_cvt_pk_bf16_f32 v32, v36, v32
	v_cvt_pk_bf16_f32 v33, v33, v34
	v_cvt_pk_bf16_f32 v34, v40, v37
	v_cvt_pk_bf16_f32 v35, v38, v35
	flat_store_dwordx4 v[48:49], v[32:35] offset:256 sc1
	v_max_f32_e32 v24, v24, v24
	v_max_f32_e32 v24, 0, v24
	v_add_u32_e32 v32, 0xa0, v140
	v_ashrrev_i32_e32 v33, 31, v32
	v_max_f32_e32 v25, v25, v25
	v_max_f32_e32 v26, v26, v26
	v_lshlrev_b64 v[32:33], 14, v[32:33]
	v_mul_f32_e32 v34, v24, v24
	v_max_f32_e32 v24, v29, v29
	v_max_f32_e32 v25, 0, v25
	v_max_f32_e32 v26, 0, v26
	v_lshl_add_u64 v[32:33], s[6:7], 0, v[32:33]
	v_max_f32_e32 v28, v28, v28
	v_max_f32_e32 v24, 0, v24
	v_mul_f32_e32 v29, v25, v25
	v_max_f32_e32 v25, v30, v30
	v_mul_f32_e32 v30, v26, v26
	v_max_f32_e32 v26, v31, v31
	v_max_f32_e32 v27, v27, v27
	v_lshl_add_u64 v[32:33], v[32:33], 0, s[44:45]
	v_max_f32_e32 v28, 0, v28
	v_mul_f32_e32 v24, v24, v24
	v_max_f32_e32 v25, 0, v25
	v_max_f32_e32 v26, 0, v26
	v_max_f32_e32 v27, 0, v27
	v_max_f32_e32 v16, v16, v16
	v_lshl_add_u64 v[32:33], v[32:33], 0, v[142:143]
	v_mul_f32_e32 v28, v28, v28
	v_mul_f32_e32 v25, v25, v25
	v_mul_f32_e32 v26, v26, v26
	v_mul_f32_e32 v27, v27, v27
	v_cvt_pk_bf16_f32 v24, v28, v24
	v_max_f32_e32 v16, 0, v16
	v_max_f32_e32 v17, v17, v17
	v_max_f32_e32 v18, v18, v18
	v_cvt_pk_bf16_f32 v25, v25, v26
	v_cvt_pk_bf16_f32 v26, v34, v29
	v_cvt_pk_bf16_f32 v27, v30, v27
	flat_store_dwordx4 v[32:33], v[24:27] sc1
	v_max_f32_e32 v17, 0, v17
	v_max_f32_e32 v18, 0, v18
	v_mul_f32_e32 v24, v16, v16
	v_max_f32_e32 v16, v21, v21
	v_max_f32_e32 v20, v20, v20
	v_max_f32_e32 v16, 0, v16
	v_mul_f32_e32 v21, v17, v17
	v_max_f32_e32 v17, v22, v22
	v_mul_f32_e32 v22, v18, v18
	v_max_f32_e32 v18, v23, v23
	v_max_f32_e32 v19, v19, v19
	v_max_f32_e32 v20, 0, v20
	v_mul_f32_e32 v16, v16, v16
	v_max_f32_e32 v17, 0, v17
	v_max_f32_e32 v18, 0, v18
	v_max_f32_e32 v19, 0, v19
	v_mul_f32_e32 v20, v20, v20
	v_mul_f32_e32 v17, v17, v17
	v_mul_f32_e32 v18, v18, v18
	v_mul_f32_e32 v19, v19, v19
	v_cvt_pk_bf16_f32 v16, v20, v16
	v_cvt_pk_bf16_f32 v17, v17, v18
	v_cvt_pk_bf16_f32 v18, v24, v21
	v_cvt_pk_bf16_f32 v19, v22, v19
	flat_store_dwordx4 v[32:33], v[16:19] offset:256 sc1
	v_max_f32_e32 v8, v8, v8
	v_max_f32_e32 v8, 0, v8
	v_add_u32_e32 v16, 0xb0, v140
	v_ashrrev_i32_e32 v17, 31, v16
	v_max_f32_e32 v9, v9, v9
	v_max_f32_e32 v10, v10, v10
	v_lshlrev_b64 v[16:17], 14, v[16:17]
	v_mul_f32_e32 v18, v8, v8
	v_max_f32_e32 v8, v13, v13
	v_max_f32_e32 v9, 0, v9
	v_max_f32_e32 v10, 0, v10
	v_lshl_add_u64 v[16:17], s[6:7], 0, v[16:17]
	v_max_f32_e32 v12, v12, v12
	v_max_f32_e32 v8, 0, v8
	v_mul_f32_e32 v13, v9, v9
	v_max_f32_e32 v9, v14, v14
	v_mul_f32_e32 v14, v10, v10
	v_max_f32_e32 v10, v15, v15
	v_max_f32_e32 v11, v11, v11
	v_lshl_add_u64 v[16:17], v[16:17], 0, s[44:45]
	v_max_f32_e32 v12, 0, v12
	v_mul_f32_e32 v8, v8, v8
	v_max_f32_e32 v9, 0, v9
	v_max_f32_e32 v10, 0, v10
	v_max_f32_e32 v11, 0, v11
	v_max_f32_e32 v0, v0, v0
	v_max_f32_e32 v1, v1, v1
	v_max_f32_e32 v2, v2, v2
	v_lshl_add_u64 v[16:17], v[16:17], 0, v[142:143]
	v_mul_f32_e32 v12, v12, v12
	v_mul_f32_e32 v9, v9, v9
	v_mul_f32_e32 v10, v10, v10
	v_mul_f32_e32 v11, v11, v11
	v_cvt_pk_bf16_f32 v8, v12, v8
	v_max_f32_e32 v0, 0, v0
	v_max_f32_e32 v1, 0, v1
	v_max_f32_e32 v2, 0, v2
	v_cvt_pk_bf16_f32 v9, v9, v10
	v_cvt_pk_bf16_f32 v10, v18, v13
	v_cvt_pk_bf16_f32 v11, v14, v11
	flat_store_dwordx4 v[16:17], v[8:11] sc1
	v_max_f32_e32 v3, v3, v3
	v_max_f32_e32 v4, v4, v4
	v_mul_f32_e32 v8, v0, v0
	v_max_f32_e32 v0, v5, v5
	v_mul_f32_e32 v5, v1, v1
	v_max_f32_e32 v1, v6, v6
	v_mul_f32_e32 v6, v2, v2
	v_max_f32_e32 v2, v7, v7
	v_max_f32_e32 v0, 0, v0
	v_max_f32_e32 v1, 0, v1
	v_max_f32_e32 v2, 0, v2
	v_max_f32_e32 v3, 0, v3
	v_max_f32_e32 v4, 0, v4
	v_mul_f32_e32 v0, v0, v0
	v_mul_f32_e32 v1, v1, v1
	v_mul_f32_e32 v2, v2, v2
	v_mul_f32_e32 v3, v3, v3
	s_and_b64 vcc, exec, s[10:11]
	s_mov_b32 s44, s64
	s_mov_b32 s45, s65
	s_mov_b64 s[48:49], s[14:15]
	s_mov_b64 s[46:47], s[12:13]
	v_mul_f32_e32 v4, v4, v4
	v_cvt_pk_bf16_f32 v0, v4, v0
	v_cvt_pk_bf16_f32 v1, v1, v2
	v_cvt_pk_bf16_f32 v2, v8, v5
	v_cvt_pk_bf16_f32 v3, v6, v3
	flat_store_dwordx4 v[16:17], v[0:3] offset:256 sc1
	s_cbranch_vccnz .LBB0_1105

.LBB0_1151:
	s_ashr_i32 s13, s12, 31
	s_lshl_b64 s[12:13], s[12:13], 3
	s_add_u32 s14, s0, s12
	s_addc_u32 s15, s1, s13
	s_lshr_b32 s12, s29, 5
	v_cvt_f32_u32_e32 v8, s12
	s_load_dwordx2 s[40:41], s[14:15], 0x0
	s_sub_i32 s14, 0, s12
	s_abs_i32 s46, s36
	v_rcp_iflag_f32_e32 v8, v8
	s_ashr_i32 s45, s36, 31
	s_mov_b32 s13, 0
	s_mov_b32 s44, 1
	v_mul_f32_e32 v8, 0x4f7ffffe, v8
	v_cvt_u32_f32_e32 v8, v8
	s_nop 0
	v_readfirstlane_b32 s15, v8
	s_mul_i32 s14, s14, s15
	s_mul_hi_u32 s14, s15, s14
	s_add_i32 s15, s15, s14
	s_mul_hi_u32 s14, s46, s15
	s_mul_i32 s15, s14, s12
	s_sub_i32 s15, s46, s15
	s_add_i32 s47, s14, 1
	s_sub_i32 s46, s15, s12
	s_cmp_ge_u32 s15, s12
	s_cselect_b32 s14, s47, s14
	s_cselect_b32 s15, s46, s15
	s_add_i32 s46, s14, 1
	s_cmp_ge_u32 s15, s12
	s_cselect_b32 s14, s46, s14
	s_xor_b32 s14, s14, s45
	s_sub_i32 s14, s14, s45
	s_mul_i32 s12, s14, s12
	s_sub_i32 s15, s36, s12
	s_lshl_b32 s12, s14, 6
	s_lshl_b32 s14, s15, 5
	s_ashr_i32 s15, s14, 31
	s_lshl_b64 s[46:47], s[14:15], 2
	s_waitcnt lgkmcnt(0)
	s_add_u32 s40, s40, s46
	s_addc_u32 s41, s41, s47
	s_mul_i32 s70, s12, s29
	s_lshl_b32 s71, s29, 2
	s_lshl_b32 s70, s70, 2
	s_add_u32 s40, s40, s70
	s_addc_u32 s41, s41, 0
	v_mad_u32_u24 v210, v0, s71, v6
	v_mad_u32_u24 v211, v0, s25, v4
	s_lshl_b32 s71, s71, 1
	global_load_dword v166, v210, s[40:41]
	s_add_u32 s40, s40, s71
	s_addc_u32 s41, s41, 0
	global_load_dword v167, v210, s[40:41]
	s_add_u32 s40, s40, s71
	s_addc_u32 s41, s41, 0
	global_load_dword v168, v210, s[40:41]
	s_add_u32 s40, s40, s71
	s_addc_u32 s41, s41, 0
	global_load_dword v169, v210, s[40:41]
	s_add_u32 s40, s40, s71
	s_addc_u32 s41, s41, 0
	global_load_dword v170, v210, s[40:41]
	s_add_u32 s40, s40, s71
	s_addc_u32 s41, s41, 0
	global_load_dword v171, v210, s[40:41]
	s_add_u32 s40, s40, s71
	s_addc_u32 s41, s41, 0
	global_load_dword v172, v210, s[40:41]
	s_add_u32 s40, s40, s71
	s_addc_u32 s41, s41, 0
	global_load_dword v173, v210, s[40:41]
	s_add_u32 s40, s40, s71
	s_addc_u32 s41, s41, 0
	global_load_dword v174, v210, s[40:41]
	s_add_u32 s40, s40, s71
	s_addc_u32 s41, s41, 0
	global_load_dword v175, v210, s[40:41]
	s_add_u32 s40, s40, s71
	s_addc_u32 s41, s41, 0
	global_load_dword v176, v210, s[40:41]
	s_add_u32 s40, s40, s71
	s_addc_u32 s41, s41, 0
	global_load_dword v177, v210, s[40:41]
	s_add_u32 s40, s40, s71
	s_addc_u32 s41, s41, 0
	global_load_dword v178, v210, s[40:41]
	s_add_u32 s40, s40, s71
	s_addc_u32 s41, s41, 0
	global_load_dword v179, v210, s[40:41]
	s_add_u32 s40, s40, s71
	s_addc_u32 s41, s41, 0
	global_load_dword v180, v210, s[40:41]
	s_add_u32 s40, s40, s71
	s_addc_u32 s41, s41, 0
	global_load_dword v181, v210, s[40:41]
	s_add_u32 s40, s40, s71
	s_addc_u32 s41, s41, 0
	global_load_dword v182, v210, s[40:41]
	s_add_u32 s40, s40, s71
	s_addc_u32 s41, s41, 0
	global_load_dword v183, v210, s[40:41]
	s_add_u32 s40, s40, s71
	s_addc_u32 s41, s41, 0
	global_load_dword v184, v210, s[40:41]
	s_add_u32 s40, s40, s71
	s_addc_u32 s41, s41, 0
	global_load_dword v185, v210, s[40:41]
	s_add_u32 s40, s40, s71
	s_addc_u32 s41, s41, 0
	global_load_dword v186, v210, s[40:41]
	s_add_u32 s40, s40, s71
	s_addc_u32 s41, s41, 0
	global_load_dword v187, v210, s[40:41]
	s_add_u32 s40, s40, s71
	s_addc_u32 s41, s41, 0
	global_load_dword v188, v210, s[40:41]
	s_add_u32 s40, s40, s71
	s_addc_u32 s41, s41, 0
	global_load_dword v189, v210, s[40:41]
	s_add_u32 s40, s40, s71
	s_addc_u32 s41, s41, 0
	global_load_dword v190, v210, s[40:41]
	s_add_u32 s40, s40, s71
	s_addc_u32 s41, s41, 0
	global_load_dword v191, v210, s[40:41]
	s_add_u32 s40, s40, s71
	s_addc_u32 s41, s41, 0
	global_load_dword v192, v210, s[40:41]
	s_add_u32 s40, s40, s71
	s_addc_u32 s41, s41, 0
	global_load_dword v193, v210, s[40:41]
	s_add_u32 s40, s40, s71
	s_addc_u32 s41, s41, 0
	global_load_dword v194, v210, s[40:41]
	s_add_u32 s40, s40, s71
	s_addc_u32 s41, s41, 0
	global_load_dword v195, v210, s[40:41]
	s_add_u32 s40, s40, s71
	s_addc_u32 s41, s41, 0
	global_load_dword v198, v210, s[40:41]
	s_add_u32 s40, s40, s71
	s_addc_u32 s41, s41, 0
	global_load_dword v199, v210, s[40:41]
	s_waitcnt vmcnt(31)
	ds_write_b32 v211, v166
	s_waitcnt vmcnt(30)
	ds_write_b32 v211, v167 offset:264
	s_waitcnt vmcnt(29)
	ds_write_b32 v211, v168 offset:528
	s_waitcnt vmcnt(28)
	ds_write_b32 v211, v169 offset:792
	s_waitcnt vmcnt(27)
	ds_write_b32 v211, v170 offset:1056
	s_waitcnt vmcnt(26)
	ds_write_b32 v211, v171 offset:1320
	s_waitcnt vmcnt(25)
	ds_write_b32 v211, v172 offset:1584
	s_waitcnt vmcnt(24)
	ds_write_b32 v211, v173 offset:1848
	s_waitcnt vmcnt(23)
	ds_write_b32 v211, v174 offset:2112
	s_waitcnt vmcnt(22)
	ds_write_b32 v211, v175 offset:2376
	s_waitcnt vmcnt(21)
	ds_write_b32 v211, v176 offset:2640
	s_waitcnt vmcnt(20)
	ds_write_b32 v211, v177 offset:2904
	s_waitcnt vmcnt(19)
	ds_write_b32 v211, v178 offset:3168
	s_waitcnt vmcnt(18)
	ds_write_b32 v211, v179 offset:3432
	s_waitcnt vmcnt(17)
	ds_write_b32 v211, v180 offset:3696
	s_waitcnt vmcnt(16)
	ds_write_b32 v211, v181 offset:3960
	s_waitcnt vmcnt(15)
	ds_write_b32 v211, v182 offset:4224
	s_waitcnt vmcnt(14)
	ds_write_b32 v211, v183 offset:4488
	s_waitcnt vmcnt(13)
	ds_write_b32 v211, v184 offset:4752
	s_waitcnt vmcnt(12)
	ds_write_b32 v211, v185 offset:5016
	s_waitcnt vmcnt(11)
	ds_write_b32 v211, v186 offset:5280
	s_waitcnt vmcnt(10)
	ds_write_b32 v211, v187 offset:5544
	s_waitcnt vmcnt(9)
	ds_write_b32 v211, v188 offset:5808
	s_waitcnt vmcnt(8)
	ds_write_b32 v211, v189 offset:6072
	s_waitcnt vmcnt(7)
	ds_write_b32 v211, v190 offset:6336
	s_waitcnt vmcnt(6)
	ds_write_b32 v211, v191 offset:6600
	s_waitcnt vmcnt(5)
	ds_write_b32 v211, v192 offset:6864
	s_waitcnt vmcnt(4)
	ds_write_b32 v211, v193 offset:7128
	s_waitcnt vmcnt(3)
	ds_write_b32 v211, v194 offset:7392
	s_waitcnt vmcnt(2)
	ds_write_b32 v211, v195 offset:7656
	s_waitcnt vmcnt(1)
	ds_write_b32 v211, v198 offset:7920
	s_waitcnt vmcnt(0)
	ds_write_b32 v211, v199 offset:8184
	s_add_u32 s13, s34, s8
	s_waitcnt lgkmcnt(0)
	s_addc_u32 s15, s35, s9
	s_add_i32 s14, s14, s37
	s_lshl_b64 s[8:9], s[10:11], 1
	s_add_u32 s10, s13, s8
	ds_read2_b32 v[166:167], v10 offset1:33
	ds_read2_b32 v[168:169], v10 offset0:66 offset1:99
	ds_read2_b32 v[170:171], v10 offset0:132 offset1:165
	ds_read2_b32 v[172:173], v10 offset0:198 offset1:231
	ds_read2_b32 v[174:175], v10 offset0:8 offset1:41
	ds_read2_b32 v[176:177], v10 offset0:74 offset1:107
	ds_read2_b32 v[178:179], v10 offset0:140 offset1:173
	ds_read2_b32 v[180:181], v10 offset0:206 offset1:239
	ds_read2_b32 v[182:183], v10 offset0:16 offset1:49
	ds_read2_b32 v[184:185], v10 offset0:82 offset1:115
	ds_read2_b32 v[186:187], v10 offset0:148 offset1:181
	ds_read2_b32 v[188:189], v10 offset0:214 offset1:247
	ds_read2_b32 v[190:191], v10 offset0:24 offset1:57
	ds_read2_b32 v[192:193], v10 offset0:90 offset1:123
	ds_read2_b32 v[194:195], v10 offset0:156 offset1:189
	ds_read2_b32 v[198:199], v10 offset0:222 offset1:255
	s_addc_u32 s11, s15, s9
	s_ashr_i32 s13, s12, 31
	s_waitcnt lgkmcnt(12)
	v_cvt_pk_bf16_f32 v14, v166, v167
	s_lshl_b64 s[8:9], s[12:13], 1
	s_waitcnt lgkmcnt(12)
	v_cvt_pk_bf16_f32 v15, v168, v169
	v_add_u32_e32 v20, s14, v5
	s_add_u32 s8, s10, s8
	v_ashrrev_i32_e32 v21, 31, v20
	s_waitcnt lgkmcnt(12)
	v_cvt_pk_bf16_f32 v16, v170, v171
	s_addc_u32 s9, s11, s9
	v_lshl_add_u64 v[18:19], s[8:9], 0, v[2:3]
	s_waitcnt lgkmcnt(12)
	v_cvt_pk_bf16_f32 v17, v172, v173
	v_mul_lo_u32 v21, s6, v21
	v_mul_lo_u32 v22, s7, v20
	v_mad_u64_u32 v[8:9], s[8:9], s6, v20, 0
	v_add3_u32 v9, v9, v21, v22
	v_lshl_add_u64 v[8:9], v[8:9], 1, v[18:19]
	global_store_dwordx4 v[8:9], v[14:17], off sc1
	s_nop 1
	s_add_i32 s3, s3, s19
	v_add_u32_e32 v17, s14, v11
	s_waitcnt lgkmcnt(8)
	v_cvt_pk_bf16_f32 v14, v174, v175
	v_ashrrev_i32_e32 v22, 31, v17
	s_waitcnt lgkmcnt(8)
	v_cvt_pk_bf16_f32 v15, v176, v177
	v_mul_lo_u32 v23, s7, v17
	v_mad_u64_u32 v[20:21], s[8:9], s6, v17, 0
	v_mul_lo_u32 v17, s6, v22
	s_waitcnt lgkmcnt(8)
	v_cvt_pk_bf16_f32 v16, v178, v179
	v_add3_u32 v21, v21, v17, v23
	s_waitcnt lgkmcnt(8)
	v_cvt_pk_bf16_f32 v17, v180, v181
	v_lshl_add_u64 v[8:9], v[20:21], 1, v[18:19]
	global_store_dwordx4 v[8:9], v[14:17], off sc1
	s_nop 1
	s_cmp_lt_i32 s3, 0x9400
	v_add_u32_e32 v17, s14, v12
	v_ashrrev_i32_e32 v22, 31, v17
	v_mul_lo_u32 v23, s7, v17
	v_mad_u64_u32 v[20:21], s[8:9], s6, v17, 0
	v_mul_lo_u32 v17, s6, v22
	s_waitcnt lgkmcnt(4)
	v_cvt_pk_bf16_f32 v14, v182, v183
	v_add3_u32 v21, v21, v17, v23
	s_waitcnt lgkmcnt(4)
	v_cvt_pk_bf16_f32 v15, v184, v185
	s_waitcnt lgkmcnt(4)
	v_cvt_pk_bf16_f32 v16, v186, v187
	v_lshl_add_u64 v[20:21], v[20:21], 1, v[18:19]
	s_waitcnt lgkmcnt(4)
	v_cvt_pk_bf16_f32 v17, v188, v189
	global_store_dwordx4 v[20:21], v[14:17], off sc1
	s_nop 1
	s_nop 0
	v_add_u32_e32 v16, s14, v13
	v_ashrrev_i32_e32 v17, 31, v16
	v_mul_lo_u32 v22, s7, v16
	v_mad_u64_u32 v[20:21], s[8:9], s6, v16, 0
	v_mul_lo_u32 v17, s6, v17
	s_waitcnt lgkmcnt(0)
	v_cvt_pk_bf16_f32 v14, v190, v191
	v_add3_u32 v21, v21, v17, v22
	s_waitcnt lgkmcnt(0)
	v_cvt_pk_bf16_f32 v15, v192, v193
	v_lshl_add_u64 v[18:19], v[20:21], 1, v[18:19]
	s_waitcnt lgkmcnt(0)
	v_cvt_pk_bf16_f32 v16, v194, v195
	s_waitcnt lgkmcnt(0)
	v_cvt_pk_bf16_f32 v17, v198, v199
	global_store_dwordx4 v[18:19], v[14:17], off sc1
	s_nop 1
	s_waitcnt lgkmcnt(0)
	s_cbranch_scc1 .LBB0_1111

.LBB0_1225:
	v_mov_b32_e32 v140, v158
	v_mov_b32_e32 v165, v159
	s_ashr_i32 s49, s48, 31
	v_add_u32_e32 v156, s71, v140
	s_cmp_lg_u32 s6, 0
	v_ashrrev_i32_e32 v157, 31, v156
	v_add_u32_e32 v154, 16, v156
	v_add_u32_e32 v152, 32, v156
	v_add_u32_e32 v150, 48, v156
	v_add_u32_e32 v148, 0x80, v156
	v_add_u32_e32 v144, 0x90, v156
	v_add_u32_e32 v142, 0xa0, v156
	v_add_u32_e32 v140, 0xb0, v156
	s_cbranch_scc0 .LBB0_1232
	s_add_i32 s6, s6, -1
	s_lshl_b64 s[52:53], s[6:7], 22
	s_add_u32 s6, s69, s52
	s_addc_u32 s54, s70, s53
	s_ashr_i32 s51, s50, 31
	s_lshl_b64 s[52:53], s[50:51], 12
	s_add_u32 s6, s6, s52
	s_addc_u32 s51, s54, s53
	s_lshl_b64 s[52:53], s[48:49], 1
	s_add_u32 s6, s6, s52
	s_addc_u32 s51, s51, s53
	s_add_u32 s52, s6, s80
	v_lshlrev_b32_e32 v146, 3, v165
	s_addc_u32 s53, s51, 0
	v_ashrrev_i32_e32 v147, 31, v146
	v_lshl_add_u64 v[146:147], v[146:147], 1, s[52:53]
	v_lshlrev_b64 v[166:167], 12, v[156:157]
	v_lshl_add_u64 v[170:171], v[146:147], 0, v[166:167]
	v_cvt_pk_bf16_f32 v166, v124, v125
	v_cvt_pk_bf16_f32 v167, v126, v127
	v_cvt_pk_bf16_f32 v168, v120, v121
	v_cvt_pk_bf16_f32 v169, v122, v123
	flat_store_dwordx4 v[170:171], v[166:169] sc1
	v_ashrrev_i32_e32 v155, 31, v154
	v_ashrrev_i32_e32 v153, 31, v152
	v_cvt_pk_bf16_f32 v166, v116, v117
	v_cvt_pk_bf16_f32 v167, v118, v119
	v_cvt_pk_bf16_f32 v168, v112, v113
	v_cvt_pk_bf16_f32 v169, v114, v115
	flat_store_dwordx4 v[170:171], v[166:169] offset:256 sc1
	v_ashrrev_i32_e32 v151, 31, v150
	v_ashrrev_i32_e32 v149, 31, v148
	v_lshlrev_b64 v[166:167], 12, v[154:155]
	v_lshl_add_u64 v[170:171], v[146:147], 0, v[166:167]
	v_cvt_pk_bf16_f32 v166, v108, v109
	v_cvt_pk_bf16_f32 v167, v110, v111
	v_cvt_pk_bf16_f32 v168, v104, v105
	v_cvt_pk_bf16_f32 v169, v106, v107
	flat_store_dwordx4 v[170:171], v[166:169] sc1
	v_ashrrev_i32_e32 v145, 31, v144
	v_ashrrev_i32_e32 v143, 31, v142
	v_cvt_pk_bf16_f32 v166, v100, v101
	v_cvt_pk_bf16_f32 v167, v102, v103
	v_cvt_pk_bf16_f32 v168, v96, v97
	v_cvt_pk_bf16_f32 v169, v98, v99
	flat_store_dwordx4 v[170:171], v[166:169] offset:256 sc1
	v_ashrrev_i32_e32 v141, 31, v140
	s_nop 0
	v_lshlrev_b64 v[166:167], 12, v[152:153]
	v_lshl_add_u64 v[170:171], v[146:147], 0, v[166:167]
	v_cvt_pk_bf16_f32 v166, v92, v93
	v_cvt_pk_bf16_f32 v167, v94, v95
	v_cvt_pk_bf16_f32 v168, v88, v89
	v_cvt_pk_bf16_f32 v169, v90, v91
	flat_store_dwordx4 v[170:171], v[166:169] sc1
	s_nop 1
	v_cvt_pk_bf16_f32 v166, v84, v85
	v_cvt_pk_bf16_f32 v167, v86, v87
	v_cvt_pk_bf16_f32 v168, v80, v81
	v_cvt_pk_bf16_f32 v169, v82, v83
	flat_store_dwordx4 v[170:171], v[166:169] offset:256 sc1
	s_nop 1
	v_lshlrev_b64 v[166:167], 12, v[150:151]
	v_lshl_add_u64 v[170:171], v[146:147], 0, v[166:167]
	v_cvt_pk_bf16_f32 v166, v76, v77
	v_cvt_pk_bf16_f32 v167, v78, v79
	v_cvt_pk_bf16_f32 v168, v72, v73
	v_cvt_pk_bf16_f32 v169, v74, v75
	flat_store_dwordx4 v[170:171], v[166:169] sc1
	s_nop 1
	v_cvt_pk_bf16_f32 v166, v68, v69
	v_cvt_pk_bf16_f32 v167, v70, v71
	v_cvt_pk_bf16_f32 v168, v64, v65
	v_cvt_pk_bf16_f32 v169, v66, v67
	flat_store_dwordx4 v[170:171], v[166:169] offset:256 sc1
	s_nop 1
	v_lshlrev_b64 v[166:167], 12, v[148:149]
	v_lshl_add_u64 v[170:171], v[146:147], 0, v[166:167]
	v_cvt_pk_bf16_f32 v166, v60, v61
	v_cvt_pk_bf16_f32 v167, v62, v63
	v_cvt_pk_bf16_f32 v168, v56, v57
	v_cvt_pk_bf16_f32 v169, v58, v59
	flat_store_dwordx4 v[170:171], v[166:169] sc1
	s_nop 1
	v_cvt_pk_bf16_f32 v166, v52, v53
	v_cvt_pk_bf16_f32 v167, v54, v55
	v_cvt_pk_bf16_f32 v168, v48, v49
	v_cvt_pk_bf16_f32 v169, v50, v51
	flat_store_dwordx4 v[170:171], v[166:169] offset:256 sc1
	s_nop 1
	v_lshlrev_b64 v[166:167], 12, v[144:145]
	v_lshl_add_u64 v[170:171], v[146:147], 0, v[166:167]
	v_cvt_pk_bf16_f32 v166, v44, v45
	v_cvt_pk_bf16_f32 v167, v46, v47
	v_cvt_pk_bf16_f32 v168, v40, v41
	v_cvt_pk_bf16_f32 v169, v42, v43
	flat_store_dwordx4 v[170:171], v[166:169] sc1
	s_nop 1
	v_cvt_pk_bf16_f32 v166, v36, v37
	v_cvt_pk_bf16_f32 v167, v38, v39
	v_cvt_pk_bf16_f32 v168, v32, v33
	v_cvt_pk_bf16_f32 v169, v34, v35
	flat_store_dwordx4 v[170:171], v[166:169] offset:256 sc1
	s_nop 1
	v_lshlrev_b64 v[166:167], 12, v[142:143]
	v_lshl_add_u64 v[170:171], v[146:147], 0, v[166:167]
	v_cvt_pk_bf16_f32 v166, v28, v29
	v_cvt_pk_bf16_f32 v167, v30, v31
	v_cvt_pk_bf16_f32 v168, v24, v25
	v_cvt_pk_bf16_f32 v169, v26, v27
	flat_store_dwordx4 v[170:171], v[166:169] sc1
	s_nop 1
	v_cvt_pk_bf16_f32 v166, v20, v21
	v_cvt_pk_bf16_f32 v167, v22, v23
	v_cvt_pk_bf16_f32 v168, v16, v17
	v_cvt_pk_bf16_f32 v169, v18, v19
	flat_store_dwordx4 v[170:171], v[166:169] offset:256 sc1
	s_nop 1
	v_lshlrev_b64 v[166:167], 12, v[140:141]
	v_lshl_add_u64 v[146:147], v[146:147], 0, v[166:167]
	v_cvt_pk_bf16_f32 v166, v12, v13
	v_cvt_pk_bf16_f32 v167, v14, v15
	v_cvt_pk_bf16_f32 v168, v8, v9
	v_cvt_pk_bf16_f32 v169, v10, v11
	flat_store_dwordx4 v[146:147], v[166:169] sc1
	s_nop 1
	v_cvt_pk_bf16_f32 v166, v4, v5
	v_cvt_pk_bf16_f32 v167, v6, v7
	v_cvt_pk_bf16_f32 v168, v0, v1
	v_cvt_pk_bf16_f32 v169, v2, v3
	flat_store_dwordx4 v[146:147], v[166:169] offset:256 sc1
	s_cbranch_execnz .LBB0_1228
.LBB0_1227:
	v_lshl_add_u32 v146, v165, 3, s72
	s_ashr_i32 s51, s50, 31
	v_ashrrev_i32_e32 v147, 31, v146
	v_lshlrev_b64 v[156:157], 11, v[156:157]
	s_lshl_b64 s[50:51], s[50:51], 12
	v_lshl_add_u64 v[156:157], v[156:157], 0, v[146:147]
	s_add_u32 s50, s67, s50
	s_addc_u32 s51, s68, s51
	v_lshlrev_b64 v[156:157], 1, v[156:157]
	v_lshl_add_u64 v[166:167], s[50:51], 0, v[156:157]
	s_lshl_b64 s[52:53], s[48:49], 1
	v_lshl_add_u64 v[170:171], v[166:167], 0, s[52:53]
	flat_load_dwordx4 v[166:169], v[170:171]
	s_add_u32 s48, s50, s52
	s_addc_u32 s49, s51, s53
	v_lshl_add_u64 v[156:157], s[48:49], 0, v[156:157]
	v_ashrrev_i32_e32 v155, 31, v154
	v_lshlrev_b64 v[154:155], 11, v[154:155]
	v_lshl_add_u64 v[154:155], v[154:155], 0, v[146:147]
	v_lshlrev_b64 v[154:155], 1, v[154:155]
	v_ashrrev_i32_e32 v153, 31, v152
	v_ashrrev_i32_e32 v151, 31, v150
	v_ashrrev_i32_e32 v149, 31, v148
	v_ashrrev_i32_e32 v145, 31, v144
	v_ashrrev_i32_e32 v143, 31, v142
	v_ashrrev_i32_e32 v141, 31, v140
	s_waitcnt vmcnt(0) lgkmcnt(0)
	v_lshlrev_b32_e32 v172, 16, v166
	v_and_b32_e32 v173, 0xffff0000, v166
	v_lshlrev_b32_e32 v166, 16, v167
	v_and_b32_e32 v167, 0xffff0000, v167
	v_lshlrev_b32_e32 v174, 16, v168
	v_and_b32_e32 v175, 0xffff0000, v168
	v_lshlrev_b32_e32 v168, 16, v169
	v_and_b32_e32 v169, 0xffff0000, v169
	v_pk_add_f32 v[126:127], v[126:127], v[166:167]
	v_pk_add_f32 v[124:125], v[124:125], v[172:173]
	v_pk_add_f32 v[166:167], v[122:123], v[168:169]
	v_pk_add_f32 v[122:123], v[120:121], v[174:175]
	v_cvt_pk_bf16_f32 v120, v124, v125
	v_cvt_pk_bf16_f32 v121, v126, v127
	s_nop 0
	v_cvt_pk_bf16_f32 v122, v122, v123
	v_cvt_pk_bf16_f32 v123, v166, v167
	flat_load_dwordx4 v[124:127], v[156:157] offset:256
	v_lshl_add_u64 v[166:167], s[50:51], 0, v[154:155]
	flat_store_dwordx4 v[170:171], v[120:123] sc1
	v_lshl_add_u64 v[166:167], v[166:167], 0, s[52:53]
	s_waitcnt vmcnt(0) lgkmcnt(0)
	v_lshlrev_b32_e32 v120, 16, v124
	v_and_b32_e32 v121, 0xffff0000, v124
	v_lshlrev_b32_e32 v122, 16, v125
	v_and_b32_e32 v123, 0xffff0000, v125
	v_lshlrev_b32_e32 v124, 16, v126
	v_and_b32_e32 v125, 0xffff0000, v126
	v_lshlrev_b32_e32 v126, 16, v127
	v_and_b32_e32 v127, 0xffff0000, v127
	v_pk_add_f32 v[116:117], v[116:117], v[120:121]
	v_pk_add_f32 v[120:121], v[114:115], v[126:127]
	v_pk_add_f32 v[114:115], v[112:113], v[124:125]
	v_pk_add_f32 v[118:119], v[118:119], v[122:123]
	v_cvt_pk_bf16_f32 v112, v116, v117
	v_lshl_add_u64 v[116:117], s[48:49], 0, v[154:155]
	v_cvt_pk_bf16_f32 v113, v118, v119
	v_cvt_pk_bf16_f32 v114, v114, v115
	v_cvt_pk_bf16_f32 v115, v120, v121
	flat_store_dwordx4 v[156:157], v[112:115] offset:256 sc1
	flat_load_dwordx4 v[112:115], v[166:167]
	s_waitcnt vmcnt(0) lgkmcnt(0)
	v_lshlrev_b32_e32 v118, 16, v112
	v_and_b32_e32 v119, 0xffff0000, v112
	v_lshlrev_b32_e32 v112, 16, v113
	v_and_b32_e32 v113, 0xffff0000, v113
	v_lshlrev_b32_e32 v120, 16, v114
	v_and_b32_e32 v121, 0xffff0000, v114
	v_lshlrev_b32_e32 v114, 16, v115
	v_and_b32_e32 v115, 0xffff0000, v115
	v_pk_add_f32 v[110:111], v[110:111], v[112:113]
	v_pk_add_f32 v[108:109], v[108:109], v[118:119]
	v_pk_add_f32 v[112:113], v[106:107], v[114:115]
	v_pk_add_f32 v[106:107], v[104:105], v[120:121]
	v_cvt_pk_bf16_f32 v104, v108, v109
	v_cvt_pk_bf16_f32 v105, v110, v111
	s_nop 0
	v_cvt_pk_bf16_f32 v106, v106, v107
	v_cvt_pk_bf16_f32 v107, v112, v113
	flat_load_dwordx4 v[108:111], v[116:117] offset:256
	v_lshlrev_b64 v[112:113], 11, v[152:153]
	v_lshl_add_u64 v[112:113], v[112:113], 0, v[146:147]
	v_lshlrev_b64 v[112:113], 1, v[112:113]
	flat_store_dwordx4 v[166:167], v[104:107] sc1
	v_lshl_add_u64 v[114:115], s[50:51], 0, v[112:113]
	v_lshl_add_u64 v[114:115], v[114:115], 0, s[52:53]
	s_waitcnt vmcnt(0) lgkmcnt(0)
	v_lshlrev_b32_e32 v104, 16, v108
	v_and_b32_e32 v105, 0xffff0000, v108
	v_lshlrev_b32_e32 v106, 16, v109
	v_and_b32_e32 v107, 0xffff0000, v109
	v_lshlrev_b32_e32 v108, 16, v110
	v_and_b32_e32 v109, 0xffff0000, v110
	v_lshlrev_b32_e32 v110, 16, v111
	v_and_b32_e32 v111, 0xffff0000, v111
	v_pk_add_f32 v[100:101], v[100:101], v[104:105]
	v_pk_add_f32 v[104:105], v[98:99], v[110:111]
	v_pk_add_f32 v[98:99], v[96:97], v[108:109]
	v_pk_add_f32 v[102:103], v[102:103], v[106:107]
	v_cvt_pk_bf16_f32 v96, v100, v101
	v_lshl_add_u64 v[100:101], s[48:49], 0, v[112:113]
	v_cvt_pk_bf16_f32 v97, v102, v103
	v_cvt_pk_bf16_f32 v98, v98, v99
	v_cvt_pk_bf16_f32 v99, v104, v105
	flat_store_dwordx4 v[116:117], v[96:99] offset:256 sc1
	flat_load_dwordx4 v[96:99], v[114:115]
	s_waitcnt vmcnt(0) lgkmcnt(0)
	v_lshlrev_b32_e32 v102, 16, v96
	v_and_b32_e32 v103, 0xffff0000, v96
	v_lshlrev_b32_e32 v96, 16, v97
	v_and_b32_e32 v97, 0xffff0000, v97
	v_lshlrev_b32_e32 v104, 16, v98
	v_and_b32_e32 v105, 0xffff0000, v98
	v_lshlrev_b32_e32 v98, 16, v99
	v_and_b32_e32 v99, 0xffff0000, v99
	v_pk_add_f32 v[94:95], v[94:95], v[96:97]
	v_pk_add_f32 v[92:93], v[92:93], v[102:103]
	v_pk_add_f32 v[96:97], v[90:91], v[98:99]
	v_pk_add_f32 v[90:91], v[88:89], v[104:105]
	v_cvt_pk_bf16_f32 v88, v92, v93
	v_cvt_pk_bf16_f32 v89, v94, v95
	s_nop 0
	v_cvt_pk_bf16_f32 v90, v90, v91
	v_cvt_pk_bf16_f32 v91, v96, v97
	flat_load_dwordx4 v[92:95], v[100:101] offset:256
	v_lshlrev_b64 v[96:97], 11, v[150:151]
	v_lshl_add_u64 v[96:97], v[96:97], 0, v[146:147]
	v_lshlrev_b64 v[96:97], 1, v[96:97]
	flat_store_dwordx4 v[114:115], v[88:91] sc1
	v_lshl_add_u64 v[98:99], s[50:51], 0, v[96:97]
	v_lshl_add_u64 v[98:99], v[98:99], 0, s[52:53]
	s_waitcnt vmcnt(0) lgkmcnt(0)
	v_lshlrev_b32_e32 v88, 16, v92
	v_and_b32_e32 v89, 0xffff0000, v92
	v_lshlrev_b32_e32 v90, 16, v93
	v_and_b32_e32 v91, 0xffff0000, v93
	v_lshlrev_b32_e32 v92, 16, v94
	v_and_b32_e32 v93, 0xffff0000, v94
	v_lshlrev_b32_e32 v94, 16, v95
	v_and_b32_e32 v95, 0xffff0000, v95
	v_pk_add_f32 v[84:85], v[84:85], v[88:89]
	v_pk_add_f32 v[88:89], v[82:83], v[94:95]
	v_pk_add_f32 v[82:83], v[80:81], v[92:93]
	v_pk_add_f32 v[86:87], v[86:87], v[90:91]
	v_cvt_pk_bf16_f32 v80, v84, v85
	v_lshl_add_u64 v[84:85], s[48:49], 0, v[96:97]
	v_cvt_pk_bf16_f32 v81, v86, v87
	v_cvt_pk_bf16_f32 v82, v82, v83
	v_cvt_pk_bf16_f32 v83, v88, v89
	flat_store_dwordx4 v[100:101], v[80:83] offset:256 sc1
	flat_load_dwordx4 v[80:83], v[98:99]
	s_waitcnt vmcnt(0) lgkmcnt(0)
	v_lshlrev_b32_e32 v86, 16, v80
	v_and_b32_e32 v87, 0xffff0000, v80
	v_lshlrev_b32_e32 v80, 16, v81
	v_and_b32_e32 v81, 0xffff0000, v81
	v_lshlrev_b32_e32 v88, 16, v82
	v_and_b32_e32 v89, 0xffff0000, v82
	v_lshlrev_b32_e32 v82, 16, v83
	v_and_b32_e32 v83, 0xffff0000, v83
	v_pk_add_f32 v[78:79], v[78:79], v[80:81]
	v_pk_add_f32 v[76:77], v[76:77], v[86:87]
	v_pk_add_f32 v[80:81], v[74:75], v[82:83]
	v_pk_add_f32 v[74:75], v[72:73], v[88:89]
	v_cvt_pk_bf16_f32 v72, v76, v77
	v_cvt_pk_bf16_f32 v73, v78, v79
	s_nop 0
	v_cvt_pk_bf16_f32 v74, v74, v75
	v_cvt_pk_bf16_f32 v75, v80, v81
	flat_load_dwordx4 v[76:79], v[84:85] offset:256
	v_lshlrev_b64 v[80:81], 11, v[148:149]
	v_lshl_add_u64 v[80:81], v[80:81], 0, v[146:147]
	v_lshlrev_b64 v[80:81], 1, v[80:81]
	flat_store_dwordx4 v[98:99], v[72:75] sc1
	v_lshl_add_u64 v[82:83], s[50:51], 0, v[80:81]
	v_lshl_add_u64 v[82:83], v[82:83], 0, s[52:53]
	s_waitcnt vmcnt(0) lgkmcnt(0)
	v_lshlrev_b32_e32 v72, 16, v76
	v_and_b32_e32 v73, 0xffff0000, v76
	v_lshlrev_b32_e32 v74, 16, v77
	v_and_b32_e32 v75, 0xffff0000, v77
	v_lshlrev_b32_e32 v76, 16, v78
	v_and_b32_e32 v77, 0xffff0000, v78
	v_lshlrev_b32_e32 v78, 16, v79
	v_and_b32_e32 v79, 0xffff0000, v79
	v_pk_add_f32 v[68:69], v[68:69], v[72:73]
	v_pk_add_f32 v[72:73], v[66:67], v[78:79]
	v_pk_add_f32 v[66:67], v[64:65], v[76:77]
	v_pk_add_f32 v[70:71], v[70:71], v[74:75]
	v_cvt_pk_bf16_f32 v64, v68, v69
	v_lshl_add_u64 v[68:69], s[48:49], 0, v[80:81]
	v_cvt_pk_bf16_f32 v65, v70, v71
	v_cvt_pk_bf16_f32 v66, v66, v67
	v_cvt_pk_bf16_f32 v67, v72, v73
	flat_store_dwordx4 v[84:85], v[64:67] offset:256 sc1
	flat_load_dwordx4 v[64:67], v[82:83]
	s_waitcnt vmcnt(0) lgkmcnt(0)
	v_lshlrev_b32_e32 v70, 16, v64
	v_and_b32_e32 v71, 0xffff0000, v64
	v_lshlrev_b32_e32 v64, 16, v65
	v_and_b32_e32 v65, 0xffff0000, v65
	v_lshlrev_b32_e32 v72, 16, v66
	v_and_b32_e32 v73, 0xffff0000, v66
	v_lshlrev_b32_e32 v66, 16, v67
	v_and_b32_e32 v67, 0xffff0000, v67
	v_pk_add_f32 v[62:63], v[62:63], v[64:65]
	v_pk_add_f32 v[60:61], v[60:61], v[70:71]
	v_pk_add_f32 v[64:65], v[58:59], v[66:67]
	v_pk_add_f32 v[58:59], v[56:57], v[72:73]
	v_cvt_pk_bf16_f32 v56, v60, v61
	v_cvt_pk_bf16_f32 v57, v62, v63
	s_nop 0
	v_cvt_pk_bf16_f32 v58, v58, v59
	v_cvt_pk_bf16_f32 v59, v64, v65
	flat_load_dwordx4 v[60:63], v[68:69] offset:256
	v_lshlrev_b64 v[64:65], 11, v[144:145]
	v_lshl_add_u64 v[64:65], v[64:65], 0, v[146:147]
	v_lshlrev_b64 v[64:65], 1, v[64:65]
	flat_store_dwordx4 v[82:83], v[56:59] sc1
	v_lshl_add_u64 v[66:67], s[50:51], 0, v[64:65]
	v_lshl_add_u64 v[66:67], v[66:67], 0, s[52:53]
	s_waitcnt vmcnt(0) lgkmcnt(0)
	v_lshlrev_b32_e32 v56, 16, v60
	v_and_b32_e32 v57, 0xffff0000, v60
	v_lshlrev_b32_e32 v58, 16, v61
	v_and_b32_e32 v59, 0xffff0000, v61
	v_lshlrev_b32_e32 v60, 16, v62
	v_and_b32_e32 v61, 0xffff0000, v62
	v_lshlrev_b32_e32 v62, 16, v63
	v_and_b32_e32 v63, 0xffff0000, v63
	v_pk_add_f32 v[52:53], v[52:53], v[56:57]
	v_pk_add_f32 v[56:57], v[50:51], v[62:63]
	v_pk_add_f32 v[50:51], v[48:49], v[60:61]
	v_pk_add_f32 v[54:55], v[54:55], v[58:59]
	v_cvt_pk_bf16_f32 v48, v52, v53
	v_lshl_add_u64 v[52:53], s[48:49], 0, v[64:65]
	v_cvt_pk_bf16_f32 v49, v54, v55
	v_cvt_pk_bf16_f32 v50, v50, v51
	v_cvt_pk_bf16_f32 v51, v56, v57
	flat_store_dwordx4 v[68:69], v[48:51] offset:256 sc1
	flat_load_dwordx4 v[48:51], v[66:67]
	s_waitcnt vmcnt(0) lgkmcnt(0)
	v_lshlrev_b32_e32 v54, 16, v48
	v_and_b32_e32 v55, 0xffff0000, v48
	v_lshlrev_b32_e32 v48, 16, v49
	v_and_b32_e32 v49, 0xffff0000, v49
	v_lshlrev_b32_e32 v56, 16, v50
	v_and_b32_e32 v57, 0xffff0000, v50
	v_lshlrev_b32_e32 v50, 16, v51
	v_and_b32_e32 v51, 0xffff0000, v51
	v_pk_add_f32 v[46:47], v[46:47], v[48:49]
	v_pk_add_f32 v[44:45], v[44:45], v[54:55]
	v_pk_add_f32 v[48:49], v[42:43], v[50:51]
	v_pk_add_f32 v[42:43], v[40:41], v[56:57]
	v_cvt_pk_bf16_f32 v40, v44, v45
	v_cvt_pk_bf16_f32 v41, v46, v47
	s_nop 0
	v_cvt_pk_bf16_f32 v42, v42, v43
	v_cvt_pk_bf16_f32 v43, v48, v49
	flat_load_dwordx4 v[44:47], v[52:53] offset:256
	v_lshlrev_b64 v[48:49], 11, v[142:143]
	v_lshl_add_u64 v[48:49], v[48:49], 0, v[146:147]
	v_lshlrev_b64 v[48:49], 1, v[48:49]
	flat_store_dwordx4 v[66:67], v[40:43] sc1
	v_lshl_add_u64 v[50:51], s[50:51], 0, v[48:49]
	v_lshl_add_u64 v[50:51], v[50:51], 0, s[52:53]
	s_waitcnt vmcnt(0) lgkmcnt(0)
	v_lshlrev_b32_e32 v40, 16, v44
	v_and_b32_e32 v41, 0xffff0000, v44
	v_lshlrev_b32_e32 v42, 16, v45
	v_and_b32_e32 v43, 0xffff0000, v45
	v_lshlrev_b32_e32 v44, 16, v46
	v_and_b32_e32 v45, 0xffff0000, v46
	v_lshlrev_b32_e32 v46, 16, v47
	v_and_b32_e32 v47, 0xffff0000, v47
	v_pk_add_f32 v[36:37], v[36:37], v[40:41]
	v_pk_add_f32 v[40:41], v[34:35], v[46:47]
	v_pk_add_f32 v[34:35], v[32:33], v[44:45]
	v_pk_add_f32 v[38:39], v[38:39], v[42:43]
	v_cvt_pk_bf16_f32 v32, v36, v37
	v_lshl_add_u64 v[36:37], s[48:49], 0, v[48:49]
	v_cvt_pk_bf16_f32 v33, v38, v39
	v_cvt_pk_bf16_f32 v34, v34, v35
	v_cvt_pk_bf16_f32 v35, v40, v41
	flat_store_dwordx4 v[52:53], v[32:35] offset:256 sc1
	flat_load_dwordx4 v[32:35], v[50:51]
	s_waitcnt vmcnt(0) lgkmcnt(0)
	v_lshlrev_b32_e32 v38, 16, v32
	v_and_b32_e32 v39, 0xffff0000, v32
	v_lshlrev_b32_e32 v32, 16, v33
	v_and_b32_e32 v33, 0xffff0000, v33
	v_lshlrev_b32_e32 v40, 16, v34
	v_and_b32_e32 v41, 0xffff0000, v34
	v_lshlrev_b32_e32 v34, 16, v35
	v_and_b32_e32 v35, 0xffff0000, v35
	v_pk_add_f32 v[30:31], v[30:31], v[32:33]
	v_pk_add_f32 v[28:29], v[28:29], v[38:39]
	v_pk_add_f32 v[32:33], v[26:27], v[34:35]
	v_pk_add_f32 v[26:27], v[24:25], v[40:41]
	v_cvt_pk_bf16_f32 v24, v28, v29
	v_cvt_pk_bf16_f32 v25, v30, v31
	s_nop 0
	v_cvt_pk_bf16_f32 v26, v26, v27
	v_cvt_pk_bf16_f32 v27, v32, v33
	flat_load_dwordx4 v[28:31], v[36:37] offset:256
	v_lshlrev_b64 v[32:33], 11, v[140:141]
	v_lshl_add_u64 v[32:33], v[32:33], 0, v[146:147]
	v_lshlrev_b64 v[32:33], 1, v[32:33]
	flat_store_dwordx4 v[50:51], v[24:27] sc1
	v_lshl_add_u64 v[34:35], s[50:51], 0, v[32:33]
	v_lshl_add_u64 v[34:35], v[34:35], 0, s[52:53]
	s_waitcnt vmcnt(0) lgkmcnt(0)
	v_lshlrev_b32_e32 v24, 16, v28
	v_and_b32_e32 v25, 0xffff0000, v28
	v_lshlrev_b32_e32 v26, 16, v29
	v_and_b32_e32 v27, 0xffff0000, v29
	v_lshlrev_b32_e32 v28, 16, v30
	v_and_b32_e32 v29, 0xffff0000, v30
	v_lshlrev_b32_e32 v30, 16, v31
	v_and_b32_e32 v31, 0xffff0000, v31
	v_pk_add_f32 v[20:21], v[20:21], v[24:25]
	v_pk_add_f32 v[24:25], v[18:19], v[30:31]
	v_pk_add_f32 v[18:19], v[16:17], v[28:29]
	v_pk_add_f32 v[22:23], v[22:23], v[26:27]
	v_cvt_pk_bf16_f32 v16, v20, v21
	v_lshl_add_u64 v[20:21], s[48:49], 0, v[32:33]
	v_cvt_pk_bf16_f32 v17, v22, v23
	v_cvt_pk_bf16_f32 v18, v18, v19
	v_cvt_pk_bf16_f32 v19, v24, v25
	flat_store_dwordx4 v[36:37], v[16:19] offset:256 sc1
	flat_load_dwordx4 v[16:19], v[34:35]
	s_waitcnt vmcnt(0) lgkmcnt(0)
	v_lshlrev_b32_e32 v22, 16, v16
	v_and_b32_e32 v23, 0xffff0000, v16
	v_lshlrev_b32_e32 v16, 16, v17
	v_and_b32_e32 v17, 0xffff0000, v17
	v_lshlrev_b32_e32 v24, 16, v18
	v_and_b32_e32 v25, 0xffff0000, v18
	v_lshlrev_b32_e32 v18, 16, v19
	v_and_b32_e32 v19, 0xffff0000, v19
	v_pk_add_f32 v[14:15], v[14:15], v[16:17]
	v_pk_add_f32 v[12:13], v[12:13], v[22:23]
	v_pk_add_f32 v[16:17], v[10:11], v[18:19]
	v_pk_add_f32 v[10:11], v[8:9], v[24:25]
	v_cvt_pk_bf16_f32 v8, v12, v13
	v_cvt_pk_bf16_f32 v9, v14, v15
	s_nop 0
	v_cvt_pk_bf16_f32 v10, v10, v11
	v_cvt_pk_bf16_f32 v11, v16, v17
	flat_load_dwordx4 v[12:15], v[20:21] offset:256
	s_nop 0
	flat_store_dwordx4 v[34:35], v[8:11] sc1
	s_waitcnt vmcnt(0) lgkmcnt(0)
	s_nop 0
	v_lshlrev_b32_e32 v8, 16, v12
	v_and_b32_e32 v9, 0xffff0000, v12
	v_lshlrev_b32_e32 v10, 16, v13
	v_and_b32_e32 v11, 0xffff0000, v13
	v_lshlrev_b32_e32 v12, 16, v14
	v_and_b32_e32 v13, 0xffff0000, v14
	v_lshlrev_b32_e32 v14, 16, v15
	v_and_b32_e32 v15, 0xffff0000, v15
	v_pk_add_f32 v[4:5], v[4:5], v[8:9]
	v_pk_add_f32 v[8:9], v[2:3], v[14:15]
	v_pk_add_f32 v[2:3], v[0:1], v[12:13]
	v_pk_add_f32 v[6:7], v[6:7], v[10:11]
	v_cvt_pk_bf16_f32 v0, v4, v5
	s_nop 0
	v_cvt_pk_bf16_f32 v1, v6, v7
	v_cvt_pk_bf16_f32 v2, v2, v3
	v_cvt_pk_bf16_f32 v3, v8, v9
	flat_store_dwordx4 v[20:21], v[0:3] offset:256 sc1
